# all 16-byte global stores made write-through (sc1) so the XCD L2 holds little dirty data at each grid barrier release
# baseline (speedup 1.0000x reference)
; __device__ __forceinline__ int pg8_opaque_tid() { int t = threadIdx.x; asm volatile("" : "+v"(t)); return t; }
; __device__ __forceinline__ void final_norm(float* x, const float* g) {
;     const int tid = pg8::pg8_opaque_tid(), lane = tid & 63, wid = __builtin_amdgcn_readfirstlane(tid >> 6);
;     const int gw = blockIdx.x * 8 + wid, NGW = gridDim.x * 8;
;     f32x4 gv[4];
; #pragma unroll
;     for (int j = 0; j < 4; ++j) gv[j] = *((const f32x4*)g + lane + 64 * j);
;     for (int row0 = gw; row0 < S; row0 += 2 * NGW) {
;         f32x4 v[2][4];
; #pragma unroll
;         for (int h = 0; h < 2; ++h)
; #pragma unroll
;             for (int j = 0; j < 4; ++j) v[h][j] = *((const f32x4*)(x + (size_t)(row0 + h * NGW) * DM) + lane + 64 * j);
; #pragma unroll
;         for (int h = 0; h < 2; ++h) {
;             f32x4* xr = (f32x4*)(x + (size_t)(row0 + h * NGW) * DM) + lane; float ss = 0.f;
; #pragma unroll
;             for (int j = 0; j < 4; ++j) ss += (v[h][j].x * v[h][j].x + v[h][j].y * v[h][j].y) + (v[h][j].z * v[h][j].z + v[h][j].w * v[h][j].w);
;             const float rstd = 1.0f / sqrtf(wave_sum(ss) * (1.0f / DM) + 1e-6f);
; #pragma unroll
;             for (int j = 0; j < 4; ++j) xr[64 * j] = v[h][j] * rstd * gv[j];
.LBB0_18:
	s_ashr_i32 s1, s0, 31
	s_lshl_b64 s[10:11], s[0:1], 12
	v_lshl_add_u64 v[60:61], v[32:33], 0, s[10:11]
	global_load_dwordx4 v[44:47], v[60:61], off
	global_load_dwordx4 v[48:51], v[60:61], off offset:1024
	global_load_dwordx4 v[52:55], v[60:61], off offset:2048
	global_load_dwordx4 v[56:59], v[60:61], off offset:3072
	s_add_i32 s10, s0, s8
	s_ashr_i32 s11, s10, 31
	s_lshl_b64 s[0:1], s[10:11], 12
	v_lshl_add_u64 v[36:37], v[32:33], 0, s[0:1]
	global_load_dwordx4 v[28:31], v[36:37], off
	global_load_dwordx4 v[24:27], v[36:37], off offset:1024
	global_load_dwordx4 v[20:23], v[36:37], off offset:2048
	global_load_dwordx4 v[16:19], v[36:37], off offset:3072
	v_readlane_b32 s8, v252, 10
	s_waitcnt vmcnt(0)
	v_pk_mul_f32 v[62:63], v[46:47], v[46:47]
	v_pk_mul_f32 v[64:65], v[44:45], v[44:45]
	s_waitcnt vmcnt(4)
	v_mul_f32_e32 v43, v56, v56
	v_pk_mov_b32 v[66:67], v[64:65], v[62:63] op_sel:[1,0]
	v_mov_b32_e32 v65, v63
	v_pk_add_f32 v[62:63], v[66:67], v[64:65]
	v_pk_mul_f32 v[64:65], v[50:51], v[50:51]
	v_pk_mul_f32 v[66:67], v[48:49], v[48:49]
	v_pk_add_f32 v[62:63], v[62:63], v[62:63] op_sel:[0,1] op_sel_hi:[1,0]
	v_pk_mov_b32 v[68:69], v[66:67], v[64:65] op_sel:[1,0]
	v_mov_b32_e32 v67, v65
	v_pk_add_f32 v[64:65], v[68:69], v[66:67]
	v_mul_f32_e32 v66, v57, v57
	v_pk_add_f32 v[64:65], v[64:65], v[64:65] op_sel:[0,1] op_sel_hi:[1,0]
	v_mov_b32_e32 v63, v43
	v_mov_b32_e32 v65, v66
	v_pk_add_f32 v[62:63], v[62:63], v[64:65]
	v_mul_f32_e32 v64, v53, v53
	v_mul_f32_e32 v67, v58, v58
	v_pk_fma_f32 v[64:65], v[52:53], v[52:53], v[64:65] op_sel_hi:[1,1,0]
	v_mul_f32_e32 v66, v55, v55
	v_mul_f32_e32 v68, v59, v59
	v_mov_b32_e32 v65, v67
	v_pk_fma_f32 v[66:67], v[54:55], v[54:55], v[66:67] op_sel_hi:[1,1,0]
	s_nop 0
	v_mov_b32_e32 v67, v68
	v_pk_add_f32 v[64:65], v[64:65], v[66:67]
	s_nop 0
	v_pk_add_f32 v[62:63], v[62:63], v[64:65]
	s_nop 0
	v_add_f32_e32 v43, v62, v63
	ds_bpermute_b32 v62, v35, v43
	s_waitcnt lgkmcnt(0)
	v_add_f32_e32 v43, v43, v62
	ds_bpermute_b32 v62, v38, v43
	s_waitcnt lgkmcnt(0)
	v_add_f32_e32 v43, v43, v62
	ds_bpermute_b32 v62, v39, v43
	s_waitcnt lgkmcnt(0)
	v_add_f32_e32 v43, v43, v62
	ds_bpermute_b32 v62, v40, v43
	s_waitcnt lgkmcnt(0)
	v_add_f32_e32 v43, v43, v62
	ds_bpermute_b32 v62, v41, v43
	s_waitcnt lgkmcnt(0)
	v_add_f32_e32 v43, v43, v62
	ds_bpermute_b32 v62, v42, v43
	s_waitcnt lgkmcnt(0)
	v_add_f32_e32 v43, v43, v62
	v_fmamk_f32 v43, v43, 0x3a800000, v229
	v_cmp_gt_f32_e32 vcc, s12, v43
	v_mul_f32_e32 v62, 0x4f800000, v43
	s_nop 0
	v_cndmask_b32_e32 v43, v43, v62, vcc
	v_sqrt_f32_e32 v62, v43
	s_nop 0
	v_add_u32_e32 v63, -1, v62
	v_fma_f32 v64, -v63, v62, v43
	v_cmp_ge_f32_e64 s[0:1], 0, v64
	v_add_u32_e32 v64, 1, v62
	s_nop 0
	v_cndmask_b32_e64 v63, v62, v63, s[0:1]
	v_fma_f32 v62, -v64, v62, v43
	v_cmp_lt_f32_e64 s[0:1], 0, v62
	s_nop 1
	v_cndmask_b32_e64 v62, v63, v64, s[0:1]
	v_mul_f32_e32 v63, 0x37800000, v62
	v_cndmask_b32_e32 v62, v62, v63, vcc
	v_cmp_class_f32_e32 vcc, v43, v230
	s_nop 1
	v_cndmask_b32_e32 v43, v62, v43, vcc
	v_div_scale_f32 v62, s[0:1], v43, v43, 1.0
	v_rcp_f32_e32 v63, v62
	s_nop 0
	v_fma_f32 v64, -v62, v63, 1.0
	v_fmac_f32_e32 v63, v64, v63
	v_div_scale_f32 v64, vcc, 1.0, v43, 1.0
	v_mul_f32_e32 v65, v64, v63
	v_fma_f32 v66, -v62, v65, v64
	v_fmac_f32_e32 v65, v66, v63
	v_fma_f32 v62, -v62, v65, v64
	v_div_fmas_f32 v62, v62, v63, v65
	v_div_fixup_f32 v62, v62, v43, 1.0
	v_pk_mul_f32 v[44:45], v[44:45], v[62:63] op_sel_hi:[1,0]
	v_pk_mul_f32 v[46:47], v[46:47], v[62:63] op_sel_hi:[1,0]
	v_pk_mul_f32 v[44:45], v[0:1], v[44:45]
	v_pk_mul_f32 v[46:47], v[2:3], v[46:47]
	global_store_dwordx4 v[60:61], v[44:47], off sc1
	s_waitcnt vmcnt(1)
; __device__ __forceinline__ void final_norm(float* x, const float* g) {
;     ...
;         for (int h = 0; h < 2; ++h) {
;             f32x4* xr = (f32x4*)(x + (size_t)(row0 + h * NGW) * DM) + lane; float ss = 0.f;
; #pragma unroll
;             for (int j = 0; j < 4; ++j) ss += (v[h][j].x * v[h][j].x + v[h][j].y * v[h][j].y) + (v[h][j].z * v[h][j].z + v[h][j].w * v[h][j].w);
;             const float rstd = 1.0f / sqrtf(wave_sum(ss) * (1.0f / DM) + 1e-6f);
; #pragma unroll
;             for (int j = 0; j < 4; ++j) xr[64 * j] = v[h][j] * rstd * gv[j];
;         }
	v_mul_f32_e32 v43, v16, v16
	v_pk_mul_f32 v[44:45], v[48:49], v[62:63] op_sel_hi:[1,0]
	v_pk_mul_f32 v[46:47], v[50:51], v[62:63] op_sel_hi:[1,0]
	v_pk_mul_f32 v[44:45], v[4:5], v[44:45]
	v_pk_mul_f32 v[46:47], v[6:7], v[46:47]
	global_store_dwordx4 v[60:61], v[44:47], off offset:1024 sc1
	s_nop 1
	v_pk_mul_f32 v[44:45], v[52:53], v[62:63] op_sel_hi:[1,0]
	v_pk_mul_f32 v[46:47], v[54:55], v[62:63] op_sel_hi:[1,0]
	v_pk_mul_f32 v[44:45], v[8:9], v[44:45]
	v_pk_mul_f32 v[46:47], v[10:11], v[46:47]
	global_store_dwordx4 v[60:61], v[44:47], off offset:2048 sc1
	s_nop 1
	v_pk_mul_f32 v[44:45], v[56:57], v[62:63] op_sel_hi:[1,0]
	v_pk_mul_f32 v[46:47], v[58:59], v[62:63] op_sel_hi:[1,0]
	v_pk_mul_f32 v[44:45], v[12:13], v[44:45]
	v_pk_mul_f32 v[46:47], v[14:15], v[46:47]
	global_store_dwordx4 v[60:61], v[44:47], off offset:3072 sc1
	s_nop 1
	v_pk_mul_f32 v[44:45], v[30:31], v[30:31]
	v_pk_mul_f32 v[46:47], v[28:29], v[28:29]
	s_nop 0
	v_pk_mov_b32 v[48:49], v[46:47], v[44:45] op_sel:[1,0]
	v_mov_b32_e32 v47, v45
	v_pk_add_f32 v[44:45], v[48:49], v[46:47]
	v_pk_mul_f32 v[46:47], v[26:27], v[26:27]
	v_pk_mul_f32 v[48:49], v[24:25], v[24:25]
	v_pk_add_f32 v[44:45], v[44:45], v[44:45] op_sel:[0,1] op_sel_hi:[1,0]
	v_pk_mov_b32 v[50:51], v[48:49], v[46:47] op_sel:[1,0]
	v_mov_b32_e32 v49, v47
	v_pk_add_f32 v[46:47], v[50:51], v[48:49]
	v_mul_f32_e32 v48, v17, v17
	v_pk_add_f32 v[46:47], v[46:47], v[46:47] op_sel:[0,1] op_sel_hi:[1,0]
	v_mov_b32_e32 v45, v43
	v_mov_b32_e32 v47, v48
	v_pk_add_f32 v[44:45], v[44:45], v[46:47]
	v_mul_f32_e32 v46, v21, v21
	v_mul_f32_e32 v49, v18, v18
	v_pk_fma_f32 v[46:47], v[20:21], v[20:21], v[46:47] op_sel_hi:[1,1,0]
	v_mul_f32_e32 v48, v23, v23
	v_mul_f32_e32 v50, v19, v19
	v_mov_b32_e32 v47, v49
	v_pk_fma_f32 v[48:49], v[22:23], v[22:23], v[48:49] op_sel_hi:[1,1,0]
	s_nop 0
	v_mov_b32_e32 v49, v50
	v_pk_add_f32 v[46:47], v[46:47], v[48:49]
	s_nop 0
	v_pk_add_f32 v[44:45], v[44:45], v[46:47]
	s_nop 0
	v_add_f32_e32 v43, v44, v45
	ds_bpermute_b32 v44, v35, v43
	s_waitcnt lgkmcnt(0)
	v_add_f32_e32 v43, v43, v44
	ds_bpermute_b32 v44, v38, v43
	s_waitcnt lgkmcnt(0)
	v_add_f32_e32 v43, v43, v44
	ds_bpermute_b32 v44, v39, v43
	s_waitcnt lgkmcnt(0)
	v_add_f32_e32 v43, v43, v44
	ds_bpermute_b32 v44, v40, v43
	s_waitcnt lgkmcnt(0)
	v_add_f32_e32 v43, v43, v44
	ds_bpermute_b32 v44, v41, v43
	s_waitcnt lgkmcnt(0)
	v_add_f32_e32 v43, v43, v44
	ds_bpermute_b32 v44, v42, v43
	s_waitcnt lgkmcnt(0)
	v_add_f32_e32 v43, v43, v44
	v_fmamk_f32 v43, v43, 0x3a800000, v229
	v_cmp_gt_f32_e32 vcc, s12, v43
	v_mul_f32_e32 v44, 0x4f800000, v43
	s_nop 0
	v_cndmask_b32_e32 v43, v43, v44, vcc
	v_sqrt_f32_e32 v44, v43
	s_nop 0
	v_add_u32_e32 v45, -1, v44
	v_fma_f32 v46, -v45, v44, v43
	v_cmp_ge_f32_e64 s[0:1], 0, v46
	v_add_u32_e32 v46, 1, v44
	s_nop 0
	v_cndmask_b32_e64 v45, v44, v45, s[0:1]
	v_fma_f32 v44, -v46, v44, v43
	v_cmp_lt_f32_e64 s[0:1], 0, v44
	s_nop 1
	v_cndmask_b32_e64 v44, v45, v46, s[0:1]
	v_mul_f32_e32 v45, 0x37800000, v44
	v_cndmask_b32_e32 v44, v44, v45, vcc
	v_cmp_class_f32_e32 vcc, v43, v230
	s_nop 1
	v_cndmask_b32_e32 v43, v44, v43, vcc
	v_div_scale_f32 v44, s[0:1], v43, v43, 1.0
	v_rcp_f32_e32 v45, v44
	s_add_i32 s0, s10, s8
	s_cmpk_gt_i32 s0, 0x3fff
	v_fma_f32 v46, -v44, v45, 1.0
	v_fmac_f32_e32 v45, v46, v45
	v_div_scale_f32 v46, vcc, 1.0, v43, 1.0
	v_mul_f32_e32 v47, v46, v45
	v_fma_f32 v48, -v44, v47, v46
	v_fmac_f32_e32 v47, v48, v45
	v_fma_f32 v44, -v44, v47, v46
	v_div_fmas_f32 v44, v44, v45, v47
	v_div_fixup_f32 v44, v44, v43, 1.0
	v_pk_mul_f32 v[28:29], v[28:29], v[44:45] op_sel_hi:[1,0]
	v_pk_mul_f32 v[30:31], v[30:31], v[44:45] op_sel_hi:[1,0]
	v_pk_mul_f32 v[24:25], v[24:25], v[44:45] op_sel_hi:[1,0]
	v_pk_mul_f32 v[26:27], v[26:27], v[44:45] op_sel_hi:[1,0]
	v_pk_mul_f32 v[20:21], v[20:21], v[44:45] op_sel_hi:[1,0]
	v_pk_mul_f32 v[22:23], v[22:23], v[44:45] op_sel_hi:[1,0]
	v_pk_mul_f32 v[16:17], v[16:17], v[44:45] op_sel_hi:[1,0]
	v_pk_mul_f32 v[18:19], v[18:19], v[44:45] op_sel_hi:[1,0]
	v_pk_mul_f32 v[30:31], v[2:3], v[30:31]
	v_pk_mul_f32 v[28:29], v[0:1], v[28:29]
	v_pk_mul_f32 v[26:27], v[6:7], v[26:27]
	v_pk_mul_f32 v[24:25], v[4:5], v[24:25]
	v_pk_mul_f32 v[22:23], v[10:11], v[22:23]
	v_pk_mul_f32 v[20:21], v[8:9], v[20:21]
	v_pk_mul_f32 v[18:19], v[14:15], v[18:19]
	v_pk_mul_f32 v[16:17], v[12:13], v[16:17]
	global_store_dwordx4 v[36:37], v[28:31], off sc1
	global_store_dwordx4 v[36:37], v[24:27], off offset:1024 sc1
	global_store_dwordx4 v[36:37], v[20:23], off offset:2048 sc1
	global_store_dwordx4 v[36:37], v[16:19], off offset:3072 sc1
	s_cbranch_scc0 .LBB0_18

; __device__ __forceinline__ unsigned pk2(float lo, float hi) { return pg8::cvt_pk_bf16(lo, hi); }
; __device__ __forceinline__ float bflo(unsigned w) { return __uint_as_float(w << 16); }
; __device__ __forceinline__ float bfhi(unsigned w) { return __uint_as_float(w & 0xffff0000u); }
;     __device__ __forceinline__ void operator()(const pg8::f32x4 (&acc)[2][2][4][2], const pg8::Unit& u, int wr, int wc, int fr, int fq) const {
;     ...
; #pragma unroll
;             for (int m = 0; m < 4; ++m)
; #pragma unroll
;                 for (int bj = 0; bj < 2; ++bj) {
;                     const int row = row0 + ai * 128 + m * 16;
;                     const u32x4 g = gv[m][bj], o = ov[m][bj]; const pg8::f32x4 a0 = acc[ai][bj][m][0], a1 = acc[ai][bj][m][1];
;                     u32x4 w; w.x = pk2(bflo(o.x) + bflo(g.x) * a0[0], bfhi(o.x) + bfhi(g.x) * a0[1]); w.y = pk2(bflo(o.y) + bflo(g.y) * a0[2], bfhi(o.y) + bfhi(g.y) * a0[3]);
;                     w.z = pk2(bflo(o.z) + bflo(g.z) * a1[0], bfhi(o.z) + bfhi(g.z) * a1[1]); w.w = pk2(bflo(o.w) + bflo(g.w) * a1[2], bfhi(o.w) + bfhi(g.w) * a1[3]);
;                     *(u32x4*)(mrg + (size_t)row * DM + col0 + bj * 128) = w;
;                 }
;             asm volatile("" ::: "memory");
;         }
.LBB0_68:
	s_waitcnt vmcnt(0)
	v_lshlrev_b32_e32 v226, 16, v192
	v_and_b32_e32 v227, 0xffff0000, v192
	v_lshlrev_b32_e32 v236, 16, v188
	v_and_b32_e32 v237, 0xffff0000, v188
	v_lshlrev_b32_e32 v192, 16, v193
	v_and_b32_e32 v193, 0xffff0000, v193
	v_lshlrev_b32_e32 v188, 16, v189
	v_and_b32_e32 v189, 0xffff0000, v189
	v_pk_fma_f32 v[128:129], v[128:129], v[236:237], v[226:227]
	v_pk_fma_f32 v[130:131], v[130:131], v[188:189], v[192:193]
	v_cvt_pk_bf16_f32 v128, v128, v129
	v_cvt_pk_bf16_f32 v129, v130, v131
	v_lshlrev_b32_e32 v130, 16, v194
	v_and_b32_e32 v131, 0xffff0000, v194
	v_lshlrev_b32_e32 v188, 16, v190
	v_and_b32_e32 v189, 0xffff0000, v190
	v_pk_fma_f32 v[124:125], v[124:125], v[188:189], v[130:131]
	v_lshlrev_b32_e32 v188, 16, v191
	v_cvt_pk_bf16_f32 v130, v124, v125
	v_lshlrev_b32_e32 v124, 16, v195
	v_and_b32_e32 v125, 0xffff0000, v195
	v_and_b32_e32 v189, 0xffff0000, v191
	v_pk_fma_f32 v[124:125], v[126:127], v[188:189], v[124:125]
	v_lshlrev_b32_e32 v126, 16, v172
	v_cvt_pk_bf16_f32 v131, v124, v125
	v_lshl_add_u64 v[124:125], s[34:35], 0, v[224:225]
	v_lshl_add_u64 v[124:125], v[124:125], 0, v[210:211]
	global_store_dwordx4 v[124:125], v[128:131], off sc1
	v_and_b32_e32 v127, 0xffff0000, v172
	s_and_b64 vcc, exec, s[0:1]
	v_lshlrev_b32_e32 v128, 16, v184
	v_and_b32_e32 v129, 0xffff0000, v184
	v_pk_fma_f32 v[120:121], v[120:121], v[128:129], v[126:127]
	v_lshlrev_b32_e32 v126, 16, v173
	v_and_b32_e32 v127, 0xffff0000, v173
	v_lshlrev_b32_e32 v128, 16, v185
	v_and_b32_e32 v129, 0xffff0000, v185
	v_pk_fma_f32 v[122:123], v[122:123], v[128:129], v[126:127]
	v_cvt_pk_bf16_f32 v120, v120, v121
	v_cvt_pk_bf16_f32 v121, v122, v123
	v_lshlrev_b32_e32 v122, 16, v174
	v_and_b32_e32 v123, 0xffff0000, v174
	v_lshlrev_b32_e32 v126, 16, v186
	v_and_b32_e32 v127, 0xffff0000, v186
	v_pk_fma_f32 v[112:113], v[112:113], v[126:127], v[122:123]
	v_lshlrev_b32_e32 v126, 16, v187
	v_cvt_pk_bf16_f32 v122, v112, v113
	v_lshlrev_b32_e32 v112, 16, v175
	v_and_b32_e32 v113, 0xffff0000, v175
	v_and_b32_e32 v127, 0xffff0000, v187
	v_pk_fma_f32 v[112:113], v[114:115], v[126:127], v[112:113]
	v_lshlrev_b32_e32 v114, 16, v176
	v_cvt_pk_bf16_f32 v123, v112, v113
	v_lshlrev_b32_e32 v112, 16, v180
	v_and_b32_e32 v113, 0xffff0000, v180
	v_and_b32_e32 v115, 0xffff0000, v176
	v_pk_fma_f32 v[112:113], v[116:117], v[114:115], v[112:113]
	v_lshlrev_b32_e32 v114, 16, v181
	v_and_b32_e32 v115, 0xffff0000, v181
	v_lshlrev_b32_e32 v116, 16, v177
	v_and_b32_e32 v117, 0xffff0000, v177
	v_pk_fma_f32 v[114:115], v[118:119], v[116:117], v[114:115]
	v_cvt_pk_bf16_f32 v112, v112, v113
	v_cvt_pk_bf16_f32 v113, v114, v115
	v_lshlrev_b32_e32 v114, 16, v182
	v_and_b32_e32 v115, 0xffff0000, v182
	v_lshlrev_b32_e32 v116, 16, v178
	v_and_b32_e32 v117, 0xffff0000, v178
	v_pk_fma_f32 v[108:109], v[108:109], v[116:117], v[114:115]
	v_lshlrev_b32_e32 v116, 16, v179
	v_cvt_pk_bf16_f32 v114, v108, v109
	v_lshlrev_b32_e32 v108, 16, v183
	v_and_b32_e32 v109, 0xffff0000, v183
	v_and_b32_e32 v117, 0xffff0000, v179
	v_pk_fma_f32 v[108:109], v[110:111], v[116:117], v[108:109]
	v_lshlrev_b32_e32 v110, 16, v160
	v_cvt_pk_bf16_f32 v115, v108, v109
	v_lshl_add_u64 v[108:109], s[34:35], 0, v[222:223]
	v_lshl_add_u64 v[108:109], v[108:109], 0, v[210:211]
	global_store_dwordx4 v[108:109], v[112:115], off sc1
	v_and_b32_e32 v111, 0xffff0000, v160
	global_store_dwordx4 v[124:125], v[120:123], off offset:256 sc1
	v_lshlrev_b32_e32 v112, 16, v168
	v_and_b32_e32 v113, 0xffff0000, v168
	v_pk_fma_f32 v[104:105], v[104:105], v[112:113], v[110:111]
	v_lshlrev_b32_e32 v110, 16, v161
	v_and_b32_e32 v111, 0xffff0000, v161
	v_lshlrev_b32_e32 v112, 16, v169
	v_and_b32_e32 v113, 0xffff0000, v169
	v_pk_fma_f32 v[106:107], v[106:107], v[112:113], v[110:111]
	v_cvt_pk_bf16_f32 v104, v104, v105
	v_cvt_pk_bf16_f32 v105, v106, v107
	v_lshlrev_b32_e32 v106, 16, v162
	v_and_b32_e32 v107, 0xffff0000, v162
	v_lshlrev_b32_e32 v110, 16, v170
	v_and_b32_e32 v111, 0xffff0000, v170
	v_pk_fma_f32 v[96:97], v[96:97], v[110:111], v[106:107]
	v_lshlrev_b32_e32 v110, 16, v171
	v_cvt_pk_bf16_f32 v106, v96, v97
	v_lshlrev_b32_e32 v96, 16, v163
	v_and_b32_e32 v97, 0xffff0000, v163
	v_and_b32_e32 v111, 0xffff0000, v171
	v_pk_fma_f32 v[96:97], v[98:99], v[110:111], v[96:97]
	v_lshlrev_b32_e32 v98, 16, v156
	v_cvt_pk_bf16_f32 v107, v96, v97
	v_lshlrev_b32_e32 v96, 16, v164
	v_and_b32_e32 v97, 0xffff0000, v164
	v_and_b32_e32 v99, 0xffff0000, v156
; __device__ __forceinline__ unsigned pk2(float lo, float hi) { return pg8::cvt_pk_bf16(lo, hi); }
; __device__ __forceinline__ float bflo(unsigned w) { return __uint_as_float(w << 16); }
; __device__ __forceinline__ float bfhi(unsigned w) { return __uint_as_float(w & 0xffff0000u); }
;     __device__ __forceinline__ void operator()(const pg8::f32x4 (&acc)[2][2][4][2], const pg8::Unit& u, int wr, int wc, int fr, int fq) const {
;     ...
;         for (int ai = 0; ai < 2; ++ai) {
;             u32x4 gv[4][2], ov[4][2];
; #pragma unroll
;             for (int m = 0; m < 4; ++m)
; #pragma unroll
;                 for (int bj = 0; bj < 2; ++bj) {
;                     const int row = row0 + ai * 128 + m * 16;
;                     gv[m][bj] = *(const u32x4*)(G + (size_t)row * NGATE + coloff + col0 + bj * 128);
;                     ov[m][bj] = (u32x4){0u, 0u, 0u, 0u}; if (!first) ov[m][bj] = *(const u32x4*)(mrg + (size_t)row * DM + col0 + bj * 128);
;                 }
;     ...
;                     const u32x4 g = gv[m][bj], o = ov[m][bj]; const pg8::f32x4 a0 = acc[ai][bj][m][0], a1 = acc[ai][bj][m][1];
;                     u32x4 w; w.x = pk2(bflo(o.x) + bflo(g.x) * a0[0], bfhi(o.x) + bfhi(g.x) * a0[1]); w.y = pk2(bflo(o.y) + bflo(g.y) * a0[2], bfhi(o.y) + bfhi(g.y) * a0[3]);
;                     w.z = pk2(bflo(o.z) + bflo(g.z) * a1[0], bfhi(o.z) + bfhi(g.z) * a1[1]); w.w = pk2(bflo(o.w) + bflo(g.w) * a1[2], bfhi(o.w) + bfhi(g.w) * a1[3]);
;                     *(u32x4*)(mrg + (size_t)row * DM + col0 + bj * 128) = w;
;                 }
;             asm volatile("" ::: "memory");
;         }
	v_pk_fma_f32 v[96:97], v[100:101], v[98:99], v[96:97]
	v_lshlrev_b32_e32 v98, 16, v165
	v_and_b32_e32 v99, 0xffff0000, v165
	v_lshlrev_b32_e32 v100, 16, v157
	v_and_b32_e32 v101, 0xffff0000, v157
	v_pk_fma_f32 v[98:99], v[102:103], v[100:101], v[98:99]
	v_cvt_pk_bf16_f32 v96, v96, v97
	v_cvt_pk_bf16_f32 v97, v98, v99
	v_lshlrev_b32_e32 v98, 16, v166
	v_and_b32_e32 v99, 0xffff0000, v166
	v_lshlrev_b32_e32 v100, 16, v158
	v_and_b32_e32 v101, 0xffff0000, v158
	v_pk_fma_f32 v[92:93], v[92:93], v[100:101], v[98:99]
	v_lshlrev_b32_e32 v100, 16, v159
	v_cvt_pk_bf16_f32 v98, v92, v93
	v_lshlrev_b32_e32 v92, 16, v167
	v_and_b32_e32 v93, 0xffff0000, v167
	v_and_b32_e32 v101, 0xffff0000, v159
	v_pk_fma_f32 v[92:93], v[94:95], v[100:101], v[92:93]
	v_lshlrev_b32_e32 v94, 16, v144
	v_cvt_pk_bf16_f32 v99, v92, v93
	v_lshl_add_u64 v[92:93], s[34:35], 0, v[220:221]
	v_lshl_add_u64 v[92:93], v[92:93], 0, v[210:211]
	global_store_dwordx4 v[92:93], v[96:99], off sc1
	v_and_b32_e32 v95, 0xffff0000, v144
	global_store_dwordx4 v[108:109], v[104:107], off offset:256 sc1
	v_lshlrev_b32_e32 v96, 16, v152
	v_and_b32_e32 v97, 0xffff0000, v152
	v_pk_fma_f32 v[88:89], v[88:89], v[96:97], v[94:95]
	v_lshlrev_b32_e32 v94, 16, v145
	v_and_b32_e32 v95, 0xffff0000, v145
	v_lshlrev_b32_e32 v96, 16, v153
	v_and_b32_e32 v97, 0xffff0000, v153
	v_pk_fma_f32 v[90:91], v[90:91], v[96:97], v[94:95]
	v_cvt_pk_bf16_f32 v88, v88, v89
	v_cvt_pk_bf16_f32 v89, v90, v91
	v_lshlrev_b32_e32 v90, 16, v146
	v_and_b32_e32 v91, 0xffff0000, v146
	v_lshlrev_b32_e32 v94, 16, v154
	v_and_b32_e32 v95, 0xffff0000, v154
	v_pk_fma_f32 v[80:81], v[80:81], v[94:95], v[90:91]
	v_lshlrev_b32_e32 v94, 16, v155
	v_cvt_pk_bf16_f32 v90, v80, v81
	v_lshlrev_b32_e32 v80, 16, v147
	v_and_b32_e32 v81, 0xffff0000, v147
	v_and_b32_e32 v95, 0xffff0000, v155
	v_pk_fma_f32 v[80:81], v[82:83], v[94:95], v[80:81]
	v_lshlrev_b32_e32 v82, 16, v140
	v_cvt_pk_bf16_f32 v91, v80, v81
	v_lshlrev_b32_e32 v80, 16, v148
	v_and_b32_e32 v81, 0xffff0000, v148
	v_and_b32_e32 v83, 0xffff0000, v140
	v_pk_fma_f32 v[80:81], v[84:85], v[82:83], v[80:81]
	v_lshlrev_b32_e32 v82, 16, v149
	v_and_b32_e32 v83, 0xffff0000, v149
	v_lshlrev_b32_e32 v84, 16, v141
	v_and_b32_e32 v85, 0xffff0000, v141
	v_pk_fma_f32 v[82:83], v[86:87], v[84:85], v[82:83]
	v_cvt_pk_bf16_f32 v80, v80, v81
	v_cvt_pk_bf16_f32 v81, v82, v83
	v_lshlrev_b32_e32 v82, 16, v150
	v_and_b32_e32 v83, 0xffff0000, v150
	v_lshlrev_b32_e32 v84, 16, v142
	v_and_b32_e32 v85, 0xffff0000, v142
	v_pk_fma_f32 v[76:77], v[76:77], v[84:85], v[82:83]
	v_lshlrev_b32_e32 v84, 16, v143
	v_cvt_pk_bf16_f32 v82, v76, v77
	v_lshlrev_b32_e32 v76, 16, v151
	v_and_b32_e32 v77, 0xffff0000, v151
	v_and_b32_e32 v85, 0xffff0000, v143
	v_pk_fma_f32 v[76:77], v[78:79], v[84:85], v[76:77]
	v_lshlrev_b32_e32 v78, 16, v132
	v_cvt_pk_bf16_f32 v83, v76, v77
	v_lshl_add_u64 v[76:77], s[34:35], 0, v[218:219]
	v_lshl_add_u64 v[76:77], v[76:77], 0, v[210:211]
	global_store_dwordx4 v[76:77], v[80:83], off sc1
	v_and_b32_e32 v79, 0xffff0000, v132
	global_store_dwordx4 v[92:93], v[88:91], off offset:256 sc1
	v_lshlrev_b32_e32 v80, 16, v136
	v_and_b32_e32 v81, 0xffff0000, v136
	v_pk_fma_f32 v[72:73], v[72:73], v[80:81], v[78:79]
	v_lshlrev_b32_e32 v78, 16, v133
	v_and_b32_e32 v79, 0xffff0000, v133
	v_lshlrev_b32_e32 v80, 16, v137
	v_and_b32_e32 v81, 0xffff0000, v137
	v_pk_fma_f32 v[74:75], v[74:75], v[80:81], v[78:79]
	v_cvt_pk_bf16_f32 v72, v72, v73
	v_cvt_pk_bf16_f32 v73, v74, v75
	v_lshlrev_b32_e32 v74, 16, v134
	v_and_b32_e32 v75, 0xffff0000, v134
	v_lshlrev_b32_e32 v78, 16, v138
	v_and_b32_e32 v79, 0xffff0000, v138
	v_pk_fma_f32 v[68:69], v[68:69], v[78:79], v[74:75]
	v_lshlrev_b32_e32 v78, 16, v139
	v_cvt_pk_bf16_f32 v74, v68, v69
	v_lshlrev_b32_e32 v68, 16, v135
	v_and_b32_e32 v69, 0xffff0000, v135
	v_and_b32_e32 v79, 0xffff0000, v139
	v_pk_fma_f32 v[68:69], v[70:71], v[78:79], v[68:69]
	v_mov_b32_e32 v112, 0
	v_cvt_pk_bf16_f32 v75, v68, v69
	global_store_dwordx4 v[76:77], v[72:75], off offset:256 sc1
	v_add_u32_e32 v68, 0x80, v212
	v_mad_i64_i32 v[70:71], s[40:41], v68, s31, v[214:215]
	global_load_dwordx4 v[124:127], v[70:71], off
	v_ashrrev_i32_e32 v69, 31, v68
	v_lshlrev_b64 v[138:139], 11, v[68:69]
	v_lshl_add_u64 v[68:69], v[216:217], 0, v[138:139]
	v_mov_b32_e32 v128, 0
	v_mov_b32_e32 v129, 0
	v_mov_b32_e32 v130, 0
	v_mov_b32_e32 v131, 0
	s_cbranch_vccnz .LBB0_70
	global_load_dwordx4 v[128:131], v[68:69], off

; __device__ __forceinline__ unsigned pk2(float lo, float hi) { return pg8::cvt_pk_bf16(lo, hi); }
; __device__ __forceinline__ float bflo(unsigned w) { return __uint_as_float(w << 16); }
; __device__ __forceinline__ float bfhi(unsigned w) { return __uint_as_float(w & 0xffff0000u); }
;     __device__ __forceinline__ void operator()(const pg8::f32x4 (&acc)[2][2][4][2], const pg8::Unit& u, int wr, int wc, int fr, int fq) const {
;     ...
; #pragma unroll
;             for (int m = 0; m < 4; ++m)
; #pragma unroll
;                 for (int bj = 0; bj < 2; ++bj) {
;                     const int row = row0 + ai * 128 + m * 16;
;                     const u32x4 g = gv[m][bj], o = ov[m][bj]; const pg8::f32x4 a0 = acc[ai][bj][m][0], a1 = acc[ai][bj][m][1];
;                     u32x4 w; w.x = pk2(bflo(o.x) + bflo(g.x) * a0[0], bfhi(o.x) + bfhi(g.x) * a0[1]); w.y = pk2(bflo(o.y) + bflo(g.y) * a0[2], bfhi(o.y) + bfhi(g.y) * a0[3]);
;                     w.z = pk2(bflo(o.z) + bflo(g.z) * a1[0], bfhi(o.z) + bfhi(g.z) * a1[1]); w.w = pk2(bflo(o.w) + bflo(g.w) * a1[2], bfhi(o.w) + bfhi(g.w) * a1[3]);
;                     *(u32x4*)(mrg + (size_t)row * DM + col0 + bj * 128) = w;
;                 }
;             asm volatile("" ::: "memory");
;         }
.LBB0_84:
	s_waitcnt vmcnt(7)
	v_lshlrev_b32_e32 v140, 16, v128
	v_and_b32_e32 v141, 0xffff0000, v128
	v_lshlrev_b32_e32 v142, 16, v124
	v_and_b32_e32 v143, 0xffff0000, v124
	v_lshlrev_b32_e32 v128, 16, v129
	v_and_b32_e32 v129, 0xffff0000, v129
	v_lshlrev_b32_e32 v124, 16, v125
	v_and_b32_e32 v125, 0xffff0000, v125
	v_pk_fma_f32 v[64:65], v[64:65], v[142:143], v[140:141]
	v_pk_fma_f32 v[66:67], v[66:67], v[124:125], v[128:129]
	v_cvt_pk_bf16_f32 v64, v64, v65
	v_cvt_pk_bf16_f32 v65, v66, v67
	v_lshlrev_b32_e32 v66, 16, v130
	v_and_b32_e32 v67, 0xffff0000, v130
	v_lshlrev_b32_e32 v124, 16, v126
	v_and_b32_e32 v125, 0xffff0000, v126
	v_pk_fma_f32 v[60:61], v[60:61], v[124:125], v[66:67]
	v_lshlrev_b32_e32 v124, 16, v127
	v_cvt_pk_bf16_f32 v66, v60, v61
	v_lshlrev_b32_e32 v60, 16, v131
	v_and_b32_e32 v61, 0xffff0000, v131
	v_and_b32_e32 v125, 0xffff0000, v127
	v_pk_fma_f32 v[60:61], v[62:63], v[124:125], v[60:61]
	s_waitcnt vmcnt(6)
	v_lshlrev_b32_e32 v62, 16, v112
	v_cvt_pk_bf16_f32 v67, v60, v61
	v_lshl_add_u64 v[60:61], s[34:35], 0, v[138:139]
	v_lshl_add_u64 v[60:61], v[60:61], 0, v[210:211]
	global_store_dwordx4 v[60:61], v[64:67], off sc1
	v_and_b32_e32 v63, 0xffff0000, v112
	s_andn2_b64 vcc, exec, s[38:39]
	v_lshlrev_b32_e32 v64, 16, v120
	v_and_b32_e32 v65, 0xffff0000, v120
	v_pk_fma_f32 v[56:57], v[56:57], v[64:65], v[62:63]
	v_lshlrev_b32_e32 v62, 16, v113
	v_and_b32_e32 v63, 0xffff0000, v113
	v_lshlrev_b32_e32 v64, 16, v121
	v_and_b32_e32 v65, 0xffff0000, v121
	v_pk_fma_f32 v[58:59], v[58:59], v[64:65], v[62:63]
	v_cvt_pk_bf16_f32 v56, v56, v57
	v_cvt_pk_bf16_f32 v57, v58, v59
	v_lshlrev_b32_e32 v58, 16, v114
	v_and_b32_e32 v59, 0xffff0000, v114
	v_lshlrev_b32_e32 v62, 16, v122
	v_and_b32_e32 v63, 0xffff0000, v122
	v_pk_fma_f32 v[48:49], v[48:49], v[62:63], v[58:59]
	v_lshlrev_b32_e32 v62, 16, v123
	v_cvt_pk_bf16_f32 v58, v48, v49
	v_lshlrev_b32_e32 v48, 16, v115
	v_and_b32_e32 v49, 0xffff0000, v115
	v_and_b32_e32 v63, 0xffff0000, v123
	v_pk_fma_f32 v[48:49], v[50:51], v[62:63], v[48:49]
	s_waitcnt vmcnt(6)
	v_lshlrev_b32_e32 v50, 16, v108
	v_cvt_pk_bf16_f32 v59, v48, v49
	v_lshlrev_b32_e32 v48, 16, v116
	v_and_b32_e32 v49, 0xffff0000, v116
	v_and_b32_e32 v51, 0xffff0000, v108
	v_pk_fma_f32 v[48:49], v[52:53], v[50:51], v[48:49]
	v_lshlrev_b32_e32 v50, 16, v117
	v_and_b32_e32 v51, 0xffff0000, v117
	v_lshlrev_b32_e32 v52, 16, v109
	v_and_b32_e32 v53, 0xffff0000, v109
	v_pk_fma_f32 v[50:51], v[54:55], v[52:53], v[50:51]
	v_cvt_pk_bf16_f32 v48, v48, v49
	v_cvt_pk_bf16_f32 v49, v50, v51
	v_lshlrev_b32_e32 v50, 16, v118
	v_and_b32_e32 v51, 0xffff0000, v118
	v_lshlrev_b32_e32 v52, 16, v110
	v_and_b32_e32 v53, 0xffff0000, v110
	v_pk_fma_f32 v[44:45], v[44:45], v[52:53], v[50:51]
	v_lshlrev_b32_e32 v52, 16, v111
	v_cvt_pk_bf16_f32 v50, v44, v45
	v_lshlrev_b32_e32 v44, 16, v119
	v_and_b32_e32 v45, 0xffff0000, v119
	v_and_b32_e32 v53, 0xffff0000, v111
	v_pk_fma_f32 v[44:45], v[46:47], v[52:53], v[44:45]
	s_waitcnt vmcnt(5)
	v_lshlrev_b32_e32 v46, 16, v96
	v_cvt_pk_bf16_f32 v51, v44, v45
	v_lshl_add_u64 v[44:45], s[34:35], 0, v[136:137]
	v_lshl_add_u64 v[44:45], v[44:45], 0, v[210:211]
	global_store_dwordx4 v[44:45], v[48:51], off sc1
	v_and_b32_e32 v47, 0xffff0000, v96
	global_store_dwordx4 v[60:61], v[56:59], off offset:256 sc1
	v_lshlrev_b32_e32 v48, 16, v104
	v_and_b32_e32 v49, 0xffff0000, v104
	v_pk_fma_f32 v[40:41], v[40:41], v[48:49], v[46:47]
	v_lshlrev_b32_e32 v46, 16, v97
	v_and_b32_e32 v47, 0xffff0000, v97
	v_lshlrev_b32_e32 v48, 16, v105
	v_and_b32_e32 v49, 0xffff0000, v105
	v_pk_fma_f32 v[42:43], v[42:43], v[48:49], v[46:47]
	v_cvt_pk_bf16_f32 v40, v40, v41
	v_cvt_pk_bf16_f32 v41, v42, v43
	v_lshlrev_b32_e32 v42, 16, v98
	v_and_b32_e32 v43, 0xffff0000, v98
	v_lshlrev_b32_e32 v46, 16, v106
	v_and_b32_e32 v47, 0xffff0000, v106
	v_pk_fma_f32 v[28:29], v[28:29], v[46:47], v[42:43]
	v_lshlrev_b32_e32 v46, 16, v107
	v_cvt_pk_bf16_f32 v42, v28, v29
	v_lshlrev_b32_e32 v28, 16, v99
	v_and_b32_e32 v29, 0xffff0000, v99
	v_and_b32_e32 v47, 0xffff0000, v107
	v_pk_fma_f32 v[28:29], v[30:31], v[46:47], v[28:29]
	s_waitcnt vmcnt(6)
; #define PG8_BAR __builtin_amdgcn_s_barrier()
; __device__ __forceinline__ unsigned pk2(float lo, float hi) { return pg8::cvt_pk_bf16(lo, hi); }
; __device__ __forceinline__ float bflo(unsigned w) { return __uint_as_float(w << 16); }
; __device__ __forceinline__ float bfhi(unsigned w) { return __uint_as_float(w & 0xffff0000u); }
; template <class Epi, class Sched, bool ALIGN_EPI = false, bool SP2 = false>
; __device__ __forceinline__ void gemm_phase(PG8_LAS unsigned char* lds, const Gemm g, const Sched& S, const Epi& E) {
;     ...
;         if (!has_next) break;
; #pragma unroll
;         for (int a = 0; a < 2; ++a)
; #pragma unroll
;             for (int b = 0; b < 2; ++b)
; #pragma unroll
;                 for (int m = 0; m < 4; ++m)
; #pragma unroll
;                     for (int n = 0; n < 2; ++n) acc[a][b][m][n] = (f32x4){0.f, 0.f, 0.f, 0.f};
;         cur = nxt; cA = nA; cB = nB; ++ui;
;         if constexpr (ALIGN_EPI) { if (wr == 1) PG8_BAR; }
;     __device__ __forceinline__ void operator()(const pg8::f32x4 (&acc)[2][2][4][2], const pg8::Unit& u, int wr, int wc, int fr, int fq) const {
;     ...
;                     const u32x4 g = gv[m][bj], o = ov[m][bj]; const pg8::f32x4 a0 = acc[ai][bj][m][0], a1 = acc[ai][bj][m][1];
;                     u32x4 w; w.x = pk2(bflo(o.x) + bflo(g.x) * a0[0], bfhi(o.x) + bfhi(g.x) * a0[1]); w.y = pk2(bflo(o.y) + bflo(g.y) * a0[2], bfhi(o.y) + bfhi(g.y) * a0[3]);
;                     w.z = pk2(bflo(o.z) + bflo(g.z) * a1[0], bfhi(o.z) + bfhi(g.z) * a1[1]); w.w = pk2(bflo(o.w) + bflo(g.w) * a1[2], bfhi(o.w) + bfhi(g.w) * a1[3]);
;                     *(u32x4*)(mrg + (size_t)row * DM + col0 + bj * 128) = w;
;                 }
;             asm volatile("" ::: "memory");
;         }
	v_lshlrev_b32_e32 v30, 16, v92
	v_cvt_pk_bf16_f32 v43, v28, v29
	v_lshlrev_b32_e32 v28, 16, v100
	v_and_b32_e32 v29, 0xffff0000, v100
	v_and_b32_e32 v31, 0xffff0000, v92
	v_pk_fma_f32 v[28:29], v[36:37], v[30:31], v[28:29]
	v_lshlrev_b32_e32 v30, 16, v101
	v_and_b32_e32 v31, 0xffff0000, v101
	v_lshlrev_b32_e32 v36, 16, v93
	v_and_b32_e32 v37, 0xffff0000, v93
	v_pk_fma_f32 v[30:31], v[38:39], v[36:37], v[30:31]
	v_cvt_pk_bf16_f32 v28, v28, v29
	v_cvt_pk_bf16_f32 v29, v30, v31
	v_lshlrev_b32_e32 v30, 16, v102
	v_and_b32_e32 v31, 0xffff0000, v102
	v_lshlrev_b32_e32 v36, 16, v94
	v_and_b32_e32 v37, 0xffff0000, v94
	v_pk_fma_f32 v[24:25], v[24:25], v[36:37], v[30:31]
	v_lshlrev_b32_e32 v36, 16, v95
	v_cvt_pk_bf16_f32 v30, v24, v25
	v_lshlrev_b32_e32 v24, 16, v103
	v_and_b32_e32 v25, 0xffff0000, v103
	v_and_b32_e32 v37, 0xffff0000, v95
	v_pk_fma_f32 v[24:25], v[26:27], v[36:37], v[24:25]
	s_waitcnt vmcnt(5)
	v_lshlrev_b32_e32 v26, 16, v80
	v_cvt_pk_bf16_f32 v31, v24, v25
	v_lshl_add_u64 v[24:25], s[34:35], 0, v[134:135]
	v_lshl_add_u64 v[24:25], v[24:25], 0, v[210:211]
	global_store_dwordx4 v[24:25], v[28:31], off sc1
	v_and_b32_e32 v27, 0xffff0000, v80
	global_store_dwordx4 v[44:45], v[40:43], off offset:256 sc1
	v_lshlrev_b32_e32 v28, 16, v88
	v_and_b32_e32 v29, 0xffff0000, v88
	v_pk_fma_f32 v[20:21], v[20:21], v[28:29], v[26:27]
	v_lshlrev_b32_e32 v26, 16, v81
	v_and_b32_e32 v27, 0xffff0000, v81
	v_lshlrev_b32_e32 v28, 16, v89
	v_and_b32_e32 v29, 0xffff0000, v89
	v_pk_fma_f32 v[22:23], v[22:23], v[28:29], v[26:27]
	v_cvt_pk_bf16_f32 v20, v20, v21
	v_cvt_pk_bf16_f32 v21, v22, v23
	v_lshlrev_b32_e32 v22, 16, v82
	v_and_b32_e32 v23, 0xffff0000, v82
	v_lshlrev_b32_e32 v26, 16, v90
	v_and_b32_e32 v27, 0xffff0000, v90
	v_pk_fma_f32 v[12:13], v[12:13], v[26:27], v[22:23]
	v_lshlrev_b32_e32 v26, 16, v91
	v_cvt_pk_bf16_f32 v22, v12, v13
	v_lshlrev_b32_e32 v12, 16, v83
	v_and_b32_e32 v13, 0xffff0000, v83
	v_and_b32_e32 v27, 0xffff0000, v91
	v_pk_fma_f32 v[12:13], v[14:15], v[26:27], v[12:13]
	s_waitcnt vmcnt(6)
	v_lshlrev_b32_e32 v14, 16, v76
	v_cvt_pk_bf16_f32 v23, v12, v13
	v_lshlrev_b32_e32 v12, 16, v84
	v_and_b32_e32 v13, 0xffff0000, v84
	v_and_b32_e32 v15, 0xffff0000, v76
	v_pk_fma_f32 v[12:13], v[16:17], v[14:15], v[12:13]
	v_lshlrev_b32_e32 v14, 16, v85
	v_and_b32_e32 v15, 0xffff0000, v85
	v_lshlrev_b32_e32 v16, 16, v77
	v_and_b32_e32 v17, 0xffff0000, v77
	v_pk_fma_f32 v[14:15], v[18:19], v[16:17], v[14:15]
	v_cvt_pk_bf16_f32 v12, v12, v13
	v_cvt_pk_bf16_f32 v13, v14, v15
	v_lshlrev_b32_e32 v14, 16, v86
	v_and_b32_e32 v15, 0xffff0000, v86
	v_lshlrev_b32_e32 v16, 16, v78
	v_and_b32_e32 v17, 0xffff0000, v78
	v_pk_fma_f32 v[8:9], v[8:9], v[16:17], v[14:15]
	v_lshlrev_b32_e32 v16, 16, v79
	v_cvt_pk_bf16_f32 v14, v8, v9
	v_lshlrev_b32_e32 v8, 16, v87
	v_and_b32_e32 v9, 0xffff0000, v87
	v_and_b32_e32 v17, 0xffff0000, v79
	v_pk_fma_f32 v[8:9], v[10:11], v[16:17], v[8:9]
	s_waitcnt vmcnt(5)
	v_lshlrev_b32_e32 v10, 16, v68
	v_cvt_pk_bf16_f32 v15, v8, v9
	v_lshl_add_u64 v[8:9], s[34:35], 0, v[132:133]
	v_lshl_add_u64 v[8:9], v[8:9], 0, v[210:211]
	global_store_dwordx4 v[8:9], v[12:15], off sc1
	v_and_b32_e32 v11, 0xffff0000, v68
	global_store_dwordx4 v[24:25], v[20:23], off offset:256 sc1
	v_lshlrev_b32_e32 v12, 16, v72
	v_and_b32_e32 v13, 0xffff0000, v72
	v_pk_fma_f32 v[4:5], v[4:5], v[12:13], v[10:11]
	v_lshlrev_b32_e32 v10, 16, v69
	v_and_b32_e32 v11, 0xffff0000, v69
	v_lshlrev_b32_e32 v12, 16, v73
	v_and_b32_e32 v13, 0xffff0000, v73
	v_pk_fma_f32 v[6:7], v[6:7], v[12:13], v[10:11]
	v_cvt_pk_bf16_f32 v4, v4, v5
	v_cvt_pk_bf16_f32 v5, v6, v7
	v_lshlrev_b32_e32 v6, 16, v70
	v_and_b32_e32 v7, 0xffff0000, v70
	v_lshlrev_b32_e32 v10, 16, v74
	v_and_b32_e32 v11, 0xffff0000, v74
	v_pk_fma_f32 v[0:1], v[0:1], v[10:11], v[6:7]
	v_lshlrev_b32_e32 v10, 16, v75
	v_cvt_pk_bf16_f32 v6, v0, v1
	v_lshlrev_b32_e32 v0, 16, v71
	v_and_b32_e32 v1, 0xffff0000, v71
	v_and_b32_e32 v11, 0xffff0000, v75
	v_pk_fma_f32 v[0:1], v[2:3], v[10:11], v[0:1]
	s_mov_b64 s[0:1], -1
	v_cvt_pk_bf16_f32 v7, v0, v1
	global_store_dwordx4 v[8:9], v[4:7], off offset:256 sc1
	s_cbranch_vccnz .LBB0_41
	s_andn2_b64 vcc, exec, s[4:5]
	s_cbranch_vccnz .LBB0_40
	s_barrier
	s_branch .LBB0_40

; __device__ __forceinline__ float rstd_of(const float* ssq, int row) {
;     const f32x4* q = (const f32x4*)(ssq + (size_t)row * 16); const f32x4 a = q[0], b = q[1], c = q[2], d = q[3];
;     const float t = (((a.x + a.y) + (a.z + a.w)) + ((b.x + b.y) + (b.z + b.w))) + (((c.x + c.y) + (c.z + c.w)) + ((d.x + d.y) + (d.z + d.w)));
;     return 1.0f / sqrtf(t * (1.0f / DM) + 1e-6f); }
;     __device__ __forceinline__ void operator()(const pg8::f32x4 (&acc)[2][2][4][2], const pg8::Unit& u, int wr, int wc, int fr, int fq) const {
;         const int row0 = u.pm * 256 + wr * 64 + fr;
;         if (u.pn < 15) {
;             const float sc = ((u.pn % 6) < 2) ? QSCALE : 1.0f;
;             const int col0 = u.pn * 256 + wc * 32 + 8 * fq;
;             const bool vt_all = (u.pn == 4) | (u.pn == 5) | (u.pn == 10) | (u.pn == 11), vt_half = (u.pn == 14);
;             const int vrow0 = (u.pn <= 5 ? (u.pn - 4) * 256 : (u.pn <= 11 ? 512 + (u.pn - 10) * 256 : 1024 - 128)) + wc * 32 + 8 * fq;
; #pragma unroll
;             for (int ai = 0; ai < 2; ++ai)
; #pragma unroll
;                 for (int m = 0; m < 4; ++m) {
;                     const int row = row0 + ai * 128 + m * 16; const float rs = rstd_of(ssq, row) * sc;
.LBB0_345:
	v_lshl_add_u32 v158, s44, 8, v35
	v_lshrrev_b32_e32 v220, 2, v158
	v_lshrrev_b32_e32 v221, 3, v158
	v_xor_b32_e32 v220, v220, v221
	v_and_b32_e32 v220, 1, v220
	v_mul_u32_u24_e32 v220, 12, v220
	v_xor_b32_e32 v220, v158, v220
	v_mov_b32_e32 v221, 0
	v_mbcnt_lo_u32_b32 v210, -1, 0
	v_mbcnt_hi_u32_b32 v210, -1, v210
	v_lshrrev_b32_e32 v211, 4, v210
	v_and_b32_e32 v212, 1, v211
	v_lshrrev_b32_e32 v211, 1, v211
	v_lshlrev_b32_e32 v212, 5, v212
	v_lshl_add_u32 v212, v211, 7, v212
	v_add_u32_e32 v212, v212, v158
	v_mov_b32_e32 v213, 0
	v_lshlrev_b64 v[212:213], 6, v[212:213]
	v_lshl_add_u64 v[212:213], s[14:15], 0, v[212:213]
	global_load_dwordx4 v[132:135], v[212:213], off
	global_load_dwordx4 v[136:139], v[212:213], off offset:16
	global_load_dwordx4 v[140:143], v[212:213], off offset:32
	global_load_dwordx4 v[144:147], v[212:213], off offset:48
	global_load_dwordx4 v[174:177], v[212:213], off offset:1024
	global_load_dwordx4 v[178:181], v[212:213], off offset:1040
	global_load_dwordx4 v[182:185], v[212:213], off offset:1056
	global_load_dwordx4 v[186:189], v[212:213], off offset:1072
	v_and_b32_e32 v214, 15, v210
	v_lshlrev_b32_e32 v214, 2, v214
	v_add_u32_e32 v215, 64, v214
	v_add_u32_e32 v216, 0x80, v214
	v_add_u32_e32 v217, 0xc0, v214
	s_waitcnt vmcnt(4)
	v_add_f32_e32 v132, v132, v133
	v_add_f32_e32 v134, v134, v135
	v_add_f32_e32 v132, v132, v134
	v_add_f32_e32 v136, v136, v137
	v_add_f32_e32 v138, v138, v139
	v_add_f32_e32 v136, v136, v138
	v_add_f32_e32 v140, v140, v141
	v_add_f32_e32 v142, v142, v143
	v_add_f32_e32 v140, v140, v142
	v_add_f32_e32 v144, v144, v145
	v_add_f32_e32 v146, v146, v147
	v_add_f32_e32 v144, v144, v146
	v_add_f32_e32 v132, v132, v136
	v_add_f32_e32 v140, v140, v144
	v_add_f32_e32 v132, v132, v140
	v_fmamk_f32 v132, v132, 0x3a800000, v229
	v_cmp_gt_f32_e32 vcc, 0xf800000, v132
	v_mul_f32_e32 v137, 0x4f800000, v132
	s_nop 0
	v_cndmask_b32_e32 v132, v132, v137, vcc
	v_sqrt_f32_e32 v137, v132
	s_nop 0
	v_add_u32_e32 v138, -1, v137
	v_fma_f32 v139, -v138, v137, v132
	v_cmp_ge_f32_e64 s[100:101], 0, v139
	v_add_u32_e32 v139, 1, v137
	s_nop 0
	v_cndmask_b32_e64 v138, v137, v138, s[100:101]
	v_fma_f32 v137, -v139, v137, v132
	v_cmp_lt_f32_e64 s[100:101], 0, v137
	s_nop 1
	v_cndmask_b32_e64 v137, v138, v139, s[100:101]
	v_mul_f32_e32 v138, 0x37800000, v137
	v_cndmask_b32_e32 v137, v137, v138, vcc
	v_cmp_class_f32_e32 vcc, v132, v230
	s_nop 1
	v_cndmask_b32_e32 v132, v137, v132, vcc
	v_div_scale_f32 v137, s[100:101], v132, v132, 1.0
	v_rcp_f32_e32 v138, v137
	s_nop 0
	v_fma_f32 v139, -v137, v138, 1.0
	v_fmac_f32_e32 v138, v139, v138
	v_div_scale_f32 v139, vcc, 1.0, v132, 1.0
	v_mul_f32_e32 v141, v139, v138
	v_fma_f32 v142, -v137, v141, v139
	v_fmac_f32_e32 v141, v142, v138
	v_fma_f32 v137, -v137, v141, v139
	v_div_fmas_f32 v137, v137, v138, v141
	v_div_fixup_f32 v218, v137, v132, 1.0
	s_waitcnt vmcnt(0)
	v_add_f32_e32 v174, v174, v175
	v_add_f32_e32 v176, v176, v177
	v_add_f32_e32 v174, v174, v176
	v_add_f32_e32 v178, v178, v179
	v_add_f32_e32 v180, v180, v181
	v_add_f32_e32 v178, v178, v180
	v_add_f32_e32 v182, v182, v183
	v_add_f32_e32 v184, v184, v185
	v_add_f32_e32 v182, v182, v184
	v_add_f32_e32 v186, v186, v187
	v_add_f32_e32 v188, v188, v189
	v_add_f32_e32 v186, v186, v188
	v_add_f32_e32 v174, v174, v178
	v_add_f32_e32 v182, v182, v186
	v_add_f32_e32 v174, v174, v182
	v_fmamk_f32 v174, v174, 0x3a800000, v229
	v_cmp_gt_f32_e32 vcc, 0xf800000, v174
	v_mul_f32_e32 v179, 0x4f800000, v174
	s_nop 0
	v_cndmask_b32_e32 v174, v174, v179, vcc
	v_sqrt_f32_e32 v179, v174
	s_nop 0
	v_add_u32_e32 v180, -1, v179
	v_fma_f32 v181, -v180, v179, v174
	v_cmp_ge_f32_e64 s[100:101], 0, v181
	v_add_u32_e32 v181, 1, v179
	s_nop 0
	v_cndmask_b32_e64 v180, v179, v180, s[100:101]
	v_fma_f32 v179, -v181, v179, v174
	v_cmp_lt_f32_e64 s[100:101], 0, v179
	s_nop 1
	v_cndmask_b32_e64 v179, v180, v181, s[100:101]
	v_mul_f32_e32 v180, 0x37800000, v179
	v_cndmask_b32_e32 v179, v179, v180, vcc
	v_cmp_class_f32_e32 vcc, v174, v230
	s_nop 1
	v_cndmask_b32_e32 v174, v179, v174, vcc
	v_div_scale_f32 v179, s[100:101], v174, v174, 1.0
	v_rcp_f32_e32 v180, v179
	s_nop 0
	v_fma_f32 v181, -v179, v180, 1.0
	v_fmac_f32_e32 v180, v181, v180
	v_div_scale_f32 v181, vcc, 1.0, v174, 1.0
	v_mul_f32_e32 v183, v181, v180
	v_fma_f32 v184, -v179, v183, v181
	v_fmac_f32_e32 v183, v184, v180
	v_fma_f32 v179, -v179, v183, v181
	v_div_fmas_f32 v179, v179, v180, v183
	v_div_fixup_f32 v219, v179, v174, 1.0
	ds_bpermute_b32 v202, v214, v218
	ds_bpermute_b32 v203, v214, v219
	ds_bpermute_b32 v204, v215, v218
	ds_bpermute_b32 v205, v215, v219
	ds_bpermute_b32 v206, v216, v218
	ds_bpermute_b32 v207, v216, v219
	ds_bpermute_b32 v208, v217, v218
	ds_bpermute_b32 v209, v217, v219
	s_waitcnt lgkmcnt(0)
	v_or_b32_e32 v164, 16, v158
	v_or_b32_e32 v162, 32, v158
	s_mov_b64 s[0:1], -1
	s_cmp_gt_i32 s57, 14
	v_ashrrev_i32_e32 v159, 31, v158
	v_ashrrev_i32_e32 v165, 31, v164
	v_ashrrev_i32_e32 v163, 31, v162
	v_or_b32_e32 v160, 48, v158
	s_cbranch_scc0 .LBB0_347
; __device__ __forceinline__ unsigned pk2(float lo, float hi) { return pg8::cvt_pk_bf16(lo, hi); }
; __device__ __forceinline__ float fast_exp2(float x) { return __builtin_amdgcn_exp2f(x); }
; __device__ __forceinline__ float fast_rcp(float x) { return __builtin_amdgcn_rcpf(x); }
;     __device__ __forceinline__ void operator()(const pg8::f32x4 (&acc)[2][2][4][2], const pg8::Unit& u, int wr, int wc, int fr, int fq) const {
;     ...
;             const int col0 = (u.pn - 15) * 256 + wc * 32 + 8 * fq;
;             f32x4 bb[2][2];
; #pragma unroll
;             for (int bj = 0; bj < 2; ++bj) { bb[bj][0] = *(const f32x4*)(bg + col0 + bj * 128); bb[bj][1] = *(const f32x4*)(bg + col0 + bj * 128 + 4); }
; #pragma unroll
;             for (int ai = 0; ai < 2; ++ai)
; #pragma unroll
;                 for (int m = 0; m < 4; ++m) {
;                     const int row = row0 + ai * 128 + m * 16; const float rs = rstd_of(ssq, row);
; #pragma unroll
;                     for (int bj = 0; bj < 2; ++bj) {
;                         float v[8];
; #pragma unroll
;                         for (int j = 0; j < 4; ++j) { v[j] = fast_rcp(1.0f + fast_exp2(-(acc[ai][bj][m][0][j] * rs + bb[bj][0][j]) * LOG2E)); v[4 + j] = fast_rcp(1.0f + fast_exp2(-(acc[ai][bj][m][1][j] * rs + bb[bj][1][j]) * LOG2E)); }
;                         u32x4 w; w.x = pk2(v[0], v[1]); w.y = pk2(v[2], v[3]); w.z = pk2(v[4], v[5]); w.w = pk2(v[6], v[7]);
;                         *(u32x4*)(G + (size_t)row * NGATE + col0 + bj * 128) = w;
;                     }
	v_lshl_add_u32 v196, s57, 8, v172
	v_lshl_add_u64 v[132:133], v[196:197], 2, s[12:13]
	global_load_dwordx4 v[144:147], v[132:133], off
	global_load_dwordx4 v[140:143], v[132:133], off offset:16
	global_load_dwordx4 v[136:139], v[132:133], off offset:512
	s_nop 0
	global_load_dwordx4 v[132:135], v[132:133], off offset:528
	s_mov_b32 s4, 0xf800000
	v_readlane_b32 s0, v252, 4
	v_readlane_b32 s1, v252, 5
	s_waitcnt vmcnt(0)
	s_nop 0
	v_mov_b64_e32 v[166:167], s[0:1]
	v_mad_i64_i32 v[174:175], s[0:1], v158, s31, v[166:167]
	s_nop 1
	v_lshlrev_b64 v[168:169], 1, v[196:197]
	s_nop 1
	v_lshl_add_u64 v[178:179], v[174:175], 0, v[168:169]
	s_nop 0
	v_mov_b32_e32 v161, v202
	v_fma_f32 v174, v128, v161, v144
	v_fma_f32 v175, v124, v161, v140
	v_fma_f32 v176, v129, v161, v145
	v_fma_f32 v177, v125, v161, v141
	v_fma_f32 v180, v130, v161, v146
	v_fma_f32 v181, v126, v161, v142
	v_fma_f32 v182, v131, v161, v147
	v_fma_f32 v183, v127, v161, v143
	v_mul_f32_e32 v174, 0xbfb8aa3b, v174
	v_mul_f32_e32 v175, 0xbfb8aa3b, v175
	v_mul_f32_e32 v176, 0xbfb8aa3b, v176
	v_mul_f32_e32 v177, 0xbfb8aa3b, v177
	v_mul_f32_e32 v180, 0xbfb8aa3b, v180
	v_mul_f32_e32 v181, 0xbfb8aa3b, v181
	v_mul_f32_e32 v182, 0xbfb8aa3b, v182
	v_mul_f32_e32 v183, 0xbfb8aa3b, v183
	v_exp_f32_e32 v174, v174
	v_exp_f32_e32 v175, v175
	v_exp_f32_e32 v176, v176
	v_exp_f32_e32 v177, v177
	v_exp_f32_e32 v180, v180
	v_exp_f32_e32 v181, v181
	v_exp_f32_e32 v182, v182
	v_exp_f32_e32 v183, v183
	v_add_f32_e32 v174, 1.0, v174
	v_add_f32_e32 v175, 1.0, v175
	v_add_f32_e32 v176, 1.0, v176
	v_add_f32_e32 v177, 1.0, v177
	v_add_f32_e32 v180, 1.0, v180
	v_add_f32_e32 v181, 1.0, v181
	v_add_f32_e32 v182, 1.0, v182
	v_add_f32_e32 v183, 1.0, v183
	v_rcp_f32_e32 v174, v174
	v_rcp_f32_e32 v188, v175
	v_rcp_f32_e32 v175, v176
	v_rcp_f32_e32 v176, v177
	v_rcp_f32_e32 v177, v180
	v_rcp_f32_e32 v180, v181
	v_rcp_f32_e32 v181, v182
	v_rcp_f32_e32 v182, v183
	v_fma_f32 v187, v117, v161, v133
	v_cvt_pk_bf16_f32 v174, v174, v175
	v_cvt_pk_bf16_f32 v175, v177, v181
	v_cvt_pk_bf16_f32 v176, v188, v176
	v_cvt_pk_bf16_f32 v177, v180, v182
	v_mul_f32_e32 v187, 0xbfb8aa3b, v187
	global_store_dwordx4 v[178:179], v[174:177], off sc1
	v_fma_f32 v180, v118, v161, v134
	v_mul_f32_e32 v180, 0xbfb8aa3b, v180
	v_fma_f32 v177, v122, v161, v138
	v_exp_f32_e32 v174, v187
	v_mul_f32_e32 v177, 0xbfb8aa3b, v177
	v_exp_f32_e32 v177, v177
	v_exp_f32_e32 v180, v180
	v_add_f32_e32 v174, 1.0, v174
	v_rcp_f32_e32 v181, v174
	v_add_f32_e32 v174, 1.0, v177
	v_fma_f32 v184, v120, v161, v136
	v_fma_f32 v185, v116, v161, v132
	v_fma_f32 v186, v121, v161, v137
	v_rcp_f32_e32 v177, v174
	v_add_f32_e32 v174, 1.0, v180
	v_fma_f32 v180, v123, v161, v139
	v_fma_f32 v161, v119, v161, v135
	v_mul_f32_e32 v184, 0xbfb8aa3b, v184
	v_mul_f32_e32 v185, 0xbfb8aa3b, v185
	v_mul_f32_e32 v186, 0xbfb8aa3b, v186
	v_mul_f32_e32 v180, 0xbfb8aa3b, v180
	v_mul_f32_e32 v161, 0xbfb8aa3b, v161
	v_exp_f32_e32 v184, v184
	v_exp_f32_e32 v185, v185
	v_exp_f32_e32 v186, v186
	v_exp_f32_e32 v180, v180
	v_exp_f32_e32 v161, v161
	v_add_f32_e32 v184, 1.0, v184
	v_add_f32_e32 v185, 1.0, v185
	v_add_f32_e32 v175, 1.0, v186
	v_rcp_f32_e32 v182, v174
	v_add_f32_e32 v174, 1.0, v180
	v_add_f32_e32 v161, 1.0, v161
	v_rcp_f32_e32 v183, v184
	v_rcp_f32_e32 v176, v185
	v_rcp_f32_e32 v175, v175
	v_rcp_f32_e32 v180, v174
	v_rcp_f32_e32 v161, v161
	v_cvt_pk_bf16_f32 v176, v176, v181
	v_cvt_pk_bf16_f32 v174, v183, v175
	v_cvt_pk_bf16_f32 v175, v177, v180
	v_cvt_pk_bf16_f32 v177, v182, v161
	global_store_dwordx4 v[178:179], v[174:177], off offset:256 sc1
	s_nop 1
	v_mov_b32_e32 v161, v203
	v_fma_f32 v175, v108, v161, v140
	v_fma_f32 v176, v113, v161, v145
	v_fma_f32 v177, v109, v161, v141
	v_fma_f32 v178, v114, v161, v146
	v_mul_f32_e32 v175, 0xbfb8aa3b, v175
	v_mul_f32_e32 v176, 0xbfb8aa3b, v176
	v_mul_f32_e32 v177, 0xbfb8aa3b, v177
	v_mul_f32_e32 v178, 0xbfb8aa3b, v178
	v_exp_f32_e32 v175, v175
	v_exp_f32_e32 v176, v176
	v_exp_f32_e32 v177, v177
	v_exp_f32_e32 v178, v178
	v_add_f32_e32 v175, 1.0, v175
	v_add_f32_e32 v176, 1.0, v176
	v_add_f32_e32 v177, 1.0, v177
	v_add_f32_e32 v178, 1.0, v178
	v_fma_f32 v174, v112, v161, v144
	v_fma_f32 v179, v110, v161, v142
	v_fma_f32 v180, v115, v161, v147
	v_rcp_f32_e32 v181, v175
	v_rcp_f32_e32 v175, v176
	v_rcp_f32_e32 v176, v177
	v_rcp_f32_e32 v177, v178
	v_fma_f32 v178, v111, v161, v143
	v_mul_f32_e32 v174, 0xbfb8aa3b, v174
	v_mul_f32_e32 v179, 0xbfb8aa3b, v179
	v_mul_f32_e32 v180, 0xbfb8aa3b, v180
	v_mul_f32_e32 v178, 0xbfb8aa3b, v178
	v_exp_f32_e32 v174, v174
	v_exp_f32_e32 v179, v179
	v_exp_f32_e32 v180, v180
	v_exp_f32_e32 v178, v178
	v_add_f32_e32 v174, 1.0, v174
	v_add_f32_e32 v179, 1.0, v179
	v_add_f32_e32 v180, 1.0, v180
	v_add_f32_e32 v178, 1.0, v178
	v_rcp_f32_e32 v174, v174
	v_rcp_f32_e32 v179, v179
	v_rcp_f32_e32 v180, v180
	v_rcp_f32_e32 v178, v178
	v_cvt_pk_bf16_f32 v174, v174, v175
	v_cvt_pk_bf16_f32 v176, v181, v176
	v_cvt_pk_bf16_f32 v175, v177, v180
	v_cvt_pk_bf16_f32 v177, v179, v178
	v_mad_i64_i32 v[178:179], s[0:1], v164, s31, v[166:167]
	v_lshl_add_u64 v[178:179], v[178:179], 0, v[168:169]
	v_fma_f32 v181, v100, v161, v132
	v_fma_f32 v180, v104, v161, v136
	v_mul_f32_e32 v181, 0xbfb8aa3b, v181
	global_store_dwordx4 v[178:179], v[174:177], off sc1
	v_mul_f32_e32 v180, 0xbfb8aa3b, v180
	v_exp_f32_e32 v181, v181
	v_fma_f32 v176, v105, v161, v137
	v_fma_f32 v177, v101, v161, v133
	v_mul_f32_e32 v176, 0xbfb8aa3b, v176
	v_mul_f32_e32 v177, 0xbfb8aa3b, v177
	v_exp_f32_e32 v180, v180
	v_exp_f32_e32 v176, v176
	v_exp_f32_e32 v177, v177
	v_add_f32_e32 v175, 1.0, v181
	v_add_f32_e32 v174, 1.0, v180
	v_rcp_f32_e32 v180, v175
	v_add_f32_e32 v175, 1.0, v176
; __device__ __forceinline__ unsigned pk2(float lo, float hi) { return pg8::cvt_pk_bf16(lo, hi); }
; __device__ __forceinline__ float fast_exp2(float x) { return __builtin_amdgcn_exp2f(x); }
; __device__ __forceinline__ float fast_rcp(float x) { return __builtin_amdgcn_rcpf(x); }
;     __device__ __forceinline__ void operator()(const pg8::f32x4 (&acc)[2][2][4][2], const pg8::Unit& u, int wr, int wc, int fr, int fq) const {
;     ...
;             for (int ai = 0; ai < 2; ++ai)
; #pragma unroll
;                 for (int m = 0; m < 4; ++m) {
;                     const int row = row0 + ai * 128 + m * 16; const float rs = rstd_of(ssq, row);
; #pragma unroll
;                     for (int bj = 0; bj < 2; ++bj) {
;                         float v[8];
; #pragma unroll
;                         for (int j = 0; j < 4; ++j) { v[j] = fast_rcp(1.0f + fast_exp2(-(acc[ai][bj][m][0][j] * rs + bb[bj][0][j]) * LOG2E)); v[4 + j] = fast_rcp(1.0f + fast_exp2(-(acc[ai][bj][m][1][j] * rs + bb[bj][1][j]) * LOG2E)); }
;                         u32x4 w; w.x = pk2(v[0], v[1]); w.y = pk2(v[2], v[3]); w.z = pk2(v[4], v[5]); w.w = pk2(v[6], v[7]);
;                         *(u32x4*)(G + (size_t)row * NGATE + col0 + bj * 128) = w;
;                     }
	v_add_f32_e32 v176, 1.0, v177
	v_fma_f32 v177, v106, v161, v138
	v_fma_f32 v181, v102, v161, v134
	v_fma_f32 v182, v107, v161, v139
	v_fma_f32 v161, v103, v161, v135
	v_mul_f32_e32 v177, 0xbfb8aa3b, v177
	v_mul_f32_e32 v181, 0xbfb8aa3b, v181
	v_mul_f32_e32 v182, 0xbfb8aa3b, v182
	v_mul_f32_e32 v161, 0xbfb8aa3b, v161
	v_exp_f32_e32 v177, v177
	v_exp_f32_e32 v181, v181
	v_exp_f32_e32 v182, v182
	v_exp_f32_e32 v161, v161
	v_add_f32_e32 v177, 1.0, v177
	v_add_f32_e32 v181, 1.0, v181
	v_add_f32_e32 v182, 1.0, v182
	v_add_f32_e32 v161, 1.0, v161
	v_rcp_f32_e32 v174, v174
	v_rcp_f32_e32 v175, v175
	v_rcp_f32_e32 v176, v176
	v_rcp_f32_e32 v177, v177
	v_rcp_f32_e32 v181, v181
	v_rcp_f32_e32 v182, v182
	v_rcp_f32_e32 v161, v161
	v_cvt_pk_bf16_f32 v174, v174, v175
	v_cvt_pk_bf16_f32 v176, v180, v176
	v_cvt_pk_bf16_f32 v175, v177, v182
	v_cvt_pk_bf16_f32 v177, v181, v161
	global_store_dwordx4 v[178:179], v[174:177], off offset:256 sc1
	s_nop 1
	v_mov_b32_e32 v161, v204
	v_fma_f32 v175, v92, v161, v140
	v_mul_f32_e32 v175, 0xbfb8aa3b, v175
	v_fma_f32 v176, v97, v161, v145
	v_fma_f32 v177, v93, v161, v141
	v_exp_f32_e32 v175, v175
	v_mul_f32_e32 v176, 0xbfb8aa3b, v176
	v_mul_f32_e32 v177, 0xbfb8aa3b, v177
	v_exp_f32_e32 v176, v176
	v_exp_f32_e32 v177, v177
	v_add_f32_e32 v175, 1.0, v175
	v_fma_f32 v174, v96, v161, v144
	v_rcp_f32_e32 v178, v175
	v_add_f32_e32 v175, 1.0, v176
	v_add_f32_e32 v176, 1.0, v177
	v_fma_f32 v177, v98, v161, v146
	v_fma_f32 v179, v94, v161, v142
	v_fma_f32 v180, v99, v161, v147
	v_fma_f32 v181, v95, v161, v143
	v_mul_f32_e32 v174, 0xbfb8aa3b, v174
	v_mul_f32_e32 v177, 0xbfb8aa3b, v177
	v_mul_f32_e32 v179, 0xbfb8aa3b, v179
	v_mul_f32_e32 v180, 0xbfb8aa3b, v180
	v_mul_f32_e32 v181, 0xbfb8aa3b, v181
	v_exp_f32_e32 v174, v174
	v_exp_f32_e32 v177, v177
	v_exp_f32_e32 v179, v179
	v_exp_f32_e32 v180, v180
	v_exp_f32_e32 v181, v181
	v_add_f32_e32 v174, 1.0, v174
	v_add_f32_e32 v177, 1.0, v177
	v_add_f32_e32 v179, 1.0, v179
	v_add_f32_e32 v180, 1.0, v180
	v_add_f32_e32 v181, 1.0, v181
	v_rcp_f32_e32 v174, v174
	v_rcp_f32_e32 v175, v175
	v_rcp_f32_e32 v176, v176
	v_rcp_f32_e32 v177, v177
	v_rcp_f32_e32 v179, v179
	v_rcp_f32_e32 v180, v180
	v_rcp_f32_e32 v181, v181
	v_cvt_pk_bf16_f32 v174, v174, v175
	v_cvt_pk_bf16_f32 v176, v178, v176
	v_cvt_pk_bf16_f32 v175, v177, v180
	v_cvt_pk_bf16_f32 v177, v179, v181
	v_mad_i64_i32 v[178:179], s[0:1], v162, s31, v[166:167]
	v_lshl_add_u64 v[178:179], v[178:179], 0, v[168:169]
	v_fma_f32 v181, v84, v161, v132
	v_fma_f32 v180, v88, v161, v136
	v_mul_f32_e32 v181, 0xbfb8aa3b, v181
	global_store_dwordx4 v[178:179], v[174:177], off sc1
	v_mul_f32_e32 v180, 0xbfb8aa3b, v180
	v_exp_f32_e32 v181, v181
	v_fma_f32 v176, v89, v161, v137
	v_fma_f32 v177, v85, v161, v133
	v_mul_f32_e32 v176, 0xbfb8aa3b, v176
	v_mul_f32_e32 v177, 0xbfb8aa3b, v177
	v_exp_f32_e32 v180, v180
	v_exp_f32_e32 v176, v176
	v_exp_f32_e32 v177, v177
	v_add_f32_e32 v175, 1.0, v181
	v_add_f32_e32 v174, 1.0, v180
	v_rcp_f32_e32 v180, v175
	v_add_f32_e32 v175, 1.0, v176
	v_add_f32_e32 v176, 1.0, v177
	v_fma_f32 v177, v90, v161, v138
	v_fma_f32 v181, v86, v161, v134
	v_fma_f32 v182, v91, v161, v139
	v_fma_f32 v161, v87, v161, v135
	v_mul_f32_e32 v177, 0xbfb8aa3b, v177
	v_mul_f32_e32 v181, 0xbfb8aa3b, v181
	v_mul_f32_e32 v182, 0xbfb8aa3b, v182
	v_mul_f32_e32 v161, 0xbfb8aa3b, v161
	v_exp_f32_e32 v177, v177
	v_exp_f32_e32 v181, v181
	v_exp_f32_e32 v182, v182
	v_exp_f32_e32 v161, v161
	v_add_f32_e32 v177, 1.0, v177
	v_add_f32_e32 v181, 1.0, v181
	v_add_f32_e32 v182, 1.0, v182
	v_add_f32_e32 v161, 1.0, v161
	v_rcp_f32_e32 v174, v174
	v_rcp_f32_e32 v175, v175
	v_rcp_f32_e32 v176, v176
	v_rcp_f32_e32 v177, v177
	v_rcp_f32_e32 v181, v181
	v_rcp_f32_e32 v182, v182
	v_rcp_f32_e32 v161, v161
	v_cvt_pk_bf16_f32 v174, v174, v175
	v_cvt_pk_bf16_f32 v176, v180, v176
	v_cvt_pk_bf16_f32 v175, v177, v182
	v_cvt_pk_bf16_f32 v177, v181, v161
	global_store_dwordx4 v[178:179], v[174:177], off offset:256 sc1
	s_nop 1
	v_add_u32_e32 v190, 0x80, v158
	v_ashrrev_i32_e32 v191, 31, v190
	s_nop 1
	v_mov_b32_e32 v161, v205
	v_fma_f32 v175, v76, v161, v140
	v_mul_f32_e32 v175, 0xbfb8aa3b, v175
	v_fma_f32 v176, v81, v161, v145
	v_fma_f32 v177, v77, v161, v141
	v_exp_f32_e32 v175, v175
	v_mul_f32_e32 v176, 0xbfb8aa3b, v176
	v_mul_f32_e32 v177, 0xbfb8aa3b, v177
	v_exp_f32_e32 v176, v176
	v_exp_f32_e32 v177, v177
	v_add_f32_e32 v175, 1.0, v175
	v_fma_f32 v174, v80, v161, v144
	v_rcp_f32_e32 v178, v175
	v_add_f32_e32 v175, 1.0, v176
	v_add_f32_e32 v176, 1.0, v177
	v_fma_f32 v177, v82, v161, v146
	v_fma_f32 v179, v78, v161, v142
	v_fma_f32 v180, v83, v161, v147
	v_fma_f32 v181, v79, v161, v143
	v_mul_f32_e32 v174, 0xbfb8aa3b, v174
	v_mul_f32_e32 v177, 0xbfb8aa3b, v177
	v_mul_f32_e32 v179, 0xbfb8aa3b, v179
	v_mul_f32_e32 v180, 0xbfb8aa3b, v180
	v_mul_f32_e32 v181, 0xbfb8aa3b, v181
	v_exp_f32_e32 v174, v174
	v_exp_f32_e32 v177, v177
	v_exp_f32_e32 v179, v179
	v_exp_f32_e32 v180, v180
	v_exp_f32_e32 v181, v181
	v_add_f32_e32 v174, 1.0, v174
	v_add_f32_e32 v177, 1.0, v177
	v_add_f32_e32 v179, 1.0, v179
	v_add_f32_e32 v180, 1.0, v180
	v_add_f32_e32 v181, 1.0, v181
	v_rcp_f32_e32 v174, v174
	v_rcp_f32_e32 v175, v175
	v_rcp_f32_e32 v176, v176
	v_rcp_f32_e32 v177, v177
	v_rcp_f32_e32 v179, v179
	v_rcp_f32_e32 v180, v180
	v_rcp_f32_e32 v181, v181
	v_cvt_pk_bf16_f32 v174, v174, v175
	v_cvt_pk_bf16_f32 v176, v178, v176
	v_cvt_pk_bf16_f32 v175, v177, v180
	v_cvt_pk_bf16_f32 v177, v179, v181
	v_mad_i64_i32 v[178:179], s[0:1], v160, s31, v[166:167]
	v_lshl_add_u64 v[178:179], v[178:179], 0, v[168:169]
	v_fma_f32 v181, v68, v161, v132
	v_fma_f32 v180, v72, v161, v136
	v_mul_f32_e32 v181, 0xbfb8aa3b, v181
; __device__ __forceinline__ unsigned pk2(float lo, float hi) { return pg8::cvt_pk_bf16(lo, hi); }
; __device__ __forceinline__ float fast_exp2(float x) { return __builtin_amdgcn_exp2f(x); }
; __device__ __forceinline__ float fast_rcp(float x) { return __builtin_amdgcn_rcpf(x); }
;     __device__ __forceinline__ void operator()(const pg8::f32x4 (&acc)[2][2][4][2], const pg8::Unit& u, int wr, int wc, int fr, int fq) const {
;     ...
;             for (int ai = 0; ai < 2; ++ai)
; #pragma unroll
;                 for (int m = 0; m < 4; ++m) {
;                     const int row = row0 + ai * 128 + m * 16; const float rs = rstd_of(ssq, row);
; #pragma unroll
;                     for (int bj = 0; bj < 2; ++bj) {
;                         float v[8];
; #pragma unroll
;                         for (int j = 0; j < 4; ++j) { v[j] = fast_rcp(1.0f + fast_exp2(-(acc[ai][bj][m][0][j] * rs + bb[bj][0][j]) * LOG2E)); v[4 + j] = fast_rcp(1.0f + fast_exp2(-(acc[ai][bj][m][1][j] * rs + bb[bj][1][j]) * LOG2E)); }
;                         u32x4 w; w.x = pk2(v[0], v[1]); w.y = pk2(v[2], v[3]); w.z = pk2(v[4], v[5]); w.w = pk2(v[6], v[7]);
;                         *(u32x4*)(G + (size_t)row * NGATE + col0 + bj * 128) = w;
;                     }
	global_store_dwordx4 v[178:179], v[174:177], off sc1
	v_mul_f32_e32 v180, 0xbfb8aa3b, v180
	v_exp_f32_e32 v181, v181
	v_fma_f32 v176, v73, v161, v137
	v_fma_f32 v177, v69, v161, v133
	v_mul_f32_e32 v176, 0xbfb8aa3b, v176
	v_mul_f32_e32 v177, 0xbfb8aa3b, v177
	v_exp_f32_e32 v180, v180
	v_exp_f32_e32 v176, v176
	v_exp_f32_e32 v177, v177
	v_add_f32_e32 v175, 1.0, v181
	v_add_f32_e32 v174, 1.0, v180
	v_rcp_f32_e32 v180, v175
	v_add_f32_e32 v175, 1.0, v176
	v_add_f32_e32 v176, 1.0, v177
	v_fma_f32 v177, v74, v161, v138
	v_fma_f32 v181, v70, v161, v134
	v_fma_f32 v182, v75, v161, v139
	v_fma_f32 v161, v71, v161, v135
	v_mul_f32_e32 v177, 0xbfb8aa3b, v177
	v_mul_f32_e32 v181, 0xbfb8aa3b, v181
	v_mul_f32_e32 v182, 0xbfb8aa3b, v182
	v_mul_f32_e32 v161, 0xbfb8aa3b, v161
	v_exp_f32_e32 v177, v177
	v_exp_f32_e32 v181, v181
	v_exp_f32_e32 v182, v182
	v_exp_f32_e32 v161, v161
	v_add_f32_e32 v177, 1.0, v177
	v_add_f32_e32 v181, 1.0, v181
	v_add_f32_e32 v182, 1.0, v182
	v_add_f32_e32 v161, 1.0, v161
	v_rcp_f32_e32 v174, v174
	v_rcp_f32_e32 v175, v175
	v_rcp_f32_e32 v176, v176
	v_rcp_f32_e32 v177, v177
	v_rcp_f32_e32 v181, v181
	v_rcp_f32_e32 v182, v182
	v_rcp_f32_e32 v161, v161
	v_cvt_pk_bf16_f32 v174, v174, v175
	v_cvt_pk_bf16_f32 v176, v180, v176
	v_cvt_pk_bf16_f32 v175, v177, v182
	v_cvt_pk_bf16_f32 v177, v181, v161
	global_store_dwordx4 v[178:179], v[174:177], off offset:256 sc1
	s_nop 1
	v_mov_b32_e32 v161, v206
	v_fma_f32 v175, v60, v161, v140
	v_mul_f32_e32 v175, 0xbfb8aa3b, v175
	v_fma_f32 v176, v65, v161, v145
	v_fma_f32 v177, v61, v161, v141
	v_exp_f32_e32 v175, v175
	v_mul_f32_e32 v176, 0xbfb8aa3b, v176
	v_mul_f32_e32 v177, 0xbfb8aa3b, v177
	v_exp_f32_e32 v176, v176
	v_exp_f32_e32 v177, v177
	v_add_f32_e32 v175, 1.0, v175
	v_fma_f32 v174, v64, v161, v144
	v_rcp_f32_e32 v178, v175
	v_add_f32_e32 v175, 1.0, v176
	v_add_f32_e32 v176, 1.0, v177
	v_fma_f32 v177, v66, v161, v146
	v_fma_f32 v179, v62, v161, v142
	v_fma_f32 v180, v67, v161, v147
	v_fma_f32 v181, v63, v161, v143
	v_mul_f32_e32 v174, 0xbfb8aa3b, v174
	v_mul_f32_e32 v177, 0xbfb8aa3b, v177
	v_mul_f32_e32 v179, 0xbfb8aa3b, v179
	v_mul_f32_e32 v180, 0xbfb8aa3b, v180
	v_mul_f32_e32 v181, 0xbfb8aa3b, v181
	v_exp_f32_e32 v174, v174
	v_exp_f32_e32 v177, v177
	v_exp_f32_e32 v179, v179
	v_exp_f32_e32 v180, v180
	v_exp_f32_e32 v181, v181
	v_add_f32_e32 v174, 1.0, v174
	v_add_f32_e32 v177, 1.0, v177
	v_add_f32_e32 v179, 1.0, v179
	v_add_f32_e32 v180, 1.0, v180
	v_add_f32_e32 v181, 1.0, v181
	v_rcp_f32_e32 v174, v174
	v_rcp_f32_e32 v175, v175
	v_rcp_f32_e32 v176, v176
	v_rcp_f32_e32 v177, v177
	v_rcp_f32_e32 v179, v179
	v_rcp_f32_e32 v180, v180
	v_rcp_f32_e32 v181, v181
	v_cvt_pk_bf16_f32 v174, v174, v175
	v_cvt_pk_bf16_f32 v176, v178, v176
	v_cvt_pk_bf16_f32 v175, v177, v180
	v_cvt_pk_bf16_f32 v177, v179, v181
	v_mad_i64_i32 v[178:179], s[0:1], v190, s31, v[166:167]
	v_lshl_add_u64 v[178:179], v[178:179], 0, v[168:169]
	v_fma_f32 v181, v52, v161, v132
	v_fma_f32 v180, v56, v161, v136
	v_mul_f32_e32 v181, 0xbfb8aa3b, v181
	global_store_dwordx4 v[178:179], v[174:177], off sc1
	v_mul_f32_e32 v180, 0xbfb8aa3b, v180
	v_exp_f32_e32 v181, v181
	v_fma_f32 v176, v57, v161, v137
	v_fma_f32 v177, v53, v161, v133
	v_mul_f32_e32 v176, 0xbfb8aa3b, v176
	v_mul_f32_e32 v177, 0xbfb8aa3b, v177
	v_exp_f32_e32 v180, v180
	v_exp_f32_e32 v176, v176
	v_exp_f32_e32 v177, v177
	v_add_f32_e32 v175, 1.0, v181
	v_add_f32_e32 v174, 1.0, v180
	v_rcp_f32_e32 v180, v175
	v_add_f32_e32 v175, 1.0, v176
	v_add_f32_e32 v176, 1.0, v177
	v_fma_f32 v177, v58, v161, v138
	v_fma_f32 v181, v54, v161, v134
	v_fma_f32 v182, v59, v161, v139
	v_fma_f32 v161, v55, v161, v135
	v_mul_f32_e32 v177, 0xbfb8aa3b, v177
	v_mul_f32_e32 v181, 0xbfb8aa3b, v181
	v_mul_f32_e32 v182, 0xbfb8aa3b, v182
	v_mul_f32_e32 v161, 0xbfb8aa3b, v161
	v_exp_f32_e32 v177, v177
	v_exp_f32_e32 v181, v181
	v_exp_f32_e32 v182, v182
	v_exp_f32_e32 v161, v161
	v_add_f32_e32 v177, 1.0, v177
	v_add_f32_e32 v181, 1.0, v181
	v_add_f32_e32 v182, 1.0, v182
	v_add_f32_e32 v161, 1.0, v161
	v_rcp_f32_e32 v174, v174
	v_rcp_f32_e32 v175, v175
	v_rcp_f32_e32 v176, v176
	v_rcp_f32_e32 v177, v177
	v_rcp_f32_e32 v181, v181
	v_rcp_f32_e32 v182, v182
	v_rcp_f32_e32 v161, v161
	v_add_u32_e32 v190, 0x90, v158
	v_cvt_pk_bf16_f32 v174, v174, v175
	v_cvt_pk_bf16_f32 v175, v177, v182
	v_cvt_pk_bf16_f32 v176, v180, v176
	v_cvt_pk_bf16_f32 v177, v181, v161
	global_store_dwordx4 v[178:179], v[174:177], off offset:256 sc1
	s_nop 1
	v_mov_b32_e32 v161, v207
	v_fma_f32 v175, v44, v161, v140
	v_mul_f32_e32 v175, 0xbfb8aa3b, v175
	v_fma_f32 v176, v49, v161, v145
	v_fma_f32 v177, v45, v161, v141
	v_exp_f32_e32 v175, v175
	v_mul_f32_e32 v176, 0xbfb8aa3b, v176
	v_mul_f32_e32 v177, 0xbfb8aa3b, v177
	v_exp_f32_e32 v176, v176
	v_exp_f32_e32 v177, v177
	v_add_f32_e32 v175, 1.0, v175
	v_fma_f32 v174, v48, v161, v144
	v_rcp_f32_e32 v178, v175
	v_add_f32_e32 v175, 1.0, v176
	v_add_f32_e32 v176, 1.0, v177
	v_fma_f32 v177, v50, v161, v146
	v_fma_f32 v179, v46, v161, v142
	v_fma_f32 v180, v51, v161, v147
	v_fma_f32 v181, v47, v161, v143
	v_mul_f32_e32 v174, 0xbfb8aa3b, v174
	v_mul_f32_e32 v177, 0xbfb8aa3b, v177
	v_mul_f32_e32 v179, 0xbfb8aa3b, v179
	v_mul_f32_e32 v180, 0xbfb8aa3b, v180
	v_mul_f32_e32 v181, 0xbfb8aa3b, v181
	v_exp_f32_e32 v174, v174
	v_exp_f32_e32 v177, v177
	v_exp_f32_e32 v179, v179
	v_exp_f32_e32 v180, v180
	v_exp_f32_e32 v181, v181
	v_add_f32_e32 v174, 1.0, v174
	v_add_f32_e32 v177, 1.0, v177
	v_add_f32_e32 v179, 1.0, v179
	v_add_f32_e32 v180, 1.0, v180
	v_add_f32_e32 v181, 1.0, v181
	v_rcp_f32_e32 v174, v174
	v_rcp_f32_e32 v175, v175
	v_rcp_f32_e32 v176, v176
	v_rcp_f32_e32 v177, v177
; __device__ __forceinline__ unsigned pk2(float lo, float hi) { return pg8::cvt_pk_bf16(lo, hi); }
; __device__ __forceinline__ float fast_exp2(float x) { return __builtin_amdgcn_exp2f(x); }
; __device__ __forceinline__ float fast_rcp(float x) { return __builtin_amdgcn_rcpf(x); }
;     __device__ __forceinline__ void operator()(const pg8::f32x4 (&acc)[2][2][4][2], const pg8::Unit& u, int wr, int wc, int fr, int fq) const {
;     ...
;             for (int ai = 0; ai < 2; ++ai)
; #pragma unroll
;                 for (int m = 0; m < 4; ++m) {
;                     const int row = row0 + ai * 128 + m * 16; const float rs = rstd_of(ssq, row);
; #pragma unroll
;                     for (int bj = 0; bj < 2; ++bj) {
;                         float v[8];
; #pragma unroll
;                         for (int j = 0; j < 4; ++j) { v[j] = fast_rcp(1.0f + fast_exp2(-(acc[ai][bj][m][0][j] * rs + bb[bj][0][j]) * LOG2E)); v[4 + j] = fast_rcp(1.0f + fast_exp2(-(acc[ai][bj][m][1][j] * rs + bb[bj][1][j]) * LOG2E)); }
;                         u32x4 w; w.x = pk2(v[0], v[1]); w.y = pk2(v[2], v[3]); w.z = pk2(v[4], v[5]); w.w = pk2(v[6], v[7]);
;                         *(u32x4*)(G + (size_t)row * NGATE + col0 + bj * 128) = w;
;                     }
	v_rcp_f32_e32 v179, v179
	v_rcp_f32_e32 v180, v180
	v_rcp_f32_e32 v181, v181
	v_cvt_pk_bf16_f32 v174, v174, v175
	v_cvt_pk_bf16_f32 v176, v178, v176
	v_cvt_pk_bf16_f32 v175, v177, v180
	v_cvt_pk_bf16_f32 v177, v179, v181
	v_mad_i64_i32 v[178:179], s[0:1], v190, s31, v[166:167]
	v_lshl_add_u64 v[178:179], v[178:179], 0, v[168:169]
	v_fma_f32 v181, v36, v161, v132
	v_fma_f32 v180, v40, v161, v136
	v_mul_f32_e32 v181, 0xbfb8aa3b, v181
	global_store_dwordx4 v[178:179], v[174:177], off sc1
	v_mul_f32_e32 v180, 0xbfb8aa3b, v180
	v_exp_f32_e32 v181, v181
	v_fma_f32 v176, v41, v161, v137
	v_fma_f32 v177, v37, v161, v133
	v_mul_f32_e32 v176, 0xbfb8aa3b, v176
	v_mul_f32_e32 v177, 0xbfb8aa3b, v177
	v_exp_f32_e32 v180, v180
	v_exp_f32_e32 v176, v176
	v_exp_f32_e32 v177, v177
	v_add_f32_e32 v175, 1.0, v181
	v_add_f32_e32 v174, 1.0, v180
	v_rcp_f32_e32 v180, v175
	v_add_f32_e32 v175, 1.0, v176
	v_add_f32_e32 v176, 1.0, v177
	v_fma_f32 v177, v42, v161, v138
	v_fma_f32 v181, v38, v161, v134
	v_fma_f32 v182, v43, v161, v139
	v_fma_f32 v161, v39, v161, v135
	v_mul_f32_e32 v177, 0xbfb8aa3b, v177
	v_mul_f32_e32 v181, 0xbfb8aa3b, v181
	v_mul_f32_e32 v182, 0xbfb8aa3b, v182
	v_mul_f32_e32 v161, 0xbfb8aa3b, v161
	v_exp_f32_e32 v177, v177
	v_exp_f32_e32 v181, v181
	v_exp_f32_e32 v182, v182
	v_exp_f32_e32 v161, v161
	v_add_f32_e32 v177, 1.0, v177
	v_add_f32_e32 v181, 1.0, v181
	v_add_f32_e32 v182, 1.0, v182
	v_add_f32_e32 v161, 1.0, v161
	v_rcp_f32_e32 v174, v174
	v_rcp_f32_e32 v175, v175
	v_rcp_f32_e32 v176, v176
	v_rcp_f32_e32 v177, v177
	v_rcp_f32_e32 v181, v181
	v_rcp_f32_e32 v182, v182
	v_rcp_f32_e32 v161, v161
	v_add_u32_e32 v190, 0xa0, v158
	v_cvt_pk_bf16_f32 v174, v174, v175
	v_cvt_pk_bf16_f32 v175, v177, v182
	v_cvt_pk_bf16_f32 v176, v180, v176
	v_cvt_pk_bf16_f32 v177, v181, v161
	global_store_dwordx4 v[178:179], v[174:177], off offset:256 sc1
	s_nop 1
	v_mov_b32_e32 v161, v208
	v_fma_f32 v175, v24, v161, v140
	v_mul_f32_e32 v175, 0xbfb8aa3b, v175
	v_fma_f32 v176, v29, v161, v145
	v_fma_f32 v177, v25, v161, v141
	v_exp_f32_e32 v175, v175
	v_mul_f32_e32 v176, 0xbfb8aa3b, v176
	v_mul_f32_e32 v177, 0xbfb8aa3b, v177
	v_exp_f32_e32 v176, v176
	v_exp_f32_e32 v177, v177
	v_add_f32_e32 v175, 1.0, v175
	v_fma_f32 v174, v28, v161, v144
	v_rcp_f32_e32 v178, v175
	v_add_f32_e32 v175, 1.0, v176
	v_add_f32_e32 v176, 1.0, v177
	v_fma_f32 v177, v30, v161, v146
	v_fma_f32 v179, v26, v161, v142
	v_fma_f32 v180, v31, v161, v147
	v_fma_f32 v181, v27, v161, v143
	v_mul_f32_e32 v174, 0xbfb8aa3b, v174
	v_mul_f32_e32 v177, 0xbfb8aa3b, v177
	v_mul_f32_e32 v179, 0xbfb8aa3b, v179
	v_mul_f32_e32 v180, 0xbfb8aa3b, v180
	v_mul_f32_e32 v181, 0xbfb8aa3b, v181
	v_exp_f32_e32 v174, v174
	v_exp_f32_e32 v177, v177
	v_exp_f32_e32 v179, v179
	v_exp_f32_e32 v180, v180
	v_exp_f32_e32 v181, v181
	v_add_f32_e32 v174, 1.0, v174
	v_add_f32_e32 v177, 1.0, v177
	v_add_f32_e32 v179, 1.0, v179
	v_add_f32_e32 v180, 1.0, v180
	v_add_f32_e32 v181, 1.0, v181
	v_rcp_f32_e32 v174, v174
	v_rcp_f32_e32 v175, v175
	v_rcp_f32_e32 v176, v176
	v_rcp_f32_e32 v177, v177
	v_rcp_f32_e32 v179, v179
	v_rcp_f32_e32 v180, v180
	v_rcp_f32_e32 v181, v181
	v_cvt_pk_bf16_f32 v174, v174, v175
	v_cvt_pk_bf16_f32 v176, v178, v176
	v_cvt_pk_bf16_f32 v175, v177, v180
	v_cvt_pk_bf16_f32 v177, v179, v181
	v_mad_i64_i32 v[178:179], s[0:1], v190, s31, v[166:167]
	v_lshl_add_u64 v[178:179], v[178:179], 0, v[168:169]
	v_fma_f32 v181, v16, v161, v132
	v_fma_f32 v180, v20, v161, v136
	v_mul_f32_e32 v181, 0xbfb8aa3b, v181
	global_store_dwordx4 v[178:179], v[174:177], off sc1
	v_mul_f32_e32 v180, 0xbfb8aa3b, v180
	v_exp_f32_e32 v181, v181
	v_fma_f32 v176, v21, v161, v137
	v_fma_f32 v177, v17, v161, v133
	v_mul_f32_e32 v176, 0xbfb8aa3b, v176
	v_mul_f32_e32 v177, 0xbfb8aa3b, v177
	v_exp_f32_e32 v180, v180
	v_exp_f32_e32 v176, v176
	v_exp_f32_e32 v177, v177
	v_add_f32_e32 v175, 1.0, v181
	v_add_f32_e32 v174, 1.0, v180
	v_rcp_f32_e32 v180, v175
	v_add_f32_e32 v175, 1.0, v176
	v_add_f32_e32 v176, 1.0, v177
; __device__ __forceinline__ unsigned pk2(float lo, float hi) { return pg8::cvt_pk_bf16(lo, hi); }
; __device__ __forceinline__ float fast_exp2(float x) { return __builtin_amdgcn_exp2f(x); }
; __device__ __forceinline__ float fast_rcp(float x) { return __builtin_amdgcn_rcpf(x); }
;     __device__ __forceinline__ void operator()(const pg8::f32x4 (&acc)[2][2][4][2], const pg8::Unit& u, int wr, int wc, int fr, int fq) const {
;     ...
;             for (int ai = 0; ai < 2; ++ai)
; #pragma unroll
;                 for (int m = 0; m < 4; ++m) {
;                     const int row = row0 + ai * 128 + m * 16; const float rs = rstd_of(ssq, row);
; #pragma unroll
;                     for (int bj = 0; bj < 2; ++bj) {
;                         float v[8];
; #pragma unroll
;                         for (int j = 0; j < 4; ++j) { v[j] = fast_rcp(1.0f + fast_exp2(-(acc[ai][bj][m][0][j] * rs + bb[bj][0][j]) * LOG2E)); v[4 + j] = fast_rcp(1.0f + fast_exp2(-(acc[ai][bj][m][1][j] * rs + bb[bj][1][j]) * LOG2E)); }
;                         u32x4 w; w.x = pk2(v[0], v[1]); w.y = pk2(v[2], v[3]); w.z = pk2(v[4], v[5]); w.w = pk2(v[6], v[7]);
;                         *(u32x4*)(G + (size_t)row * NGATE + col0 + bj * 128) = w;
;                     }
	v_fma_f32 v177, v22, v161, v138
	v_fma_f32 v181, v18, v161, v134
	v_fma_f32 v182, v23, v161, v139
	v_fma_f32 v161, v19, v161, v135
	v_mul_f32_e32 v177, 0xbfb8aa3b, v177
	v_mul_f32_e32 v181, 0xbfb8aa3b, v181
	v_mul_f32_e32 v182, 0xbfb8aa3b, v182
	v_mul_f32_e32 v161, 0xbfb8aa3b, v161
	v_exp_f32_e32 v177, v177
	v_exp_f32_e32 v181, v181
	v_exp_f32_e32 v182, v182
	v_exp_f32_e32 v161, v161
	v_add_f32_e32 v177, 1.0, v177
	v_add_f32_e32 v181, 1.0, v181
	v_add_f32_e32 v182, 1.0, v182
	v_add_f32_e32 v161, 1.0, v161
	v_rcp_f32_e32 v174, v174
	v_rcp_f32_e32 v175, v175
	v_rcp_f32_e32 v176, v176
	v_rcp_f32_e32 v177, v177
	v_rcp_f32_e32 v181, v181
	v_rcp_f32_e32 v182, v182
	v_rcp_f32_e32 v161, v161
	v_add_u32_e32 v190, 0xb0, v158
	v_cvt_pk_bf16_f32 v174, v174, v175
	v_cvt_pk_bf16_f32 v175, v177, v182
	v_cvt_pk_bf16_f32 v176, v180, v176
	v_cvt_pk_bf16_f32 v177, v181, v161
	global_store_dwordx4 v[178:179], v[174:177], off offset:256 sc1
	s_nop 1
	v_mov_b32_e32 v161, v209
	v_fma_f32 v140, v8, v161, v140
	v_mul_f32_e32 v140, 0xbfb8aa3b, v140
	v_fma_f32 v145, v13, v161, v145
	v_exp_f32_e32 v140, v140
	v_mul_f32_e32 v145, 0xbfb8aa3b, v145
	v_exp_f32_e32 v145, v145
	v_fma_f32 v141, v9, v161, v141
	v_add_f32_e32 v140, 1.0, v140
	v_mul_f32_e32 v141, 0xbfb8aa3b, v141
	v_rcp_f32_e32 v174, v140
	v_add_f32_e32 v140, 1.0, v145
	v_fma_f32 v145, v14, v161, v146
	v_exp_f32_e32 v141, v141
	v_mul_f32_e32 v145, 0xbfb8aa3b, v145
	v_exp_f32_e32 v145, v145
	v_fma_f32 v144, v12, v161, v144
	v_fma_f32 v142, v10, v161, v142
	v_mul_f32_e32 v144, 0xbfb8aa3b, v144
	v_add_f32_e32 v141, 1.0, v141
	v_mul_f32_e32 v142, 0xbfb8aa3b, v142
	v_fmac_f32_e32 v147, v15, v161
	v_fmac_f32_e32 v143, v11, v161
	v_exp_f32_e32 v144, v144
	v_exp_f32_e32 v142, v142
	v_rcp_f32_e32 v146, v141
	v_add_f32_e32 v141, 1.0, v145
	v_mul_f32_e32 v145, 0xbfb8aa3b, v147
	v_mul_f32_e32 v143, 0xbfb8aa3b, v143
	v_exp_f32_e32 v145, v145
	v_exp_f32_e32 v143, v143
	v_add_f32_e32 v144, 1.0, v144
	v_add_f32_e32 v142, 1.0, v142
	v_fma_f32 v132, v0, v161, v132
	v_rcp_f32_e32 v144, v144
	v_rcp_f32_e32 v140, v140
	v_rcp_f32_e32 v147, v142
	v_add_f32_e32 v142, 1.0, v145
	v_add_f32_e32 v143, 1.0, v143
	v_mul_f32_e32 v132, 0xbfb8aa3b, v132
	v_fma_f32 v137, v5, v161, v137
	v_rcp_f32_e32 v141, v141
	v_rcp_f32_e32 v142, v142
	v_rcp_f32_e32 v143, v143
	v_exp_f32_e32 v132, v132
	v_mul_f32_e32 v137, 0xbfb8aa3b, v137
	v_exp_f32_e32 v137, v137
	v_cvt_pk_bf16_f32 v140, v144, v140
	v_mad_i64_i32 v[144:145], s[0:1], v190, s31, v[166:167]
	v_cvt_pk_bf16_f32 v141, v141, v142
	v_cvt_pk_bf16_f32 v142, v174, v146
	v_cvt_pk_bf16_f32 v143, v147, v143
	v_lshl_add_u64 v[144:145], v[144:145], 0, v[168:169]
	v_add_f32_e32 v132, 1.0, v132
	v_fma_f32 v133, v1, v161, v133
	global_store_dwordx4 v[144:145], v[140:143], off sc1
	v_mul_f32_e32 v133, 0xbfb8aa3b, v133
	v_exp_f32_e32 v133, v133
	v_rcp_f32_e32 v140, v132
	v_add_f32_e32 v132, 1.0, v137
	v_fma_f32 v137, v6, v161, v138
	v_mul_f32_e32 v137, 0xbfb8aa3b, v137
	v_exp_f32_e32 v137, v137
	v_fma_f32 v134, v2, v161, v134
	v_fma_f32 v136, v4, v161, v136
	v_add_f32_e32 v133, 1.0, v133
	v_mul_f32_e32 v134, 0xbfb8aa3b, v134
	v_fmac_f32_e32 v139, v7, v161
	v_fmac_f32_e32 v135, v3, v161
	v_mul_f32_e32 v136, 0xbfb8aa3b, v136
	v_exp_f32_e32 v134, v134
	v_rcp_f32_e32 v138, v133
	v_add_f32_e32 v133, 1.0, v137
	v_mul_f32_e32 v137, 0xbfb8aa3b, v139
	v_mul_f32_e32 v135, 0xbfb8aa3b, v135
	v_exp_f32_e32 v136, v136
	v_exp_f32_e32 v137, v137
	v_exp_f32_e32 v135, v135
	v_add_f32_e32 v134, 1.0, v134
	v_add_f32_e32 v136, 1.0, v136
	v_rcp_f32_e32 v139, v134
	v_add_f32_e32 v134, 1.0, v137
	v_add_f32_e32 v135, 1.0, v135
	v_rcp_f32_e32 v136, v136
	v_rcp_f32_e32 v132, v132
	v_rcp_f32_e32 v133, v133
	v_rcp_f32_e32 v134, v134
	v_rcp_f32_e32 v135, v135
	v_cvt_pk_bf16_f32 v132, v136, v132
	s_mov_b64 s[0:1], 0
	v_cvt_pk_bf16_f32 v133, v133, v134
	v_cvt_pk_bf16_f32 v134, v140, v138
	v_cvt_pk_bf16_f32 v135, v139, v135
	global_store_dwordx4 v[144:145], v[132:135], off offset:256 sc1

; __device__ __forceinline__ unsigned pk2(float lo, float hi) { return pg8::cvt_pk_bf16(lo, hi); }
;     __device__ __forceinline__ void operator()(const pg8::f32x4 (&acc)[2][2][4][2], const pg8::Unit& u, int wr, int wc, int fr, int fq) const {
;     ...
;             const float sc = ((u.pn % 6) < 2) ? QSCALE : 1.0f;
;             const int col0 = u.pn * 256 + wc * 32 + 8 * fq;
;             const bool vt_all = (u.pn == 4) | (u.pn == 5) | (u.pn == 10) | (u.pn == 11), vt_half = (u.pn == 14);
;             const int vrow0 = (u.pn <= 5 ? (u.pn - 4) * 256 : (u.pn <= 11 ? 512 + (u.pn - 10) * 256 : 1024 - 128)) + wc * 32 + 8 * fq;
; #pragma unroll
;             for (int ai = 0; ai < 2; ++ai)
; #pragma unroll
;                 for (int m = 0; m < 4; ++m) {
;                     const int row = row0 + ai * 128 + m * 16; const float rs = rstd_of(ssq, row) * sc;
; #pragma unroll
;                     for (int bj = 0; bj < 2; ++bj) {
;                         const pg8::f32x4 v0 = acc[ai][bj][m][0] * rs, v1 = acc[ai][bj][m][1] * rs;
;                         u32x4 w; w.x = pk2(v0[0], v0[1]); w.y = pk2(v0[2], v0[3]); w.z = pk2(v1[0], v1[1]); w.w = pk2(v1[2], v1[3]);
;                         if (vt_all || (vt_half && bj == 1)) {
;                             bf16_t* vp = vt + (size_t)(vrow0 + bj * 128) * S + row;
;                             vp[0 * (size_t)S] = (bf16_t)(w.x & 0xffffu); vp[1 * (size_t)S] = (bf16_t)(w.x >> 16); vp[2 * (size_t)S] = (bf16_t)(w.y & 0xffffu); vp[3 * (size_t)S] = (bf16_t)(w.y >> 16);
;                             vp[4 * (size_t)S] = (bf16_t)(w.z & 0xffffu); vp[5 * (size_t)S] = (bf16_t)(w.z >> 16); vp[6 * (size_t)S] = (bf16_t)(w.w & 0xffffu); vp[7 * (size_t)S] = (bf16_t)(w.w >> 16);
;                         } else {
;                             *(u32x4*)(proj + (size_t)row * NPROJ + col0 + bj * 128) = w;
.LBB0_352:
	v_mov_b32_e32 v132, 0x3e38aa3b
	v_cndmask_b32_e64 v138, 1.0, v132, s[0:1]
	v_mov_b32_e32 v134, v202
	v_mul_f32_e32 v136, v138, v134
	v_or_b32_e32 v132, s19, v171
	s_movk_i32 s0, 0x1e00
	v_pk_mul_f32 v[130:131], v[130:131], v[136:137] op_sel_hi:[1,0]
	v_pk_mul_f32 v[128:129], v[128:129], v[136:137] op_sel_hi:[1,0]
	v_pk_mul_f32 v[140:141], v[126:127], v[136:137] op_sel_hi:[1,0]
	v_pk_mul_f32 v[126:127], v[124:125], v[136:137] op_sel_hi:[1,0]
	v_ashrrev_i32_e32 v133, 31, v132
	v_mad_i64_i32 v[134:135], s[0:1], v158, s0, 0
	v_cvt_pk_bf16_f32 v124, v128, v129
	v_cvt_pk_bf16_f32 v125, v130, v131
	v_cvt_pk_bf16_f32 v126, v126, v127
	s_andn2_b64 vcc, exec, s[42:43]
	v_cvt_pk_bf16_f32 v127, v140, v141
	s_cbranch_vccnz .LBB0_354
	v_lshl_add_u64 v[128:129], s[34:35], 0, v[134:135]
	v_lshl_add_u64 v[128:129], v[132:133], 1, v[128:129]
	global_store_dwordx4 v[128:129], v[124:127], off sc1
	s_mov_b64 s[4:5], 0

; __device__ __forceinline__ unsigned pk2(float lo, float hi) { return pg8::cvt_pk_bf16(lo, hi); }
;     __device__ __forceinline__ void operator()(const pg8::f32x4 (&acc)[2][2][4][2], const pg8::Unit& u, int wr, int wc, int fr, int fq) const {
;     ...
;                     const int row = row0 + ai * 128 + m * 16; const float rs = rstd_of(ssq, row) * sc;
; #pragma unroll
;                     for (int bj = 0; bj < 2; ++bj) {
;                         const pg8::f32x4 v0 = acc[ai][bj][m][0] * rs, v1 = acc[ai][bj][m][1] * rs;
;                         u32x4 w; w.x = pk2(v0[0], v0[1]); w.y = pk2(v0[2], v0[3]); w.z = pk2(v1[0], v1[1]); w.w = pk2(v1[2], v1[3]);
;                         if (vt_all || (vt_half && bj == 1)) {
;                             bf16_t* vp = vt + (size_t)(vrow0 + bj * 128) * S + row;
;                             vp[0 * (size_t)S] = (bf16_t)(w.x & 0xffffu); vp[1 * (size_t)S] = (bf16_t)(w.x >> 16); vp[2 * (size_t)S] = (bf16_t)(w.y & 0xffffu); vp[3 * (size_t)S] = (bf16_t)(w.y >> 16);
;                             vp[4 * (size_t)S] = (bf16_t)(w.z & 0xffffu); vp[5 * (size_t)S] = (bf16_t)(w.z >> 16); vp[6 * (size_t)S] = (bf16_t)(w.w & 0xffffu); vp[7 * (size_t)S] = (bf16_t)(w.w >> 16);
;                         } else {
;                             *(u32x4*)(proj + (size_t)row * NPROJ + col0 + bj * 128) = w;
.LBB0_360:
	v_mov_b32_e32 v124, v136
	v_mov_b32_e32 v125, v136
	v_pk_mul_f32 v[122:123], v[122:123], v[124:125]
	v_pk_mul_f32 v[120:121], v[120:121], v[136:137]
	v_pk_mul_f32 v[124:125], v[118:119], v[124:125]
	v_pk_mul_f32 v[118:119], v[116:117], v[136:137]
	v_cvt_pk_bf16_f32 v116, v120, v121
	v_cvt_pk_bf16_f32 v117, v122, v123
	v_cvt_pk_bf16_f32 v118, v118, v119
	s_andn2_b64 vcc, exec, s[44:45]
	v_cvt_pk_bf16_f32 v119, v124, v125
	s_cbranch_vccnz .LBB0_363
	s_and_b64 vcc, exec, s[42:43]
	s_mov_b64 s[0:1], s[4:5]
	s_cbranch_vccz .LBB0_363
	v_lshl_add_u64 v[120:121], s[34:35], 0, v[134:135]
	v_lshl_add_u64 v[120:121], v[132:133], 1, v[120:121]
	global_store_dwordx4 v[120:121], v[116:119], off offset:256 sc1
	s_mov_b64 s[0:1], s[4:5]

; __device__ __forceinline__ unsigned pk2(float lo, float hi) { return pg8::cvt_pk_bf16(lo, hi); }
;     __device__ __forceinline__ void operator()(const pg8::f32x4 (&acc)[2][2][4][2], const pg8::Unit& u, int wr, int wc, int fr, int fq) const {
;     ...
;                     const int row = row0 + ai * 128 + m * 16; const float rs = rstd_of(ssq, row) * sc;
; #pragma unroll
;                     for (int bj = 0; bj < 2; ++bj) {
;                         const pg8::f32x4 v0 = acc[ai][bj][m][0] * rs, v1 = acc[ai][bj][m][1] * rs;
;                         u32x4 w; w.x = pk2(v0[0], v0[1]); w.y = pk2(v0[2], v0[3]); w.z = pk2(v1[0], v1[1]); w.w = pk2(v1[2], v1[3]);
;                         if (vt_all || (vt_half && bj == 1)) {
;                             bf16_t* vp = vt + (size_t)(vrow0 + bj * 128) * S + row;
;                             vp[0 * (size_t)S] = (bf16_t)(w.x & 0xffffu); vp[1 * (size_t)S] = (bf16_t)(w.x >> 16); vp[2 * (size_t)S] = (bf16_t)(w.y & 0xffffu); vp[3 * (size_t)S] = (bf16_t)(w.y >> 16);
;                             vp[4 * (size_t)S] = (bf16_t)(w.z & 0xffffu); vp[5 * (size_t)S] = (bf16_t)(w.z >> 16); vp[6 * (size_t)S] = (bf16_t)(w.w & 0xffffu); vp[7 * (size_t)S] = (bf16_t)(w.w >> 16);
;                         } else {
;                             *(u32x4*)(proj + (size_t)row * NPROJ + col0 + bj * 128) = w;
.LBB0_373:
	v_lshl_add_u64 v[112:113], s[34:35], 0, v[116:117]
	v_lshl_add_u64 v[112:113], v[132:133], 1, v[112:113]
	global_store_dwordx4 v[112:113], v[108:111], off sc1
	s_cbranch_execnz .LBB0_371

; __device__ __forceinline__ unsigned pk2(float lo, float hi) { return pg8::cvt_pk_bf16(lo, hi); }
;     __device__ __forceinline__ void operator()(const pg8::f32x4 (&acc)[2][2][4][2], const pg8::Unit& u, int wr, int wc, int fr, int fq) const {
;     ...
;                     const int row = row0 + ai * 128 + m * 16; const float rs = rstd_of(ssq, row) * sc;
; #pragma unroll
;                     for (int bj = 0; bj < 2; ++bj) {
;                         const pg8::f32x4 v0 = acc[ai][bj][m][0] * rs, v1 = acc[ai][bj][m][1] * rs;
;                         u32x4 w; w.x = pk2(v0[0], v0[1]); w.y = pk2(v0[2], v0[3]); w.z = pk2(v1[0], v1[1]); w.w = pk2(v1[2], v1[3]);
;                         if (vt_all || (vt_half && bj == 1)) {
;                             bf16_t* vp = vt + (size_t)(vrow0 + bj * 128) * S + row;
;                             vp[0 * (size_t)S] = (bf16_t)(w.x & 0xffffu); vp[1 * (size_t)S] = (bf16_t)(w.x >> 16); vp[2 * (size_t)S] = (bf16_t)(w.y & 0xffffu); vp[3 * (size_t)S] = (bf16_t)(w.y >> 16);
;                             vp[4 * (size_t)S] = (bf16_t)(w.z & 0xffffu); vp[5 * (size_t)S] = (bf16_t)(w.z >> 16); vp[6 * (size_t)S] = (bf16_t)(w.w & 0xffffu); vp[7 * (size_t)S] = (bf16_t)(w.w >> 16);
;                         } else {
;                             *(u32x4*)(proj + (size_t)row * NPROJ + col0 + bj * 128) = w;
.LBB0_377:
	v_mov_b32_e32 v108, v118
	v_mov_b32_e32 v109, v118
	v_pk_mul_f32 v[106:107], v[106:107], v[108:109]
	v_pk_mul_f32 v[104:105], v[104:105], v[118:119]
	v_pk_mul_f32 v[108:109], v[102:103], v[108:109]
	v_pk_mul_f32 v[102:103], v[100:101], v[118:119]
	v_cvt_pk_bf16_f32 v100, v104, v105
	v_cvt_pk_bf16_f32 v101, v106, v107
	v_cvt_pk_bf16_f32 v102, v102, v103
	s_andn2_b64 vcc, exec, s[44:45]
	v_cvt_pk_bf16_f32 v103, v108, v109
	s_cbranch_vccnz .LBB0_380
	s_and_b64 vcc, exec, s[42:43]
	s_mov_b64 s[0:1], s[4:5]
	s_cbranch_vccz .LBB0_380
	v_lshl_add_u64 v[104:105], s[34:35], 0, v[116:117]
	v_lshl_add_u64 v[104:105], v[132:133], 1, v[104:105]
	global_store_dwordx4 v[104:105], v[100:103], off offset:256 sc1
	s_mov_b64 s[0:1], s[4:5]

; __device__ __forceinline__ unsigned pk2(float lo, float hi) { return pg8::cvt_pk_bf16(lo, hi); }
;     __device__ __forceinline__ void operator()(const pg8::f32x4 (&acc)[2][2][4][2], const pg8::Unit& u, int wr, int wc, int fr, int fq) const {
;     ...
;                     const int row = row0 + ai * 128 + m * 16; const float rs = rstd_of(ssq, row) * sc;
; #pragma unroll
;                     for (int bj = 0; bj < 2; ++bj) {
;                         const pg8::f32x4 v0 = acc[ai][bj][m][0] * rs, v1 = acc[ai][bj][m][1] * rs;
;                         u32x4 w; w.x = pk2(v0[0], v0[1]); w.y = pk2(v0[2], v0[3]); w.z = pk2(v1[0], v1[1]); w.w = pk2(v1[2], v1[3]);
;                         if (vt_all || (vt_half && bj == 1)) {
;                             bf16_t* vp = vt + (size_t)(vrow0 + bj * 128) * S + row;
;                             vp[0 * (size_t)S] = (bf16_t)(w.x & 0xffffu); vp[1 * (size_t)S] = (bf16_t)(w.x >> 16); vp[2 * (size_t)S] = (bf16_t)(w.y & 0xffffu); vp[3 * (size_t)S] = (bf16_t)(w.y >> 16);
;                             vp[4 * (size_t)S] = (bf16_t)(w.z & 0xffffu); vp[5 * (size_t)S] = (bf16_t)(w.z >> 16); vp[6 * (size_t)S] = (bf16_t)(w.w & 0xffffu); vp[7 * (size_t)S] = (bf16_t)(w.w >> 16);
;                         } else {
;                             *(u32x4*)(proj + (size_t)row * NPROJ + col0 + bj * 128) = w;
.LBB0_390:
	v_lshl_add_u64 v[96:97], s[34:35], 0, v[100:101]
	v_lshl_add_u64 v[96:97], v[132:133], 1, v[96:97]
	global_store_dwordx4 v[96:97], v[92:95], off sc1
	s_cbranch_execnz .LBB0_388

; __device__ __forceinline__ unsigned pk2(float lo, float hi) { return pg8::cvt_pk_bf16(lo, hi); }
;     __device__ __forceinline__ void operator()(const pg8::f32x4 (&acc)[2][2][4][2], const pg8::Unit& u, int wr, int wc, int fr, int fq) const {
;     ...
;                     const int row = row0 + ai * 128 + m * 16; const float rs = rstd_of(ssq, row) * sc;
; #pragma unroll
;                     for (int bj = 0; bj < 2; ++bj) {
;                         const pg8::f32x4 v0 = acc[ai][bj][m][0] * rs, v1 = acc[ai][bj][m][1] * rs;
;                         u32x4 w; w.x = pk2(v0[0], v0[1]); w.y = pk2(v0[2], v0[3]); w.z = pk2(v1[0], v1[1]); w.w = pk2(v1[2], v1[3]);
;                         if (vt_all || (vt_half && bj == 1)) {
;                             bf16_t* vp = vt + (size_t)(vrow0 + bj * 128) * S + row;
;                             vp[0 * (size_t)S] = (bf16_t)(w.x & 0xffffu); vp[1 * (size_t)S] = (bf16_t)(w.x >> 16); vp[2 * (size_t)S] = (bf16_t)(w.y & 0xffffu); vp[3 * (size_t)S] = (bf16_t)(w.y >> 16);
;                             vp[4 * (size_t)S] = (bf16_t)(w.z & 0xffffu); vp[5 * (size_t)S] = (bf16_t)(w.z >> 16); vp[6 * (size_t)S] = (bf16_t)(w.w & 0xffffu); vp[7 * (size_t)S] = (bf16_t)(w.w >> 16);
;                         } else {
;                             *(u32x4*)(proj + (size_t)row * NPROJ + col0 + bj * 128) = w;
.LBB0_394:
	v_mov_b32_e32 v92, v102
	v_mov_b32_e32 v93, v102
	v_pk_mul_f32 v[90:91], v[90:91], v[92:93]
	v_pk_mul_f32 v[88:89], v[88:89], v[102:103]
	v_pk_mul_f32 v[92:93], v[86:87], v[92:93]
	v_pk_mul_f32 v[86:87], v[84:85], v[102:103]
	v_cvt_pk_bf16_f32 v84, v88, v89
	v_cvt_pk_bf16_f32 v85, v90, v91
	v_cvt_pk_bf16_f32 v86, v86, v87
	s_andn2_b64 vcc, exec, s[44:45]
	v_cvt_pk_bf16_f32 v87, v92, v93
	s_cbranch_vccnz .LBB0_397
	s_and_b64 vcc, exec, s[42:43]
	s_mov_b64 s[0:1], s[4:5]
	s_cbranch_vccz .LBB0_397
	v_lshl_add_u64 v[88:89], s[34:35], 0, v[100:101]
	v_lshl_add_u64 v[88:89], v[132:133], 1, v[88:89]
	global_store_dwordx4 v[88:89], v[84:87], off offset:256 sc1
	s_mov_b64 s[0:1], s[4:5]

; __device__ __forceinline__ unsigned pk2(float lo, float hi) { return pg8::cvt_pk_bf16(lo, hi); }
;     __device__ __forceinline__ void operator()(const pg8::f32x4 (&acc)[2][2][4][2], const pg8::Unit& u, int wr, int wc, int fr, int fq) const {
;     ...
;                     const int row = row0 + ai * 128 + m * 16; const float rs = rstd_of(ssq, row) * sc;
; #pragma unroll
;                     for (int bj = 0; bj < 2; ++bj) {
;                         const pg8::f32x4 v0 = acc[ai][bj][m][0] * rs, v1 = acc[ai][bj][m][1] * rs;
;                         u32x4 w; w.x = pk2(v0[0], v0[1]); w.y = pk2(v0[2], v0[3]); w.z = pk2(v1[0], v1[1]); w.w = pk2(v1[2], v1[3]);
;                         if (vt_all || (vt_half && bj == 1)) {
;                             bf16_t* vp = vt + (size_t)(vrow0 + bj * 128) * S + row;
;                             vp[0 * (size_t)S] = (bf16_t)(w.x & 0xffffu); vp[1 * (size_t)S] = (bf16_t)(w.x >> 16); vp[2 * (size_t)S] = (bf16_t)(w.y & 0xffffu); vp[3 * (size_t)S] = (bf16_t)(w.y >> 16);
;                             vp[4 * (size_t)S] = (bf16_t)(w.z & 0xffffu); vp[5 * (size_t)S] = (bf16_t)(w.z >> 16); vp[6 * (size_t)S] = (bf16_t)(w.w & 0xffffu); vp[7 * (size_t)S] = (bf16_t)(w.w >> 16);
;                         } else {
;                             *(u32x4*)(proj + (size_t)row * NPROJ + col0 + bj * 128) = w;
.LBB0_407:
	v_lshl_add_u64 v[80:81], s[34:35], 0, v[84:85]
	v_lshl_add_u64 v[80:81], v[132:133], 1, v[80:81]
	global_store_dwordx4 v[80:81], v[76:79], off sc1
	s_cbranch_execnz .LBB0_405

; __device__ __forceinline__ unsigned pk2(float lo, float hi) { return pg8::cvt_pk_bf16(lo, hi); }
;     __device__ __forceinline__ void operator()(const pg8::f32x4 (&acc)[2][2][4][2], const pg8::Unit& u, int wr, int wc, int fr, int fq) const {
;     ...
;                     const int row = row0 + ai * 128 + m * 16; const float rs = rstd_of(ssq, row) * sc;
; #pragma unroll
;                     for (int bj = 0; bj < 2; ++bj) {
;                         const pg8::f32x4 v0 = acc[ai][bj][m][0] * rs, v1 = acc[ai][bj][m][1] * rs;
;                         u32x4 w; w.x = pk2(v0[0], v0[1]); w.y = pk2(v0[2], v0[3]); w.z = pk2(v1[0], v1[1]); w.w = pk2(v1[2], v1[3]);
;                         if (vt_all || (vt_half && bj == 1)) {
;                             bf16_t* vp = vt + (size_t)(vrow0 + bj * 128) * S + row;
;                             vp[0 * (size_t)S] = (bf16_t)(w.x & 0xffffu); vp[1 * (size_t)S] = (bf16_t)(w.x >> 16); vp[2 * (size_t)S] = (bf16_t)(w.y & 0xffffu); vp[3 * (size_t)S] = (bf16_t)(w.y >> 16);
;                             vp[4 * (size_t)S] = (bf16_t)(w.z & 0xffffu); vp[5 * (size_t)S] = (bf16_t)(w.z >> 16); vp[6 * (size_t)S] = (bf16_t)(w.w & 0xffffu); vp[7 * (size_t)S] = (bf16_t)(w.w >> 16);
;                         } else {
;                             *(u32x4*)(proj + (size_t)row * NPROJ + col0 + bj * 128) = w;
.LBB0_411:
	v_mov_b32_e32 v76, v86
	v_mov_b32_e32 v77, v86
	v_pk_mul_f32 v[74:75], v[74:75], v[76:77]
	v_pk_mul_f32 v[72:73], v[72:73], v[86:87]
	v_pk_mul_f32 v[76:77], v[70:71], v[76:77]
	v_pk_mul_f32 v[70:71], v[68:69], v[86:87]
	v_cvt_pk_bf16_f32 v68, v72, v73
	v_cvt_pk_bf16_f32 v69, v74, v75
	v_cvt_pk_bf16_f32 v70, v70, v71
	s_andn2_b64 vcc, exec, s[44:45]
	v_cvt_pk_bf16_f32 v71, v76, v77
	s_cbranch_vccnz .LBB0_414
	s_and_b64 vcc, exec, s[42:43]
	s_mov_b64 s[0:1], s[4:5]
	s_cbranch_vccz .LBB0_414
	v_lshl_add_u64 v[72:73], s[34:35], 0, v[84:85]
	v_lshl_add_u64 v[72:73], v[132:133], 1, v[72:73]
	global_store_dwordx4 v[72:73], v[68:71], off offset:256 sc1
	s_mov_b64 s[0:1], s[4:5]

; __device__ __forceinline__ unsigned pk2(float lo, float hi) { return pg8::cvt_pk_bf16(lo, hi); }
;     __device__ __forceinline__ void operator()(const pg8::f32x4 (&acc)[2][2][4][2], const pg8::Unit& u, int wr, int wc, int fr, int fq) const {
;     ...
;                     const int row = row0 + ai * 128 + m * 16; const float rs = rstd_of(ssq, row) * sc;
; #pragma unroll
;                     for (int bj = 0; bj < 2; ++bj) {
;                         const pg8::f32x4 v0 = acc[ai][bj][m][0] * rs, v1 = acc[ai][bj][m][1] * rs;
;                         u32x4 w; w.x = pk2(v0[0], v0[1]); w.y = pk2(v0[2], v0[3]); w.z = pk2(v1[0], v1[1]); w.w = pk2(v1[2], v1[3]);
;                         if (vt_all || (vt_half && bj == 1)) {
;                             bf16_t* vp = vt + (size_t)(vrow0 + bj * 128) * S + row;
;                             vp[0 * (size_t)S] = (bf16_t)(w.x & 0xffffu); vp[1 * (size_t)S] = (bf16_t)(w.x >> 16); vp[2 * (size_t)S] = (bf16_t)(w.y & 0xffffu); vp[3 * (size_t)S] = (bf16_t)(w.y >> 16);
;                             vp[4 * (size_t)S] = (bf16_t)(w.z & 0xffffu); vp[5 * (size_t)S] = (bf16_t)(w.z >> 16); vp[6 * (size_t)S] = (bf16_t)(w.w & 0xffffu); vp[7 * (size_t)S] = (bf16_t)(w.w >> 16);
;                         } else {
;                             *(u32x4*)(proj + (size_t)row * NPROJ + col0 + bj * 128) = w;
.LBB0_424:
	v_lshl_add_u64 v[64:65], s[34:35], 0, v[68:69]
	v_lshl_add_u64 v[64:65], v[132:133], 1, v[64:65]
	global_store_dwordx4 v[64:65], v[60:63], off sc1
	s_cbranch_execnz .LBB0_422

; __device__ __forceinline__ unsigned pk2(float lo, float hi) { return pg8::cvt_pk_bf16(lo, hi); }
;     __device__ __forceinline__ void operator()(const pg8::f32x4 (&acc)[2][2][4][2], const pg8::Unit& u, int wr, int wc, int fr, int fq) const {
;     ...
;                     const int row = row0 + ai * 128 + m * 16; const float rs = rstd_of(ssq, row) * sc;
; #pragma unroll
;                     for (int bj = 0; bj < 2; ++bj) {
;                         const pg8::f32x4 v0 = acc[ai][bj][m][0] * rs, v1 = acc[ai][bj][m][1] * rs;
;                         u32x4 w; w.x = pk2(v0[0], v0[1]); w.y = pk2(v0[2], v0[3]); w.z = pk2(v1[0], v1[1]); w.w = pk2(v1[2], v1[3]);
;                         if (vt_all || (vt_half && bj == 1)) {
;                             bf16_t* vp = vt + (size_t)(vrow0 + bj * 128) * S + row;
;                             vp[0 * (size_t)S] = (bf16_t)(w.x & 0xffffu); vp[1 * (size_t)S] = (bf16_t)(w.x >> 16); vp[2 * (size_t)S] = (bf16_t)(w.y & 0xffffu); vp[3 * (size_t)S] = (bf16_t)(w.y >> 16);
;                             vp[4 * (size_t)S] = (bf16_t)(w.z & 0xffffu); vp[5 * (size_t)S] = (bf16_t)(w.z >> 16); vp[6 * (size_t)S] = (bf16_t)(w.w & 0xffffu); vp[7 * (size_t)S] = (bf16_t)(w.w >> 16);
;                         } else {
;                             *(u32x4*)(proj + (size_t)row * NPROJ + col0 + bj * 128) = w;
.LBB0_428:
	v_mov_b32_e32 v60, v70
	v_mov_b32_e32 v61, v70
	v_pk_mul_f32 v[58:59], v[58:59], v[60:61]
	v_pk_mul_f32 v[56:57], v[56:57], v[70:71]
	v_pk_mul_f32 v[60:61], v[54:55], v[60:61]
	v_pk_mul_f32 v[54:55], v[52:53], v[70:71]
	v_cvt_pk_bf16_f32 v52, v56, v57
	v_cvt_pk_bf16_f32 v53, v58, v59
	v_cvt_pk_bf16_f32 v54, v54, v55
	s_andn2_b64 vcc, exec, s[44:45]
	v_cvt_pk_bf16_f32 v55, v60, v61
	s_cbranch_vccnz .LBB0_431
	s_and_b64 vcc, exec, s[42:43]
	s_mov_b64 s[0:1], s[4:5]
	s_cbranch_vccz .LBB0_431
	v_lshl_add_u64 v[56:57], s[34:35], 0, v[68:69]
	v_lshl_add_u64 v[56:57], v[132:133], 1, v[56:57]
	global_store_dwordx4 v[56:57], v[52:55], off offset:256 sc1
	s_mov_b64 s[0:1], s[4:5]

; __device__ __forceinline__ unsigned pk2(float lo, float hi) { return pg8::cvt_pk_bf16(lo, hi); }
;     __device__ __forceinline__ void operator()(const pg8::f32x4 (&acc)[2][2][4][2], const pg8::Unit& u, int wr, int wc, int fr, int fq) const {
;     ...
;                     const int row = row0 + ai * 128 + m * 16; const float rs = rstd_of(ssq, row) * sc;
; #pragma unroll
;                     for (int bj = 0; bj < 2; ++bj) {
;                         const pg8::f32x4 v0 = acc[ai][bj][m][0] * rs, v1 = acc[ai][bj][m][1] * rs;
;                         u32x4 w; w.x = pk2(v0[0], v0[1]); w.y = pk2(v0[2], v0[3]); w.z = pk2(v1[0], v1[1]); w.w = pk2(v1[2], v1[3]);
;                         if (vt_all || (vt_half && bj == 1)) {
;                             bf16_t* vp = vt + (size_t)(vrow0 + bj * 128) * S + row;
;                             vp[0 * (size_t)S] = (bf16_t)(w.x & 0xffffu); vp[1 * (size_t)S] = (bf16_t)(w.x >> 16); vp[2 * (size_t)S] = (bf16_t)(w.y & 0xffffu); vp[3 * (size_t)S] = (bf16_t)(w.y >> 16);
;                             vp[4 * (size_t)S] = (bf16_t)(w.z & 0xffffu); vp[5 * (size_t)S] = (bf16_t)(w.z >> 16); vp[6 * (size_t)S] = (bf16_t)(w.w & 0xffffu); vp[7 * (size_t)S] = (bf16_t)(w.w >> 16);
;                         } else {
;                             *(u32x4*)(proj + (size_t)row * NPROJ + col0 + bj * 128) = w;
.LBB0_441:
	v_lshl_add_u64 v[48:49], s[34:35], 0, v[52:53]
	v_lshl_add_u64 v[48:49], v[132:133], 1, v[48:49]
	global_store_dwordx4 v[48:49], v[44:47], off sc1
	s_cbranch_execnz .LBB0_439

; __device__ __forceinline__ unsigned pk2(float lo, float hi) { return pg8::cvt_pk_bf16(lo, hi); }
;     __device__ __forceinline__ void operator()(const pg8::f32x4 (&acc)[2][2][4][2], const pg8::Unit& u, int wr, int wc, int fr, int fq) const {
;     ...
;                     const int row = row0 + ai * 128 + m * 16; const float rs = rstd_of(ssq, row) * sc;
; #pragma unroll
;                     for (int bj = 0; bj < 2; ++bj) {
;                         const pg8::f32x4 v0 = acc[ai][bj][m][0] * rs, v1 = acc[ai][bj][m][1] * rs;
;                         u32x4 w; w.x = pk2(v0[0], v0[1]); w.y = pk2(v0[2], v0[3]); w.z = pk2(v1[0], v1[1]); w.w = pk2(v1[2], v1[3]);
;                         if (vt_all || (vt_half && bj == 1)) {
;                             bf16_t* vp = vt + (size_t)(vrow0 + bj * 128) * S + row;
;                             vp[0 * (size_t)S] = (bf16_t)(w.x & 0xffffu); vp[1 * (size_t)S] = (bf16_t)(w.x >> 16); vp[2 * (size_t)S] = (bf16_t)(w.y & 0xffffu); vp[3 * (size_t)S] = (bf16_t)(w.y >> 16);
;                             vp[4 * (size_t)S] = (bf16_t)(w.z & 0xffffu); vp[5 * (size_t)S] = (bf16_t)(w.z >> 16); vp[6 * (size_t)S] = (bf16_t)(w.w & 0xffffu); vp[7 * (size_t)S] = (bf16_t)(w.w >> 16);
;                         } else {
;                             *(u32x4*)(proj + (size_t)row * NPROJ + col0 + bj * 128) = w;
.LBB0_445:
	v_mov_b32_e32 v44, v54
	v_mov_b32_e32 v45, v54
	v_pk_mul_f32 v[42:43], v[42:43], v[44:45]
	v_pk_mul_f32 v[40:41], v[40:41], v[54:55]
	v_pk_mul_f32 v[44:45], v[38:39], v[44:45]
	v_pk_mul_f32 v[38:39], v[36:37], v[54:55]
	v_cvt_pk_bf16_f32 v36, v40, v41
	v_cvt_pk_bf16_f32 v37, v42, v43
	v_cvt_pk_bf16_f32 v38, v38, v39
	s_andn2_b64 vcc, exec, s[44:45]
	v_cvt_pk_bf16_f32 v39, v44, v45
	s_cbranch_vccnz .LBB0_448
	s_and_b64 vcc, exec, s[42:43]
	s_mov_b64 s[0:1], s[4:5]
	s_cbranch_vccz .LBB0_448
	v_lshl_add_u64 v[40:41], s[34:35], 0, v[52:53]
	v_lshl_add_u64 v[40:41], v[132:133], 1, v[40:41]
	global_store_dwordx4 v[40:41], v[36:39], off offset:256 sc1
	s_mov_b64 s[0:1], s[4:5]

; __device__ __forceinline__ unsigned pk2(float lo, float hi) { return pg8::cvt_pk_bf16(lo, hi); }
;     __device__ __forceinline__ void operator()(const pg8::f32x4 (&acc)[2][2][4][2], const pg8::Unit& u, int wr, int wc, int fr, int fq) const {
;     ...
;                     const int row = row0 + ai * 128 + m * 16; const float rs = rstd_of(ssq, row) * sc;
; #pragma unroll
;                     for (int bj = 0; bj < 2; ++bj) {
;                         const pg8::f32x4 v0 = acc[ai][bj][m][0] * rs, v1 = acc[ai][bj][m][1] * rs;
;                         u32x4 w; w.x = pk2(v0[0], v0[1]); w.y = pk2(v0[2], v0[3]); w.z = pk2(v1[0], v1[1]); w.w = pk2(v1[2], v1[3]);
;                         if (vt_all || (vt_half && bj == 1)) {
;                             bf16_t* vp = vt + (size_t)(vrow0 + bj * 128) * S + row;
;                             vp[0 * (size_t)S] = (bf16_t)(w.x & 0xffffu); vp[1 * (size_t)S] = (bf16_t)(w.x >> 16); vp[2 * (size_t)S] = (bf16_t)(w.y & 0xffffu); vp[3 * (size_t)S] = (bf16_t)(w.y >> 16);
;                             vp[4 * (size_t)S] = (bf16_t)(w.z & 0xffffu); vp[5 * (size_t)S] = (bf16_t)(w.z >> 16); vp[6 * (size_t)S] = (bf16_t)(w.w & 0xffffu); vp[7 * (size_t)S] = (bf16_t)(w.w >> 16);
;                         } else {
;                             *(u32x4*)(proj + (size_t)row * NPROJ + col0 + bj * 128) = w;
.LBB0_458:
	v_lshl_add_u64 v[28:29], s[34:35], 0, v[36:37]
	v_lshl_add_u64 v[28:29], v[132:133], 1, v[28:29]
	global_store_dwordx4 v[28:29], v[24:27], off sc1
	s_cbranch_execnz .LBB0_456

; __device__ __forceinline__ unsigned pk2(float lo, float hi) { return pg8::cvt_pk_bf16(lo, hi); }
;     __device__ __forceinline__ void operator()(const pg8::f32x4 (&acc)[2][2][4][2], const pg8::Unit& u, int wr, int wc, int fr, int fq) const {
;     ...
;                     const int row = row0 + ai * 128 + m * 16; const float rs = rstd_of(ssq, row) * sc;
; #pragma unroll
;                     for (int bj = 0; bj < 2; ++bj) {
;                         const pg8::f32x4 v0 = acc[ai][bj][m][0] * rs, v1 = acc[ai][bj][m][1] * rs;
;                         u32x4 w; w.x = pk2(v0[0], v0[1]); w.y = pk2(v0[2], v0[3]); w.z = pk2(v1[0], v1[1]); w.w = pk2(v1[2], v1[3]);
;                         if (vt_all || (vt_half && bj == 1)) {
;                             bf16_t* vp = vt + (size_t)(vrow0 + bj * 128) * S + row;
;                             vp[0 * (size_t)S] = (bf16_t)(w.x & 0xffffu); vp[1 * (size_t)S] = (bf16_t)(w.x >> 16); vp[2 * (size_t)S] = (bf16_t)(w.y & 0xffffu); vp[3 * (size_t)S] = (bf16_t)(w.y >> 16);
;                             vp[4 * (size_t)S] = (bf16_t)(w.z & 0xffffu); vp[5 * (size_t)S] = (bf16_t)(w.z >> 16); vp[6 * (size_t)S] = (bf16_t)(w.w & 0xffffu); vp[7 * (size_t)S] = (bf16_t)(w.w >> 16);
;                         } else {
;                             *(u32x4*)(proj + (size_t)row * NPROJ + col0 + bj * 128) = w;
.LBB0_462:
	v_mov_b32_e32 v24, v38
	v_mov_b32_e32 v25, v38
	v_pk_mul_f32 v[22:23], v[22:23], v[24:25]
	v_pk_mul_f32 v[20:21], v[20:21], v[38:39]
	v_pk_mul_f32 v[24:25], v[18:19], v[24:25]
	v_pk_mul_f32 v[18:19], v[16:17], v[38:39]
	v_cvt_pk_bf16_f32 v16, v20, v21
	v_cvt_pk_bf16_f32 v17, v22, v23
	v_cvt_pk_bf16_f32 v18, v18, v19
	s_andn2_b64 vcc, exec, s[44:45]
	v_cvt_pk_bf16_f32 v19, v24, v25
	s_cbranch_vccnz .LBB0_465
	s_and_b64 vcc, exec, s[42:43]
	s_mov_b64 s[0:1], s[4:5]
	s_cbranch_vccz .LBB0_465
	v_lshl_add_u64 v[20:21], s[34:35], 0, v[36:37]
	v_lshl_add_u64 v[20:21], v[132:133], 1, v[20:21]
	global_store_dwordx4 v[20:21], v[16:19], off offset:256 sc1
	s_mov_b64 s[0:1], s[4:5]

; __device__ __forceinline__ unsigned pk2(float lo, float hi) { return pg8::cvt_pk_bf16(lo, hi); }
;     __device__ __forceinline__ void operator()(const pg8::f32x4 (&acc)[2][2][4][2], const pg8::Unit& u, int wr, int wc, int fr, int fq) const {
;     ...
;                     const int row = row0 + ai * 128 + m * 16; const float rs = rstd_of(ssq, row) * sc;
; #pragma unroll
;                     for (int bj = 0; bj < 2; ++bj) {
;                         const pg8::f32x4 v0 = acc[ai][bj][m][0] * rs, v1 = acc[ai][bj][m][1] * rs;
;                         u32x4 w; w.x = pk2(v0[0], v0[1]); w.y = pk2(v0[2], v0[3]); w.z = pk2(v1[0], v1[1]); w.w = pk2(v1[2], v1[3]);
;                         if (vt_all || (vt_half && bj == 1)) {
;                             bf16_t* vp = vt + (size_t)(vrow0 + bj * 128) * S + row;
;                             vp[0 * (size_t)S] = (bf16_t)(w.x & 0xffffu); vp[1 * (size_t)S] = (bf16_t)(w.x >> 16); vp[2 * (size_t)S] = (bf16_t)(w.y & 0xffffu); vp[3 * (size_t)S] = (bf16_t)(w.y >> 16);
;                             vp[4 * (size_t)S] = (bf16_t)(w.z & 0xffffu); vp[5 * (size_t)S] = (bf16_t)(w.z >> 16); vp[6 * (size_t)S] = (bf16_t)(w.w & 0xffffu); vp[7 * (size_t)S] = (bf16_t)(w.w >> 16);
;                         } else {
;                             *(u32x4*)(proj + (size_t)row * NPROJ + col0 + bj * 128) = w;
.LBB0_475:
	v_lshl_add_u64 v[12:13], s[34:35], 0, v[16:17]
	v_lshl_add_u64 v[12:13], v[132:133], 1, v[12:13]
	global_store_dwordx4 v[12:13], v[8:11], off sc1
	s_cbranch_execnz .LBB0_473

; __device__ __forceinline__ unsigned pk2(float lo, float hi) { return pg8::cvt_pk_bf16(lo, hi); }
;     __device__ __forceinline__ void operator()(const pg8::f32x4 (&acc)[2][2][4][2], const pg8::Unit& u, int wr, int wc, int fr, int fq) const {
;     ...
;                     const int row = row0 + ai * 128 + m * 16; const float rs = rstd_of(ssq, row) * sc;
; #pragma unroll
;                     for (int bj = 0; bj < 2; ++bj) {
;                         const pg8::f32x4 v0 = acc[ai][bj][m][0] * rs, v1 = acc[ai][bj][m][1] * rs;
;                         u32x4 w; w.x = pk2(v0[0], v0[1]); w.y = pk2(v0[2], v0[3]); w.z = pk2(v1[0], v1[1]); w.w = pk2(v1[2], v1[3]);
;                         if (vt_all || (vt_half && bj == 1)) {
;                             bf16_t* vp = vt + (size_t)(vrow0 + bj * 128) * S + row;
;                             vp[0 * (size_t)S] = (bf16_t)(w.x & 0xffffu); vp[1 * (size_t)S] = (bf16_t)(w.x >> 16); vp[2 * (size_t)S] = (bf16_t)(w.y & 0xffffu); vp[3 * (size_t)S] = (bf16_t)(w.y >> 16);
;                             vp[4 * (size_t)S] = (bf16_t)(w.z & 0xffffu); vp[5 * (size_t)S] = (bf16_t)(w.z >> 16); vp[6 * (size_t)S] = (bf16_t)(w.w & 0xffffu); vp[7 * (size_t)S] = (bf16_t)(w.w >> 16);
;                         } else {
;                             *(u32x4*)(proj + (size_t)row * NPROJ + col0 + bj * 128) = w;
.LBB0_479:
	v_mov_b32_e32 v8, v18
	v_mov_b32_e32 v9, v18
	v_pk_mul_f32 v[6:7], v[6:7], v[8:9]
	v_pk_mul_f32 v[4:5], v[4:5], v[18:19]
	v_pk_mul_f32 v[8:9], v[2:3], v[8:9]
	v_pk_mul_f32 v[2:3], v[0:1], v[18:19]
	v_cvt_pk_bf16_f32 v0, v4, v5
	v_cvt_pk_bf16_f32 v1, v6, v7
	v_cvt_pk_bf16_f32 v2, v2, v3
	s_andn2_b64 vcc, exec, s[44:45]
	v_cvt_pk_bf16_f32 v3, v8, v9
	s_cbranch_vccnz .LBB0_483
	s_and_b64 vcc, exec, s[42:43]
	s_cbranch_vccz .LBB0_482
	v_lshl_add_u64 v[4:5], s[34:35], 0, v[16:17]
	v_lshl_add_u64 v[4:5], v[132:133], 1, v[4:5]
	global_store_dwordx4 v[4:5], v[0:3], off offset:256 sc1

; #define LAS __attribute__((address_space(3)))
; __device__ __forceinline__ unsigned pk2(float lo, float hi) { return pg8::cvt_pk_bf16(lo, hi); }
; __device__ __forceinline__ void transpose_tile(const float* src, int srcN, const float* gk, bf16_t* dst, int dstK, LAS float* scr, int lane) {
;     ...
;     for (int i = 0; i < 32; ++i) scr[(2 * i + (lane >> 5)) * 33 + (lane & 31)] = tv[i];
;     asm volatile("s_waitcnt lgkmcnt(0)" ::: "memory");
;     const int c = lane & 7;
; #pragma unroll
;     for (int j = 0; j < 4; ++j) {
;         const int n = (lane >> 3) + 8 * j; const LAS float* s = scr + (8 * c) * 33 + n;
;         u32x4 o; o.x = pk2(s[0 * 33], s[1 * 33]); o.y = pk2(s[2 * 33], s[3 * 33]); o.z = pk2(s[4 * 33], s[5 * 33]); o.w = pk2(s[6 * 33], s[7 * 33]);
;         *(u32x4*)(dst + (size_t)n * dstK + 8 * c) = o;
;     }
;     asm volatile("s_waitcnt lgkmcnt(0)" ::: "memory");
; __device__ __forceinline__ void convert_layer(const Params& p, int l, LAS unsigned char* lds, int it_lo, int it_hi, int worker, int nworkers) {
;     ...
;         if (r < 2 * I_GU) {
;             const int f = r / I_GU; r -= f * I_GU; const int nb = r / (DM / 64), kb = r % (DM / 64), n0 = nb * 32, k0 = kb * 64;
;             const int pn = n0 >> 8, w = n0 & 255; const float* src = ((w < 128) ? p.ffn_w_gate : p.ffn_w_up) + (size_t)(l * 2 + f) * DM * DFF;
;             transpose_tile(src + (size_t)k0 * DFF + pn * 128 + (w & 127), DFF, ng + (f ? 2 : 0) * DM + k0, W + (f ? O_WGU1 : O_WGU0) + (size_t)n0 * DM + k0, DM, scr, lane); continue; }
.LBB0_520:
	v_add_u32_e32 v79, v1, v3
	s_waitcnt vmcnt(30)
	ds_write2_b32 v79, v88, v89 offset1:66
	s_waitcnt vmcnt(28)
	ds_write2_b32 v79, v94, v95 offset0:132 offset1:198
	v_add_u32_e32 v79, 0x400, v79
	s_waitcnt vmcnt(26)
	ds_write2_b32 v79, v92, v93 offset0:8 offset1:74
	v_add_u32_e32 v79, v1, v5
	s_waitcnt vmcnt(24)
	ds_write2_b32 v79, v90, v91 offset1:66
	s_waitcnt vmcnt(22)
	ds_write2_b32 v79, v100, v101 offset0:132 offset1:198
	v_add_u32_e32 v79, 0x400, v79
	s_waitcnt vmcnt(20)
	ds_write2_b32 v79, v98, v99 offset0:8 offset1:74
	v_add_u32_e32 v79, v1, v7
	s_waitcnt vmcnt(18)
	ds_write2_b32 v79, v96, v97 offset1:66
	s_waitcnt vmcnt(16)
	ds_write2_b32 v79, v106, v107 offset0:132 offset1:198
	v_add_u32_e32 v79, 0x400, v79
	s_lshl_b32 s14, s8, 5
	s_waitcnt vmcnt(14)
	ds_write2_b32 v79, v104, v105 offset0:8 offset1:74
	v_add_u32_e32 v79, v1, v9
	s_and_b64 s[12:13], s[12:13], exec
	s_waitcnt vmcnt(12)
	ds_write2_b32 v79, v102, v103 offset1:66
	s_waitcnt vmcnt(10)
	ds_write2_b32 v79, v112, v113 offset0:132 offset1:198
	v_add_u32_e32 v79, 0x400, v79
	s_cselect_b32 s8, 0, 0x2300000
	s_waitcnt vmcnt(8)
	ds_write2_b32 v79, v110, v111 offset0:8 offset1:74
	v_add_u32_e32 v79, v1, v11
	s_add_u32 s8, s16, s8
	s_waitcnt vmcnt(6)
	ds_write2_b32 v79, v108, v109 offset1:66
	s_waitcnt vmcnt(4)
	ds_write2_b32 v79, v118, v119 offset0:132 offset1:198
	v_add_u32_e32 v79, 0x400, v79
	s_addc_u32 s48, s17, 0
	s_ashr_i32 s15, s14, 31
	s_waitcnt vmcnt(2)
	ds_write2_b32 v79, v116, v117 offset0:8 offset1:74
	s_waitcnt vmcnt(0)
	ds_write2_b32 v79, v114, v115 offset0:140 offset1:206
	s_lshl_b64 s[12:13], s[14:15], 11
	s_waitcnt lgkmcnt(0)
	s_add_u32 s8, s8, s12
	ds_read2_b32 v[92:93], v13 offset0:33 offset1:41
	ds_read2_b32 v[94:95], v13 offset1:8
	ds_read2_b32 v[96:97], v13 offset0:66 offset1:74
	ds_read2_b32 v[98:99], v13 offset0:99 offset1:107
	ds_read2_b32 v[100:101], v13 offset0:132 offset1:140
	ds_read2_b32 v[102:103], v13 offset0:165 offset1:173
	ds_read2_b32 v[104:105], v13 offset0:198 offset1:206
	ds_read2_b32 v[106:107], v13 offset0:231 offset1:239
	s_addc_u32 s12, s48, s13
	s_lshl_b64 s[10:11], s[10:11], 1
	s_add_u32 s10, s8, s10
	s_addc_u32 s11, s12, s11
	v_lshlrev_b32_e32 v196, 1, v66
	v_lshl_add_u64 v[108:109], s[10:11], 0, v[196:197]
	v_lshlrev_b32_e32 v196, 1, v68
	s_waitcnt lgkmcnt(6)
	v_cvt_pk_bf16_f32 v88, v94, v92
	s_waitcnt lgkmcnt(4)
	v_cvt_pk_bf16_f32 v89, v96, v98
	s_waitcnt lgkmcnt(2)
	v_cvt_pk_bf16_f32 v90, v100, v102
	s_waitcnt lgkmcnt(0)
	v_cvt_pk_bf16_f32 v91, v104, v106
	v_lshl_add_u64 v[110:111], v[108:109], 0, v[196:197]
	global_store_dwordx4 v[110:111], v[88:91], off sc1
	v_lshlrev_b32_e32 v196, 1, v70
	s_nop 0
	v_cvt_pk_bf16_f32 v88, v95, v93
	v_cvt_pk_bf16_f32 v89, v97, v99
	v_cvt_pk_bf16_f32 v90, v101, v103
	v_cvt_pk_bf16_f32 v91, v105, v107
	ds_read2_b32 v[94:95], v13 offset0:49 offset1:57
	ds_read2_b32 v[96:97], v13 offset0:16 offset1:24
	ds_read2_b32 v[98:99], v13 offset0:82 offset1:90
	ds_read2_b32 v[100:101], v13 offset0:115 offset1:123
	ds_read2_b32 v[102:103], v13 offset0:148 offset1:156
	ds_read2_b32 v[104:105], v13 offset0:181 offset1:189
	ds_read2_b32 v[106:107], v13 offset0:214 offset1:222
	ds_read2_b32 v[110:111], v13 offset0:247 offset1:255
	v_lshl_add_u64 v[92:93], v[108:109], 0, v[196:197]
	v_lshlrev_b32_e32 v196, 1, v72
	global_store_dwordx4 v[92:93], v[88:91], off sc1
	v_lshl_add_u64 v[92:93], v[108:109], 0, v[196:197]
	v_lshlrev_b32_e32 v196, 1, v74
	s_waitcnt lgkmcnt(6)
	v_cvt_pk_bf16_f32 v88, v96, v94
	s_waitcnt lgkmcnt(4)
	v_cvt_pk_bf16_f32 v89, v98, v100
	s_waitcnt lgkmcnt(2)
	v_cvt_pk_bf16_f32 v90, v102, v104
	s_waitcnt lgkmcnt(0)
	v_cvt_pk_bf16_f32 v91, v106, v110
	global_store_dwordx4 v[92:93], v[88:91], off sc1
	v_lshl_add_u64 v[92:93], v[108:109], 0, v[196:197]
	s_nop 0
	v_cvt_pk_bf16_f32 v88, v97, v95
	v_cvt_pk_bf16_f32 v89, v99, v101
	v_cvt_pk_bf16_f32 v90, v103, v105
	v_cvt_pk_bf16_f32 v91, v107, v111
	global_store_dwordx4 v[92:93], v[88:91], off sc1
	s_waitcnt lgkmcnt(0)

; #define LAS __attribute__((address_space(3)))
; __device__ __forceinline__ unsigned pk2(float lo, float hi) { return pg8::cvt_pk_bf16(lo, hi); }
; __device__ __forceinline__ void transpose_tile(const float* src, int srcN, const float* gk, bf16_t* dst, int dstK, LAS float* scr, int lane) {
;     ...
;     for (int i = 0; i < 32; ++i) tv[i] = src[(size_t)(2 * i + (lane >> 5)) * srcN + (lane & 31)];
;     if (gk) {
; #pragma unroll
;         for (int i = 0; i < 32; ++i) tv[i] *= gk[2 * i + (lane >> 5)];
;     }
; #pragma unroll
;     for (int i = 0; i < 32; ++i) scr[(2 * i + (lane >> 5)) * 33 + (lane & 31)] = tv[i];
;     asm volatile("s_waitcnt lgkmcnt(0)" ::: "memory");
;     const int c = lane & 7;
; #pragma unroll
;     for (int j = 0; j < 4; ++j) {
;         const int n = (lane >> 3) + 8 * j; const LAS float* s = scr + (8 * c) * 33 + n;
;         u32x4 o; o.x = pk2(s[0 * 33], s[1 * 33]); o.y = pk2(s[2 * 33], s[3 * 33]); o.z = pk2(s[4 * 33], s[5 * 33]); o.w = pk2(s[6 * 33], s[7 * 33]);
;         *(u32x4*)(dst + (size_t)n * dstK + 8 * c) = o;
;     }
;     asm volatile("s_waitcnt lgkmcnt(0)" ::: "memory");
; __device__ __forceinline__ void convert_layer(const Params& p, int l, LAS unsigned char* lds, int it_lo, int it_hi, int worker, int nworkers) {
;     ...
;         r -= 3 * I_B;
;         {
;             const int nb = r / (DM / 64), kb = r % (DM / 64), n0 = nb * 32, k0 = kb * 64;
;             transpose_tile(p.w_o + (size_t)l * DM * DM + (size_t)k0 * DM + n0, DM, nullptr, W + O_WO + (size_t)n0 * DM + k0, DM, scr, lane); }
.LBB0_522:
	s_add_i32 s48, s46, 0x2e80
	s_cmpk_gt_i32 s48, 0x15ff
	s_mov_b64 s[10:11], -1
	s_cbranch_scc0 .LBB0_539
	s_cmpk_gt_u32 s48, 0x20ff
	s_cbranch_scc0 .LBB0_536
	s_cmpk_gt_u32 s48, 0x2e7f
	s_cbranch_scc0 .LBB0_530
	s_cmpk_gt_u32 s48, 0x317f
	s_cbranch_scc0 .LBB0_527
	s_and_b32 s8, s44, 0x7fffffe0
	s_and_b32 s14, s45, 0x3c0
	s_addk_i32 s8, 0x9d00
	s_lshl_b32 s10, s14, 12
	s_add_u32 s12, s38, s10
	s_addc_u32 s13, s39, 0
	s_lshl_b64 s[10:11], s[8:9], 2
	s_add_u32 s12, s12, s10
	s_addc_u32 s13, s13, s11
	v_lshlrev_b32_e32 v79, 2, v0
	v_lshlrev_b32_e32 v81, 2, v2
	global_load_dword v79, v79, s[12:13]
	v_lshlrev_b32_e32 v83, 2, v4
	global_load_dword v81, v81, s[12:13]
	v_lshlrev_b32_e32 v85, 2, v6
	v_lshlrev_b32_e32 v87, 2, v8
	v_lshlrev_b32_e32 v88, 2, v10
	global_load_dword v83, v83, s[12:13]
	v_lshlrev_b32_e32 v89, 2, v12
	global_load_dword v85, v85, s[12:13]
	v_lshlrev_b32_e32 v90, 2, v14
	global_load_dword v87, v87, s[12:13]
	v_lshlrev_b32_e32 v91, 2, v16
	global_load_dword v88, v88, s[12:13]
	v_lshlrev_b32_e32 v92, 2, v18
	global_load_dword v89, v89, s[12:13]
	v_lshlrev_b32_e32 v93, 2, v20
	global_load_dword v90, v90, s[12:13]
	v_lshlrev_b32_e32 v94, 2, v22
	global_load_dword v91, v91, s[12:13]
	v_lshlrev_b32_e32 v95, 2, v24
	global_load_dword v92, v92, s[12:13]
	v_lshlrev_b32_e32 v96, 2, v26
	global_load_dword v93, v93, s[12:13]
	v_lshlrev_b32_e32 v97, 2, v28
	global_load_dword v94, v94, s[12:13]
	v_lshlrev_b32_e32 v98, 2, v30
	global_load_dword v95, v95, s[12:13]
	v_lshlrev_b32_e32 v99, 2, v32
	global_load_dword v96, v96, s[12:13]
	v_lshlrev_b32_e32 v100, 2, v36
	global_load_dword v97, v97, s[12:13]
	v_lshlrev_b32_e32 v101, 2, v38
	global_load_dword v98, v98, s[12:13]
	v_lshlrev_b32_e32 v102, 2, v40
	global_load_dword v99, v99, s[12:13]
	v_lshlrev_b32_e32 v103, 2, v42
	global_load_dword v100, v100, s[12:13]
	v_lshlrev_b32_e32 v104, 2, v44
	global_load_dword v101, v101, s[12:13]
	v_lshlrev_b32_e32 v105, 2, v46
	global_load_dword v102, v102, s[12:13]
	v_lshlrev_b32_e32 v106, 2, v48
	global_load_dword v103, v103, s[12:13]
	v_lshlrev_b32_e32 v107, 2, v50
	global_load_dword v104, v104, s[12:13]
	v_lshlrev_b32_e32 v108, 2, v52
	global_load_dword v105, v105, s[12:13]
	v_lshlrev_b32_e32 v109, 2, v54
	global_load_dword v106, v106, s[12:13]
	v_lshlrev_b32_e32 v110, 2, v56
	global_load_dword v107, v107, s[12:13]
	v_lshlrev_b32_e32 v111, 2, v58
	global_load_dword v108, v108, s[12:13]
	v_lshlrev_b32_e32 v112, 2, v60
	global_load_dword v109, v109, s[12:13]
	v_lshlrev_b32_e32 v113, 2, v62
	global_load_dword v110, v110, s[12:13]
	v_lshlrev_b32_e32 v114, 2, v64
	global_load_dword v111, v111, s[12:13]
	v_add_u32_e32 v115, v1, v3
	global_load_dword v112, v112, s[12:13]
	s_lshl_b64 s[10:11], s[8:9], 11
	global_load_dword v113, v113, s[12:13]
	s_add_u32 s8, s1, s10
	global_load_dword v114, v114, s[12:13]
	s_addc_u32 s11, s18, s11
	s_lshl_b32 s10, s14, 1
	s_add_u32 s10, s8, s10
	s_addc_u32 s11, s11, 0
	v_lshlrev_b32_e32 v196, 1, v66
	s_waitcnt vmcnt(30)
	ds_write2_b32 v115, v79, v81 offset1:66
	s_waitcnt vmcnt(28)
	ds_write2_b32 v115, v83, v85 offset0:132 offset1:198
	v_add_u32_e32 v79, 0x400, v115
	s_waitcnt vmcnt(26)
	ds_write2_b32 v79, v87, v88 offset0:8 offset1:74
	v_add_u32_e32 v79, v1, v5
	s_waitcnt vmcnt(24)
	ds_write2_b32 v79, v89, v90 offset1:66
	s_waitcnt vmcnt(22)
	ds_write2_b32 v79, v91, v92 offset0:132 offset1:198
	v_add_u32_e32 v79, 0x400, v79
	s_waitcnt vmcnt(20)
	ds_write2_b32 v79, v93, v94 offset0:8 offset1:74
	v_add_u32_e32 v79, v1, v7
	s_waitcnt vmcnt(18)
	ds_write2_b32 v79, v95, v96 offset1:66
	s_waitcnt vmcnt(16)
	ds_write2_b32 v79, v97, v98 offset0:132 offset1:198
	v_add_u32_e32 v79, 0x400, v79
	v_lshl_add_u64 v[92:93], s[10:11], 0, v[196:197]
	v_lshlrev_b32_e32 v196, 1, v68
	s_mov_b64 s[10:11], 0
	s_waitcnt vmcnt(14)
	ds_write2_b32 v79, v99, v100 offset0:8 offset1:74
	v_add_u32_e32 v79, v1, v9
	s_waitcnt vmcnt(12)
	ds_write2_b32 v79, v101, v102 offset1:66
	s_waitcnt vmcnt(10)
	ds_write2_b32 v79, v103, v104 offset0:132 offset1:198
	v_add_u32_e32 v79, 0x400, v79
	s_waitcnt vmcnt(8)
	ds_write2_b32 v79, v105, v106 offset0:8 offset1:74
	v_add_u32_e32 v79, v1, v11
	s_waitcnt vmcnt(6)
	ds_write2_b32 v79, v107, v108 offset1:66
	s_waitcnt vmcnt(4)
	ds_write2_b32 v79, v109, v110 offset0:132 offset1:198
	v_add_u32_e32 v79, 0x400, v79
	s_waitcnt vmcnt(2)
	ds_write2_b32 v79, v111, v112 offset0:8 offset1:74
	s_waitcnt vmcnt(0)
	ds_write2_b32 v79, v113, v114 offset0:140 offset1:206
	s_waitcnt lgkmcnt(0)
	ds_read2_b32 v[94:95], v13 offset0:33 offset1:41
	ds_read2_b32 v[96:97], v13 offset1:8
	ds_read2_b32 v[98:99], v13 offset0:66 offset1:74
	ds_read2_b32 v[100:101], v13 offset0:99 offset1:107
	ds_read2_b32 v[102:103], v13 offset0:132 offset1:140
	ds_read2_b32 v[104:105], v13 offset0:165 offset1:173
	ds_read2_b32 v[106:107], v13 offset0:198 offset1:206
	ds_read2_b32 v[108:109], v13 offset0:231 offset1:239
	v_lshl_add_u64 v[110:111], v[92:93], 0, v[196:197]
	s_waitcnt lgkmcnt(6)
	v_cvt_pk_bf16_f32 v88, v96, v94
	s_waitcnt lgkmcnt(4)
	v_cvt_pk_bf16_f32 v89, v98, v100
	s_waitcnt lgkmcnt(2)
	v_cvt_pk_bf16_f32 v90, v102, v104
	s_waitcnt lgkmcnt(0)
	v_cvt_pk_bf16_f32 v91, v106, v108
	v_lshlrev_b32_e32 v196, 1, v70
	global_store_dwordx4 v[110:111], v[88:91], off sc1
	s_nop 1
	v_cvt_pk_bf16_f32 v88, v97, v95
	v_cvt_pk_bf16_f32 v89, v99, v101
	v_cvt_pk_bf16_f32 v90, v103, v105
	v_cvt_pk_bf16_f32 v91, v107, v109
	v_lshl_add_u64 v[94:95], v[92:93], 0, v[196:197]
	global_store_dwordx4 v[94:95], v[88:91], off sc1
	ds_read2_b32 v[94:95], v13 offset0:49 offset1:57
	ds_read2_b32 v[96:97], v13 offset0:16 offset1:24
	ds_read2_b32 v[98:99], v13 offset0:82 offset1:90
	ds_read2_b32 v[100:101], v13 offset0:115 offset1:123
	ds_read2_b32 v[102:103], v13 offset0:148 offset1:156
	ds_read2_b32 v[104:105], v13 offset0:181 offset1:189
	ds_read2_b32 v[106:107], v13 offset0:214 offset1:222
	ds_read2_b32 v[108:109], v13 offset0:247 offset1:255
	v_lshlrev_b32_e32 v196, 1, v72
	s_waitcnt lgkmcnt(6)
	v_cvt_pk_bf16_f32 v88, v96, v94
	s_waitcnt lgkmcnt(4)
	v_cvt_pk_bf16_f32 v89, v98, v100
	s_waitcnt lgkmcnt(2)
	v_cvt_pk_bf16_f32 v90, v102, v104
	s_waitcnt lgkmcnt(0)
	v_cvt_pk_bf16_f32 v91, v106, v108
	v_lshl_add_u64 v[110:111], v[92:93], 0, v[196:197]
	v_lshlrev_b32_e32 v196, 1, v74
	global_store_dwordx4 v[110:111], v[88:91], off sc1
	v_lshl_add_u64 v[92:93], v[92:93], 0, v[196:197]
	s_nop 0
	v_cvt_pk_bf16_f32 v88, v97, v95
	v_cvt_pk_bf16_f32 v89, v99, v101
	v_cvt_pk_bf16_f32 v90, v103, v105
	v_cvt_pk_bf16_f32 v91, v107, v109
	global_store_dwordx4 v[92:93], v[88:91], off sc1
	s_waitcnt lgkmcnt(0)
; #define LAS __attribute__((address_space(3)))
; __device__ __forceinline__ unsigned pk2(float lo, float hi) { return pg8::cvt_pk_bf16(lo, hi); }
; __device__ __forceinline__ void transpose_tile(const float* src, int srcN, const float* gk, bf16_t* dst, int dstK, LAS float* scr, int lane) {
;     ...
;     for (int i = 0; i < 32; ++i) tv[i] = src[(size_t)(2 * i + (lane >> 5)) * srcN + (lane & 31)];
;     if (gk) {
; #pragma unroll
;         for (int i = 0; i < 32; ++i) tv[i] *= gk[2 * i + (lane >> 5)];
;     }
; #pragma unroll
;     for (int i = 0; i < 32; ++i) scr[(2 * i + (lane >> 5)) * 33 + (lane & 31)] = tv[i];
;     asm volatile("s_waitcnt lgkmcnt(0)" ::: "memory");
;     const int c = lane & 7;
; #pragma unroll
;     for (int j = 0; j < 4; ++j) {
;         const int n = (lane >> 3) + 8 * j; const LAS float* s = scr + (8 * c) * 33 + n;
;         u32x4 o; o.x = pk2(s[0 * 33], s[1 * 33]); o.y = pk2(s[2 * 33], s[3 * 33]); o.z = pk2(s[4 * 33], s[5 * 33]); o.w = pk2(s[6 * 33], s[7 * 33]);
;         *(u32x4*)(dst + (size_t)n * dstK + 8 * c) = o;
;     }
;     asm volatile("s_waitcnt lgkmcnt(0)" ::: "memory");
; __device__ __forceinline__ void convert_layer(const Params& p, int l, LAS unsigned char* lds, int it_lo, int it_hi, int worker, int nworkers) {
;     ...
;         if (r < 3 * I_B) {
;             const int i = r / I_B; r -= i * I_B; const int nb = r / 8, kb = r % 8, n0 = nb * 32, k0 = kb * 64;
;             transpose_tile(p.w_branch + (size_t)(l * 3 + i) * 512 * DM + (size_t)k0 * DM + n0, DM, nullptr, W + O_WB + (size_t)i * E_WB + (size_t)n0 * 512 + k0, 512, scr, lane); continue; }
.LBB0_527:
	s_andn2_b64 vcc, exec, s[10:11]
	s_cbranch_vccnz .LBB0_529
	s_lshr_b32 s8, s46, 8
	s_mul_i32 s10, s0, 3
	s_add_i32 s10, s8, s10
	s_ashr_i32 s11, s10, 31
	s_and_b32 s14, s47, 0x3e0
	s_and_b32 s15, s45, 0x1c0
	s_lshl_b64 s[10:11], s[10:11], 21
	s_add_u32 s10, s76, s10
	s_addc_u32 s11, s77, s11
	s_lshl_b32 s12, s15, 12
	s_add_u32 s10, s10, s12
	s_addc_u32 s11, s11, 0
	s_lshl_b32 s12, s14, 2
	s_add_u32 s12, s10, s12
	s_addc_u32 s13, s11, 0
	v_lshlrev_b32_e32 v79, 2, v0
	v_lshlrev_b32_e32 v81, 2, v2
	global_load_dword v79, v79, s[12:13]
	v_lshlrev_b32_e32 v83, 2, v4
	global_load_dword v81, v81, s[12:13]
	v_lshlrev_b32_e32 v85, 2, v6
	v_lshlrev_b32_e32 v87, 2, v8
	v_lshlrev_b32_e32 v88, 2, v10
	global_load_dword v83, v83, s[12:13]
	v_lshlrev_b32_e32 v89, 2, v12
	global_load_dword v85, v85, s[12:13]
	v_lshlrev_b32_e32 v90, 2, v14
	global_load_dword v87, v87, s[12:13]
	v_lshlrev_b32_e32 v91, 2, v16
	global_load_dword v88, v88, s[12:13]
	v_lshlrev_b32_e32 v92, 2, v18
	global_load_dword v89, v89, s[12:13]
	v_lshlrev_b32_e32 v93, 2, v20
	global_load_dword v90, v90, s[12:13]
	v_lshlrev_b32_e32 v94, 2, v22
	global_load_dword v91, v91, s[12:13]
	v_lshlrev_b32_e32 v95, 2, v24
	global_load_dword v92, v92, s[12:13]
	v_lshlrev_b32_e32 v96, 2, v26
	global_load_dword v93, v93, s[12:13]
	v_lshlrev_b32_e32 v97, 2, v28
	global_load_dword v94, v94, s[12:13]
	v_lshlrev_b32_e32 v98, 2, v30
	global_load_dword v95, v95, s[12:13]
	v_lshlrev_b32_e32 v99, 2, v32
	global_load_dword v96, v96, s[12:13]
	v_lshlrev_b32_e32 v100, 2, v36
	global_load_dword v97, v97, s[12:13]
	v_lshlrev_b32_e32 v101, 2, v38
	global_load_dword v98, v98, s[12:13]
	v_lshlrev_b32_e32 v102, 2, v40
	global_load_dword v99, v99, s[12:13]
	v_lshlrev_b32_e32 v103, 2, v42
	global_load_dword v100, v100, s[12:13]
	v_lshlrev_b32_e32 v104, 2, v44
	global_load_dword v101, v101, s[12:13]
	v_lshlrev_b32_e32 v105, 2, v46
	global_load_dword v102, v102, s[12:13]
	v_lshlrev_b32_e32 v106, 2, v48
	global_load_dword v103, v103, s[12:13]
	v_lshlrev_b32_e32 v107, 2, v50
	global_load_dword v104, v104, s[12:13]
	v_lshlrev_b32_e32 v108, 2, v52
	global_load_dword v105, v105, s[12:13]
	v_lshlrev_b32_e32 v109, 2, v54
	global_load_dword v106, v106, s[12:13]
	v_lshlrev_b32_e32 v110, 2, v56
	global_load_dword v107, v107, s[12:13]
	v_lshlrev_b32_e32 v111, 2, v58
	global_load_dword v108, v108, s[12:13]
	v_lshlrev_b32_e32 v112, 2, v60
	global_load_dword v109, v109, s[12:13]
	v_lshlrev_b32_e32 v113, 2, v62
	global_load_dword v110, v110, s[12:13]
	v_lshlrev_b32_e32 v114, 2, v64
	global_load_dword v111, v111, s[12:13]
	v_add_u32_e32 v115, v1, v3
	global_load_dword v112, v112, s[12:13]
	s_lshl_b64 s[10:11], s[8:9], 20
	global_load_dword v113, v113, s[12:13]
	s_add_u32 s8, s19, s10
	global_load_dword v114, v114, s[12:13]
	s_addc_u32 s10, s20, s11
	s_lshl_b32 s11, s14, 10
	s_add_u32 s8, s8, s11
	s_addc_u32 s11, s10, 0
	s_lshl_b32 s10, s15, 1
	s_add_u32 s10, s8, s10
	s_addc_u32 s11, s11, 0
	v_lshlrev_b32_e32 v196, 1, v66
	s_waitcnt vmcnt(30)
	ds_write2_b32 v115, v79, v81 offset1:66
	s_waitcnt vmcnt(28)
	ds_write2_b32 v115, v83, v85 offset0:132 offset1:198
	v_add_u32_e32 v79, 0x400, v115
	v_mov_b32_e32 v81, v197
	v_mov_b32_e32 v83, v197
	v_mov_b32_e32 v85, v197
	s_waitcnt vmcnt(26)
	ds_write2_b32 v79, v87, v88 offset0:8 offset1:74
	v_add_u32_e32 v79, v1, v5
	s_waitcnt vmcnt(24)
	ds_write2_b32 v79, v89, v90 offset1:66
	s_waitcnt vmcnt(22)
	ds_write2_b32 v79, v91, v92 offset0:132 offset1:198
	v_add_u32_e32 v79, 0x400, v79
	s_waitcnt vmcnt(20)
	ds_write2_b32 v79, v93, v94 offset0:8 offset1:74
	v_add_u32_e32 v79, v1, v7
	s_waitcnt vmcnt(18)
	ds_write2_b32 v79, v95, v96 offset1:66
	s_waitcnt vmcnt(16)
	ds_write2_b32 v79, v97, v98 offset0:132 offset1:198
	v_add_u32_e32 v79, 0x400, v79
	v_lshl_add_u64 v[92:93], s[10:11], 0, v[196:197]
	s_waitcnt vmcnt(14)
	ds_write2_b32 v79, v99, v100 offset0:8 offset1:74
	v_add_u32_e32 v79, v1, v9
	s_waitcnt vmcnt(12)
	ds_write2_b32 v79, v101, v102 offset1:66
	s_waitcnt vmcnt(10)
	ds_write2_b32 v79, v103, v104 offset0:132 offset1:198
	v_add_u32_e32 v79, 0x400, v79
	s_waitcnt vmcnt(8)
	ds_write2_b32 v79, v105, v106 offset0:8 offset1:74
	v_add_u32_e32 v79, v1, v11
	s_waitcnt vmcnt(6)
	ds_write2_b32 v79, v107, v108 offset1:66
	s_waitcnt vmcnt(4)
	ds_write2_b32 v79, v109, v110 offset0:132 offset1:198
	v_add_u32_e32 v79, 0x400, v79
	s_waitcnt vmcnt(2)
	ds_write2_b32 v79, v111, v112 offset0:8 offset1:74
	s_waitcnt vmcnt(0)
	ds_write2_b32 v79, v113, v114 offset0:140 offset1:206
	s_waitcnt lgkmcnt(0)
	ds_read2_b32 v[94:95], v13 offset0:33 offset1:41
	ds_read2_b32 v[96:97], v13 offset1:8
	ds_read2_b32 v[98:99], v13 offset0:66 offset1:74
	ds_read2_b32 v[100:101], v13 offset0:99 offset1:107
	ds_read2_b32 v[102:103], v13 offset0:132 offset1:140
	ds_read2_b32 v[104:105], v13 offset0:165 offset1:173
	ds_read2_b32 v[106:107], v13 offset0:198 offset1:206
	ds_read2_b32 v[108:109], v13 offset0:231 offset1:239
	v_mov_b32_e32 v79, v197
	s_waitcnt lgkmcnt(6)
	v_cvt_pk_bf16_f32 v88, v96, v94
	s_waitcnt lgkmcnt(4)
	v_cvt_pk_bf16_f32 v89, v98, v100
	s_waitcnt lgkmcnt(2)
	v_cvt_pk_bf16_f32 v90, v102, v104
	s_waitcnt lgkmcnt(0)
	v_cvt_pk_bf16_f32 v91, v106, v108
	v_lshl_add_u64 v[110:111], v[92:93], 0, v[78:79]
	global_store_dwordx4 v[110:111], v[88:91], off sc1
	v_lshl_add_u64 v[110:111], v[92:93], 0, v[82:83]
	s_nop 0
	v_cvt_pk_bf16_f32 v88, v97, v95
	v_cvt_pk_bf16_f32 v89, v99, v101
	v_cvt_pk_bf16_f32 v90, v103, v105
	v_cvt_pk_bf16_f32 v91, v107, v109
	v_lshl_add_u64 v[94:95], v[92:93], 0, v[80:81]
	global_store_dwordx4 v[94:95], v[88:91], off sc1
	ds_read2_b32 v[94:95], v13 offset0:49 offset1:57
	ds_read2_b32 v[96:97], v13 offset0:16 offset1:24
	ds_read2_b32 v[98:99], v13 offset0:82 offset1:90
	ds_read2_b32 v[100:101], v13 offset0:115 offset1:123
	ds_read2_b32 v[102:103], v13 offset0:148 offset1:156
	ds_read2_b32 v[104:105], v13 offset0:181 offset1:189
	ds_read2_b32 v[106:107], v13 offset0:214 offset1:222
	ds_read2_b32 v[108:109], v13 offset0:247 offset1:255
	v_lshl_add_u64 v[92:93], v[92:93], 0, v[84:85]
	s_waitcnt lgkmcnt(6)
	v_cvt_pk_bf16_f32 v88, v96, v94
	s_waitcnt lgkmcnt(4)
	v_cvt_pk_bf16_f32 v89, v98, v100
	s_waitcnt lgkmcnt(2)
	v_cvt_pk_bf16_f32 v90, v102, v104
	s_waitcnt lgkmcnt(0)
	v_cvt_pk_bf16_f32 v91, v106, v108
	global_store_dwordx4 v[110:111], v[88:91], off sc1
	s_nop 1
	v_cvt_pk_bf16_f32 v88, v97, v95
	v_cvt_pk_bf16_f32 v89, v99, v101
	v_cvt_pk_bf16_f32 v90, v103, v105
	v_cvt_pk_bf16_f32 v91, v107, v109
	global_store_dwordx4 v[92:93], v[88:91], off sc1
	s_waitcnt lgkmcnt(0)

; __device__ __forceinline__ void transpose_tile(const float* src, int srcN, const float* gk, bf16_t* dst, int dstK, LAS float* scr, int lane) {
;     ...
;     for (int i = 0; i < 32; ++i) tv[i] = src[(size_t)(2 * i + (lane >> 5)) * srcN + (lane & 31)];
;     if (gk) {
; #pragma unroll
;         for (int i = 0; i < 32; ++i) tv[i] *= gk[2 * i + (lane >> 5)];
; __device__ __forceinline__ void convert_layer(const Params& p, int l, LAS unsigned char* lds, int it_lo, int it_hi, int worker, int nworkers) {
;     ...
;         if (r < I_ING) {
;             const int nb = r / (DM / 64), kb = r % (DM / 64), n0 = nb * 32, k0 = kb * 64;
;             if (n0 < NPROJ) transpose_tile(p.w_in + (size_t)l * DM * NPROJ + (size_t)k0 * NPROJ + n0, NPROJ, ng + DM + k0, W + O_WING + (size_t)n0 * DM + k0, DM, scr, lane);
;             else transpose_tile(p.w_gate + (size_t)l * DM * NGATE + (size_t)k0 * NGATE + (n0 - NPROJ), NGATE, ng + DM + k0, W + O_WING + (size_t)n0 * DM + k0, DM, scr, lane);
.LBB0_530:
	s_andn2_b64 vcc, exec, s[10:11]
	s_cbranch_vccnz .LBB0_535
	s_and_b32 s13, s44, 0x7fe0
	s_add_i32 s8, s13, 0xffffbe00
	s_and_b32 s12, s45, 0x3c0
	s_cmpk_gt_u32 s8, 0xeff
	s_mov_b64 s[10:11], -1
	s_cbranch_scc0 .LBB0_533
	s_mul_i32 s10, s12, 0x3000
	s_add_u32 s10, s40, s10
	s_addc_u32 s11, s41, 0
	s_lshl_b32 s13, s13, 2
	s_add_u32 s10, s10, s13
	s_addc_u32 s11, s11, 0
	s_add_u32 s14, s10, 0xfffebc00
	s_addc_u32 s15, s11, -1
	s_lshl_b64 s[10:11], s[8:9], 11
	s_add_u32 s10, s21, s10
	s_addc_u32 s11, s22, s11
	s_lshl_b32 s13, s12, 1
	s_add_u32 s10, s10, s13
	s_addc_u32 s11, s11, 0
	global_load_dword v79, v15, s[14:15]
	global_load_dword v81, v17, s[14:15]
	global_load_dword v83, v19, s[14:15]
	global_load_dword v85, v21, s[14:15]
	global_load_dword v87, v23, s[14:15]
	global_load_dword v90, v25, s[14:15]
	global_load_dword v91, v27, s[14:15]
	global_load_dword v92, v29, s[14:15]
	global_load_dword v93, v31, s[14:15]
	global_load_dword v94, v33, s[14:15]
	global_load_dword v95, v35, s[14:15]
	global_load_dword v96, v37, s[14:15]
	global_load_dword v97, v39, s[14:15]
	global_load_dword v98, v41, s[14:15]
	global_load_dword v99, v43, s[14:15]
	global_load_dword v100, v45, s[14:15]
	global_load_dword v101, v47, s[14:15]
	global_load_dword v102, v49, s[14:15]
	global_load_dword v103, v51, s[14:15]
	global_load_dword v104, v53, s[14:15]
	global_load_dword v105, v55, s[14:15]
	global_load_dword v106, v57, s[14:15]
	global_load_dword v107, v59, s[14:15]
	global_load_dword v108, v61, s[14:15]
	global_load_dword v109, v63, s[14:15]
	global_load_dword v110, v65, s[14:15]
	global_load_dword v111, v67, s[14:15]
	global_load_dword v112, v69, s[14:15]
	global_load_dword v113, v71, s[14:15]
	global_load_dword v114, v73, s[14:15]
	global_load_dword v115, v75, s[14:15]
	global_load_dword v116, v121, s[14:15]
	s_lshl_b32 s14, s12, 2
	s_mov_b32 s15, s9
	v_lshl_add_u64 v[88:89], v[76:77], 0, s[14:15]
	global_load_dword v117, v[88:89], off
	v_lshlrev_b32_e32 v196, 1, v66
	s_waitcnt vmcnt(0)
	v_mul_f32_e32 v79, v79, v117
	global_load_dword v117, v[88:89], off offset:8
	s_waitcnt vmcnt(0)
	v_mul_f32_e32 v81, v81, v117
	global_load_dword v117, v[88:89], off offset:16
	s_waitcnt vmcnt(0)
	v_mul_f32_e32 v83, v83, v117
	global_load_dword v117, v[88:89], off offset:24
	s_waitcnt vmcnt(0)
	v_mul_f32_e32 v85, v85, v117
	global_load_dword v117, v[88:89], off offset:32
	s_waitcnt vmcnt(0)
	v_mul_f32_e32 v87, v87, v117
	global_load_dword v117, v[88:89], off offset:40
	s_waitcnt vmcnt(0)
	v_mul_f32_e32 v90, v90, v117
	global_load_dword v117, v[88:89], off offset:48
	s_waitcnt vmcnt(0)
	v_mul_f32_e32 v91, v91, v117
	global_load_dword v117, v[88:89], off offset:56
	s_waitcnt vmcnt(0)
	v_mul_f32_e32 v92, v92, v117
	global_load_dword v117, v[88:89], off offset:64
	s_waitcnt vmcnt(0)
	v_mul_f32_e32 v93, v93, v117
	global_load_dword v117, v[88:89], off offset:72
	s_waitcnt vmcnt(0)
	v_mul_f32_e32 v94, v94, v117
	global_load_dword v117, v[88:89], off offset:80
	s_waitcnt vmcnt(0)
	v_mul_f32_e32 v95, v95, v117
	global_load_dword v117, v[88:89], off offset:88
	s_waitcnt vmcnt(0)
	v_mul_f32_e32 v96, v96, v117
	global_load_dword v117, v[88:89], off offset:96
	s_waitcnt vmcnt(0)
	v_mul_f32_e32 v97, v97, v117
	global_load_dword v117, v[88:89], off offset:104
	s_waitcnt vmcnt(0)
	v_mul_f32_e32 v98, v98, v117
	global_load_dword v117, v[88:89], off offset:112
	s_waitcnt vmcnt(0)
	v_mul_f32_e32 v99, v99, v117
	global_load_dword v117, v[88:89], off offset:120
	s_waitcnt vmcnt(0)
	v_mul_f32_e32 v100, v100, v117
	global_load_dword v117, v[88:89], off offset:128
	s_waitcnt vmcnt(0)
	v_mul_f32_e32 v101, v101, v117
	global_load_dword v117, v[88:89], off offset:136
	s_waitcnt vmcnt(0)
	v_mul_f32_e32 v102, v102, v117
	global_load_dword v117, v[88:89], off offset:144
	s_waitcnt vmcnt(0)
	v_mul_f32_e32 v103, v103, v117
	global_load_dword v117, v[88:89], off offset:152
	s_waitcnt vmcnt(0)
	v_mul_f32_e32 v104, v104, v117
	global_load_dword v117, v[88:89], off offset:160
	s_waitcnt vmcnt(0)
	v_mul_f32_e32 v105, v105, v117
	global_load_dword v117, v[88:89], off offset:168
	s_waitcnt vmcnt(0)
	v_mul_f32_e32 v106, v106, v117
	global_load_dword v117, v[88:89], off offset:176
	s_waitcnt vmcnt(0)
	v_mul_f32_e32 v107, v107, v117
	global_load_dword v117, v[88:89], off offset:184
	s_waitcnt vmcnt(0)
	v_mul_f32_e32 v108, v108, v117
	global_load_dword v117, v[88:89], off offset:192
	s_waitcnt vmcnt(0)
	v_mul_f32_e32 v109, v109, v117
	global_load_dword v117, v[88:89], off offset:200
	s_waitcnt vmcnt(0)
	v_mul_f32_e32 v110, v110, v117
	global_load_dword v117, v[88:89], off offset:208
	s_waitcnt vmcnt(0)
	v_mul_f32_e32 v111, v111, v117
	global_load_dword v117, v[88:89], off offset:216
	s_waitcnt vmcnt(0)
	v_mul_f32_e32 v112, v112, v117
	global_load_dword v117, v[88:89], off offset:224
	s_waitcnt vmcnt(0)
	v_mul_f32_e32 v113, v113, v117
	global_load_dword v117, v[88:89], off offset:232
	s_waitcnt vmcnt(0)
	v_mul_f32_e32 v114, v114, v117
	global_load_dword v117, v[88:89], off offset:240
	s_waitcnt vmcnt(0)
; #define LAS __attribute__((address_space(3)))
; __device__ __forceinline__ unsigned pk2(float lo, float hi) { return pg8::cvt_pk_bf16(lo, hi); }
; __device__ __forceinline__ void transpose_tile(const float* src, int srcN, const float* gk, bf16_t* dst, int dstK, LAS float* scr, int lane) {
;     ...
;     for (int i = 0; i < 32; ++i) tv[i] = src[(size_t)(2 * i + (lane >> 5)) * srcN + (lane & 31)];
;     if (gk) {
; #pragma unroll
;         for (int i = 0; i < 32; ++i) tv[i] *= gk[2 * i + (lane >> 5)];
;     }
; #pragma unroll
;     for (int i = 0; i < 32; ++i) scr[(2 * i + (lane >> 5)) * 33 + (lane & 31)] = tv[i];
;     asm volatile("s_waitcnt lgkmcnt(0)" ::: "memory");
;     const int c = lane & 7;
; #pragma unroll
;     for (int j = 0; j < 4; ++j) {
;         const int n = (lane >> 3) + 8 * j; const LAS float* s = scr + (8 * c) * 33 + n;
;         u32x4 o; o.x = pk2(s[0 * 33], s[1 * 33]); o.y = pk2(s[2 * 33], s[3 * 33]); o.z = pk2(s[4 * 33], s[5 * 33]); o.w = pk2(s[6 * 33], s[7 * 33]);
;         *(u32x4*)(dst + (size_t)n * dstK + 8 * c) = o;
;     }
;     asm volatile("s_waitcnt lgkmcnt(0)" ::: "memory");
; __device__ __forceinline__ void convert_layer(const Params& p, int l, LAS unsigned char* lds, int it_lo, int it_hi, int worker, int nworkers) {
;     ...
;         if (r < I_ING) {
;             const int nb = r / (DM / 64), kb = r % (DM / 64), n0 = nb * 32, k0 = kb * 64;
;             if (n0 < NPROJ) transpose_tile(p.w_in + (size_t)l * DM * NPROJ + (size_t)k0 * NPROJ + n0, NPROJ, ng + DM + k0, W + O_WING + (size_t)n0 * DM + k0, DM, scr, lane);
;             else transpose_tile(p.w_gate + (size_t)l * DM * NGATE + (size_t)k0 * NGATE + (n0 - NPROJ), NGATE, ng + DM + k0, W + O_WING + (size_t)n0 * DM + k0, DM, scr, lane);
	v_mul_f32_e32 v115, v115, v117
	global_load_dword v88, v[88:89], off offset:248
	v_add_u32_e32 v89, v1, v3
	ds_write2_b32 v89, v79, v81 offset1:66
	ds_write2_b32 v89, v83, v85 offset0:132 offset1:198
	v_add_u32_e32 v79, 0x400, v89
	ds_write2_b32 v79, v87, v90 offset0:8 offset1:74
	v_add_u32_e32 v79, v1, v5
	ds_write2_b32 v79, v91, v92 offset1:66
	ds_write2_b32 v79, v93, v94 offset0:132 offset1:198
	v_add_u32_e32 v79, 0x400, v79
	ds_write2_b32 v79, v95, v96 offset0:8 offset1:74
	v_add_u32_e32 v79, v1, v7
	ds_write2_b32 v79, v97, v98 offset1:66
	ds_write2_b32 v79, v99, v100 offset0:132 offset1:198
	v_add_u32_e32 v79, 0x400, v79
	ds_write2_b32 v79, v101, v102 offset0:8 offset1:74
	v_add_u32_e32 v79, v1, v9
	ds_write2_b32 v79, v103, v104 offset1:66
	ds_write2_b32 v79, v105, v106 offset0:132 offset1:198
	v_add_u32_e32 v79, 0x400, v79
	ds_write2_b32 v79, v107, v108 offset0:8 offset1:74
	v_add_u32_e32 v79, v1, v11
	ds_write2_b32 v79, v109, v110 offset1:66
	ds_write2_b32 v79, v111, v112 offset0:132 offset1:198
	v_add_u32_e32 v79, 0x400, v79
	v_lshl_add_u64 v[92:93], s[10:11], 0, v[196:197]
	v_lshlrev_b32_e32 v196, 1, v68
	v_lshl_add_u64 v[110:111], v[92:93], 0, v[196:197]
	v_lshlrev_b32_e32 v196, 1, v70
	s_mov_b64 s[10:11], 0
	s_waitcnt vmcnt(0)
	v_mul_f32_e32 v88, v116, v88
	ds_write2_b32 v79, v113, v114 offset0:8 offset1:74
	ds_write2_b32 v79, v115, v88 offset0:140 offset1:206
	s_waitcnt lgkmcnt(0)
	ds_read2_b32 v[94:95], v13 offset0:33 offset1:41
	ds_read2_b32 v[96:97], v13 offset1:8
	ds_read2_b32 v[98:99], v13 offset0:66 offset1:74
	ds_read2_b32 v[100:101], v13 offset0:99 offset1:107
	ds_read2_b32 v[102:103], v13 offset0:132 offset1:140
	ds_read2_b32 v[104:105], v13 offset0:165 offset1:173
	ds_read2_b32 v[106:107], v13 offset0:198 offset1:206
	ds_read2_b32 v[108:109], v13 offset0:231 offset1:239
	s_waitcnt lgkmcnt(6)
	v_cvt_pk_bf16_f32 v88, v96, v94
	s_waitcnt lgkmcnt(4)
	v_cvt_pk_bf16_f32 v89, v98, v100
	s_waitcnt lgkmcnt(2)
	v_cvt_pk_bf16_f32 v90, v102, v104
	s_waitcnt lgkmcnt(0)
	v_cvt_pk_bf16_f32 v91, v106, v108
	global_store_dwordx4 v[110:111], v[88:91], off sc1
	s_nop 1
	v_cvt_pk_bf16_f32 v88, v97, v95
	v_cvt_pk_bf16_f32 v89, v99, v101
	v_cvt_pk_bf16_f32 v90, v103, v105
	v_cvt_pk_bf16_f32 v91, v107, v109
	v_lshl_add_u64 v[94:95], v[92:93], 0, v[196:197]
	global_store_dwordx4 v[94:95], v[88:91], off sc1
	ds_read2_b32 v[94:95], v13 offset0:49 offset1:57
	ds_read2_b32 v[96:97], v13 offset0:16 offset1:24
	ds_read2_b32 v[98:99], v13 offset0:82 offset1:90
	ds_read2_b32 v[100:101], v13 offset0:115 offset1:123
	ds_read2_b32 v[102:103], v13 offset0:148 offset1:156
	ds_read2_b32 v[104:105], v13 offset0:181 offset1:189
	ds_read2_b32 v[106:107], v13 offset0:214 offset1:222
	ds_read2_b32 v[108:109], v13 offset0:247 offset1:255
	v_lshlrev_b32_e32 v196, 1, v72
	s_waitcnt lgkmcnt(6)
	v_cvt_pk_bf16_f32 v88, v96, v94
	s_waitcnt lgkmcnt(4)
	v_cvt_pk_bf16_f32 v89, v98, v100
	s_waitcnt lgkmcnt(2)
	v_cvt_pk_bf16_f32 v90, v102, v104
	s_waitcnt lgkmcnt(0)
	v_cvt_pk_bf16_f32 v91, v106, v108
	v_lshl_add_u64 v[110:111], v[92:93], 0, v[196:197]
	v_lshlrev_b32_e32 v196, 1, v74
	global_store_dwordx4 v[110:111], v[88:91], off sc1
	v_lshl_add_u64 v[92:93], v[92:93], 0, v[196:197]
	s_nop 0
	v_cvt_pk_bf16_f32 v88, v97, v95
	v_cvt_pk_bf16_f32 v89, v99, v101
	v_cvt_pk_bf16_f32 v90, v103, v105
	v_cvt_pk_bf16_f32 v91, v107, v109
	global_store_dwordx4 v[92:93], v[88:91], off sc1
	s_waitcnt lgkmcnt(0)
.LBB0_533:
	s_andn2_b64 vcc, exec, s[10:11]
	s_cbranch_vccnz .LBB0_535
	s_mul_i32 s10, s12, 0x3c00
	s_add_u32 s13, s42, s10
	s_addc_u32 s15, s43, 0
	s_lshl_b64 s[10:11], s[8:9], 2
	s_add_u32 s14, s13, s10
	s_addc_u32 s15, s15, s11
	s_lshl_b64 s[10:11], s[8:9], 11
	s_add_u32 s8, s21, s10
	s_addc_u32 s11, s22, s11
	s_lshl_b32 s10, s12, 1
	s_add_u32 s10, s8, s10
	s_addc_u32 s11, s11, 0
	s_lshl_b32 s8, s12, 2
	v_lshl_add_u64 v[88:89], v[76:77], 0, s[8:9]
	global_load_dword v79, v187, s[14:15]
	global_load_dword v81, v123, s[14:15]
	global_load_dword v83, v189, s[14:15]
	global_load_dword v85, v125, s[14:15]
	global_load_dword v87, v191, s[14:15]
	global_load_dword v90, v127, s[14:15]
	global_load_dword v91, v193, s[14:15]
	global_load_dword v92, v129, s[14:15]
	global_load_dword v93, v195, s[14:15]
	global_load_dword v94, v130, s[14:15]
	global_load_dword v95, v131, s[14:15]
	global_load_dword v96, v132, s[14:15]
	global_load_dword v97, v133, s[14:15]
	global_load_dword v98, v134, s[14:15]
	global_load_dword v99, v135, s[14:15]
	global_load_dword v100, v136, s[14:15]
	global_load_dword v101, v137, s[14:15]
	global_load_dword v102, v138, s[14:15]
	global_load_dword v103, v139, s[14:15]
	global_load_dword v104, v140, s[14:15]
	global_load_dword v105, v141, s[14:15]
	global_load_dword v106, v142, s[14:15]
	global_load_dword v107, v143, s[14:15]
	global_load_dword v108, v144, s[14:15]
	global_load_dword v109, v145, s[14:15]
	global_load_dword v110, v146, s[14:15]
	global_load_dword v111, v147, s[14:15]
	global_load_dword v112, v148, s[14:15]
	global_load_dword v113, v149, s[14:15]
	global_load_dword v114, v150, s[14:15]
	global_load_dword v115, v151, s[14:15]
	global_load_dword v116, v152, s[14:15]
	global_load_dword v117, v[88:89], off
	v_lshlrev_b32_e32 v196, 1, v66
	s_waitcnt vmcnt(0)
	v_mul_f32_e32 v79, v79, v117
	global_load_dword v117, v[88:89], off offset:8
	s_waitcnt vmcnt(0)
	v_mul_f32_e32 v81, v81, v117
	global_load_dword v117, v[88:89], off offset:16
	s_waitcnt vmcnt(0)
	v_mul_f32_e32 v83, v83, v117
	global_load_dword v117, v[88:89], off offset:24
	s_waitcnt vmcnt(0)
	v_mul_f32_e32 v85, v85, v117
	global_load_dword v117, v[88:89], off offset:32
	s_waitcnt vmcnt(0)
; #define LAS __attribute__((address_space(3)))
; __device__ __forceinline__ unsigned pk2(float lo, float hi) { return pg8::cvt_pk_bf16(lo, hi); }
; __device__ __forceinline__ void transpose_tile(const float* src, int srcN, const float* gk, bf16_t* dst, int dstK, LAS float* scr, int lane) {
;     ...
;     for (int i = 0; i < 32; ++i) tv[i] = src[(size_t)(2 * i + (lane >> 5)) * srcN + (lane & 31)];
;     if (gk) {
; #pragma unroll
;         for (int i = 0; i < 32; ++i) tv[i] *= gk[2 * i + (lane >> 5)];
;     }
; #pragma unroll
;     for (int i = 0; i < 32; ++i) scr[(2 * i + (lane >> 5)) * 33 + (lane & 31)] = tv[i];
;     asm volatile("s_waitcnt lgkmcnt(0)" ::: "memory");
;     const int c = lane & 7;
; #pragma unroll
;     for (int j = 0; j < 4; ++j) {
;         const int n = (lane >> 3) + 8 * j; const LAS float* s = scr + (8 * c) * 33 + n;
;         u32x4 o; o.x = pk2(s[0 * 33], s[1 * 33]); o.y = pk2(s[2 * 33], s[3 * 33]); o.z = pk2(s[4 * 33], s[5 * 33]); o.w = pk2(s[6 * 33], s[7 * 33]);
;         *(u32x4*)(dst + (size_t)n * dstK + 8 * c) = o;
;     }
;     asm volatile("s_waitcnt lgkmcnt(0)" ::: "memory");
; __device__ __forceinline__ void convert_layer(const Params& p, int l, LAS unsigned char* lds, int it_lo, int it_hi, int worker, int nworkers) {
;     ...
;             if (n0 < NPROJ) transpose_tile(p.w_in + (size_t)l * DM * NPROJ + (size_t)k0 * NPROJ + n0, NPROJ, ng + DM + k0, W + O_WING + (size_t)n0 * DM + k0, DM, scr, lane);
	v_mul_f32_e32 v87, v87, v117
	global_load_dword v117, v[88:89], off offset:40
	s_waitcnt vmcnt(0)
	v_mul_f32_e32 v90, v90, v117
	global_load_dword v117, v[88:89], off offset:48
	s_waitcnt vmcnt(0)
	v_mul_f32_e32 v91, v91, v117
	global_load_dword v117, v[88:89], off offset:56
	s_waitcnt vmcnt(0)
	v_mul_f32_e32 v92, v92, v117
	global_load_dword v117, v[88:89], off offset:64
	s_waitcnt vmcnt(0)
	v_mul_f32_e32 v93, v93, v117
	global_load_dword v117, v[88:89], off offset:72
	s_waitcnt vmcnt(0)
	v_mul_f32_e32 v94, v94, v117
	global_load_dword v117, v[88:89], off offset:80
	s_waitcnt vmcnt(0)
	v_mul_f32_e32 v95, v95, v117
	global_load_dword v117, v[88:89], off offset:88
	s_waitcnt vmcnt(0)
	v_mul_f32_e32 v96, v96, v117
	global_load_dword v117, v[88:89], off offset:96
	s_waitcnt vmcnt(0)
	v_mul_f32_e32 v97, v97, v117
	global_load_dword v117, v[88:89], off offset:104
	s_waitcnt vmcnt(0)
	v_mul_f32_e32 v98, v98, v117
	global_load_dword v117, v[88:89], off offset:112
	s_waitcnt vmcnt(0)
	v_mul_f32_e32 v99, v99, v117
	global_load_dword v117, v[88:89], off offset:120
	s_waitcnt vmcnt(0)
	v_mul_f32_e32 v100, v100, v117
	global_load_dword v117, v[88:89], off offset:128
	s_waitcnt vmcnt(0)
	v_mul_f32_e32 v101, v101, v117
	global_load_dword v117, v[88:89], off offset:136
	s_waitcnt vmcnt(0)
	v_mul_f32_e32 v102, v102, v117
	global_load_dword v117, v[88:89], off offset:144
	s_waitcnt vmcnt(0)
	v_mul_f32_e32 v103, v103, v117
	global_load_dword v117, v[88:89], off offset:152
	s_waitcnt vmcnt(0)
	v_mul_f32_e32 v104, v104, v117
	global_load_dword v117, v[88:89], off offset:160
	s_waitcnt vmcnt(0)
	v_mul_f32_e32 v105, v105, v117
	global_load_dword v117, v[88:89], off offset:168
	s_waitcnt vmcnt(0)
	v_mul_f32_e32 v106, v106, v117
	global_load_dword v117, v[88:89], off offset:176
	s_waitcnt vmcnt(0)
	v_mul_f32_e32 v107, v107, v117
	global_load_dword v117, v[88:89], off offset:184
	s_waitcnt vmcnt(0)
	v_mul_f32_e32 v108, v108, v117
	global_load_dword v117, v[88:89], off offset:192
	s_waitcnt vmcnt(0)
	v_mul_f32_e32 v109, v109, v117
	global_load_dword v117, v[88:89], off offset:200
	s_waitcnt vmcnt(0)
	v_mul_f32_e32 v110, v110, v117
	global_load_dword v117, v[88:89], off offset:208
	s_waitcnt vmcnt(0)
	v_mul_f32_e32 v111, v111, v117
	global_load_dword v117, v[88:89], off offset:216
	s_waitcnt vmcnt(0)
	v_mul_f32_e32 v112, v112, v117
	global_load_dword v117, v[88:89], off offset:224
	s_waitcnt vmcnt(0)
	v_mul_f32_e32 v113, v113, v117
	global_load_dword v117, v[88:89], off offset:232
	s_waitcnt vmcnt(0)
	v_mul_f32_e32 v114, v114, v117
	global_load_dword v117, v[88:89], off offset:240
	s_waitcnt vmcnt(0)
	v_mul_f32_e32 v115, v115, v117
	global_load_dword v88, v[88:89], off offset:248
	v_add_u32_e32 v89, v1, v3
	ds_write2_b32 v89, v79, v81 offset1:66
	ds_write2_b32 v89, v83, v85 offset0:132 offset1:198
	v_add_u32_e32 v79, 0x400, v89
	ds_write2_b32 v79, v87, v90 offset0:8 offset1:74
	v_add_u32_e32 v79, v1, v5
	ds_write2_b32 v79, v91, v92 offset1:66
	ds_write2_b32 v79, v93, v94 offset0:132 offset1:198
	v_add_u32_e32 v79, 0x400, v79
	ds_write2_b32 v79, v95, v96 offset0:8 offset1:74
	v_add_u32_e32 v79, v1, v7
	ds_write2_b32 v79, v97, v98 offset1:66
	ds_write2_b32 v79, v99, v100 offset0:132 offset1:198
	v_add_u32_e32 v79, 0x400, v79
	ds_write2_b32 v79, v101, v102 offset0:8 offset1:74
	v_add_u32_e32 v79, v1, v9
	ds_write2_b32 v79, v103, v104 offset1:66
	ds_write2_b32 v79, v105, v106 offset0:132 offset1:198
	v_add_u32_e32 v79, 0x400, v79
	ds_write2_b32 v79, v107, v108 offset0:8 offset1:74
	v_add_u32_e32 v79, v1, v11
	ds_write2_b32 v79, v109, v110 offset1:66
	ds_write2_b32 v79, v111, v112 offset0:132 offset1:198
	v_add_u32_e32 v79, 0x400, v79
	v_lshl_add_u64 v[92:93], s[10:11], 0, v[196:197]
	v_lshlrev_b32_e32 v196, 1, v68
	v_lshl_add_u64 v[110:111], v[92:93], 0, v[196:197]
	v_lshlrev_b32_e32 v196, 1, v70
	s_waitcnt vmcnt(0)
	v_mul_f32_e32 v88, v116, v88
	ds_write2_b32 v79, v113, v114 offset0:8 offset1:74
	ds_write2_b32 v79, v115, v88 offset0:140 offset1:206
	s_waitcnt lgkmcnt(0)
	ds_read2_b32 v[94:95], v13 offset0:33 offset1:41
	ds_read2_b32 v[96:97], v13 offset1:8
	ds_read2_b32 v[98:99], v13 offset0:66 offset1:74
	ds_read2_b32 v[100:101], v13 offset0:99 offset1:107
	ds_read2_b32 v[102:103], v13 offset0:132 offset1:140
	ds_read2_b32 v[104:105], v13 offset0:165 offset1:173
	ds_read2_b32 v[106:107], v13 offset0:198 offset1:206
	ds_read2_b32 v[108:109], v13 offset0:231 offset1:239
	s_waitcnt lgkmcnt(6)
	v_cvt_pk_bf16_f32 v88, v96, v94
	s_waitcnt lgkmcnt(4)
	v_cvt_pk_bf16_f32 v89, v98, v100
	s_waitcnt lgkmcnt(2)
	v_cvt_pk_bf16_f32 v90, v102, v104
	s_waitcnt lgkmcnt(0)
	v_cvt_pk_bf16_f32 v91, v106, v108
	global_store_dwordx4 v[110:111], v[88:91], off sc1
	s_nop 1
	v_cvt_pk_bf16_f32 v88, v97, v95
	v_cvt_pk_bf16_f32 v89, v99, v101
	v_cvt_pk_bf16_f32 v90, v103, v105
	v_cvt_pk_bf16_f32 v91, v107, v109
	v_lshl_add_u64 v[94:95], v[92:93], 0, v[196:197]
	global_store_dwordx4 v[94:95], v[88:91], off sc1
	ds_read2_b32 v[94:95], v13 offset0:49 offset1:57
	ds_read2_b32 v[96:97], v13 offset0:16 offset1:24
	ds_read2_b32 v[98:99], v13 offset0:82 offset1:90
	ds_read2_b32 v[100:101], v13 offset0:115 offset1:123
	ds_read2_b32 v[102:103], v13 offset0:148 offset1:156
	ds_read2_b32 v[104:105], v13 offset0:181 offset1:189
	ds_read2_b32 v[106:107], v13 offset0:214 offset1:222
	ds_read2_b32 v[108:109], v13 offset0:247 offset1:255
	v_lshlrev_b32_e32 v196, 1, v72
	s_waitcnt lgkmcnt(6)
	v_cvt_pk_bf16_f32 v88, v96, v94
	s_waitcnt lgkmcnt(4)
	v_cvt_pk_bf16_f32 v89, v98, v100
	s_waitcnt lgkmcnt(2)
	v_cvt_pk_bf16_f32 v90, v102, v104
	s_waitcnt lgkmcnt(0)
	v_cvt_pk_bf16_f32 v91, v106, v108
	v_lshl_add_u64 v[110:111], v[92:93], 0, v[196:197]
	v_lshlrev_b32_e32 v196, 1, v74
	global_store_dwordx4 v[110:111], v[88:91], off sc1
	v_lshl_add_u64 v[92:93], v[92:93], 0, v[196:197]
	s_nop 0
	v_cvt_pk_bf16_f32 v88, v97, v95
	v_cvt_pk_bf16_f32 v89, v99, v101
	v_cvt_pk_bf16_f32 v90, v103, v105
	v_cvt_pk_bf16_f32 v91, v107, v109
	global_store_dwordx4 v[92:93], v[88:91], off sc1
	s_waitcnt lgkmcnt(0)

; __device__ __forceinline__ void transpose_tile(const float* src, int srcN, const float* gk, bf16_t* dst, int dstK, LAS float* scr, int lane) {
;     ...
;     for (int i = 0; i < 32; ++i) tv[i] = src[(size_t)(2 * i + (lane >> 5)) * srcN + (lane & 31)];
;     if (gk) {
; __device__ __forceinline__ void convert_layer(const Params& p, int l, LAS unsigned char* lds, int it_lo, int it_hi, int worker, int nworkers) {
;     ...
;         if (r < 2 * I_D) {
;             const int f = r / I_D; r -= f * I_D; const int nb = r / (DFF / 64), kb = r % (DFF / 64), n0 = nb * 32, k0 = kb * 64;
;             const float* src = p.ffn_w_down + (size_t)(l * 2 + f) * DFF * DM;
;             transpose_tile(src + (size_t)k0 * DM + n0, DM, nullptr, W + (f ? O_WD1 : O_WD0) + (size_t)n0 * DFF + k0, DFF, scr, lane); continue; }
.LBB0_536:
	s_andn2_b64 vcc, exec, s[10:11]
	s_cbranch_vccnz .LBB0_538
	s_add_i32 s8, s46, 0x1880
	s_cmpk_gt_u32 s8, 0x57f
	s_cselect_b64 s[10:11], -1, 0
	v_cndmask_b32_e64 v79, 0, 1, s[10:11]
	s_and_b64 s[10:11], s[10:11], exec
	s_cselect_b32 s10, 0xfa80, 0
	s_add_i32 s10, s8, s10
	s_sext_i32_i16 s11, s10
	s_mulk_i32 s11, 0xba3
	s_lshr_b32 s12, s11, 31
	s_ashr_i32 s11, s11, 17
	s_add_i32 s49, s11, s12
	s_mul_i32 s11, s49, 44
	s_sub_i32 s10, s10, s11
	v_readfirstlane_b32 s11, v79
	s_sext_i32_i16 s10, s10
	s_or_b32 s11, s23, s11
	v_readlane_b32 s52, v254, 57
	s_lshl_b32 s12, s49, 5
	s_lshl_b32 s10, s10, 6
	s_mul_hi_i32 s13, s11, 0xb00000
	s_mul_i32 s11, s11, 0xb00000
	v_readlane_b32 s56, v254, 61
	v_readlane_b32 s57, v254, 62
	s_add_u32 s50, s56, s11
	s_addc_u32 s13, s57, s13
	s_ashr_i32 s11, s10, 31
	s_lshl_b64 s[14:15], s[10:11], 12
	s_add_u32 s50, s50, s14
	s_addc_u32 s51, s13, s15
	s_ashr_i32 s13, s12, 31
	s_lshl_b64 s[14:15], s[12:13], 2
	s_add_u32 s14, s50, s14
	s_addc_u32 s15, s51, s15
	v_lshlrev_b32_e32 v79, 2, v0
	v_lshlrev_b32_e32 v81, 2, v2
	v_lshlrev_b32_e32 v83, 2, v4
	v_lshlrev_b32_e32 v85, 2, v6
	v_lshlrev_b32_e32 v87, 2, v8
	v_lshlrev_b32_e32 v88, 2, v10
	v_lshlrev_b32_e32 v89, 2, v12
	v_lshlrev_b32_e32 v90, 2, v14
	global_load_dword v79, v79, s[14:15]
	s_nop 0
	global_load_dword v81, v81, s[14:15]
	s_nop 0
	global_load_dword v83, v83, s[14:15]
	s_nop 0
	global_load_dword v85, v85, s[14:15]
	s_nop 0
	global_load_dword v87, v87, s[14:15]
	s_nop 0
	global_load_dword v88, v88, s[14:15]
	s_nop 0
	global_load_dword v89, v89, s[14:15]
	s_nop 0
	global_load_dword v90, v90, s[14:15]
	v_lshlrev_b32_e32 v91, 2, v16
	v_lshlrev_b32_e32 v92, 2, v18
	v_lshlrev_b32_e32 v93, 2, v20
	v_lshlrev_b32_e32 v94, 2, v22
	v_lshlrev_b32_e32 v95, 2, v24
	v_lshlrev_b32_e32 v96, 2, v26
	v_lshlrev_b32_e32 v97, 2, v28
	v_lshlrev_b32_e32 v98, 2, v30
	global_load_dword v91, v91, s[14:15]
	s_nop 0
	global_load_dword v92, v92, s[14:15]
	s_nop 0
	global_load_dword v93, v93, s[14:15]
	s_nop 0
	global_load_dword v94, v94, s[14:15]
	s_nop 0
	global_load_dword v95, v95, s[14:15]
	s_nop 0
	global_load_dword v96, v96, s[14:15]
	s_nop 0
	global_load_dword v97, v97, s[14:15]
	s_nop 0
	global_load_dword v98, v98, s[14:15]
	v_lshlrev_b32_e32 v99, 2, v32
	v_lshlrev_b32_e32 v100, 2, v36
	v_lshlrev_b32_e32 v101, 2, v38
	v_lshlrev_b32_e32 v102, 2, v40
	v_lshlrev_b32_e32 v103, 2, v42
	v_lshlrev_b32_e32 v104, 2, v44
	v_lshlrev_b32_e32 v105, 2, v46
	v_lshlrev_b32_e32 v106, 2, v48
	global_load_dword v99, v99, s[14:15]
	s_nop 0
	global_load_dword v100, v100, s[14:15]
	s_nop 0
	global_load_dword v101, v101, s[14:15]
	s_nop 0
	global_load_dword v102, v102, s[14:15]
	s_nop 0
	global_load_dword v103, v103, s[14:15]
	s_nop 0
	global_load_dword v104, v104, s[14:15]
	s_nop 0
	global_load_dword v105, v105, s[14:15]
	s_nop 0
	global_load_dword v106, v106, s[14:15]
	v_lshlrev_b32_e32 v107, 2, v50
	v_lshlrev_b32_e32 v108, 2, v52
	v_lshlrev_b32_e32 v109, 2, v54
	v_lshlrev_b32_e32 v110, 2, v56
	v_lshlrev_b32_e32 v111, 2, v58
	v_lshlrev_b32_e32 v112, 2, v60
	v_lshlrev_b32_e32 v113, 2, v62
	v_lshlrev_b32_e32 v114, 2, v64
	global_load_dword v107, v107, s[14:15]
	s_nop 0
	global_load_dword v108, v108, s[14:15]
	s_nop 0
	global_load_dword v109, v109, s[14:15]
	s_nop 0
	global_load_dword v110, v110, s[14:15]
	s_nop 0
	global_load_dword v111, v111, s[14:15]
	s_nop 0
	global_load_dword v112, v112, s[14:15]
	s_nop 0
	global_load_dword v113, v113, s[14:15]
	s_nop 0
	global_load_dword v114, v114, s[14:15]
	v_add_u32_e32 v115, v1, v3
	s_cmpk_lt_u32 s8, 0x580
	s_mov_b32 s8, 0x2e00000
	s_cselect_b32 s8, 0xb00000, s8
	s_add_u32 s8, s16, s8
	s_addc_u32 s13, s17, 0
	s_mul_i32 s49, s49, 0x2c000
	s_mul_hi_i32 s12, s12, 0x1600
	s_add_u32 s8, s8, s49
	s_addc_u32 s12, s13, s12
	s_lshl_b64 s[10:11], s[10:11], 1
	s_add_u32 s10, s8, s10
	s_addc_u32 s11, s12, s11
	v_lshlrev_b32_e32 v196, 1, v66
	s_mov_b32 s8, 0xb000
	v_readlane_b32 s53, v254, 58
	v_readlane_b32 s54, v254, 59
	v_readlane_b32 s55, v254, 60
	v_readlane_b32 s58, v254, 63
	v_readlane_b32 s59, v255, 0
	v_readlane_b32 s60, v255, 1
	v_readlane_b32 s61, v255, 2
	v_readlane_b32 s62, v255, 3
	v_readlane_b32 s63, v255, 4
	v_readlane_b32 s64, v255, 5
	v_readlane_b32 s65, v255, 6
	v_readlane_b32 s66, v255, 7
	v_readlane_b32 s67, v255, 8
	s_waitcnt vmcnt(30)
; #define LAS __attribute__((address_space(3)))
; __device__ __forceinline__ unsigned pk2(float lo, float hi) { return pg8::cvt_pk_bf16(lo, hi); }
; __device__ __forceinline__ void transpose_tile(const float* src, int srcN, const float* gk, bf16_t* dst, int dstK, LAS float* scr, int lane) {
;     ...
;     for (int i = 0; i < 32; ++i) scr[(2 * i + (lane >> 5)) * 33 + (lane & 31)] = tv[i];
;     asm volatile("s_waitcnt lgkmcnt(0)" ::: "memory");
;     const int c = lane & 7;
; #pragma unroll
;     for (int j = 0; j < 4; ++j) {
;         const int n = (lane >> 3) + 8 * j; const LAS float* s = scr + (8 * c) * 33 + n;
;         u32x4 o; o.x = pk2(s[0 * 33], s[1 * 33]); o.y = pk2(s[2 * 33], s[3 * 33]); o.z = pk2(s[4 * 33], s[5 * 33]); o.w = pk2(s[6 * 33], s[7 * 33]);
;         *(u32x4*)(dst + (size_t)n * dstK + 8 * c) = o;
;     }
;     asm volatile("s_waitcnt lgkmcnt(0)" ::: "memory");
	ds_write2_b32 v115, v79, v81 offset1:66
	s_waitcnt vmcnt(28)
	ds_write2_b32 v115, v83, v85 offset0:132 offset1:198
	v_add_u32_e32 v79, 0x400, v115
	s_waitcnt vmcnt(26)
	ds_write2_b32 v79, v87, v88 offset0:8 offset1:74
	v_add_u32_e32 v79, v1, v5
	s_waitcnt vmcnt(24)
	ds_write2_b32 v79, v89, v90 offset1:66
	s_waitcnt vmcnt(22)
	ds_write2_b32 v79, v91, v92 offset0:132 offset1:198
	v_add_u32_e32 v79, 0x400, v79
	s_waitcnt vmcnt(20)
	ds_write2_b32 v79, v93, v94 offset0:8 offset1:74
	v_add_u32_e32 v79, v1, v7
	s_waitcnt vmcnt(18)
	ds_write2_b32 v79, v95, v96 offset1:66
	s_waitcnt vmcnt(16)
	ds_write2_b32 v79, v97, v98 offset0:132 offset1:198
	v_add_u32_e32 v79, 0x400, v79
	v_mov_b32_e32 v87, v197
	s_waitcnt vmcnt(14)
	ds_write2_b32 v79, v99, v100 offset0:8 offset1:74
	v_add_u32_e32 v79, v1, v9
	s_waitcnt vmcnt(12)
	ds_write2_b32 v79, v101, v102 offset1:66
	s_waitcnt vmcnt(10)
	ds_write2_b32 v79, v103, v104 offset0:132 offset1:198
	v_add_u32_e32 v79, 0x400, v79
	s_waitcnt vmcnt(8)
	ds_write2_b32 v79, v105, v106 offset0:8 offset1:74
	v_add_u32_e32 v79, v1, v11
	s_waitcnt vmcnt(6)
	ds_write2_b32 v79, v107, v108 offset1:66
	s_waitcnt vmcnt(4)
	ds_write2_b32 v79, v109, v110 offset0:132 offset1:198
	v_add_u32_e32 v79, 0x400, v79
	s_waitcnt vmcnt(2)
	ds_write2_b32 v79, v111, v112 offset0:8 offset1:74
	s_waitcnt vmcnt(0)
	ds_write2_b32 v79, v113, v114 offset0:140 offset1:206
	s_waitcnt lgkmcnt(0)
	ds_read2_b32 v[92:93], v13 offset0:33 offset1:41
	ds_read2_b32 v[94:95], v13 offset1:8
	ds_read2_b32 v[96:97], v13 offset0:66 offset1:74
	ds_read2_b32 v[98:99], v13 offset0:99 offset1:107
	ds_read2_b32 v[100:101], v13 offset0:132 offset1:140
	ds_read2_b32 v[102:103], v13 offset0:165 offset1:173
	ds_read2_b32 v[104:105], v13 offset0:198 offset1:206
	ds_read2_b32 v[106:107], v13 offset0:231 offset1:239
	v_lshl_add_u64 v[108:109], s[10:11], 0, v[196:197]
	s_waitcnt lgkmcnt(6)
	v_cvt_pk_bf16_f32 v88, v94, v92
	s_waitcnt lgkmcnt(4)
	v_cvt_pk_bf16_f32 v89, v96, v98
	s_waitcnt lgkmcnt(2)
	v_cvt_pk_bf16_f32 v90, v100, v102
	s_waitcnt lgkmcnt(0)
	v_cvt_pk_bf16_f32 v91, v104, v106
	v_lshl_add_u64 v[108:109], v[108:109], 0, v[86:87]
	global_store_dwordx4 v[108:109], v[88:91], off sc1
	v_add_co_u32_e32 v92, vcc, s8, v108
	s_nop 0
	v_cvt_pk_bf16_f32 v88, v95, v93
	v_cvt_pk_bf16_f32 v89, v97, v99
	v_cvt_pk_bf16_f32 v90, v101, v103
	v_cvt_pk_bf16_f32 v91, v105, v107
	ds_read2_b32 v[94:95], v13 offset0:49 offset1:57
	ds_read2_b32 v[96:97], v13 offset0:16 offset1:24
	ds_read2_b32 v[98:99], v13 offset0:82 offset1:90
	ds_read2_b32 v[100:101], v13 offset0:115 offset1:123
	ds_read2_b32 v[102:103], v13 offset0:148 offset1:156
	ds_read2_b32 v[104:105], v13 offset0:181 offset1:189
	ds_read2_b32 v[106:107], v13 offset0:214 offset1:222
	ds_read2_b32 v[110:111], v13 offset0:247 offset1:255
	v_addc_co_u32_e32 v93, vcc, 0, v109, vcc
	s_mov_b32 s8, 0x16000
	global_store_dwordx4 v[92:93], v[88:91], off sc1
	v_add_co_u32_e32 v92, vcc, s8, v108
	s_waitcnt lgkmcnt(6)
	v_cvt_pk_bf16_f32 v88, v96, v94
	s_waitcnt lgkmcnt(4)
	v_cvt_pk_bf16_f32 v89, v98, v100
	s_waitcnt lgkmcnt(2)
	v_cvt_pk_bf16_f32 v90, v102, v104
	s_waitcnt lgkmcnt(0)
	v_cvt_pk_bf16_f32 v91, v106, v110
	v_addc_co_u32_e32 v93, vcc, 0, v109, vcc
	global_store_dwordx4 v[92:93], v[88:91], off sc1
	v_add_co_u32_e32 v92, vcc, 0x21000, v108
	s_nop 0
	v_cvt_pk_bf16_f32 v88, v97, v95
	v_cvt_pk_bf16_f32 v89, v99, v101
	v_cvt_pk_bf16_f32 v90, v103, v105
	v_cvt_pk_bf16_f32 v91, v107, v111
	v_addc_co_u32_e32 v93, vcc, 0, v109, vcc
	global_store_dwordx4 v[92:93], v[88:91], off sc1
	s_waitcnt lgkmcnt(0)

; #define LAS __attribute__((address_space(3)))
; __device__ __forceinline__ unsigned pk2(float lo, float hi) { return pg8::cvt_pk_bf16(lo, hi); }
; __device__ __forceinline__ void transpose_tile(const float* src, int srcN, const float* gk, bf16_t* dst, int dstK, LAS float* scr, int lane) {
;     ...
;     for (int i = 0; i < 32; ++i) scr[(2 * i + (lane >> 5)) * 33 + (lane & 31)] = tv[i];
;     asm volatile("s_waitcnt lgkmcnt(0)" ::: "memory");
;     const int c = lane & 7;
; #pragma unroll
;     for (int j = 0; j < 4; ++j) {
;         const int n = (lane >> 3) + 8 * j; const LAS float* s = scr + (8 * c) * 33 + n;
;         u32x4 o; o.x = pk2(s[0 * 33], s[1 * 33]); o.y = pk2(s[2 * 33], s[3 * 33]); o.z = pk2(s[4 * 33], s[5 * 33]); o.w = pk2(s[6 * 33], s[7 * 33]);
;         *(u32x4*)(dst + (size_t)n * dstK + 8 * c) = o;
;     }
;     asm volatile("s_waitcnt lgkmcnt(0)" ::: "memory");
; __device__ __forceinline__ void convert_layer(const Params& p, int l, LAS unsigned char* lds, int it_lo, int it_hi, int worker, int nworkers) {
;     ...
;         if (r < 2 * I_GU) {
;             const int f = r / I_GU; r -= f * I_GU; const int nb = r / (DM / 64), kb = r % (DM / 64), n0 = nb * 32, k0 = kb * 64;
;             const int pn = n0 >> 8, w = n0 & 255; const float* src = ((w < 128) ? p.ffn_w_gate : p.ffn_w_up) + (size_t)(l * 2 + f) * DM * DFF;
;             transpose_tile(src + (size_t)k0 * DFF + pn * 128 + (w & 127), DFF, ng + (f ? 2 : 0) * DM + k0, W + (f ? O_WGU1 : O_WGU0) + (size_t)n0 * DM + k0, DM, scr, lane); continue; }
.LBB0_546:
	v_add_u32_e32 v79, v1, v3
	s_waitcnt vmcnt(30)
	ds_write2_b32 v79, v88, v89 offset1:66
	s_waitcnt vmcnt(28)
	ds_write2_b32 v79, v94, v95 offset0:132 offset1:198
	v_add_u32_e32 v79, 0x400, v79
	s_waitcnt vmcnt(26)
	ds_write2_b32 v79, v92, v93 offset0:8 offset1:74
	v_add_u32_e32 v79, v1, v5
	s_waitcnt vmcnt(24)
	ds_write2_b32 v79, v90, v91 offset1:66
	s_waitcnt vmcnt(22)
	ds_write2_b32 v79, v100, v101 offset0:132 offset1:198
	v_add_u32_e32 v79, 0x400, v79
	s_waitcnt vmcnt(20)
	ds_write2_b32 v79, v98, v99 offset0:8 offset1:74
	v_add_u32_e32 v79, v1, v7
	s_waitcnt vmcnt(18)
	ds_write2_b32 v79, v96, v97 offset1:66
	s_waitcnt vmcnt(16)
	ds_write2_b32 v79, v106, v107 offset0:132 offset1:198
	v_add_u32_e32 v79, 0x400, v79
	s_lshl_b32 s12, s8, 5
	s_waitcnt vmcnt(14)
	ds_write2_b32 v79, v104, v105 offset0:8 offset1:74
	v_add_u32_e32 v79, v1, v9
	s_and_b64 s[10:11], s[10:11], exec
	s_waitcnt vmcnt(12)
	ds_write2_b32 v79, v102, v103 offset1:66
	s_waitcnt vmcnt(10)
	ds_write2_b32 v79, v112, v113 offset0:132 offset1:198
	v_add_u32_e32 v79, 0x400, v79
	s_cselect_b32 s8, 0, 0x2300000
	s_waitcnt vmcnt(8)
	ds_write2_b32 v79, v110, v111 offset0:8 offset1:74
	v_add_u32_e32 v79, v1, v11
	s_add_u32 s8, s14, s8
	s_waitcnt vmcnt(6)
	ds_write2_b32 v79, v108, v109 offset1:66
	s_waitcnt vmcnt(4)
	ds_write2_b32 v79, v118, v119 offset0:132 offset1:198
	v_add_u32_e32 v79, 0x400, v79
	s_addc_u32 s48, s15, 0
	s_ashr_i32 s13, s12, 31
	s_waitcnt vmcnt(2)
	ds_write2_b32 v79, v116, v117 offset0:8 offset1:74
	s_waitcnt vmcnt(0)
	ds_write2_b32 v79, v114, v115 offset0:140 offset1:206
	s_lshl_b64 s[10:11], s[12:13], 11
	s_waitcnt lgkmcnt(0)
	s_add_u32 s8, s8, s10
	ds_read2_b32 v[92:93], v13 offset0:33 offset1:41
	ds_read2_b32 v[94:95], v13 offset1:8
	ds_read2_b32 v[96:97], v13 offset0:66 offset1:74
	ds_read2_b32 v[98:99], v13 offset0:99 offset1:107
	ds_read2_b32 v[100:101], v13 offset0:132 offset1:140
	ds_read2_b32 v[102:103], v13 offset0:165 offset1:173
	ds_read2_b32 v[104:105], v13 offset0:198 offset1:206
	ds_read2_b32 v[106:107], v13 offset0:231 offset1:239
	s_addc_u32 s10, s48, s11
	s_lshl_b64 s[0:1], s[0:1], 1
	s_add_u32 s0, s8, s0
	s_addc_u32 s1, s10, s1
	v_lshlrev_b32_e32 v196, 1, v66
	v_lshl_add_u64 v[108:109], s[0:1], 0, v[196:197]
	v_lshlrev_b32_e32 v196, 1, v68
	s_waitcnt lgkmcnt(6)
	v_cvt_pk_bf16_f32 v88, v94, v92
	s_waitcnt lgkmcnt(4)
	v_cvt_pk_bf16_f32 v89, v96, v98
	s_waitcnt lgkmcnt(2)
	v_cvt_pk_bf16_f32 v90, v100, v102
	s_waitcnt lgkmcnt(0)
	v_cvt_pk_bf16_f32 v91, v104, v106
	v_lshl_add_u64 v[110:111], v[108:109], 0, v[196:197]
	global_store_dwordx4 v[110:111], v[88:91], off sc1
	v_lshlrev_b32_e32 v196, 1, v70
	s_nop 0
	v_cvt_pk_bf16_f32 v88, v95, v93
	v_cvt_pk_bf16_f32 v89, v97, v99
	v_cvt_pk_bf16_f32 v90, v101, v103
	v_cvt_pk_bf16_f32 v91, v105, v107
	ds_read2_b32 v[94:95], v13 offset0:49 offset1:57
	ds_read2_b32 v[96:97], v13 offset0:16 offset1:24
	ds_read2_b32 v[98:99], v13 offset0:82 offset1:90
	ds_read2_b32 v[100:101], v13 offset0:115 offset1:123
	ds_read2_b32 v[102:103], v13 offset0:148 offset1:156
	ds_read2_b32 v[104:105], v13 offset0:181 offset1:189
	ds_read2_b32 v[106:107], v13 offset0:214 offset1:222
	ds_read2_b32 v[110:111], v13 offset0:247 offset1:255
	v_lshl_add_u64 v[92:93], v[108:109], 0, v[196:197]
	v_lshlrev_b32_e32 v196, 1, v72
	global_store_dwordx4 v[92:93], v[88:91], off sc1
	v_lshl_add_u64 v[92:93], v[108:109], 0, v[196:197]
	v_lshlrev_b32_e32 v196, 1, v74
	s_waitcnt lgkmcnt(6)
	v_cvt_pk_bf16_f32 v88, v96, v94
	s_waitcnt lgkmcnt(4)
	v_cvt_pk_bf16_f32 v89, v98, v100
	s_waitcnt lgkmcnt(2)
	v_cvt_pk_bf16_f32 v90, v102, v104
	s_waitcnt lgkmcnt(0)
	v_cvt_pk_bf16_f32 v91, v106, v110
	global_store_dwordx4 v[92:93], v[88:91], off sc1
	v_lshl_add_u64 v[92:93], v[108:109], 0, v[196:197]
	s_nop 0
	v_cvt_pk_bf16_f32 v88, v97, v95
	v_cvt_pk_bf16_f32 v89, v99, v101
	v_cvt_pk_bf16_f32 v90, v103, v105
	v_cvt_pk_bf16_f32 v91, v107, v111
	global_store_dwordx4 v[92:93], v[88:91], off sc1
	s_waitcnt lgkmcnt(0)

; #define LAS __attribute__((address_space(3)))
; __device__ __forceinline__ unsigned pk2(float lo, float hi) { return pg8::cvt_pk_bf16(lo, hi); }
; __device__ __forceinline__ void transpose_tile(const float* src, int srcN, const float* gk, bf16_t* dst, int dstK, LAS float* scr, int lane) {
;     float tv[32];
; #pragma unroll
;     for (int i = 0; i < 32; ++i) tv[i] = src[(size_t)(2 * i + (lane >> 5)) * srcN + (lane & 31)];
;     if (gk) {
; #pragma unroll
;         for (int i = 0; i < 32; ++i) tv[i] *= gk[2 * i + (lane >> 5)];
;     }
; #pragma unroll
;     for (int i = 0; i < 32; ++i) scr[(2 * i + (lane >> 5)) * 33 + (lane & 31)] = tv[i];
;     asm volatile("s_waitcnt lgkmcnt(0)" ::: "memory");
;     const int c = lane & 7;
; #pragma unroll
;     for (int j = 0; j < 4; ++j) {
;         const int n = (lane >> 3) + 8 * j; const LAS float* s = scr + (8 * c) * 33 + n;
;         u32x4 o; o.x = pk2(s[0 * 33], s[1 * 33]); o.y = pk2(s[2 * 33], s[3 * 33]); o.z = pk2(s[4 * 33], s[5 * 33]); o.w = pk2(s[6 * 33], s[7 * 33]);
;         *(u32x4*)(dst + (size_t)n * dstK + 8 * c) = o;
;     }
;     asm volatile("s_waitcnt lgkmcnt(0)" ::: "memory");
; }
; __device__ __forceinline__ void convert_layer(const Params& p, int l, LAS unsigned char* lds, int it_lo, int it_hi, int worker, int nworkers) {
;     ...
;         r -= I_ING;
;         if (r < 3 * I_B) {
;             const int i = r / I_B; r -= i * I_B; const int nb = r / 8, kb = r % 8, n0 = nb * 32, k0 = kb * 64;
;             transpose_tile(p.w_branch + (size_t)(l * 3 + i) * 512 * DM + (size_t)k0 * DM + n0, DM, nullptr, W + O_WB + (size_t)i * E_WB + (size_t)n0 * 512 + k0, 512, scr, lane); continue; }
;         r -= 3 * I_B;
;         {
;             const int nb = r / (DM / 64), kb = r % (DM / 64), n0 = nb * 32, k0 = kb * 64;
;             transpose_tile(p.w_o + (size_t)l * DM * DM + (size_t)k0 * DM + n0, DM, nullptr, W + O_WO + (size_t)n0 * DM + k0, DM, scr, lane); }
.LBB0_548:
	s_add_i32 s48, s46, 0x2e80
	s_cmpk_gt_i32 s48, 0x15ff
	s_mov_b64 s[0:1], -1
	s_cbranch_scc0 .LBB0_565
	s_cmpk_gt_u32 s48, 0x20ff
	s_cbranch_scc0 .LBB0_562
	s_cmpk_gt_u32 s48, 0x2e7f
	s_cbranch_scc0 .LBB0_556
	s_cmpk_gt_u32 s48, 0x317f
	s_cbranch_scc0 .LBB0_553
	s_and_b32 s0, s44, 0x7fffffe0
	s_and_b32 s12, s45, 0x3c0
	s_add_i32 s8, s0, 0xffff9d00
	s_lshl_b32 s0, s12, 12
	s_add_u32 s10, s38, s0
	s_addc_u32 s11, s39, 0
	s_lshl_b64 s[0:1], s[8:9], 2
	s_add_u32 s10, s10, s0
	s_addc_u32 s11, s11, s1
	v_lshlrev_b32_e32 v79, 2, v0
	v_lshlrev_b32_e32 v81, 2, v2
	global_load_dword v79, v79, s[10:11]
	v_lshlrev_b32_e32 v83, 2, v4
	global_load_dword v81, v81, s[10:11]
	v_lshlrev_b32_e32 v85, 2, v6
	v_lshlrev_b32_e32 v87, 2, v8
	v_lshlrev_b32_e32 v88, 2, v10
	global_load_dword v83, v83, s[10:11]
	v_lshlrev_b32_e32 v89, 2, v12
	global_load_dword v85, v85, s[10:11]
	v_lshlrev_b32_e32 v90, 2, v14
	global_load_dword v87, v87, s[10:11]
	v_lshlrev_b32_e32 v91, 2, v16
	global_load_dword v88, v88, s[10:11]
	v_lshlrev_b32_e32 v92, 2, v18
	global_load_dword v89, v89, s[10:11]
	v_lshlrev_b32_e32 v93, 2, v20
	global_load_dword v90, v90, s[10:11]
	v_lshlrev_b32_e32 v94, 2, v22
	global_load_dword v91, v91, s[10:11]
	v_lshlrev_b32_e32 v95, 2, v24
	global_load_dword v92, v92, s[10:11]
	v_lshlrev_b32_e32 v96, 2, v26
	global_load_dword v93, v93, s[10:11]
	v_lshlrev_b32_e32 v97, 2, v28
	global_load_dword v94, v94, s[10:11]
	v_lshlrev_b32_e32 v98, 2, v30
	global_load_dword v95, v95, s[10:11]
	v_lshlrev_b32_e32 v99, 2, v32
	global_load_dword v96, v96, s[10:11]
	v_lshlrev_b32_e32 v100, 2, v36
	global_load_dword v97, v97, s[10:11]
	v_lshlrev_b32_e32 v101, 2, v38
	global_load_dword v98, v98, s[10:11]
	v_lshlrev_b32_e32 v102, 2, v40
	global_load_dword v99, v99, s[10:11]
	v_lshlrev_b32_e32 v103, 2, v42
	global_load_dword v100, v100, s[10:11]
	v_lshlrev_b32_e32 v104, 2, v44
	global_load_dword v101, v101, s[10:11]
	v_lshlrev_b32_e32 v105, 2, v46
	global_load_dword v102, v102, s[10:11]
	v_lshlrev_b32_e32 v106, 2, v48
	global_load_dword v103, v103, s[10:11]
	v_lshlrev_b32_e32 v107, 2, v50
	global_load_dword v104, v104, s[10:11]
	v_lshlrev_b32_e32 v108, 2, v52
	global_load_dword v105, v105, s[10:11]
	v_lshlrev_b32_e32 v109, 2, v54
	global_load_dword v106, v106, s[10:11]
	v_lshlrev_b32_e32 v110, 2, v56
	global_load_dword v107, v107, s[10:11]
	v_lshlrev_b32_e32 v111, 2, v58
	global_load_dword v108, v108, s[10:11]
	v_lshlrev_b32_e32 v112, 2, v60
	global_load_dword v109, v109, s[10:11]
	v_lshlrev_b32_e32 v113, 2, v62
	global_load_dword v110, v110, s[10:11]
	v_lshlrev_b32_e32 v114, 2, v64
	global_load_dword v111, v111, s[10:11]
	v_add_u32_e32 v115, v1, v3
	global_load_dword v112, v112, s[10:11]
	s_lshl_b64 s[0:1], s[8:9], 11
	global_load_dword v113, v113, s[10:11]
	s_add_u32 s0, s16, s0
	global_load_dword v114, v114, s[10:11]
	s_addc_u32 s1, s17, s1
	s_lshl_b32 s8, s12, 1
	s_add_u32 s0, s0, s8
	s_addc_u32 s1, s1, 0
	v_lshlrev_b32_e32 v196, 1, v66
	s_waitcnt vmcnt(30)
	ds_write2_b32 v115, v79, v81 offset1:66
	s_waitcnt vmcnt(28)
	ds_write2_b32 v115, v83, v85 offset0:132 offset1:198
	v_add_u32_e32 v79, 0x400, v115
	s_waitcnt vmcnt(26)
	ds_write2_b32 v79, v87, v88 offset0:8 offset1:74
	v_add_u32_e32 v79, v1, v5
	s_waitcnt vmcnt(24)
	ds_write2_b32 v79, v89, v90 offset1:66
	s_waitcnt vmcnt(22)
	ds_write2_b32 v79, v91, v92 offset0:132 offset1:198
	v_add_u32_e32 v79, 0x400, v79
	s_waitcnt vmcnt(20)
	ds_write2_b32 v79, v93, v94 offset0:8 offset1:74
	v_add_u32_e32 v79, v1, v7
	s_waitcnt vmcnt(18)
	ds_write2_b32 v79, v95, v96 offset1:66
	s_waitcnt vmcnt(16)
	ds_write2_b32 v79, v97, v98 offset0:132 offset1:198
	v_add_u32_e32 v79, 0x400, v79
	v_lshl_add_u64 v[92:93], s[0:1], 0, v[196:197]
	v_lshlrev_b32_e32 v196, 1, v68
	s_mov_b64 s[0:1], 0
	s_waitcnt vmcnt(14)
	ds_write2_b32 v79, v99, v100 offset0:8 offset1:74
	v_add_u32_e32 v79, v1, v9
	s_waitcnt vmcnt(12)
	ds_write2_b32 v79, v101, v102 offset1:66
	s_waitcnt vmcnt(10)
	ds_write2_b32 v79, v103, v104 offset0:132 offset1:198
	v_add_u32_e32 v79, 0x400, v79
	s_waitcnt vmcnt(8)
	ds_write2_b32 v79, v105, v106 offset0:8 offset1:74
	v_add_u32_e32 v79, v1, v11
	s_waitcnt vmcnt(6)
	ds_write2_b32 v79, v107, v108 offset1:66
	s_waitcnt vmcnt(4)
	ds_write2_b32 v79, v109, v110 offset0:132 offset1:198
	v_add_u32_e32 v79, 0x400, v79
	s_waitcnt vmcnt(2)
	ds_write2_b32 v79, v111, v112 offset0:8 offset1:74
	s_waitcnt vmcnt(0)
	ds_write2_b32 v79, v113, v114 offset0:140 offset1:206
	s_waitcnt lgkmcnt(0)
	ds_read2_b32 v[94:95], v13 offset0:33 offset1:41
	ds_read2_b32 v[96:97], v13 offset1:8
	ds_read2_b32 v[98:99], v13 offset0:66 offset1:74
	ds_read2_b32 v[100:101], v13 offset0:99 offset1:107
	ds_read2_b32 v[102:103], v13 offset0:132 offset1:140
	ds_read2_b32 v[104:105], v13 offset0:165 offset1:173
	ds_read2_b32 v[106:107], v13 offset0:198 offset1:206
	ds_read2_b32 v[108:109], v13 offset0:231 offset1:239
	v_lshl_add_u64 v[110:111], v[92:93], 0, v[196:197]
	s_waitcnt lgkmcnt(6)
	v_cvt_pk_bf16_f32 v88, v96, v94
	s_waitcnt lgkmcnt(4)
	v_cvt_pk_bf16_f32 v89, v98, v100
	s_waitcnt lgkmcnt(2)
	v_cvt_pk_bf16_f32 v90, v102, v104
	s_waitcnt lgkmcnt(0)
	v_cvt_pk_bf16_f32 v91, v106, v108
	v_lshlrev_b32_e32 v196, 1, v70
	global_store_dwordx4 v[110:111], v[88:91], off sc1
	s_nop 1
	v_cvt_pk_bf16_f32 v88, v97, v95
	v_cvt_pk_bf16_f32 v89, v99, v101
	v_cvt_pk_bf16_f32 v90, v103, v105
	v_cvt_pk_bf16_f32 v91, v107, v109
	v_lshl_add_u64 v[94:95], v[92:93], 0, v[196:197]
	global_store_dwordx4 v[94:95], v[88:91], off sc1
	ds_read2_b32 v[94:95], v13 offset0:49 offset1:57
	ds_read2_b32 v[96:97], v13 offset0:16 offset1:24
	ds_read2_b32 v[98:99], v13 offset0:82 offset1:90
	ds_read2_b32 v[100:101], v13 offset0:115 offset1:123
	ds_read2_b32 v[102:103], v13 offset0:148 offset1:156
	ds_read2_b32 v[104:105], v13 offset0:181 offset1:189
	ds_read2_b32 v[106:107], v13 offset0:214 offset1:222
	ds_read2_b32 v[108:109], v13 offset0:247 offset1:255
	v_lshlrev_b32_e32 v196, 1, v72
	s_waitcnt lgkmcnt(6)
	v_cvt_pk_bf16_f32 v88, v96, v94
	s_waitcnt lgkmcnt(4)
	v_cvt_pk_bf16_f32 v89, v98, v100
	s_waitcnt lgkmcnt(2)
	v_cvt_pk_bf16_f32 v90, v102, v104
	s_waitcnt lgkmcnt(0)
	v_cvt_pk_bf16_f32 v91, v106, v108
	v_lshl_add_u64 v[110:111], v[92:93], 0, v[196:197]
	v_lshlrev_b32_e32 v196, 1, v74
	global_store_dwordx4 v[110:111], v[88:91], off sc1
	v_lshl_add_u64 v[92:93], v[92:93], 0, v[196:197]
	s_nop 0
	v_cvt_pk_bf16_f32 v88, v97, v95
	v_cvt_pk_bf16_f32 v89, v99, v101
	v_cvt_pk_bf16_f32 v90, v103, v105
	v_cvt_pk_bf16_f32 v91, v107, v109
	global_store_dwordx4 v[92:93], v[88:91], off sc1
	s_waitcnt lgkmcnt(0)
; #define LAS __attribute__((address_space(3)))
; __device__ __forceinline__ unsigned pk2(float lo, float hi) { return pg8::cvt_pk_bf16(lo, hi); }
; __device__ __forceinline__ void transpose_tile(const float* src, int srcN, const float* gk, bf16_t* dst, int dstK, LAS float* scr, int lane) {
;     float tv[32];
; #pragma unroll
;     for (int i = 0; i < 32; ++i) tv[i] = src[(size_t)(2 * i + (lane >> 5)) * srcN + (lane & 31)];
;     if (gk) {
; #pragma unroll
;         for (int i = 0; i < 32; ++i) tv[i] *= gk[2 * i + (lane >> 5)];
;     }
; #pragma unroll
;     for (int i = 0; i < 32; ++i) scr[(2 * i + (lane >> 5)) * 33 + (lane & 31)] = tv[i];
;     asm volatile("s_waitcnt lgkmcnt(0)" ::: "memory");
;     const int c = lane & 7;
; #pragma unroll
;     for (int j = 0; j < 4; ++j) {
;         const int n = (lane >> 3) + 8 * j; const LAS float* s = scr + (8 * c) * 33 + n;
;         u32x4 o; o.x = pk2(s[0 * 33], s[1 * 33]); o.y = pk2(s[2 * 33], s[3 * 33]); o.z = pk2(s[4 * 33], s[5 * 33]); o.w = pk2(s[6 * 33], s[7 * 33]);
;         *(u32x4*)(dst + (size_t)n * dstK + 8 * c) = o;
;     }
;     asm volatile("s_waitcnt lgkmcnt(0)" ::: "memory");
; }
; __device__ __forceinline__ void convert_layer(const Params& p, int l, LAS unsigned char* lds, int it_lo, int it_hi, int worker, int nworkers) {
;     ...
;         if (r < 3 * I_B) {
;             const int i = r / I_B; r -= i * I_B; const int nb = r / 8, kb = r % 8, n0 = nb * 32, k0 = kb * 64;
;             transpose_tile(p.w_branch + (size_t)(l * 3 + i) * 512 * DM + (size_t)k0 * DM + n0, DM, nullptr, W + O_WB + (size_t)i * E_WB + (size_t)n0 * 512 + k0, 512, scr, lane); continue; }
.LBB0_553:
	s_andn2_b64 vcc, exec, s[0:1]
	s_cbranch_vccnz .LBB0_555
	s_lshr_b32 s8, s46, 8
	s_add_i32 s0, s8, s18
	s_ashr_i32 s1, s0, 31
	s_and_b32 s12, s47, 0x3e0
	s_and_b32 s13, s45, 0x1c0
	s_lshl_b64 s[0:1], s[0:1], 21
	s_add_u32 s0, s76, s0
	s_addc_u32 s1, s77, s1
	s_lshl_b32 s10, s13, 12
	s_add_u32 s0, s0, s10
	s_addc_u32 s1, s1, 0
	s_lshl_b32 s10, s12, 2
	s_add_u32 s10, s0, s10
	s_addc_u32 s11, s1, 0
	v_lshlrev_b32_e32 v79, 2, v0
	v_lshlrev_b32_e32 v81, 2, v2
	global_load_dword v79, v79, s[10:11]
	v_lshlrev_b32_e32 v83, 2, v4
	global_load_dword v81, v81, s[10:11]
	v_lshlrev_b32_e32 v85, 2, v6
	v_lshlrev_b32_e32 v87, 2, v8
	v_lshlrev_b32_e32 v88, 2, v10
	global_load_dword v83, v83, s[10:11]
	v_lshlrev_b32_e32 v89, 2, v12
	global_load_dword v85, v85, s[10:11]
	v_lshlrev_b32_e32 v90, 2, v14
	global_load_dword v87, v87, s[10:11]
	v_lshlrev_b32_e32 v91, 2, v16
	global_load_dword v88, v88, s[10:11]
	v_lshlrev_b32_e32 v92, 2, v18
	global_load_dword v89, v89, s[10:11]
	v_lshlrev_b32_e32 v93, 2, v20
	global_load_dword v90, v90, s[10:11]
	v_lshlrev_b32_e32 v94, 2, v22
	global_load_dword v91, v91, s[10:11]
	v_lshlrev_b32_e32 v95, 2, v24
	global_load_dword v92, v92, s[10:11]
	v_lshlrev_b32_e32 v96, 2, v26
	global_load_dword v93, v93, s[10:11]
	v_lshlrev_b32_e32 v97, 2, v28
	global_load_dword v94, v94, s[10:11]
	v_lshlrev_b32_e32 v98, 2, v30
	global_load_dword v95, v95, s[10:11]
	v_lshlrev_b32_e32 v99, 2, v32
	global_load_dword v96, v96, s[10:11]
	v_lshlrev_b32_e32 v100, 2, v36
	global_load_dword v97, v97, s[10:11]
	v_lshlrev_b32_e32 v101, 2, v38
	global_load_dword v98, v98, s[10:11]
	v_lshlrev_b32_e32 v102, 2, v40
	global_load_dword v99, v99, s[10:11]
	v_lshlrev_b32_e32 v103, 2, v42
	global_load_dword v100, v100, s[10:11]
	v_lshlrev_b32_e32 v104, 2, v44
	global_load_dword v101, v101, s[10:11]
	v_lshlrev_b32_e32 v105, 2, v46
	global_load_dword v102, v102, s[10:11]
	v_lshlrev_b32_e32 v106, 2, v48
	global_load_dword v103, v103, s[10:11]
	v_lshlrev_b32_e32 v107, 2, v50
	global_load_dword v104, v104, s[10:11]
	v_lshlrev_b32_e32 v108, 2, v52
	global_load_dword v105, v105, s[10:11]
	v_lshlrev_b32_e32 v109, 2, v54
	global_load_dword v106, v106, s[10:11]
	v_lshlrev_b32_e32 v110, 2, v56
	global_load_dword v107, v107, s[10:11]
	v_lshlrev_b32_e32 v111, 2, v58
	global_load_dword v108, v108, s[10:11]
	v_lshlrev_b32_e32 v112, 2, v60
	global_load_dword v109, v109, s[10:11]
	v_lshlrev_b32_e32 v113, 2, v62
	global_load_dword v110, v110, s[10:11]
	v_lshlrev_b32_e32 v114, 2, v64
	global_load_dword v111, v111, s[10:11]
	v_add_u32_e32 v115, v1, v3
	global_load_dword v112, v112, s[10:11]
	s_lshl_b64 s[0:1], s[8:9], 20
	global_load_dword v113, v113, s[10:11]
	s_add_u32 s0, s19, s0
	global_load_dword v114, v114, s[10:11]
	s_addc_u32 s1, s20, s1
	s_lshl_b32 s8, s12, 10
	s_add_u32 s0, s0, s8
	s_addc_u32 s1, s1, 0
	s_lshl_b32 s8, s13, 1
	s_add_u32 s0, s0, s8
	s_addc_u32 s1, s1, 0
	v_lshlrev_b32_e32 v196, 1, v66
	s_waitcnt vmcnt(30)
	ds_write2_b32 v115, v79, v81 offset1:66
	s_waitcnt vmcnt(28)
	ds_write2_b32 v115, v83, v85 offset0:132 offset1:198
	v_add_u32_e32 v79, 0x400, v115
	v_mov_b32_e32 v81, v197
	v_mov_b32_e32 v83, v197
	v_mov_b32_e32 v85, v197
	s_waitcnt vmcnt(26)
	ds_write2_b32 v79, v87, v88 offset0:8 offset1:74
	v_add_u32_e32 v79, v1, v5
	s_waitcnt vmcnt(24)
	ds_write2_b32 v79, v89, v90 offset1:66
	s_waitcnt vmcnt(22)
	ds_write2_b32 v79, v91, v92 offset0:132 offset1:198
	v_add_u32_e32 v79, 0x400, v79
	s_waitcnt vmcnt(20)
	ds_write2_b32 v79, v93, v94 offset0:8 offset1:74
	v_add_u32_e32 v79, v1, v7
	s_waitcnt vmcnt(18)
	ds_write2_b32 v79, v95, v96 offset1:66
	s_waitcnt vmcnt(16)
	ds_write2_b32 v79, v97, v98 offset0:132 offset1:198
	v_add_u32_e32 v79, 0x400, v79
	v_lshl_add_u64 v[92:93], s[0:1], 0, v[196:197]
	s_waitcnt vmcnt(14)
	ds_write2_b32 v79, v99, v100 offset0:8 offset1:74
	v_add_u32_e32 v79, v1, v9
	s_waitcnt vmcnt(12)
	ds_write2_b32 v79, v101, v102 offset1:66
	s_waitcnt vmcnt(10)
	ds_write2_b32 v79, v103, v104 offset0:132 offset1:198
	v_add_u32_e32 v79, 0x400, v79
	s_waitcnt vmcnt(8)
	ds_write2_b32 v79, v105, v106 offset0:8 offset1:74
	v_add_u32_e32 v79, v1, v11
	s_waitcnt vmcnt(6)
	ds_write2_b32 v79, v107, v108 offset1:66
	s_waitcnt vmcnt(4)
	ds_write2_b32 v79, v109, v110 offset0:132 offset1:198
	v_add_u32_e32 v79, 0x400, v79
	s_waitcnt vmcnt(2)
	ds_write2_b32 v79, v111, v112 offset0:8 offset1:74
	s_waitcnt vmcnt(0)
	ds_write2_b32 v79, v113, v114 offset0:140 offset1:206
	s_waitcnt lgkmcnt(0)
	ds_read2_b32 v[94:95], v13 offset0:33 offset1:41
	ds_read2_b32 v[96:97], v13 offset1:8
	ds_read2_b32 v[98:99], v13 offset0:66 offset1:74
	ds_read2_b32 v[100:101], v13 offset0:99 offset1:107
	ds_read2_b32 v[102:103], v13 offset0:132 offset1:140
	ds_read2_b32 v[104:105], v13 offset0:165 offset1:173
	ds_read2_b32 v[106:107], v13 offset0:198 offset1:206
	ds_read2_b32 v[108:109], v13 offset0:231 offset1:239
	v_mov_b32_e32 v79, v197
	s_waitcnt lgkmcnt(6)
	v_cvt_pk_bf16_f32 v88, v96, v94
	s_waitcnt lgkmcnt(4)
	v_cvt_pk_bf16_f32 v89, v98, v100
	s_waitcnt lgkmcnt(2)
	v_cvt_pk_bf16_f32 v90, v102, v104
	s_waitcnt lgkmcnt(0)
	v_cvt_pk_bf16_f32 v91, v106, v108
	v_lshl_add_u64 v[110:111], v[92:93], 0, v[78:79]
	global_store_dwordx4 v[110:111], v[88:91], off sc1
	v_lshl_add_u64 v[110:111], v[92:93], 0, v[82:83]
	s_nop 0
	v_cvt_pk_bf16_f32 v88, v97, v95
	v_cvt_pk_bf16_f32 v89, v99, v101
	v_cvt_pk_bf16_f32 v90, v103, v105
	v_cvt_pk_bf16_f32 v91, v107, v109
	v_lshl_add_u64 v[94:95], v[92:93], 0, v[80:81]
	global_store_dwordx4 v[94:95], v[88:91], off sc1
	ds_read2_b32 v[94:95], v13 offset0:49 offset1:57
	ds_read2_b32 v[96:97], v13 offset0:16 offset1:24
	ds_read2_b32 v[98:99], v13 offset0:82 offset1:90
	ds_read2_b32 v[100:101], v13 offset0:115 offset1:123
	ds_read2_b32 v[102:103], v13 offset0:148 offset1:156
	ds_read2_b32 v[104:105], v13 offset0:181 offset1:189
	ds_read2_b32 v[106:107], v13 offset0:214 offset1:222
	ds_read2_b32 v[108:109], v13 offset0:247 offset1:255
	v_lshl_add_u64 v[92:93], v[92:93], 0, v[84:85]
	s_waitcnt lgkmcnt(6)
	v_cvt_pk_bf16_f32 v88, v96, v94
	s_waitcnt lgkmcnt(4)
	v_cvt_pk_bf16_f32 v89, v98, v100
	s_waitcnt lgkmcnt(2)
	v_cvt_pk_bf16_f32 v90, v102, v104
	s_waitcnt lgkmcnt(0)
	v_cvt_pk_bf16_f32 v91, v106, v108
	global_store_dwordx4 v[110:111], v[88:91], off sc1
	s_nop 1
	v_cvt_pk_bf16_f32 v88, v97, v95
	v_cvt_pk_bf16_f32 v89, v99, v101
	v_cvt_pk_bf16_f32 v90, v103, v105
	v_cvt_pk_bf16_f32 v91, v107, v109
	global_store_dwordx4 v[92:93], v[88:91], off sc1
	s_waitcnt lgkmcnt(0)

; #define LAS __attribute__((address_space(3)))
; __device__ __forceinline__ void transpose_tile(const float* src, int srcN, const float* gk, bf16_t* dst, int dstK, LAS float* scr, int lane) {
;     float tv[32];
; #pragma unroll
;     for (int i = 0; i < 32; ++i) tv[i] = src[(size_t)(2 * i + (lane >> 5)) * srcN + (lane & 31)];
;     if (gk) {
; #pragma unroll
;         for (int i = 0; i < 32; ++i) tv[i] *= gk[2 * i + (lane >> 5)];
;     }
; #pragma unroll
;     for (int i = 0; i < 32; ++i) scr[(2 * i + (lane >> 5)) * 33 + (lane & 31)] = tv[i];
; __device__ __forceinline__ void convert_layer(const Params& p, int l, LAS unsigned char* lds, int it_lo, int it_hi, int worker, int nworkers) {
;     ...
;         if (r < I_ING) {
;             const int nb = r / (DM / 64), kb = r % (DM / 64), n0 = nb * 32, k0 = kb * 64;
;             if (n0 < NPROJ) transpose_tile(p.w_in + (size_t)l * DM * NPROJ + (size_t)k0 * NPROJ + n0, NPROJ, ng + DM + k0, W + O_WING + (size_t)n0 * DM + k0, DM, scr, lane);
;             else transpose_tile(p.w_gate + (size_t)l * DM * NGATE + (size_t)k0 * NGATE + (n0 - NPROJ), NGATE, ng + DM + k0, W + O_WING + (size_t)n0 * DM + k0, DM, scr, lane);
.LBB0_556:
	s_andn2_b64 vcc, exec, s[0:1]
	s_cbranch_vccnz .LBB0_561
	s_and_b32 s11, s44, 0x7fe0
	s_add_i32 s8, s11, 0xffffbe00
	s_and_b32 s10, s45, 0x3c0
	s_cmpk_gt_u32 s8, 0xeff
	s_mov_b64 s[0:1], -1
	s_cbranch_scc0 .LBB0_559
	s_mul_i32 s0, s10, 0x3000
	s_add_u32 s0, s40, s0
	s_addc_u32 s1, s41, 0
	s_lshl_b32 s11, s11, 2
	s_add_u32 s0, s0, s11
	s_addc_u32 s1, s1, 0
	s_add_u32 s12, s0, 0xfffebc00
	s_addc_u32 s13, s1, -1
	s_lshl_b64 s[0:1], s[8:9], 11
	s_add_u32 s0, s21, s0
	s_addc_u32 s1, s22, s1
	s_lshl_b32 s11, s10, 1
	s_add_u32 s0, s0, s11
	s_addc_u32 s1, s1, 0
	global_load_dword v79, v15, s[12:13]
	global_load_dword v81, v17, s[12:13]
	global_load_dword v83, v19, s[12:13]
	global_load_dword v85, v21, s[12:13]
	global_load_dword v87, v23, s[12:13]
	global_load_dword v90, v25, s[12:13]
	global_load_dword v91, v27, s[12:13]
	global_load_dword v92, v29, s[12:13]
	global_load_dword v93, v31, s[12:13]
	global_load_dword v94, v33, s[12:13]
	global_load_dword v95, v35, s[12:13]
	global_load_dword v96, v37, s[12:13]
	global_load_dword v97, v39, s[12:13]
	global_load_dword v98, v41, s[12:13]
	global_load_dword v99, v43, s[12:13]
	global_load_dword v100, v45, s[12:13]
	global_load_dword v101, v47, s[12:13]
	global_load_dword v102, v49, s[12:13]
	global_load_dword v103, v51, s[12:13]
	global_load_dword v104, v53, s[12:13]
	global_load_dword v105, v55, s[12:13]
	global_load_dword v106, v57, s[12:13]
	global_load_dword v107, v59, s[12:13]
	global_load_dword v108, v61, s[12:13]
	global_load_dword v109, v63, s[12:13]
	global_load_dword v110, v65, s[12:13]
	global_load_dword v111, v67, s[12:13]
	global_load_dword v112, v69, s[12:13]
	global_load_dword v113, v71, s[12:13]
	global_load_dword v114, v73, s[12:13]
	global_load_dword v115, v75, s[12:13]
	global_load_dword v116, v121, s[12:13]
	s_lshl_b32 s12, s10, 2
	s_mov_b32 s13, s9
	v_lshl_add_u64 v[88:89], v[76:77], 0, s[12:13]
	global_load_dword v117, v[88:89], off
	v_lshlrev_b32_e32 v196, 1, v66
	s_waitcnt vmcnt(0)
	v_mul_f32_e32 v79, v79, v117
	global_load_dword v117, v[88:89], off offset:8
	s_waitcnt vmcnt(0)
	v_mul_f32_e32 v81, v81, v117
	global_load_dword v117, v[88:89], off offset:16
	s_waitcnt vmcnt(0)
	v_mul_f32_e32 v83, v83, v117
	global_load_dword v117, v[88:89], off offset:24
	s_waitcnt vmcnt(0)
	v_mul_f32_e32 v85, v85, v117
	global_load_dword v117, v[88:89], off offset:32
	s_waitcnt vmcnt(0)
	v_mul_f32_e32 v87, v87, v117
	global_load_dword v117, v[88:89], off offset:40
	s_waitcnt vmcnt(0)
	v_mul_f32_e32 v90, v90, v117
	global_load_dword v117, v[88:89], off offset:48
	s_waitcnt vmcnt(0)
	v_mul_f32_e32 v91, v91, v117
	global_load_dword v117, v[88:89], off offset:56
	s_waitcnt vmcnt(0)
	v_mul_f32_e32 v92, v92, v117
	global_load_dword v117, v[88:89], off offset:64
	s_waitcnt vmcnt(0)
	v_mul_f32_e32 v93, v93, v117
	global_load_dword v117, v[88:89], off offset:72
	s_waitcnt vmcnt(0)
	v_mul_f32_e32 v94, v94, v117
	global_load_dword v117, v[88:89], off offset:80
	s_waitcnt vmcnt(0)
	v_mul_f32_e32 v95, v95, v117
	global_load_dword v117, v[88:89], off offset:88
	s_waitcnt vmcnt(0)
	v_mul_f32_e32 v96, v96, v117
	global_load_dword v117, v[88:89], off offset:96
	s_waitcnt vmcnt(0)
	v_mul_f32_e32 v97, v97, v117
	global_load_dword v117, v[88:89], off offset:104
	s_waitcnt vmcnt(0)
	v_mul_f32_e32 v98, v98, v117
	global_load_dword v117, v[88:89], off offset:112
	s_waitcnt vmcnt(0)
	v_mul_f32_e32 v99, v99, v117
	global_load_dword v117, v[88:89], off offset:120
	s_waitcnt vmcnt(0)
	v_mul_f32_e32 v100, v100, v117
	global_load_dword v117, v[88:89], off offset:128
	s_waitcnt vmcnt(0)
	v_mul_f32_e32 v101, v101, v117
	global_load_dword v117, v[88:89], off offset:136
	s_waitcnt vmcnt(0)
	v_mul_f32_e32 v102, v102, v117
	global_load_dword v117, v[88:89], off offset:144
	s_waitcnt vmcnt(0)
	v_mul_f32_e32 v103, v103, v117
	global_load_dword v117, v[88:89], off offset:152
	s_waitcnt vmcnt(0)
	v_mul_f32_e32 v104, v104, v117
	global_load_dword v117, v[88:89], off offset:160
	s_waitcnt vmcnt(0)
	v_mul_f32_e32 v105, v105, v117
	global_load_dword v117, v[88:89], off offset:168
	s_waitcnt vmcnt(0)
	v_mul_f32_e32 v106, v106, v117
	global_load_dword v117, v[88:89], off offset:176
	s_waitcnt vmcnt(0)
	v_mul_f32_e32 v107, v107, v117
	global_load_dword v117, v[88:89], off offset:184
	s_waitcnt vmcnt(0)
	v_mul_f32_e32 v108, v108, v117
	global_load_dword v117, v[88:89], off offset:192
	s_waitcnt vmcnt(0)
	v_mul_f32_e32 v109, v109, v117
	global_load_dword v117, v[88:89], off offset:200
	s_waitcnt vmcnt(0)
	v_mul_f32_e32 v110, v110, v117
	global_load_dword v117, v[88:89], off offset:208
	s_waitcnt vmcnt(0)
	v_mul_f32_e32 v111, v111, v117
	global_load_dword v117, v[88:89], off offset:216
	s_waitcnt vmcnt(0)
	v_mul_f32_e32 v112, v112, v117
	global_load_dword v117, v[88:89], off offset:224
	s_waitcnt vmcnt(0)
	v_mul_f32_e32 v113, v113, v117
	global_load_dword v117, v[88:89], off offset:232
	s_waitcnt vmcnt(0)
	v_mul_f32_e32 v114, v114, v117
	global_load_dword v117, v[88:89], off offset:240
	s_waitcnt vmcnt(0)
	v_mul_f32_e32 v115, v115, v117
	global_load_dword v88, v[88:89], off offset:248
	v_add_u32_e32 v89, v1, v3
	ds_write2_b32 v89, v79, v81 offset1:66
	ds_write2_b32 v89, v83, v85 offset0:132 offset1:198
	v_add_u32_e32 v79, 0x400, v89
	ds_write2_b32 v79, v87, v90 offset0:8 offset1:74
	v_add_u32_e32 v79, v1, v5
	ds_write2_b32 v79, v91, v92 offset1:66
	ds_write2_b32 v79, v93, v94 offset0:132 offset1:198
	v_add_u32_e32 v79, 0x400, v79
	ds_write2_b32 v79, v95, v96 offset0:8 offset1:74
	v_add_u32_e32 v79, v1, v7
	ds_write2_b32 v79, v97, v98 offset1:66
	ds_write2_b32 v79, v99, v100 offset0:132 offset1:198
	v_add_u32_e32 v79, 0x400, v79
	ds_write2_b32 v79, v101, v102 offset0:8 offset1:74
	v_add_u32_e32 v79, v1, v9
	ds_write2_b32 v79, v103, v104 offset1:66
	ds_write2_b32 v79, v105, v106 offset0:132 offset1:198
	v_add_u32_e32 v79, 0x400, v79
	ds_write2_b32 v79, v107, v108 offset0:8 offset1:74
	v_add_u32_e32 v79, v1, v11
	ds_write2_b32 v79, v109, v110 offset1:66
	ds_write2_b32 v79, v111, v112 offset0:132 offset1:198
	v_add_u32_e32 v79, 0x400, v79
	v_lshl_add_u64 v[92:93], s[0:1], 0, v[196:197]
	v_lshlrev_b32_e32 v196, 1, v68
	v_lshl_add_u64 v[110:111], v[92:93], 0, v[196:197]
	v_lshlrev_b32_e32 v196, 1, v70
	s_mov_b64 s[0:1], 0
	s_waitcnt vmcnt(0)
; #define LAS __attribute__((address_space(3)))
; __device__ __forceinline__ unsigned pk2(float lo, float hi) { return pg8::cvt_pk_bf16(lo, hi); }
; __device__ __forceinline__ void transpose_tile(const float* src, int srcN, const float* gk, bf16_t* dst, int dstK, LAS float* scr, int lane) {
;     ...
;     for (int i = 0; i < 32; ++i) scr[(2 * i + (lane >> 5)) * 33 + (lane & 31)] = tv[i];
;     asm volatile("s_waitcnt lgkmcnt(0)" ::: "memory");
;     const int c = lane & 7;
; #pragma unroll
;     for (int j = 0; j < 4; ++j) {
;         const int n = (lane >> 3) + 8 * j; const LAS float* s = scr + (8 * c) * 33 + n;
;         u32x4 o; o.x = pk2(s[0 * 33], s[1 * 33]); o.y = pk2(s[2 * 33], s[3 * 33]); o.z = pk2(s[4 * 33], s[5 * 33]); o.w = pk2(s[6 * 33], s[7 * 33]);
;         *(u32x4*)(dst + (size_t)n * dstK + 8 * c) = o;
;     }
;     asm volatile("s_waitcnt lgkmcnt(0)" ::: "memory");
; }
; __device__ __forceinline__ void convert_layer(const Params& p, int l, LAS unsigned char* lds, int it_lo, int it_hi, int worker, int nworkers) {
;     ...
;         if (r < I_ING) {
;             const int nb = r / (DM / 64), kb = r % (DM / 64), n0 = nb * 32, k0 = kb * 64;
;             if (n0 < NPROJ) transpose_tile(p.w_in + (size_t)l * DM * NPROJ + (size_t)k0 * NPROJ + n0, NPROJ, ng + DM + k0, W + O_WING + (size_t)n0 * DM + k0, DM, scr, lane);
;             else transpose_tile(p.w_gate + (size_t)l * DM * NGATE + (size_t)k0 * NGATE + (n0 - NPROJ), NGATE, ng + DM + k0, W + O_WING + (size_t)n0 * DM + k0, DM, scr, lane);
;             continue; }
	v_mul_f32_e32 v88, v116, v88
	ds_write2_b32 v79, v113, v114 offset0:8 offset1:74
	ds_write2_b32 v79, v115, v88 offset0:140 offset1:206
	s_waitcnt lgkmcnt(0)
	ds_read2_b32 v[94:95], v13 offset0:33 offset1:41
	ds_read2_b32 v[96:97], v13 offset1:8
	ds_read2_b32 v[98:99], v13 offset0:66 offset1:74
	ds_read2_b32 v[100:101], v13 offset0:99 offset1:107
	ds_read2_b32 v[102:103], v13 offset0:132 offset1:140
	ds_read2_b32 v[104:105], v13 offset0:165 offset1:173
	ds_read2_b32 v[106:107], v13 offset0:198 offset1:206
	ds_read2_b32 v[108:109], v13 offset0:231 offset1:239
	s_waitcnt lgkmcnt(6)
	v_cvt_pk_bf16_f32 v88, v96, v94
	s_waitcnt lgkmcnt(4)
	v_cvt_pk_bf16_f32 v89, v98, v100
	s_waitcnt lgkmcnt(2)
	v_cvt_pk_bf16_f32 v90, v102, v104
	s_waitcnt lgkmcnt(0)
	v_cvt_pk_bf16_f32 v91, v106, v108
	global_store_dwordx4 v[110:111], v[88:91], off sc1
	s_nop 1
	v_cvt_pk_bf16_f32 v88, v97, v95
	v_cvt_pk_bf16_f32 v89, v99, v101
	v_cvt_pk_bf16_f32 v90, v103, v105
	v_cvt_pk_bf16_f32 v91, v107, v109
	v_lshl_add_u64 v[94:95], v[92:93], 0, v[196:197]
	global_store_dwordx4 v[94:95], v[88:91], off sc1
	ds_read2_b32 v[94:95], v13 offset0:49 offset1:57
	ds_read2_b32 v[96:97], v13 offset0:16 offset1:24
	ds_read2_b32 v[98:99], v13 offset0:82 offset1:90
	ds_read2_b32 v[100:101], v13 offset0:115 offset1:123
	ds_read2_b32 v[102:103], v13 offset0:148 offset1:156
	ds_read2_b32 v[104:105], v13 offset0:181 offset1:189
	ds_read2_b32 v[106:107], v13 offset0:214 offset1:222
	ds_read2_b32 v[108:109], v13 offset0:247 offset1:255
	v_lshlrev_b32_e32 v196, 1, v72
	s_waitcnt lgkmcnt(6)
	v_cvt_pk_bf16_f32 v88, v96, v94
	s_waitcnt lgkmcnt(4)
	v_cvt_pk_bf16_f32 v89, v98, v100
	s_waitcnt lgkmcnt(2)
	v_cvt_pk_bf16_f32 v90, v102, v104
	s_waitcnt lgkmcnt(0)
	v_cvt_pk_bf16_f32 v91, v106, v108
	v_lshl_add_u64 v[110:111], v[92:93], 0, v[196:197]
	v_lshlrev_b32_e32 v196, 1, v74
	global_store_dwordx4 v[110:111], v[88:91], off sc1
	v_lshl_add_u64 v[92:93], v[92:93], 0, v[196:197]
	s_nop 0
	v_cvt_pk_bf16_f32 v88, v97, v95
	v_cvt_pk_bf16_f32 v89, v99, v101
	v_cvt_pk_bf16_f32 v90, v103, v105
	v_cvt_pk_bf16_f32 v91, v107, v109
	global_store_dwordx4 v[92:93], v[88:91], off sc1
	s_waitcnt lgkmcnt(0)
.LBB0_559:
	s_andn2_b64 vcc, exec, s[0:1]
	s_cbranch_vccnz .LBB0_561
	s_mul_i32 s0, s10, 0x3c00
	s_add_u32 s11, s42, s0
	s_addc_u32 s13, s43, 0
	s_lshl_b64 s[0:1], s[8:9], 2
	s_add_u32 s12, s11, s0
	s_addc_u32 s13, s13, s1
	s_lshl_b64 s[0:1], s[8:9], 11
	s_add_u32 s0, s21, s0
	s_addc_u32 s1, s22, s1
	s_lshl_b32 s8, s10, 1
	s_add_u32 s0, s0, s8
	s_addc_u32 s1, s1, 0
	s_lshl_b32 s8, s10, 2
	v_lshl_add_u64 v[88:89], v[76:77], 0, s[8:9]
	global_load_dword v79, v187, s[12:13]
	global_load_dword v81, v123, s[12:13]
	global_load_dword v83, v189, s[12:13]
	global_load_dword v85, v125, s[12:13]
	global_load_dword v87, v191, s[12:13]
	global_load_dword v90, v127, s[12:13]
	global_load_dword v91, v193, s[12:13]
	global_load_dword v92, v129, s[12:13]
	global_load_dword v93, v195, s[12:13]
	global_load_dword v94, v130, s[12:13]
	global_load_dword v95, v131, s[12:13]
	global_load_dword v96, v132, s[12:13]
	global_load_dword v97, v133, s[12:13]
	global_load_dword v98, v134, s[12:13]
	global_load_dword v99, v135, s[12:13]
	global_load_dword v100, v136, s[12:13]
	global_load_dword v101, v137, s[12:13]
	global_load_dword v102, v138, s[12:13]
	global_load_dword v103, v139, s[12:13]
	global_load_dword v104, v140, s[12:13]
	global_load_dword v105, v141, s[12:13]
	global_load_dword v106, v142, s[12:13]
	global_load_dword v107, v143, s[12:13]
	global_load_dword v108, v144, s[12:13]
	global_load_dword v109, v145, s[12:13]
	global_load_dword v110, v146, s[12:13]
	global_load_dword v111, v147, s[12:13]
	global_load_dword v112, v148, s[12:13]
	global_load_dword v113, v149, s[12:13]
	global_load_dword v114, v150, s[12:13]
	global_load_dword v115, v151, s[12:13]
	global_load_dword v116, v152, s[12:13]
	global_load_dword v117, v[88:89], off
	v_lshlrev_b32_e32 v196, 1, v66
	s_waitcnt vmcnt(0)
	v_mul_f32_e32 v79, v79, v117
	global_load_dword v117, v[88:89], off offset:8
	s_waitcnt vmcnt(0)
	v_mul_f32_e32 v81, v81, v117
	global_load_dword v117, v[88:89], off offset:16
	s_waitcnt vmcnt(0)
	v_mul_f32_e32 v83, v83, v117
	global_load_dword v117, v[88:89], off offset:24
	s_waitcnt vmcnt(0)
	v_mul_f32_e32 v85, v85, v117
	global_load_dword v117, v[88:89], off offset:32
	s_waitcnt vmcnt(0)
	v_mul_f32_e32 v87, v87, v117
	global_load_dword v117, v[88:89], off offset:40
	s_waitcnt vmcnt(0)
	v_mul_f32_e32 v90, v90, v117
	global_load_dword v117, v[88:89], off offset:48
	s_waitcnt vmcnt(0)
	v_mul_f32_e32 v91, v91, v117
	global_load_dword v117, v[88:89], off offset:56
	s_waitcnt vmcnt(0)
	v_mul_f32_e32 v92, v92, v117
	global_load_dword v117, v[88:89], off offset:64
	s_waitcnt vmcnt(0)
	v_mul_f32_e32 v93, v93, v117
	global_load_dword v117, v[88:89], off offset:72
	s_waitcnt vmcnt(0)
	v_mul_f32_e32 v94, v94, v117
	global_load_dword v117, v[88:89], off offset:80
	s_waitcnt vmcnt(0)
	v_mul_f32_e32 v95, v95, v117
	global_load_dword v117, v[88:89], off offset:88
	s_waitcnt vmcnt(0)
	v_mul_f32_e32 v96, v96, v117
	global_load_dword v117, v[88:89], off offset:96
	s_waitcnt vmcnt(0)
; #define LAS __attribute__((address_space(3)))
; __device__ __forceinline__ unsigned pk2(float lo, float hi) { return pg8::cvt_pk_bf16(lo, hi); }
; __device__ __forceinline__ void transpose_tile(const float* src, int srcN, const float* gk, bf16_t* dst, int dstK, LAS float* scr, int lane) {
;     float tv[32];
; #pragma unroll
;     for (int i = 0; i < 32; ++i) tv[i] = src[(size_t)(2 * i + (lane >> 5)) * srcN + (lane & 31)];
;     if (gk) {
; #pragma unroll
;         for (int i = 0; i < 32; ++i) tv[i] *= gk[2 * i + (lane >> 5)];
;     }
; #pragma unroll
;     for (int i = 0; i < 32; ++i) scr[(2 * i + (lane >> 5)) * 33 + (lane & 31)] = tv[i];
;     asm volatile("s_waitcnt lgkmcnt(0)" ::: "memory");
;     const int c = lane & 7;
; #pragma unroll
;     for (int j = 0; j < 4; ++j) {
;         const int n = (lane >> 3) + 8 * j; const LAS float* s = scr + (8 * c) * 33 + n;
;         u32x4 o; o.x = pk2(s[0 * 33], s[1 * 33]); o.y = pk2(s[2 * 33], s[3 * 33]); o.z = pk2(s[4 * 33], s[5 * 33]); o.w = pk2(s[6 * 33], s[7 * 33]);
;         *(u32x4*)(dst + (size_t)n * dstK + 8 * c) = o;
;     }
;     asm volatile("s_waitcnt lgkmcnt(0)" ::: "memory");
; }
; __device__ __forceinline__ void convert_layer(const Params& p, int l, LAS unsigned char* lds, int it_lo, int it_hi, int worker, int nworkers) {
;     ...
;         if (r < I_ING) {
;             const int nb = r / (DM / 64), kb = r % (DM / 64), n0 = nb * 32, k0 = kb * 64;
;             if (n0 < NPROJ) transpose_tile(p.w_in + (size_t)l * DM * NPROJ + (size_t)k0 * NPROJ + n0, NPROJ, ng + DM + k0, W + O_WING + (size_t)n0 * DM + k0, DM, scr, lane);
;             else transpose_tile(p.w_gate + (size_t)l * DM * NGATE + (size_t)k0 * NGATE + (n0 - NPROJ), NGATE, ng + DM + k0, W + O_WING + (size_t)n0 * DM + k0, DM, scr, lane);
;             continue; }
	v_mul_f32_e32 v97, v97, v117
	global_load_dword v117, v[88:89], off offset:104
	s_waitcnt vmcnt(0)
	v_mul_f32_e32 v98, v98, v117
	global_load_dword v117, v[88:89], off offset:112
	s_waitcnt vmcnt(0)
	v_mul_f32_e32 v99, v99, v117
	global_load_dword v117, v[88:89], off offset:120
	s_waitcnt vmcnt(0)
	v_mul_f32_e32 v100, v100, v117
	global_load_dword v117, v[88:89], off offset:128
	s_waitcnt vmcnt(0)
	v_mul_f32_e32 v101, v101, v117
	global_load_dword v117, v[88:89], off offset:136
	s_waitcnt vmcnt(0)
	v_mul_f32_e32 v102, v102, v117
	global_load_dword v117, v[88:89], off offset:144
	s_waitcnt vmcnt(0)
	v_mul_f32_e32 v103, v103, v117
	global_load_dword v117, v[88:89], off offset:152
	s_waitcnt vmcnt(0)
	v_mul_f32_e32 v104, v104, v117
	global_load_dword v117, v[88:89], off offset:160
	s_waitcnt vmcnt(0)
	v_mul_f32_e32 v105, v105, v117
	global_load_dword v117, v[88:89], off offset:168
	s_waitcnt vmcnt(0)
	v_mul_f32_e32 v106, v106, v117
	global_load_dword v117, v[88:89], off offset:176
	s_waitcnt vmcnt(0)
	v_mul_f32_e32 v107, v107, v117
	global_load_dword v117, v[88:89], off offset:184
	s_waitcnt vmcnt(0)
	v_mul_f32_e32 v108, v108, v117
	global_load_dword v117, v[88:89], off offset:192
	s_waitcnt vmcnt(0)
	v_mul_f32_e32 v109, v109, v117
	global_load_dword v117, v[88:89], off offset:200
	s_waitcnt vmcnt(0)
	v_mul_f32_e32 v110, v110, v117
	global_load_dword v117, v[88:89], off offset:208
	s_waitcnt vmcnt(0)
	v_mul_f32_e32 v111, v111, v117
	global_load_dword v117, v[88:89], off offset:216
	s_waitcnt vmcnt(0)
	v_mul_f32_e32 v112, v112, v117
	global_load_dword v117, v[88:89], off offset:224
	s_waitcnt vmcnt(0)
	v_mul_f32_e32 v113, v113, v117
	global_load_dword v117, v[88:89], off offset:232
	s_waitcnt vmcnt(0)
	v_mul_f32_e32 v114, v114, v117
	global_load_dword v117, v[88:89], off offset:240
	s_waitcnt vmcnt(0)
	v_mul_f32_e32 v115, v115, v117
	global_load_dword v88, v[88:89], off offset:248
	v_add_u32_e32 v89, v1, v3
	ds_write2_b32 v89, v79, v81 offset1:66
	ds_write2_b32 v89, v83, v85 offset0:132 offset1:198
	v_add_u32_e32 v79, 0x400, v89
	ds_write2_b32 v79, v87, v90 offset0:8 offset1:74
	v_add_u32_e32 v79, v1, v5
	ds_write2_b32 v79, v91, v92 offset1:66
	ds_write2_b32 v79, v93, v94 offset0:132 offset1:198
	v_add_u32_e32 v79, 0x400, v79
	ds_write2_b32 v79, v95, v96 offset0:8 offset1:74
	v_add_u32_e32 v79, v1, v7
	ds_write2_b32 v79, v97, v98 offset1:66
	ds_write2_b32 v79, v99, v100 offset0:132 offset1:198
	v_add_u32_e32 v79, 0x400, v79
	ds_write2_b32 v79, v101, v102 offset0:8 offset1:74
	v_add_u32_e32 v79, v1, v9
	ds_write2_b32 v79, v103, v104 offset1:66
	ds_write2_b32 v79, v105, v106 offset0:132 offset1:198
	v_add_u32_e32 v79, 0x400, v79
	ds_write2_b32 v79, v107, v108 offset0:8 offset1:74
	v_add_u32_e32 v79, v1, v11
	ds_write2_b32 v79, v109, v110 offset1:66
	ds_write2_b32 v79, v111, v112 offset0:132 offset1:198
	v_add_u32_e32 v79, 0x400, v79
	v_lshl_add_u64 v[92:93], s[0:1], 0, v[196:197]
	v_lshlrev_b32_e32 v196, 1, v68
	v_lshl_add_u64 v[110:111], v[92:93], 0, v[196:197]
	v_lshlrev_b32_e32 v196, 1, v70
	s_waitcnt vmcnt(0)
	v_mul_f32_e32 v88, v116, v88
	ds_write2_b32 v79, v113, v114 offset0:8 offset1:74
	ds_write2_b32 v79, v115, v88 offset0:140 offset1:206
	s_waitcnt lgkmcnt(0)
	ds_read2_b32 v[94:95], v13 offset0:33 offset1:41
	ds_read2_b32 v[96:97], v13 offset1:8
	ds_read2_b32 v[98:99], v13 offset0:66 offset1:74
	ds_read2_b32 v[100:101], v13 offset0:99 offset1:107
	ds_read2_b32 v[102:103], v13 offset0:132 offset1:140
	ds_read2_b32 v[104:105], v13 offset0:165 offset1:173
	ds_read2_b32 v[106:107], v13 offset0:198 offset1:206
	ds_read2_b32 v[108:109], v13 offset0:231 offset1:239
	s_waitcnt lgkmcnt(6)
	v_cvt_pk_bf16_f32 v88, v96, v94
	s_waitcnt lgkmcnt(4)
	v_cvt_pk_bf16_f32 v89, v98, v100
	s_waitcnt lgkmcnt(2)
	v_cvt_pk_bf16_f32 v90, v102, v104
	s_waitcnt lgkmcnt(0)
	v_cvt_pk_bf16_f32 v91, v106, v108
	global_store_dwordx4 v[110:111], v[88:91], off sc1
	s_nop 1
	v_cvt_pk_bf16_f32 v88, v97, v95
	v_cvt_pk_bf16_f32 v89, v99, v101
	v_cvt_pk_bf16_f32 v90, v103, v105
	v_cvt_pk_bf16_f32 v91, v107, v109
	v_lshl_add_u64 v[94:95], v[92:93], 0, v[196:197]
	global_store_dwordx4 v[94:95], v[88:91], off sc1
	ds_read2_b32 v[94:95], v13 offset0:49 offset1:57
	ds_read2_b32 v[96:97], v13 offset0:16 offset1:24
	ds_read2_b32 v[98:99], v13 offset0:82 offset1:90
	ds_read2_b32 v[100:101], v13 offset0:115 offset1:123
	ds_read2_b32 v[102:103], v13 offset0:148 offset1:156
	ds_read2_b32 v[104:105], v13 offset0:181 offset1:189
	ds_read2_b32 v[106:107], v13 offset0:214 offset1:222
	ds_read2_b32 v[108:109], v13 offset0:247 offset1:255
	v_lshlrev_b32_e32 v196, 1, v72
	s_waitcnt lgkmcnt(6)
	v_cvt_pk_bf16_f32 v88, v96, v94
	s_waitcnt lgkmcnt(4)
	v_cvt_pk_bf16_f32 v89, v98, v100
	s_waitcnt lgkmcnt(2)
	v_cvt_pk_bf16_f32 v90, v102, v104
	s_waitcnt lgkmcnt(0)
	v_cvt_pk_bf16_f32 v91, v106, v108
	v_lshl_add_u64 v[110:111], v[92:93], 0, v[196:197]
	v_lshlrev_b32_e32 v196, 1, v74
	global_store_dwordx4 v[110:111], v[88:91], off sc1
	v_lshl_add_u64 v[92:93], v[92:93], 0, v[196:197]
	s_nop 0
	v_cvt_pk_bf16_f32 v88, v97, v95
	v_cvt_pk_bf16_f32 v89, v99, v101
	v_cvt_pk_bf16_f32 v90, v103, v105
	v_cvt_pk_bf16_f32 v91, v107, v109
	global_store_dwordx4 v[92:93], v[88:91], off sc1
	s_waitcnt lgkmcnt(0)

; #define LAS __attribute__((address_space(3)))
; __device__ __forceinline__ void transpose_tile(const float* src, int srcN, const float* gk, bf16_t* dst, int dstK, LAS float* scr, int lane) {
;     float tv[32];
; #pragma unroll
;     for (int i = 0; i < 32; ++i) tv[i] = src[(size_t)(2 * i + (lane >> 5)) * srcN + (lane & 31)];
;     if (gk) {
; #pragma unroll
;         for (int i = 0; i < 32; ++i) tv[i] *= gk[2 * i + (lane >> 5)];
;     }
; #pragma unroll
;     for (int i = 0; i < 32; ++i) scr[(2 * i + (lane >> 5)) * 33 + (lane & 31)] = tv[i];
; __device__ __forceinline__ void convert_layer(const Params& p, int l, LAS unsigned char* lds, int it_lo, int it_hi, int worker, int nworkers) {
;     ...
;             const int f = r / I_GU; r -= f * I_GU; const int nb = r / (DM / 64), kb = r % (DM / 64), n0 = nb * 32, k0 = kb * 64;
;             const int pn = n0 >> 8, w = n0 & 255; const float* src = ((w < 128) ? p.ffn_w_gate : p.ffn_w_up) + (size_t)(l * 2 + f) * DM * DFF;
;             transpose_tile(src + (size_t)k0 * DFF + pn * 128 + (w & 127), DFF, ng + (f ? 2 : 0) * DM + k0, W + (f ? O_WGU1 : O_WGU0) + (size_t)n0 * DM + k0, DM, scr, lane); continue; }
;         r -= 2 * I_GU;
;         if (r < 2 * I_D) {
;             const int f = r / I_D; r -= f * I_D; const int nb = r / (DFF / 64), kb = r % (DFF / 64), n0 = nb * 32, k0 = kb * 64;
;             const float* src = p.ffn_w_down + (size_t)(l * 2 + f) * DFF * DM;
;             transpose_tile(src + (size_t)k0 * DM + n0, DM, nullptr, W + (f ? O_WD1 : O_WD0) + (size_t)n0 * DFF + k0, DFF, scr, lane); continue; }
.LBB0_562:
	s_andn2_b64 vcc, exec, s[0:1]
	s_cbranch_vccnz .LBB0_564
	s_add_i32 s8, s46, 0x1880
	s_cmpk_gt_u32 s8, 0x57f
	s_cselect_b64 s[0:1], -1, 0
	v_cndmask_b32_e64 v79, 0, 1, s[0:1]
	s_and_b64 s[0:1], s[0:1], exec
	s_cselect_b32 s0, 0xfa80, 0
	s_add_i32 s0, s8, s0
	s_sext_i32_i16 s1, s0
	s_mulk_i32 s1, 0xba3
	s_lshr_b32 s10, s1, 31
	s_ashr_i32 s1, s1, 17
	s_add_i32 s49, s1, s10
	s_mul_i32 s1, s49, 44
	s_sub_i32 s0, s0, s1
	v_readfirstlane_b32 s1, v79
	s_sext_i32_i16 s0, s0
	s_or_b32 s1, s23, s1
	v_readlane_b32 s52, v254, 57
	s_lshl_b32 s10, s49, 5
	s_lshl_b32 s0, s0, 6
	s_mul_hi_i32 s11, s1, 0xb00000
	s_mul_i32 s1, s1, 0xb00000
	v_readlane_b32 s56, v254, 61
	v_readlane_b32 s57, v254, 62
	s_add_u32 s50, s56, s1
	s_addc_u32 s11, s57, s11
	s_ashr_i32 s1, s0, 31
	s_lshl_b64 s[12:13], s[0:1], 12
	s_add_u32 s50, s50, s12
	s_addc_u32 s51, s11, s13
	s_ashr_i32 s11, s10, 31
	s_lshl_b64 s[12:13], s[10:11], 2
	s_add_u32 s12, s50, s12
	s_addc_u32 s13, s51, s13
	v_lshlrev_b32_e32 v79, 2, v0
	v_lshlrev_b32_e32 v81, 2, v2
	v_lshlrev_b32_e32 v83, 2, v4
	v_lshlrev_b32_e32 v85, 2, v6
	v_lshlrev_b32_e32 v87, 2, v8
	v_lshlrev_b32_e32 v88, 2, v10
	v_lshlrev_b32_e32 v89, 2, v12
	v_lshlrev_b32_e32 v90, 2, v14
	global_load_dword v79, v79, s[12:13]
	s_nop 0
	global_load_dword v81, v81, s[12:13]
	s_nop 0
	global_load_dword v83, v83, s[12:13]
	s_nop 0
	global_load_dword v85, v85, s[12:13]
	s_nop 0
	global_load_dword v87, v87, s[12:13]
	s_nop 0
	global_load_dword v88, v88, s[12:13]
	s_nop 0
	global_load_dword v89, v89, s[12:13]
	s_nop 0
	global_load_dword v90, v90, s[12:13]
	v_lshlrev_b32_e32 v91, 2, v16
	v_lshlrev_b32_e32 v92, 2, v18
	v_lshlrev_b32_e32 v93, 2, v20
	v_lshlrev_b32_e32 v94, 2, v22
	v_lshlrev_b32_e32 v95, 2, v24
	v_lshlrev_b32_e32 v96, 2, v26
	v_lshlrev_b32_e32 v97, 2, v28
	v_lshlrev_b32_e32 v98, 2, v30
	global_load_dword v91, v91, s[12:13]
	s_nop 0
	global_load_dword v92, v92, s[12:13]
	s_nop 0
	global_load_dword v93, v93, s[12:13]
	s_nop 0
	global_load_dword v94, v94, s[12:13]
	s_nop 0
	global_load_dword v95, v95, s[12:13]
	s_nop 0
	global_load_dword v96, v96, s[12:13]
	s_nop 0
	global_load_dword v97, v97, s[12:13]
	s_nop 0
	global_load_dword v98, v98, s[12:13]
	v_lshlrev_b32_e32 v99, 2, v32
	v_lshlrev_b32_e32 v100, 2, v36
	v_lshlrev_b32_e32 v101, 2, v38
	v_lshlrev_b32_e32 v102, 2, v40
	v_lshlrev_b32_e32 v103, 2, v42
	v_lshlrev_b32_e32 v104, 2, v44
	v_lshlrev_b32_e32 v105, 2, v46
	v_lshlrev_b32_e32 v106, 2, v48
	global_load_dword v99, v99, s[12:13]
	s_nop 0
	global_load_dword v100, v100, s[12:13]
	s_nop 0
	global_load_dword v101, v101, s[12:13]
	s_nop 0
	global_load_dword v102, v102, s[12:13]
	s_nop 0
	global_load_dword v103, v103, s[12:13]
	s_nop 0
	global_load_dword v104, v104, s[12:13]
	s_nop 0
	global_load_dword v105, v105, s[12:13]
	s_nop 0
	global_load_dword v106, v106, s[12:13]
	v_lshlrev_b32_e32 v107, 2, v50
	v_lshlrev_b32_e32 v108, 2, v52
	v_lshlrev_b32_e32 v109, 2, v54
	v_lshlrev_b32_e32 v110, 2, v56
	v_lshlrev_b32_e32 v111, 2, v58
	v_lshlrev_b32_e32 v112, 2, v60
	v_lshlrev_b32_e32 v113, 2, v62
	v_lshlrev_b32_e32 v114, 2, v64
	global_load_dword v107, v107, s[12:13]
	s_nop 0
	global_load_dword v108, v108, s[12:13]
	s_nop 0
	global_load_dword v109, v109, s[12:13]
	s_nop 0
	global_load_dword v110, v110, s[12:13]
	s_nop 0
	global_load_dword v111, v111, s[12:13]
	s_nop 0
	global_load_dword v112, v112, s[12:13]
	s_nop 0
	global_load_dword v113, v113, s[12:13]
	s_nop 0
	global_load_dword v114, v114, s[12:13]
	v_add_u32_e32 v115, v1, v3
	s_cmpk_lt_u32 s8, 0x580
	s_mov_b32 s8, 0x2e00000
	s_cselect_b32 s8, 0xb00000, s8
	s_add_u32 s8, s14, s8
	s_addc_u32 s11, s15, 0
	s_mul_i32 s49, s49, 0x2c000
	s_mul_hi_i32 s10, s10, 0x1600
	s_add_u32 s8, s8, s49
	s_addc_u32 s10, s11, s10
	s_lshl_b64 s[0:1], s[0:1], 1
	s_add_u32 s0, s8, s0
	s_addc_u32 s1, s10, s1
	v_lshlrev_b32_e32 v196, 1, v66
	v_readlane_b32 s53, v254, 58
	v_readlane_b32 s54, v254, 59
	v_readlane_b32 s55, v254, 60
	v_readlane_b32 s58, v254, 63
	v_readlane_b32 s59, v255, 0
	v_readlane_b32 s60, v255, 1
	v_readlane_b32 s61, v255, 2
	v_readlane_b32 s62, v255, 3
	v_readlane_b32 s63, v255, 4
	v_readlane_b32 s64, v255, 5
	v_readlane_b32 s65, v255, 6
	v_readlane_b32 s66, v255, 7
	v_readlane_b32 s67, v255, 8
	s_waitcnt vmcnt(30)
; #define LAS __attribute__((address_space(3)))
; __device__ __forceinline__ unsigned pk2(float lo, float hi) { return pg8::cvt_pk_bf16(lo, hi); }
; __device__ __forceinline__ void transpose_tile(const float* src, int srcN, const float* gk, bf16_t* dst, int dstK, LAS float* scr, int lane) {
;     ...
;     asm volatile("s_waitcnt lgkmcnt(0)" ::: "memory");
;     const int c = lane & 7;
; #pragma unroll
;     for (int j = 0; j < 4; ++j) {
;         const int n = (lane >> 3) + 8 * j; const LAS float* s = scr + (8 * c) * 33 + n;
;         u32x4 o; o.x = pk2(s[0 * 33], s[1 * 33]); o.y = pk2(s[2 * 33], s[3 * 33]); o.z = pk2(s[4 * 33], s[5 * 33]); o.w = pk2(s[6 * 33], s[7 * 33]);
;         *(u32x4*)(dst + (size_t)n * dstK + 8 * c) = o;
;     }
;     asm volatile("s_waitcnt lgkmcnt(0)" ::: "memory");
; }
	ds_write2_b32 v115, v79, v81 offset1:66
	s_waitcnt vmcnt(28)
	ds_write2_b32 v115, v83, v85 offset0:132 offset1:198
	v_add_u32_e32 v79, 0x400, v115
	s_waitcnt vmcnt(26)
	ds_write2_b32 v79, v87, v88 offset0:8 offset1:74
	v_add_u32_e32 v79, v1, v5
	s_waitcnt vmcnt(24)
	ds_write2_b32 v79, v89, v90 offset1:66
	s_waitcnt vmcnt(22)
	ds_write2_b32 v79, v91, v92 offset0:132 offset1:198
	v_add_u32_e32 v79, 0x400, v79
	s_waitcnt vmcnt(20)
	ds_write2_b32 v79, v93, v94 offset0:8 offset1:74
	v_add_u32_e32 v79, v1, v7
	s_waitcnt vmcnt(18)
	ds_write2_b32 v79, v95, v96 offset1:66
	s_waitcnt vmcnt(16)
	ds_write2_b32 v79, v97, v98 offset0:132 offset1:198
	v_add_u32_e32 v79, 0x400, v79
	v_mov_b32_e32 v87, v197
	s_waitcnt vmcnt(14)
	ds_write2_b32 v79, v99, v100 offset0:8 offset1:74
	v_add_u32_e32 v79, v1, v9
	s_waitcnt vmcnt(12)
	ds_write2_b32 v79, v101, v102 offset1:66
	s_waitcnt vmcnt(10)
	ds_write2_b32 v79, v103, v104 offset0:132 offset1:198
	v_add_u32_e32 v79, 0x400, v79
	s_waitcnt vmcnt(8)
	ds_write2_b32 v79, v105, v106 offset0:8 offset1:74
	v_add_u32_e32 v79, v1, v11
	s_waitcnt vmcnt(6)
	ds_write2_b32 v79, v107, v108 offset1:66
	s_waitcnt vmcnt(4)
	ds_write2_b32 v79, v109, v110 offset0:132 offset1:198
	v_add_u32_e32 v79, 0x400, v79
	s_waitcnt vmcnt(2)
	ds_write2_b32 v79, v111, v112 offset0:8 offset1:74
	s_waitcnt vmcnt(0)
	ds_write2_b32 v79, v113, v114 offset0:140 offset1:206
	s_waitcnt lgkmcnt(0)
	ds_read2_b32 v[92:93], v13 offset0:33 offset1:41
	ds_read2_b32 v[94:95], v13 offset1:8
	ds_read2_b32 v[96:97], v13 offset0:66 offset1:74
	ds_read2_b32 v[98:99], v13 offset0:99 offset1:107
	ds_read2_b32 v[100:101], v13 offset0:132 offset1:140
	ds_read2_b32 v[102:103], v13 offset0:165 offset1:173
	ds_read2_b32 v[104:105], v13 offset0:198 offset1:206
	ds_read2_b32 v[106:107], v13 offset0:231 offset1:239
	v_lshl_add_u64 v[108:109], s[0:1], 0, v[196:197]
	s_waitcnt lgkmcnt(6)
	v_cvt_pk_bf16_f32 v88, v94, v92
	s_waitcnt lgkmcnt(4)
	v_cvt_pk_bf16_f32 v89, v96, v98
	s_waitcnt lgkmcnt(2)
	v_cvt_pk_bf16_f32 v90, v100, v102
	s_waitcnt lgkmcnt(0)
	v_cvt_pk_bf16_f32 v91, v104, v106
	v_lshl_add_u64 v[108:109], v[108:109], 0, v[86:87]
	global_store_dwordx4 v[108:109], v[88:91], off sc1
	s_mov_b32 s0, 0xb000
	v_add_co_u32_e32 v92, vcc, s0, v108
	v_cvt_pk_bf16_f32 v88, v95, v93
	v_cvt_pk_bf16_f32 v89, v97, v99
	v_cvt_pk_bf16_f32 v90, v101, v103
	v_cvt_pk_bf16_f32 v91, v105, v107
	ds_read2_b32 v[94:95], v13 offset0:49 offset1:57
	ds_read2_b32 v[96:97], v13 offset0:16 offset1:24
	ds_read2_b32 v[98:99], v13 offset0:82 offset1:90
	ds_read2_b32 v[100:101], v13 offset0:115 offset1:123
	ds_read2_b32 v[102:103], v13 offset0:148 offset1:156
	ds_read2_b32 v[104:105], v13 offset0:181 offset1:189
	ds_read2_b32 v[106:107], v13 offset0:214 offset1:222
	ds_read2_b32 v[110:111], v13 offset0:247 offset1:255
	v_addc_co_u32_e32 v93, vcc, 0, v109, vcc
	s_mov_b32 s0, 0x16000
	global_store_dwordx4 v[92:93], v[88:91], off sc1
	v_add_co_u32_e32 v92, vcc, s0, v108
	s_waitcnt lgkmcnt(6)
	v_cvt_pk_bf16_f32 v88, v96, v94
	s_waitcnt lgkmcnt(4)
	v_cvt_pk_bf16_f32 v89, v98, v100
	s_waitcnt lgkmcnt(2)
	v_cvt_pk_bf16_f32 v90, v102, v104
	s_waitcnt lgkmcnt(0)
	v_cvt_pk_bf16_f32 v91, v106, v110
	v_addc_co_u32_e32 v93, vcc, 0, v109, vcc
	global_store_dwordx4 v[92:93], v[88:91], off sc1
	v_add_co_u32_e32 v92, vcc, 0x21000, v108
	s_nop 0
	v_cvt_pk_bf16_f32 v88, v97, v95
	v_cvt_pk_bf16_f32 v89, v99, v101
	v_cvt_pk_bf16_f32 v90, v103, v105
	v_cvt_pk_bf16_f32 v91, v107, v111
	v_addc_co_u32_e32 v93, vcc, 0, v109, vcc
	global_store_dwordx4 v[92:93], v[88:91], off sc1
	s_waitcnt lgkmcnt(0)

; __device__ __forceinline__ unsigned pk2(float lo, float hi) { return pg8::cvt_pk_bf16(lo, hi); }
;     __device__ __forceinline__ void operator()(const pg8::f32x4 (&acc)[2][2][4][2], const pg8::Unit& u, int wr, int wc, int fr, int fq) const {
;         const int row0 = u.pm * 256 + wr * 64 + fr, col0 = u.pn * 256 + wc * 32 + 8 * fq;
; #pragma unroll
;         for (int ai = 0; ai < 2; ++ai) {
;             f32x4 bv[4][2][2];
; #pragma unroll
;             for (int m = 0; m < 4; ++m)
; #pragma unroll
;                 for (int bj = 0; bj < 2; ++bj) { const size_t off = (size_t)(row0 + ai * 128 + m * 16) * DM + col0 + bj * 128; bv[m][bj][0] = *(const f32x4*)(base + off); bv[m][bj][1] = *(const f32x4*)(base + off + 4); }
; #pragma unroll
;             for (int m = 0; m < 4; ++m) {
;                 const int row = row0 + ai * 128 + m * 16; float ss = 0.f;
; #pragma unroll
;                 for (int bj = 0; bj < 2; ++bj) {
;                     const size_t off = (size_t)row * DM + col0 + bj * 128;
;                     const f32x4 x0 = bv[m][bj][0] + acc[ai][bj][m][0] * alpha, x1 = bv[m][bj][1] + acc[ai][bj][m][1] * alpha;
;                     *(f32x4*)(out + off) = x0; *(f32x4*)(out + off + 4) = x1;
;                     u32x4 w; w.x = pk2(x0[0], x0[1]); w.y = pk2(x0[2], x0[3]); w.z = pk2(x1[0], x1[1]); w.w = pk2(x1[2], x1[3]);
;                     *(u32x4*)(xb + off) = w;
;                     ss += ((x0[0] * x0[0] + x0[1] * x0[1]) + (x0[2] * x0[2] + x0[3] * x0[3])) + ((x1[0] * x1[0] + x1[1] * x1[1]) + (x1[2] * x1[2] + x1[3] * x1[3]));
;                 }
;                 ss += __shfl_xor(ss, 16); ss += __shfl_xor(ss, 32);
;                 if (ssq && fq == 0) ssq[(size_t)row * 16 + u.pn * 4 + wc] = ss;
;             }
;             asm volatile("" ::: "memory");
;         }
;     }
.LBB0_592:
	v_xor_b32_e32 v132, 16, v233
	v_cmp_lt_i32_e32 vcc, v132, v234
	v_lshl_add_u32 v208, s59, 8, v35
	v_lshl_or_b32 v206, s8, 8, v219
	v_cndmask_b32_e32 v132, v233, v132, vcc
	v_lshlrev_b32_e32 v222, 2, v132
	v_xor_b32_e32 v132, 32, v233
	v_cmp_lt_i32_e32 vcc, v132, v234
	v_ashrrev_i32_e32 v207, 31, v206
	v_ashrrev_i32_e32 v209, 31, v208
	v_cndmask_b32_e32 v132, v233, v132, vcc
	v_lshlrev_b32_e32 v221, 2, v132
	v_lshl_add_u64 v[210:211], v[206:207], 2, s[12:13]
	v_lshlrev_b64 v[132:133], 12, v[208:209]
	v_lshl_add_u64 v[132:133], v[210:211], 0, v[132:133]
	global_load_dwordx4 v[224:227], v[132:133], off offset:16
	global_load_dwordx4 v[248:251], v[132:133], off
	global_load_dwordx4 v[180:183], v[132:133], off offset:528
	global_load_dwordx4 v[184:187], v[132:133], off offset:512
	v_or_b32_e32 v216, 16, v208
	v_ashrrev_i32_e32 v217, 31, v216
	v_lshlrev_b64 v[132:133], 12, v[216:217]
	v_or_b32_e32 v214, 32, v208
	v_lshl_add_u64 v[132:133], v[210:211], 0, v[132:133]
	v_ashrrev_i32_e32 v215, 31, v214
	global_load_dwordx4 v[172:175], v[132:133], off offset:16
	global_load_dwordx4 v[176:179], v[132:133], off
	global_load_dwordx4 v[164:167], v[132:133], off offset:528
	global_load_dwordx4 v[168:171], v[132:133], off offset:512
	v_lshlrev_b64 v[132:133], 12, v[214:215]
	v_or_b32_e32 v212, 48, v208
	v_lshl_add_u64 v[132:133], v[210:211], 0, v[132:133]
	v_ashrrev_i32_e32 v213, 31, v212
	global_load_dwordx4 v[156:159], v[132:133], off offset:16
	global_load_dwordx4 v[160:163], v[132:133], off
	global_load_dwordx4 v[140:143], v[132:133], off offset:528
	global_load_dwordx4 v[148:151], v[132:133], off offset:512
	v_lshlrev_b64 v[132:133], 12, v[212:213]
	v_lshl_add_u64 v[136:137], v[210:211], 0, v[132:133]
	global_load_dwordx4 v[144:147], v[136:137], off offset:16
	global_load_dwordx4 v[152:155], v[136:137], off
	global_load_dwordx4 v[132:135], v[136:137], off offset:528
	s_nop 0
	global_load_dwordx4 v[136:139], v[136:137], off offset:512
	v_lshlrev_b64 v[236:237], 10, v[208:209]
	v_lshl_add_u64 v[236:237], v[236:237], 0, v[206:207]
	v_mov_b32_e32 v193, v192
	v_lshl_add_u64 v[238:239], v[236:237], 2, s[24:25]
	v_lshlrev_b64 v[236:237], 1, v[236:237]
	v_lshl_add_u64 v[240:241], s[2:3], 0, v[236:237]
	s_lshl_b32 s22, s8, 2
	v_or_b32_e32 v236, 0x100, v236
	s_ashr_i32 s23, s22, 31
	s_waitcnt vmcnt(0)
	v_pk_fma_f32 v[124:125], v[194:195], v[124:125], v[224:225]
	v_pk_fma_f32 v[130:131], v[192:193], v[130:131], v[250:251]
	v_pk_fma_f32 v[128:129], v[194:195], v[128:129], v[248:249]
	v_pk_fma_f32 v[126:127], v[192:193], v[126:127], v[226:227]
	global_store_dwordx4 v[238:239], v[128:131], off sc1
	global_store_dwordx4 v[238:239], v[124:127], off offset:16 sc1
	v_cvt_pk_bf16_f32 v224, v128, v129
	v_cvt_pk_bf16_f32 v226, v124, v125
	v_mul_f32_e32 v129, v129, v129
	v_mul_f32_e32 v125, v125, v125
	v_fmac_f32_e32 v129, v128, v128
	v_mul_f32_e32 v128, v131, v131
	v_fmac_f32_e32 v125, v124, v124
	v_mul_f32_e32 v124, v127, v127
	v_fmac_f32_e32 v128, v130, v130
	v_fmac_f32_e32 v124, v126, v126
	v_cvt_pk_bf16_f32 v225, v130, v131
	v_cvt_pk_bf16_f32 v227, v126, v127
	v_add_f32_e32 v128, v129, v128
	v_add_f32_e32 v124, v125, v124
	v_pk_fma_f32 v[122:123], v[192:193], v[122:123], v[186:187]
	v_pk_fma_f32 v[120:121], v[194:195], v[120:121], v[184:185]
	v_pk_fma_f32 v[116:117], v[194:195], v[116:117], v[180:181]
	global_store_dwordx4 v[240:241], v[224:227], off sc1
	v_add_f32_e32 v130, v128, v124
	v_pk_fma_f32 v[118:119], v[192:193], v[118:119], v[182:183]
	global_store_dwordx4 v[238:239], v[120:123], off offset:512 sc1
	global_store_dwordx4 v[238:239], v[116:119], off offset:528 sc1
	v_cvt_pk_bf16_f32 v124, v120, v121
	v_cvt_pk_bf16_f32 v126, v116, v117
	v_mul_f32_e32 v121, v121, v121
	v_mul_f32_e32 v117, v117, v117
	v_fmac_f32_e32 v121, v120, v120
	v_mul_f32_e32 v120, v123, v123
	v_fmac_f32_e32 v117, v116, v116
	v_mul_f32_e32 v116, v119, v119
	v_fmac_f32_e32 v120, v122, v122
	v_fmac_f32_e32 v116, v118, v118
	v_add_f32_e32 v120, v121, v120
	v_add_f32_e32 v116, v117, v116
	v_add_f32_e32 v116, v120, v116
	v_add_f32_e32 v116, v130, v116
	ds_bpermute_b32 v117, v222, v116
	v_cvt_pk_bf16_f32 v125, v122, v123
	v_cvt_pk_bf16_f32 v127, v118, v119
	v_lshl_add_u64 v[128:129], s[2:3], 0, v[236:237]
	global_store_dwordx4 v[128:129], v[124:127], off sc1
	s_waitcnt lgkmcnt(0)
	v_add_f32_e32 v116, v116, v117
	ds_bpermute_b32 v117, v221, v116
	s_and_saveexec_b64 s[40:41], s[18:19]
	s_cbranch_execz .LBB0_594
	s_waitcnt lgkmcnt(0)
	v_add_f32_e32 v118, v116, v117
	v_lshlrev_b64 v[116:117], 6, v[208:209]
	v_lshl_add_u64 v[116:117], s[14:15], 0, v[116:117]
	v_lshl_add_u64 v[116:117], s[22:23], 2, v[116:117]
	s_lshl_b32 s8, s54, 2
	v_lshl_add_u64 v[116:117], v[116:117], 0, s[8:9]
	global_store_dword v[116:117], v118, off
; __device__ __forceinline__ unsigned pk2(float lo, float hi) { return pg8::cvt_pk_bf16(lo, hi); }
;     __device__ __forceinline__ void operator()(const pg8::f32x4 (&acc)[2][2][4][2], const pg8::Unit& u, int wr, int wc, int fr, int fq) const {
;         const int row0 = u.pm * 256 + wr * 64 + fr, col0 = u.pn * 256 + wc * 32 + 8 * fq;
; #pragma unroll
;         for (int ai = 0; ai < 2; ++ai) {
;             f32x4 bv[4][2][2];
; #pragma unroll
;             for (int m = 0; m < 4; ++m)
; #pragma unroll
;                 for (int bj = 0; bj < 2; ++bj) { const size_t off = (size_t)(row0 + ai * 128 + m * 16) * DM + col0 + bj * 128; bv[m][bj][0] = *(const f32x4*)(base + off); bv[m][bj][1] = *(const f32x4*)(base + off + 4); }
; #pragma unroll
;             for (int m = 0; m < 4; ++m) {
;                 const int row = row0 + ai * 128 + m * 16; float ss = 0.f;
; #pragma unroll
;                 for (int bj = 0; bj < 2; ++bj) {
;                     const size_t off = (size_t)row * DM + col0 + bj * 128;
;                     const f32x4 x0 = bv[m][bj][0] + acc[ai][bj][m][0] * alpha, x1 = bv[m][bj][1] + acc[ai][bj][m][1] * alpha;
;                     *(f32x4*)(out + off) = x0; *(f32x4*)(out + off + 4) = x1;
;                     u32x4 w; w.x = pk2(x0[0], x0[1]); w.y = pk2(x0[2], x0[3]); w.z = pk2(x1[0], x1[1]); w.w = pk2(x1[2], x1[3]);
;                     *(u32x4*)(xb + off) = w;
;                     ss += ((x0[0] * x0[0] + x0[1] * x0[1]) + (x0[2] * x0[2] + x0[3] * x0[3])) + ((x1[0] * x1[0] + x1[1] * x1[1]) + (x1[2] * x1[2] + x1[3] * x1[3]));
;                 }
;                 ss += __shfl_xor(ss, 16); ss += __shfl_xor(ss, 32);
;                 if (ssq && fq == 0) ssq[(size_t)row * 16 + u.pn * 4 + wc] = ss;
;             }
;             asm volatile("" ::: "memory");
;         }
;     }
.LBB0_594:
	s_or_b64 exec, exec, s[40:41]
	s_waitcnt lgkmcnt(0)
	v_lshlrev_b64 v[116:117], 10, v[216:217]
	v_lshl_add_u64 v[120:121], v[116:117], 0, v[206:207]
	v_pk_fma_f32 v[114:115], v[192:193], v[114:115], v[178:179]
	v_pk_fma_f32 v[112:113], v[194:195], v[112:113], v[176:177]
	v_pk_fma_f32 v[108:109], v[194:195], v[108:109], v[172:173]
	v_lshl_add_u64 v[122:123], v[120:121], 2, s[24:25]
	v_pk_fma_f32 v[110:111], v[192:193], v[110:111], v[174:175]
	global_store_dwordx4 v[122:123], v[112:115], off sc1
	global_store_dwordx4 v[122:123], v[108:111], off offset:16 sc1
	v_cvt_pk_bf16_f32 v118, v108, v109
	v_pk_fma_f32 v[106:107], v[192:193], v[106:107], v[170:171]
	v_mul_f32_e32 v109, v109, v109
	v_fmac_f32_e32 v109, v108, v108
	v_mul_f32_e32 v108, v111, v111
	v_fmac_f32_e32 v108, v110, v110
	v_pk_fma_f32 v[104:105], v[194:195], v[104:105], v[168:169]
	v_cvt_pk_bf16_f32 v119, v110, v111
	v_add_f32_e32 v108, v109, v108
	v_mul_f32_e32 v109, v105, v105
	v_mul_f32_e32 v110, v107, v107
	v_cvt_pk_bf16_f32 v116, v112, v113
	v_mul_f32_e32 v113, v113, v113
	v_pk_fma_f32 v[102:103], v[192:193], v[102:103], v[166:167]
	v_pk_fma_f32 v[100:101], v[194:195], v[100:101], v[164:165]
	v_fmac_f32_e32 v109, v104, v104
	v_fmac_f32_e32 v110, v106, v106
	v_fmac_f32_e32 v113, v112, v112
	v_mul_f32_e32 v112, v115, v115
	v_add_f32_e32 v109, v109, v110
	v_mul_f32_e32 v110, v101, v101
	v_mul_f32_e32 v111, v103, v103
	v_fmac_f32_e32 v112, v114, v114
	v_fmac_f32_e32 v110, v100, v100
	v_fmac_f32_e32 v111, v102, v102
	v_add_f32_e32 v112, v113, v112
	v_add_f32_e32 v110, v110, v111
	v_add_f32_e32 v108, v112, v108
	v_add_f32_e32 v109, v109, v110
	v_add_f32_e32 v108, v108, v109
	ds_bpermute_b32 v109, v222, v108
	v_lshlrev_b64 v[120:121], 1, v[120:121]
	v_cvt_pk_bf16_f32 v117, v114, v115
	v_lshl_add_u64 v[124:125], s[2:3], 0, v[120:121]
	global_store_dwordx4 v[124:125], v[116:119], off sc1
	global_store_dwordx4 v[122:123], v[104:107], off offset:512 sc1
	global_store_dwordx4 v[122:123], v[100:103], off offset:528 sc1
	v_or_b32_e32 v120, 0x100, v120
	v_cvt_pk_bf16_f32 v104, v104, v105
	v_cvt_pk_bf16_f32 v105, v106, v107
	v_cvt_pk_bf16_f32 v106, v100, v101
	s_waitcnt lgkmcnt(0)
	v_add_f32_e32 v100, v108, v109
	ds_bpermute_b32 v101, v221, v100
	v_cvt_pk_bf16_f32 v107, v102, v103
	v_lshl_add_u64 v[102:103], s[2:3], 0, v[120:121]
	global_store_dwordx4 v[102:103], v[104:107], off sc1
	s_and_saveexec_b64 s[40:41], s[18:19]
	s_cbranch_execz .LBB0_596
	s_waitcnt lgkmcnt(0)
	v_add_f32_e32 v102, v100, v101
	v_lshlrev_b64 v[100:101], 6, v[216:217]
	v_lshl_add_u64 v[100:101], s[14:15], 0, v[100:101]
	v_lshl_add_u64 v[100:101], s[22:23], 2, v[100:101]
	s_lshl_b32 s8, s54, 2
	v_lshl_add_u64 v[100:101], v[100:101], 0, s[8:9]
	global_store_dword v[100:101], v102, off
.LBB0_596:
	s_or_b64 exec, exec, s[40:41]
	s_waitcnt lgkmcnt(0)
	v_lshlrev_b64 v[100:101], 10, v[214:215]
	v_lshl_add_u64 v[104:105], v[100:101], 0, v[206:207]
	v_mov_b32_e32 v193, v192
	v_pk_fma_f32 v[98:99], v[192:193], v[98:99], v[162:163]
	v_pk_fma_f32 v[96:97], v[194:195], v[96:97], v[160:161]
	v_pk_fma_f32 v[92:93], v[194:195], v[92:93], v[156:157]
	v_lshl_add_u64 v[106:107], v[104:105], 2, s[24:25]
	v_pk_fma_f32 v[94:95], v[192:193], v[94:95], v[158:159]
	global_store_dwordx4 v[106:107], v[96:99], off sc1
	global_store_dwordx4 v[106:107], v[92:95], off offset:16 sc1
	v_cvt_pk_bf16_f32 v102, v92, v93
	v_pk_fma_f32 v[90:91], v[192:193], v[90:91], v[150:151]
	v_mul_f32_e32 v93, v93, v93
	v_fmac_f32_e32 v93, v92, v92
	v_mul_f32_e32 v92, v95, v95
	v_fmac_f32_e32 v92, v94, v94
	v_pk_fma_f32 v[88:89], v[194:195], v[88:89], v[148:149]
	v_cvt_pk_bf16_f32 v103, v94, v95
	v_add_f32_e32 v92, v93, v92
	v_mul_f32_e32 v93, v89, v89
	v_mul_f32_e32 v94, v91, v91
	v_cvt_pk_bf16_f32 v100, v96, v97
	v_mul_f32_e32 v97, v97, v97
	v_pk_fma_f32 v[86:87], v[192:193], v[86:87], v[142:143]
	v_pk_fma_f32 v[84:85], v[194:195], v[84:85], v[140:141]
	v_fmac_f32_e32 v93, v88, v88
	v_fmac_f32_e32 v94, v90, v90
	v_fmac_f32_e32 v97, v96, v96
	v_mul_f32_e32 v96, v99, v99
	v_add_f32_e32 v93, v93, v94
	v_mul_f32_e32 v94, v85, v85
	v_mul_f32_e32 v95, v87, v87
	v_fmac_f32_e32 v96, v98, v98
	v_fmac_f32_e32 v94, v84, v84
	v_fmac_f32_e32 v95, v86, v86
	v_add_f32_e32 v96, v97, v96
	v_add_f32_e32 v94, v94, v95
	v_add_f32_e32 v92, v96, v92
	v_add_f32_e32 v93, v93, v94
	v_add_f32_e32 v92, v92, v93
	ds_bpermute_b32 v93, v222, v92
	v_lshlrev_b64 v[104:105], 1, v[104:105]
	v_cvt_pk_bf16_f32 v101, v98, v99
	v_lshl_add_u64 v[108:109], s[2:3], 0, v[104:105]
	global_store_dwordx4 v[108:109], v[100:103], off sc1
	global_store_dwordx4 v[106:107], v[88:91], off offset:512 sc1
	global_store_dwordx4 v[106:107], v[84:87], off offset:528 sc1
	v_or_b32_e32 v104, 0x100, v104
	v_cvt_pk_bf16_f32 v88, v88, v89
	v_cvt_pk_bf16_f32 v89, v90, v91
	v_cvt_pk_bf16_f32 v90, v84, v85
	s_waitcnt lgkmcnt(0)
	v_add_f32_e32 v84, v92, v93
	ds_bpermute_b32 v85, v221, v84
	v_cvt_pk_bf16_f32 v91, v86, v87
	v_lshl_add_u64 v[86:87], s[2:3], 0, v[104:105]
	global_store_dwordx4 v[86:87], v[88:91], off sc1
	s_and_saveexec_b64 s[40:41], s[18:19]
	s_cbranch_execz .LBB0_598
	s_waitcnt lgkmcnt(0)
	v_add_f32_e32 v86, v84, v85
	v_lshlrev_b64 v[84:85], 6, v[214:215]
	v_lshl_add_u64 v[84:85], s[14:15], 0, v[84:85]
	v_lshl_add_u64 v[84:85], s[22:23], 2, v[84:85]
	s_lshl_b32 s8, s54, 2
	v_lshl_add_u64 v[84:85], v[84:85], 0, s[8:9]
	global_store_dword v[84:85], v86, off
; __device__ __forceinline__ unsigned pk2(float lo, float hi) { return pg8::cvt_pk_bf16(lo, hi); }
;     __device__ __forceinline__ void operator()(const pg8::f32x4 (&acc)[2][2][4][2], const pg8::Unit& u, int wr, int wc, int fr, int fq) const {
;         const int row0 = u.pm * 256 + wr * 64 + fr, col0 = u.pn * 256 + wc * 32 + 8 * fq;
; #pragma unroll
;         for (int ai = 0; ai < 2; ++ai) {
;             f32x4 bv[4][2][2];
; #pragma unroll
;             for (int m = 0; m < 4; ++m)
; #pragma unroll
;                 for (int bj = 0; bj < 2; ++bj) { const size_t off = (size_t)(row0 + ai * 128 + m * 16) * DM + col0 + bj * 128; bv[m][bj][0] = *(const f32x4*)(base + off); bv[m][bj][1] = *(const f32x4*)(base + off + 4); }
; #pragma unroll
;             for (int m = 0; m < 4; ++m) {
;                 const int row = row0 + ai * 128 + m * 16; float ss = 0.f;
; #pragma unroll
;                 for (int bj = 0; bj < 2; ++bj) {
;                     const size_t off = (size_t)row * DM + col0 + bj * 128;
;                     const f32x4 x0 = bv[m][bj][0] + acc[ai][bj][m][0] * alpha, x1 = bv[m][bj][1] + acc[ai][bj][m][1] * alpha;
;                     *(f32x4*)(out + off) = x0; *(f32x4*)(out + off + 4) = x1;
;                     u32x4 w; w.x = pk2(x0[0], x0[1]); w.y = pk2(x0[2], x0[3]); w.z = pk2(x1[0], x1[1]); w.w = pk2(x1[2], x1[3]);
;                     *(u32x4*)(xb + off) = w;
;                     ss += ((x0[0] * x0[0] + x0[1] * x0[1]) + (x0[2] * x0[2] + x0[3] * x0[3])) + ((x1[0] * x1[0] + x1[1] * x1[1]) + (x1[2] * x1[2] + x1[3] * x1[3]));
;                 }
;                 ss += __shfl_xor(ss, 16); ss += __shfl_xor(ss, 32);
;                 if (ssq && fq == 0) ssq[(size_t)row * 16 + u.pn * 4 + wc] = ss;
;             }
;             asm volatile("" ::: "memory");
;         }
;     }
.LBB0_598:
	s_or_b64 exec, exec, s[40:41]
	s_waitcnt lgkmcnt(0)
	v_lshlrev_b64 v[84:85], 10, v[212:213]
	v_lshl_add_u64 v[88:89], v[84:85], 0, v[206:207]
	v_pk_fma_f32 v[82:83], v[192:193], v[82:83], v[154:155]
	v_pk_fma_f32 v[80:81], v[194:195], v[80:81], v[152:153]
	v_pk_fma_f32 v[76:77], v[194:195], v[76:77], v[144:145]
	v_lshl_add_u64 v[90:91], v[88:89], 2, s[24:25]
	v_pk_fma_f32 v[78:79], v[192:193], v[78:79], v[146:147]
	global_store_dwordx4 v[90:91], v[80:83], off sc1
	global_store_dwordx4 v[90:91], v[76:79], off offset:16 sc1
	v_cvt_pk_bf16_f32 v86, v76, v77
	v_pk_fma_f32 v[74:75], v[192:193], v[74:75], v[138:139]
	v_mul_f32_e32 v77, v77, v77
	v_fmac_f32_e32 v77, v76, v76
	v_mul_f32_e32 v76, v79, v79
	v_fmac_f32_e32 v76, v78, v78
	v_pk_fma_f32 v[72:73], v[194:195], v[72:73], v[136:137]
	v_cvt_pk_bf16_f32 v87, v78, v79
	v_add_f32_e32 v76, v77, v76
	v_mul_f32_e32 v77, v73, v73
	v_mul_f32_e32 v78, v75, v75
	v_cvt_pk_bf16_f32 v84, v80, v81
	v_mul_f32_e32 v81, v81, v81
	v_pk_fma_f32 v[70:71], v[192:193], v[70:71], v[134:135]
	v_pk_fma_f32 v[68:69], v[194:195], v[68:69], v[132:133]
	v_fmac_f32_e32 v77, v72, v72
	v_fmac_f32_e32 v78, v74, v74
	v_fmac_f32_e32 v81, v80, v80
	v_mul_f32_e32 v80, v83, v83
	v_add_f32_e32 v77, v77, v78
	v_mul_f32_e32 v78, v69, v69
	v_mul_f32_e32 v79, v71, v71
	v_fmac_f32_e32 v80, v82, v82
	v_fmac_f32_e32 v78, v68, v68
	v_fmac_f32_e32 v79, v70, v70
	v_add_f32_e32 v80, v81, v80
	v_add_f32_e32 v78, v78, v79
	v_add_f32_e32 v76, v80, v76
	v_add_f32_e32 v77, v77, v78
	v_add_f32_e32 v76, v76, v77
	ds_bpermute_b32 v77, v222, v76
	v_lshlrev_b64 v[88:89], 1, v[88:89]
	v_cvt_pk_bf16_f32 v85, v82, v83
	v_lshl_add_u64 v[92:93], s[2:3], 0, v[88:89]
	global_store_dwordx4 v[92:93], v[84:87], off sc1
	global_store_dwordx4 v[90:91], v[72:75], off offset:512 sc1
	global_store_dwordx4 v[90:91], v[68:71], off offset:528 sc1
	v_or_b32_e32 v88, 0x100, v88
	v_cvt_pk_bf16_f32 v72, v72, v73
	v_cvt_pk_bf16_f32 v73, v74, v75
	v_cvt_pk_bf16_f32 v74, v68, v69
	s_waitcnt lgkmcnt(0)
	v_add_f32_e32 v68, v76, v77
	ds_bpermute_b32 v69, v221, v68
	v_cvt_pk_bf16_f32 v75, v70, v71
	v_lshl_add_u64 v[70:71], s[2:3], 0, v[88:89]
	global_store_dwordx4 v[70:71], v[72:75], off sc1
	s_and_saveexec_b64 s[40:41], s[18:19]
	s_cbranch_execz .LBB0_600
	s_waitcnt lgkmcnt(0)
	v_add_f32_e32 v70, v68, v69
	v_lshlrev_b64 v[68:69], 6, v[212:213]
	v_lshl_add_u64 v[68:69], s[14:15], 0, v[68:69]
	v_lshl_add_u64 v[68:69], s[22:23], 2, v[68:69]
	s_lshl_b32 s8, s54, 2
	v_lshl_add_u64 v[68:69], v[68:69], 0, s[8:9]
	global_store_dword v[68:69], v70, off
.LBB0_600:
	s_or_b64 exec, exec, s[40:41]
	v_add_u32_e32 v130, 0x80, v208
	v_ashrrev_i32_e32 v131, 31, v130
	s_waitcnt lgkmcnt(0)
	v_lshlrev_b64 v[68:69], 12, v[130:131]
	v_lshl_add_u64 v[68:69], v[210:211], 0, v[68:69]
	global_load_dwordx4 v[132:135], v[68:69], off offset:16
	global_load_dwordx4 v[136:139], v[68:69], off
	global_load_dwordx4 v[116:119], v[68:69], off offset:528
	global_load_dwordx4 v[120:123], v[68:69], off offset:512
	v_add_u32_e32 v128, 0x90, v208
	v_ashrrev_i32_e32 v129, 31, v128
	v_lshlrev_b64 v[68:69], 12, v[128:129]
	v_add_u32_e32 v126, 0xa0, v208
	v_lshl_add_u64 v[68:69], v[210:211], 0, v[68:69]
	v_ashrrev_i32_e32 v127, 31, v126
	global_load_dwordx4 v[108:111], v[68:69], off offset:16
	global_load_dwordx4 v[112:115], v[68:69], off
	global_load_dwordx4 v[100:103], v[68:69], off offset:528
	global_load_dwordx4 v[104:107], v[68:69], off offset:512
	v_lshlrev_b64 v[68:69], 12, v[126:127]
	v_add_u32_e32 v124, 0xb0, v208
	v_lshl_add_u64 v[68:69], v[210:211], 0, v[68:69]
	v_ashrrev_i32_e32 v125, 31, v124
	global_load_dwordx4 v[92:95], v[68:69], off offset:16
	global_load_dwordx4 v[96:99], v[68:69], off
	global_load_dwordx4 v[76:79], v[68:69], off offset:528
	global_load_dwordx4 v[84:87], v[68:69], off offset:512
	v_lshlrev_b64 v[68:69], 12, v[124:125]
	v_lshl_add_u64 v[72:73], v[210:211], 0, v[68:69]
	global_load_dwordx4 v[80:83], v[72:73], off offset:16
	global_load_dwordx4 v[88:91], v[72:73], off
	global_load_dwordx4 v[68:71], v[72:73], off offset:528
	s_nop 0
	global_load_dwordx4 v[72:75], v[72:73], off offset:512
	v_lshlrev_b64 v[140:141], 10, v[130:131]
	v_lshl_add_u64 v[140:141], v[140:141], 0, v[206:207]
	v_mov_b32_e32 v193, v192
	s_waitcnt vmcnt(15)
	v_pk_fma_f32 v[60:61], v[194:195], v[60:61], v[132:133]
	s_waitcnt vmcnt(14)
	v_pk_fma_f32 v[66:67], v[192:193], v[66:67], v[138:139]
	v_pk_fma_f32 v[64:65], v[194:195], v[64:65], v[136:137]
	v_lshl_add_u64 v[136:137], v[140:141], 2, s[24:25]
	v_pk_fma_f32 v[62:63], v[192:193], v[62:63], v[134:135]
	global_store_dwordx4 v[136:137], v[64:67], off sc1
	global_store_dwordx4 v[136:137], v[60:63], off offset:16 sc1
	v_cvt_pk_bf16_f32 v132, v64, v65
	v_cvt_pk_bf16_f32 v134, v60, v61
	v_mul_f32_e32 v65, v65, v65
	v_mul_f32_e32 v61, v61, v61
	v_fmac_f32_e32 v65, v64, v64
	v_mul_f32_e32 v64, v67, v67
	v_fmac_f32_e32 v61, v60, v60
	v_mul_f32_e32 v60, v63, v63
	v_lshlrev_b64 v[138:139], 1, v[140:141]
	v_fmac_f32_e32 v64, v66, v66
	v_fmac_f32_e32 v60, v62, v62
	v_cvt_pk_bf16_f32 v133, v66, v67
	v_cvt_pk_bf16_f32 v135, v62, v63
	v_lshl_add_u64 v[140:141], s[2:3], 0, v[138:139]
	v_add_f32_e32 v64, v65, v64
	v_add_f32_e32 v60, v61, v60
	s_waitcnt vmcnt(14)
	v_pk_fma_f32 v[58:59], v[192:193], v[58:59], v[122:123]
	v_pk_fma_f32 v[56:57], v[194:195], v[56:57], v[120:121]
	v_pk_fma_f32 v[52:53], v[194:195], v[52:53], v[116:117]
	global_store_dwordx4 v[140:141], v[132:135], off sc1
	v_add_f32_e32 v66, v64, v60
	v_pk_fma_f32 v[54:55], v[192:193], v[54:55], v[118:119]
	global_store_dwordx4 v[136:137], v[56:59], off offset:512 sc1
	global_store_dwordx4 v[136:137], v[52:55], off offset:528 sc1
	v_cvt_pk_bf16_f32 v60, v56, v57
	v_cvt_pk_bf16_f32 v62, v52, v53
	v_mul_f32_e32 v57, v57, v57
	v_mul_f32_e32 v53, v53, v53
	v_fmac_f32_e32 v57, v56, v56
	v_mul_f32_e32 v56, v59, v59
	v_fmac_f32_e32 v53, v52, v52
	v_mul_f32_e32 v52, v55, v55
	v_fmac_f32_e32 v56, v58, v58
	v_fmac_f32_e32 v52, v54, v54
	v_add_f32_e32 v56, v57, v56
	v_add_f32_e32 v52, v53, v52
	v_add_f32_e32 v52, v56, v52
	v_add_f32_e32 v52, v66, v52
	ds_bpermute_b32 v53, v222, v52
	v_or_b32_e32 v138, 0x100, v138
	v_cvt_pk_bf16_f32 v61, v58, v59
	v_cvt_pk_bf16_f32 v63, v54, v55
	v_lshl_add_u64 v[64:65], s[2:3], 0, v[138:139]
	s_waitcnt lgkmcnt(0)
	v_add_f32_e32 v52, v52, v53
	ds_bpermute_b32 v53, v221, v52
	global_store_dwordx4 v[64:65], v[60:63], off sc1
	s_and_saveexec_b64 s[40:41], s[18:19]
	s_cbranch_execz .LBB0_602
	s_waitcnt lgkmcnt(0)
	v_add_f32_e32 v54, v52, v53
	v_lshlrev_b64 v[52:53], 6, v[130:131]
	v_lshl_add_u64 v[52:53], s[14:15], 0, v[52:53]
	v_lshl_add_u64 v[52:53], s[22:23], 2, v[52:53]
	s_lshl_b32 s8, s54, 2
	v_lshl_add_u64 v[52:53], v[52:53], 0, s[8:9]
	global_store_dword v[52:53], v54, off
; __device__ __forceinline__ unsigned pk2(float lo, float hi) { return pg8::cvt_pk_bf16(lo, hi); }
;     __device__ __forceinline__ void operator()(const pg8::f32x4 (&acc)[2][2][4][2], const pg8::Unit& u, int wr, int wc, int fr, int fq) const {
;         const int row0 = u.pm * 256 + wr * 64 + fr, col0 = u.pn * 256 + wc * 32 + 8 * fq;
; #pragma unroll
;         for (int ai = 0; ai < 2; ++ai) {
;             f32x4 bv[4][2][2];
; #pragma unroll
;             for (int m = 0; m < 4; ++m)
; #pragma unroll
;                 for (int bj = 0; bj < 2; ++bj) { const size_t off = (size_t)(row0 + ai * 128 + m * 16) * DM + col0 + bj * 128; bv[m][bj][0] = *(const f32x4*)(base + off); bv[m][bj][1] = *(const f32x4*)(base + off + 4); }
; #pragma unroll
;             for (int m = 0; m < 4; ++m) {
;                 const int row = row0 + ai * 128 + m * 16; float ss = 0.f;
; #pragma unroll
;                 for (int bj = 0; bj < 2; ++bj) {
;                     const size_t off = (size_t)row * DM + col0 + bj * 128;
;                     const f32x4 x0 = bv[m][bj][0] + acc[ai][bj][m][0] * alpha, x1 = bv[m][bj][1] + acc[ai][bj][m][1] * alpha;
;                     *(f32x4*)(out + off) = x0; *(f32x4*)(out + off + 4) = x1;
;                     u32x4 w; w.x = pk2(x0[0], x0[1]); w.y = pk2(x0[2], x0[3]); w.z = pk2(x1[0], x1[1]); w.w = pk2(x1[2], x1[3]);
;                     *(u32x4*)(xb + off) = w;
;                     ss += ((x0[0] * x0[0] + x0[1] * x0[1]) + (x0[2] * x0[2] + x0[3] * x0[3])) + ((x1[0] * x1[0] + x1[1] * x1[1]) + (x1[2] * x1[2] + x1[3] * x1[3]));
;                 }
;                 ss += __shfl_xor(ss, 16); ss += __shfl_xor(ss, 32);
;                 if (ssq && fq == 0) ssq[(size_t)row * 16 + u.pn * 4 + wc] = ss;
;             }
;             asm volatile("" ::: "memory");
;         }
;     }
.LBB0_602:
	s_or_b64 exec, exec, s[40:41]
	s_waitcnt lgkmcnt(0)
	v_lshlrev_b64 v[52:53], 10, v[128:129]
	v_lshl_add_u64 v[56:57], v[52:53], 0, v[206:207]
	s_waitcnt vmcnt(16)
	v_pk_fma_f32 v[50:51], v[192:193], v[50:51], v[114:115]
	v_pk_fma_f32 v[48:49], v[194:195], v[48:49], v[112:113]
	v_pk_fma_f32 v[44:45], v[194:195], v[44:45], v[108:109]
	v_lshl_add_u64 v[58:59], v[56:57], 2, s[24:25]
	v_pk_fma_f32 v[46:47], v[192:193], v[46:47], v[110:111]
	global_store_dwordx4 v[58:59], v[48:51], off sc1
	global_store_dwordx4 v[58:59], v[44:47], off offset:16 sc1
	v_cvt_pk_bf16_f32 v54, v44, v45
	s_waitcnt vmcnt(16)
	v_pk_fma_f32 v[42:43], v[192:193], v[42:43], v[106:107]
	v_mul_f32_e32 v45, v45, v45
	v_fmac_f32_e32 v45, v44, v44
	v_mul_f32_e32 v44, v47, v47
	v_fmac_f32_e32 v44, v46, v46
	v_pk_fma_f32 v[40:41], v[194:195], v[40:41], v[104:105]
	v_cvt_pk_bf16_f32 v55, v46, v47
	v_add_f32_e32 v44, v45, v44
	v_mul_f32_e32 v45, v41, v41
	v_mul_f32_e32 v46, v43, v43
	v_cvt_pk_bf16_f32 v52, v48, v49
	v_mul_f32_e32 v49, v49, v49
	v_pk_fma_f32 v[38:39], v[192:193], v[38:39], v[102:103]
	v_pk_fma_f32 v[36:37], v[194:195], v[36:37], v[100:101]
	v_fmac_f32_e32 v45, v40, v40
	v_fmac_f32_e32 v46, v42, v42
	v_fmac_f32_e32 v49, v48, v48
	v_mul_f32_e32 v48, v51, v51
	v_add_f32_e32 v45, v45, v46
	v_mul_f32_e32 v46, v37, v37
	v_mul_f32_e32 v47, v39, v39
	v_fmac_f32_e32 v48, v50, v50
	v_fmac_f32_e32 v46, v36, v36
	v_fmac_f32_e32 v47, v38, v38
	v_add_f32_e32 v48, v49, v48
	v_add_f32_e32 v46, v46, v47
	v_add_f32_e32 v44, v48, v44
	v_add_f32_e32 v45, v45, v46
	v_add_f32_e32 v44, v44, v45
	ds_bpermute_b32 v45, v222, v44
	v_lshlrev_b64 v[56:57], 1, v[56:57]
	v_cvt_pk_bf16_f32 v53, v50, v51
	v_lshl_add_u64 v[60:61], s[2:3], 0, v[56:57]
	global_store_dwordx4 v[60:61], v[52:55], off sc1
	global_store_dwordx4 v[58:59], v[40:43], off offset:512 sc1
	global_store_dwordx4 v[58:59], v[36:39], off offset:528 sc1
	v_or_b32_e32 v56, 0x100, v56
	v_cvt_pk_bf16_f32 v40, v40, v41
	v_cvt_pk_bf16_f32 v41, v42, v43
	v_cvt_pk_bf16_f32 v42, v36, v37
	s_waitcnt lgkmcnt(0)
	v_add_f32_e32 v36, v44, v45
	ds_bpermute_b32 v37, v221, v36
	v_cvt_pk_bf16_f32 v43, v38, v39
	v_lshl_add_u64 v[38:39], s[2:3], 0, v[56:57]
	global_store_dwordx4 v[38:39], v[40:43], off sc1
	s_and_saveexec_b64 s[40:41], s[18:19]
	s_cbranch_execz .LBB0_604
	s_waitcnt lgkmcnt(0)
	v_add_f32_e32 v38, v36, v37
	v_lshlrev_b64 v[36:37], 6, v[128:129]
	v_lshl_add_u64 v[36:37], s[14:15], 0, v[36:37]
	v_lshl_add_u64 v[36:37], s[22:23], 2, v[36:37]
	s_lshl_b32 s8, s54, 2
	v_lshl_add_u64 v[36:37], v[36:37], 0, s[8:9]
	global_store_dword v[36:37], v38, off
; __device__ __forceinline__ unsigned pk2(float lo, float hi) { return pg8::cvt_pk_bf16(lo, hi); }
;     __device__ __forceinline__ void operator()(const pg8::f32x4 (&acc)[2][2][4][2], const pg8::Unit& u, int wr, int wc, int fr, int fq) const {
;         const int row0 = u.pm * 256 + wr * 64 + fr, col0 = u.pn * 256 + wc * 32 + 8 * fq;
; #pragma unroll
;         for (int ai = 0; ai < 2; ++ai) {
;             f32x4 bv[4][2][2];
; #pragma unroll
;             for (int m = 0; m < 4; ++m)
; #pragma unroll
;                 for (int bj = 0; bj < 2; ++bj) { const size_t off = (size_t)(row0 + ai * 128 + m * 16) * DM + col0 + bj * 128; bv[m][bj][0] = *(const f32x4*)(base + off); bv[m][bj][1] = *(const f32x4*)(base + off + 4); }
; #pragma unroll
;             for (int m = 0; m < 4; ++m) {
;                 const int row = row0 + ai * 128 + m * 16; float ss = 0.f;
; #pragma unroll
;                 for (int bj = 0; bj < 2; ++bj) {
;                     const size_t off = (size_t)row * DM + col0 + bj * 128;
;                     const f32x4 x0 = bv[m][bj][0] + acc[ai][bj][m][0] * alpha, x1 = bv[m][bj][1] + acc[ai][bj][m][1] * alpha;
;                     *(f32x4*)(out + off) = x0; *(f32x4*)(out + off + 4) = x1;
;                     u32x4 w; w.x = pk2(x0[0], x0[1]); w.y = pk2(x0[2], x0[3]); w.z = pk2(x1[0], x1[1]); w.w = pk2(x1[2], x1[3]);
;                     *(u32x4*)(xb + off) = w;
;                     ss += ((x0[0] * x0[0] + x0[1] * x0[1]) + (x0[2] * x0[2] + x0[3] * x0[3])) + ((x1[0] * x1[0] + x1[1] * x1[1]) + (x1[2] * x1[2] + x1[3] * x1[3]));
;                 }
;                 ss += __shfl_xor(ss, 16); ss += __shfl_xor(ss, 32);
;                 if (ssq && fq == 0) ssq[(size_t)row * 16 + u.pn * 4 + wc] = ss;
;             }
;             asm volatile("" ::: "memory");
;         }
;     }
.LBB0_604:
	s_or_b64 exec, exec, s[40:41]
	s_waitcnt lgkmcnt(0)
	v_lshlrev_b64 v[36:37], 10, v[126:127]
	v_lshl_add_u64 v[40:41], v[36:37], 0, v[206:207]
	v_mov_b32_e32 v193, v192
	s_waitcnt vmcnt(18)
	v_pk_fma_f32 v[30:31], v[192:193], v[30:31], v[98:99]
	v_pk_fma_f32 v[28:29], v[194:195], v[28:29], v[96:97]
	v_pk_fma_f32 v[24:25], v[194:195], v[24:25], v[92:93]
	v_lshl_add_u64 v[42:43], v[40:41], 2, s[24:25]
	v_pk_fma_f32 v[26:27], v[192:193], v[26:27], v[94:95]
	global_store_dwordx4 v[42:43], v[28:31], off sc1
	global_store_dwordx4 v[42:43], v[24:27], off offset:16 sc1
	v_cvt_pk_bf16_f32 v38, v24, v25
	s_waitcnt vmcnt(18)
	v_pk_fma_f32 v[22:23], v[192:193], v[22:23], v[86:87]
	v_mul_f32_e32 v25, v25, v25
	v_fmac_f32_e32 v25, v24, v24
	v_mul_f32_e32 v24, v27, v27
	v_fmac_f32_e32 v24, v26, v26
	v_pk_fma_f32 v[20:21], v[194:195], v[20:21], v[84:85]
	v_cvt_pk_bf16_f32 v39, v26, v27
	v_add_f32_e32 v24, v25, v24
	v_mul_f32_e32 v25, v21, v21
	v_mul_f32_e32 v26, v23, v23
	v_cvt_pk_bf16_f32 v36, v28, v29
	v_mul_f32_e32 v29, v29, v29
	v_pk_fma_f32 v[18:19], v[192:193], v[18:19], v[78:79]
	v_pk_fma_f32 v[16:17], v[194:195], v[16:17], v[76:77]
	v_fmac_f32_e32 v25, v20, v20
	v_fmac_f32_e32 v26, v22, v22
	v_fmac_f32_e32 v29, v28, v28
	v_mul_f32_e32 v28, v31, v31
	v_add_f32_e32 v25, v25, v26
	v_mul_f32_e32 v26, v17, v17
	v_mul_f32_e32 v27, v19, v19
	v_fmac_f32_e32 v28, v30, v30
	v_fmac_f32_e32 v26, v16, v16
	v_fmac_f32_e32 v27, v18, v18
	v_add_f32_e32 v28, v29, v28
	v_add_f32_e32 v26, v26, v27
	v_add_f32_e32 v24, v28, v24
	v_add_f32_e32 v25, v25, v26
	v_add_f32_e32 v24, v24, v25
	ds_bpermute_b32 v25, v222, v24
	v_lshlrev_b64 v[40:41], 1, v[40:41]
	v_cvt_pk_bf16_f32 v37, v30, v31
	v_lshl_add_u64 v[44:45], s[2:3], 0, v[40:41]
	global_store_dwordx4 v[44:45], v[36:39], off sc1
	global_store_dwordx4 v[42:43], v[20:23], off offset:512 sc1
	global_store_dwordx4 v[42:43], v[16:19], off offset:528 sc1
	v_or_b32_e32 v40, 0x100, v40
	v_cvt_pk_bf16_f32 v20, v20, v21
	v_cvt_pk_bf16_f32 v21, v22, v23
	v_cvt_pk_bf16_f32 v22, v16, v17
	s_waitcnt lgkmcnt(0)
	v_add_f32_e32 v16, v24, v25
	ds_bpermute_b32 v17, v221, v16
	v_cvt_pk_bf16_f32 v23, v18, v19
	v_lshl_add_u64 v[18:19], s[2:3], 0, v[40:41]
	global_store_dwordx4 v[18:19], v[20:23], off sc1
	s_and_saveexec_b64 s[40:41], s[18:19]
	s_cbranch_execz .LBB0_606
	s_waitcnt lgkmcnt(0)
	v_add_f32_e32 v18, v16, v17
	v_lshlrev_b64 v[16:17], 6, v[126:127]
	v_lshl_add_u64 v[16:17], s[14:15], 0, v[16:17]
	v_lshl_add_u64 v[16:17], s[22:23], 2, v[16:17]
	s_lshl_b32 s8, s54, 2
	v_lshl_add_u64 v[16:17], v[16:17], 0, s[8:9]
	global_store_dword v[16:17], v18, off
.LBB0_606:
	s_or_b64 exec, exec, s[40:41]
	s_waitcnt lgkmcnt(0)
	v_lshlrev_b64 v[16:17], 10, v[124:125]
	v_lshl_add_u64 v[20:21], v[16:17], 0, v[206:207]
	s_waitcnt vmcnt(20)
	v_pk_fma_f32 v[14:15], v[192:193], v[14:15], v[90:91]
	v_pk_fma_f32 v[12:13], v[194:195], v[12:13], v[88:89]
	v_pk_fma_f32 v[8:9], v[194:195], v[8:9], v[80:81]
	v_lshl_add_u64 v[22:23], v[20:21], 2, s[24:25]
	v_pk_fma_f32 v[10:11], v[192:193], v[10:11], v[82:83]
	global_store_dwordx4 v[22:23], v[12:15], off sc1
	global_store_dwordx4 v[22:23], v[8:11], off offset:16 sc1
	v_cvt_pk_bf16_f32 v18, v8, v9
	s_waitcnt vmcnt(20)
	v_pk_fma_f32 v[6:7], v[192:193], v[6:7], v[74:75]
	v_mul_f32_e32 v9, v9, v9
	v_fmac_f32_e32 v9, v8, v8
	v_mul_f32_e32 v8, v11, v11
	v_fmac_f32_e32 v8, v10, v10
	v_pk_fma_f32 v[4:5], v[194:195], v[4:5], v[72:73]
	v_cvt_pk_bf16_f32 v19, v10, v11
	v_add_f32_e32 v8, v9, v8
	v_mul_f32_e32 v9, v5, v5
	v_mul_f32_e32 v10, v7, v7
	v_cvt_pk_bf16_f32 v16, v12, v13
	v_mul_f32_e32 v13, v13, v13
	v_pk_fma_f32 v[2:3], v[192:193], v[2:3], v[70:71]
	v_pk_fma_f32 v[0:1], v[194:195], v[0:1], v[68:69]
	v_fmac_f32_e32 v9, v4, v4
	v_fmac_f32_e32 v10, v6, v6
	v_fmac_f32_e32 v13, v12, v12
	v_mul_f32_e32 v12, v15, v15
	v_add_f32_e32 v9, v9, v10
	v_mul_f32_e32 v10, v1, v1
	v_mul_f32_e32 v11, v3, v3
	v_fmac_f32_e32 v12, v14, v14
	v_fmac_f32_e32 v10, v0, v0
	v_fmac_f32_e32 v11, v2, v2
	v_add_f32_e32 v12, v13, v12
	v_add_f32_e32 v10, v10, v11
	v_add_f32_e32 v8, v12, v8
	v_add_f32_e32 v9, v9, v10
	v_add_f32_e32 v8, v8, v9
	ds_bpermute_b32 v9, v222, v8
	v_lshlrev_b64 v[20:21], 1, v[20:21]
	v_cvt_pk_bf16_f32 v17, v14, v15
	v_lshl_add_u64 v[24:25], s[2:3], 0, v[20:21]
	global_store_dwordx4 v[24:25], v[16:19], off sc1
	global_store_dwordx4 v[22:23], v[4:7], off offset:512 sc1
	global_store_dwordx4 v[22:23], v[0:3], off offset:528 sc1
	v_or_b32_e32 v20, 0x100, v20
	v_cvt_pk_bf16_f32 v4, v4, v5
	v_cvt_pk_bf16_f32 v5, v6, v7
	v_cvt_pk_bf16_f32 v6, v0, v1
	s_waitcnt lgkmcnt(0)
	v_add_f32_e32 v0, v8, v9
	ds_bpermute_b32 v1, v221, v0
	v_cvt_pk_bf16_f32 v7, v2, v3
	v_lshl_add_u64 v[2:3], s[2:3], 0, v[20:21]
	global_store_dwordx4 v[2:3], v[4:7], off sc1
	s_and_saveexec_b64 s[40:41], s[18:19]
	s_cbranch_execz .LBB0_608
	s_waitcnt lgkmcnt(0)
	v_add_f32_e32 v2, v0, v1
	v_lshlrev_b64 v[0:1], 6, v[124:125]
	v_lshl_add_u64 v[0:1], s[14:15], 0, v[0:1]
	v_lshl_add_u64 v[0:1], s[22:23], 2, v[0:1]
	s_lshl_b32 s8, s54, 2
	v_lshl_add_u64 v[0:1], v[0:1], 0, s[8:9]
	global_store_dword v[0:1], v2, off

; __device__ __forceinline__ float rstd_of(const float* ssq, int row) {
;     const f32x4* q = (const f32x4*)(ssq + (size_t)row * 16); const f32x4 a = q[0], b = q[1], c = q[2], d = q[3];
;     const float t = (((a.x + a.y) + (a.z + a.w)) + ((b.x + b.y) + (b.z + b.w))) + (((c.x + c.y) + (c.z + c.w)) + ((d.x + d.y) + (d.z + d.w)));
;     return 1.0f / sqrtf(t * (1.0f / DM) + 1e-6f); }
;     __device__ __forceinline__ void operator()(const pg8::f32x4 (&acc)[2][2][4][2], const pg8::Unit& u, int wr, int wc, int fr, int fq) const {
;         const int row0 = u.pm * 256 + wr * 64 + fr, col0 = u.pn * 128 + wc * 32 + 8 * fq;
; #pragma unroll
;         for (int ai = 0; ai < 2; ++ai)
; #pragma unroll
;             for (int m = 0; m < 4; ++m) {
;                 const int row = row0 + ai * 128 + m * 16; const float rs = rstd_of(ssq, row);
.LBB0_626:
	v_lshl_add_u32 v142, s52, 8, v35
	v_mbcnt_lo_u32_b32 v206, -1, 0
	v_mbcnt_hi_u32_b32 v206, -1, v206
	v_lshrrev_b32_e32 v207, 4, v206
	v_and_b32_e32 v208, 1, v207
	v_lshrrev_b32_e32 v207, 1, v207
	v_lshlrev_b32_e32 v208, 5, v208
	v_lshl_add_u32 v208, v207, 7, v208
	v_add_u32_e32 v208, v208, v142
	v_mov_b32_e32 v209, 0
	v_lshlrev_b64 v[208:209], 6, v[208:209]
	v_lshl_add_u64 v[208:209], s[10:11], 0, v[208:209]
	global_load_dwordx4 v[166:169], v[208:209], off
	global_load_dwordx4 v[170:173], v[208:209], off offset:16
	global_load_dwordx4 v[174:177], v[208:209], off offset:32
	global_load_dwordx4 v[178:181], v[208:209], off offset:48
	global_load_dwordx4 v[182:185], v[208:209], off offset:1024
	global_load_dwordx4 v[186:189], v[208:209], off offset:1040
	global_load_dwordx4 v[190:193], v[208:209], off offset:1056
	global_load_dwordx4 v[202:205], v[208:209], off offset:1072
	v_and_b32_e32 v210, 15, v206
	v_lshlrev_b32_e32 v210, 2, v210
	v_add_u32_e32 v211, 64, v210
	v_add_u32_e32 v212, 0x80, v210
	v_add_u32_e32 v213, 0xc0, v210
	s_waitcnt vmcnt(4)
	v_add_f32_e32 v166, v166, v167
	v_add_f32_e32 v168, v168, v169
	v_add_f32_e32 v166, v166, v168
	v_add_f32_e32 v170, v170, v171
	v_add_f32_e32 v172, v172, v173
	v_add_f32_e32 v170, v170, v172
	v_add_f32_e32 v174, v174, v175
	v_add_f32_e32 v176, v176, v177
	v_add_f32_e32 v174, v174, v176
	v_add_f32_e32 v178, v178, v179
	v_add_f32_e32 v180, v180, v181
	v_add_f32_e32 v178, v178, v180
	v_add_f32_e32 v166, v166, v170
	v_add_f32_e32 v174, v174, v178
	v_add_f32_e32 v166, v166, v174
	v_fmamk_f32 v166, v166, 0x3a800000, v229
	v_cmp_gt_f32_e32 vcc, 0xf800000, v166
	v_mul_f32_e32 v171, 0x4f800000, v166
	s_nop 0
	v_cndmask_b32_e32 v166, v166, v171, vcc
	v_sqrt_f32_e32 v171, v166
	s_nop 0
	v_add_u32_e32 v172, -1, v171
	v_fma_f32 v173, -v172, v171, v166
	v_cmp_ge_f32_e64 s[100:101], 0, v173
	v_add_u32_e32 v173, 1, v171
	s_nop 0
	v_cndmask_b32_e64 v172, v171, v172, s[100:101]
	v_fma_f32 v171, -v173, v171, v166
	v_cmp_lt_f32_e64 s[100:101], 0, v171
	s_nop 1
	v_cndmask_b32_e64 v171, v172, v173, s[100:101]
	v_mul_f32_e32 v172, 0x37800000, v171
	v_cndmask_b32_e32 v171, v171, v172, vcc
	v_cmp_class_f32_e32 vcc, v166, v230
	s_nop 1
	v_cndmask_b32_e32 v166, v171, v166, vcc
	v_div_scale_f32 v171, s[100:101], v166, v166, 1.0
	v_rcp_f32_e32 v172, v171
	s_nop 0
	v_fma_f32 v173, -v171, v172, 1.0
	v_fmac_f32_e32 v172, v173, v172
	v_div_scale_f32 v173, vcc, 1.0, v166, 1.0
	v_mul_f32_e32 v175, v173, v172
	v_fma_f32 v176, -v171, v175, v173
	v_fmac_f32_e32 v175, v176, v172
	v_fma_f32 v171, -v171, v175, v173
	v_div_fmas_f32 v171, v171, v172, v175
	v_div_fixup_f32 v214, v171, v166, 1.0
	s_waitcnt vmcnt(0)
	v_add_f32_e32 v182, v182, v183
	v_add_f32_e32 v184, v184, v185
	v_add_f32_e32 v182, v182, v184
	v_add_f32_e32 v186, v186, v187
	v_add_f32_e32 v188, v188, v189
	v_add_f32_e32 v186, v186, v188
	v_add_f32_e32 v190, v190, v191
	v_add_f32_e32 v192, v192, v193
	v_add_f32_e32 v190, v190, v192
	v_add_f32_e32 v202, v202, v203
	v_add_f32_e32 v204, v204, v205
	v_add_f32_e32 v202, v202, v204
	v_add_f32_e32 v182, v182, v186
	v_add_f32_e32 v190, v190, v202
	v_add_f32_e32 v182, v182, v190
	v_fmamk_f32 v182, v182, 0x3a800000, v229
	v_cmp_gt_f32_e32 vcc, 0xf800000, v182
	v_mul_f32_e32 v187, 0x4f800000, v182
	s_nop 0
	v_cndmask_b32_e32 v182, v182, v187, vcc
	v_sqrt_f32_e32 v187, v182
	s_nop 0
	v_add_u32_e32 v188, -1, v187
	v_fma_f32 v189, -v188, v187, v182
	v_cmp_ge_f32_e64 s[100:101], 0, v189
	v_add_u32_e32 v189, 1, v187
	s_nop 0
	v_cndmask_b32_e64 v188, v187, v188, s[100:101]
	v_fma_f32 v187, -v189, v187, v182
	v_cmp_lt_f32_e64 s[100:101], 0, v187
	s_nop 1
	v_cndmask_b32_e64 v187, v188, v189, s[100:101]
	v_mul_f32_e32 v188, 0x37800000, v187
	v_cndmask_b32_e32 v187, v187, v188, vcc
	v_cmp_class_f32_e32 vcc, v182, v230
	s_nop 1
	v_cndmask_b32_e32 v182, v187, v182, vcc
	v_div_scale_f32 v187, s[100:101], v182, v182, 1.0
	v_rcp_f32_e32 v188, v187
	s_nop 0
	v_fma_f32 v189, -v187, v188, 1.0
	v_fmac_f32_e32 v188, v189, v188
	v_div_scale_f32 v189, vcc, 1.0, v182, 1.0
	v_mul_f32_e32 v191, v189, v188
	v_fma_f32 v192, -v187, v191, v189
	v_fmac_f32_e32 v191, v192, v188
	v_fma_f32 v187, -v187, v191, v189
	v_div_fmas_f32 v187, v187, v188, v191
	v_div_fixup_f32 v215, v187, v182, 1.0
	ds_bpermute_b32 v218, v210, v214
	ds_bpermute_b32 v219, v210, v215
	ds_bpermute_b32 v220, v211, v214
	ds_bpermute_b32 v221, v211, v215
	ds_bpermute_b32 v222, v212, v214
	ds_bpermute_b32 v223, v212, v215
	ds_bpermute_b32 v194, v213, v214
	ds_bpermute_b32 v195, v213, v215
	s_waitcnt lgkmcnt(0)
; __device__ __forceinline__ unsigned pk2(float lo, float hi) { return pg8::cvt_pk_bf16(lo, hi); }
; __device__ __forceinline__ float fast_exp2(float x) { return __builtin_amdgcn_exp2f(x); }
; __device__ __forceinline__ float fast_rcp(float x) { return __builtin_amdgcn_rcpf(x); }
;     __device__ __forceinline__ void operator()(const pg8::f32x4 (&acc)[2][2][4][2], const pg8::Unit& u, int wr, int wc, int fr, int fq) const {
;         const int row0 = u.pm * 256 + wr * 64 + fr, col0 = u.pn * 128 + wc * 32 + 8 * fq;
; #pragma unroll
;         for (int ai = 0; ai < 2; ++ai)
; #pragma unroll
;             for (int m = 0; m < 4; ++m) {
;                 const int row = row0 + ai * 128 + m * 16; const float rs = rstd_of(ssq, row);
;                 bf16_t* dst = O + (size_t)row * DFF + col0;
;                 float v[8];
; #pragma unroll
;                 for (int n = 0; n < 2; ++n)
; #pragma unroll
;                     for (int j = 0; j < 4; ++j) { const float g = acc[ai][0][m][n][j] * rs, uu = acc[ai][1][m][n][j] * rs; v[n * 4 + j] = g * fast_rcp(1.0f + fast_exp2(-g * LOG2E)) * uu; }
;                 u32x4 w; w.x = pk2(v[0], v[1]); w.y = pk2(v[2], v[3]); w.z = pk2(v[4], v[5]); w.w = pk2(v[6], v[7]);
;                 *(u32x4*)dst = w;
;             }
	s_mov_b32 s15, 0xf800000
	v_lshl_or_b32 v144, s51, 7, v148
	v_ashrrev_i32_e32 v145, 31, v144
	s_movk_i32 s17, 0x1600
	s_nop 1
	v_readlane_b32 s0, v252, 4
	v_readlane_b32 s1, v252, 5
	v_mov_b32_e32 v146, v218
	v_pk_mul_f32 v[128:129], v[128:129], v[146:147] op_sel_hi:[1,0]
	v_pk_mul_f32 v[120:121], v[120:121], v[146:147] op_sel_hi:[1,0]
	v_mul_f32_e32 v143, 0xbfb8aa3b, v128
	v_exp_f32_e32 v143, v143
	v_pk_mul_f32 v[122:123], v[122:123], v[146:147] op_sel_hi:[1,0]
	v_pk_mul_f32 v[124:125], v[124:125], v[146:147] op_sel_hi:[1,0]
	v_pk_mul_f32 v[116:117], v[116:117], v[146:147] op_sel_hi:[1,0]
	v_add_f32_e32 v143, 1.0, v143
	v_rcp_f32_e32 v152, v143
	v_mul_f32_e32 v143, 0xbfb8aa3b, v129
	v_exp_f32_e32 v143, v143
	v_pk_mul_f32 v[118:119], v[118:119], v[146:147] op_sel_hi:[1,0]
	v_mov_b64_e32 v[140:141], s[0:1]
	v_mad_i64_i32 v[150:151], s[0:1], v142, s17, v[140:141]
	v_add_f32_e32 v143, 1.0, v143
	v_rcp_f32_e32 v153, v143
	s_nop 0
	v_pk_mul_f32 v[128:129], v[128:129], v[152:153]
	s_nop 0
	v_pk_mul_f32 v[120:121], v[120:121], v[128:129]
	v_pk_mul_f32 v[128:129], v[130:131], v[146:147] op_sel_hi:[1,0]
	s_nop 0
	v_mul_f32_e32 v130, 0xbfb8aa3b, v128
	v_mul_f32_e32 v131, 0xbfb8aa3b, v129
	v_exp_f32_e32 v130, v130
	v_exp_f32_e32 v131, v131
	v_add_f32_e32 v130, 1.0, v130
	v_add_f32_e32 v131, 1.0, v131
	v_rcp_f32_e32 v130, v130
	v_rcp_f32_e32 v131, v131
	s_nop 0
	v_pk_mul_f32 v[128:129], v[128:129], v[130:131]
	s_nop 0
	v_pk_mul_f32 v[122:123], v[122:123], v[128:129]
	v_mul_f32_e32 v128, 0xbfb8aa3b, v124
	v_mul_f32_e32 v129, 0xbfb8aa3b, v125
	v_exp_f32_e32 v128, v128
	v_exp_f32_e32 v129, v129
	v_add_f32_e32 v128, 1.0, v128
	v_add_f32_e32 v129, 1.0, v129
	v_rcp_f32_e32 v128, v128
	v_rcp_f32_e32 v129, v129
	s_nop 0
	v_pk_mul_f32 v[124:125], v[124:125], v[128:129]
	s_nop 0
	v_pk_mul_f32 v[128:129], v[116:117], v[124:125]
	v_pk_mul_f32 v[116:117], v[126:127], v[146:147] op_sel_hi:[1,0]
	s_nop 0
	v_mul_f32_e32 v124, 0xbfb8aa3b, v116
	v_mul_f32_e32 v125, 0xbfb8aa3b, v117
	v_exp_f32_e32 v124, v124
	v_exp_f32_e32 v125, v125
	v_add_f32_e32 v124, 1.0, v124
	v_add_f32_e32 v125, 1.0, v125
	v_rcp_f32_e32 v124, v124
	v_rcp_f32_e32 v125, v125
	s_nop 0
	v_pk_mul_f32 v[116:117], v[116:117], v[124:125]
	s_nop 0
	v_pk_mul_f32 v[126:127], v[118:119], v[116:117]
	v_lshlrev_b64 v[124:125], 1, v[144:145]
	v_cvt_pk_bf16_f32 v119, v126, v127
	v_or_b32_e32 v126, 16, v142
	v_lshl_add_u64 v[130:131], v[150:151], 0, v[124:125]
	v_cvt_pk_bf16_f32 v116, v120, v121
	v_cvt_pk_bf16_f32 v117, v122, v123
	v_cvt_pk_bf16_f32 v118, v128, v129
	global_store_dwordx4 v[130:131], v[116:119], off sc1
	s_nop 1
	v_mov_b32_e32 v116, v219
	v_pk_mul_f32 v[112:113], v[112:113], v[116:117] op_sel_hi:[1,0]
	v_mad_i64_i32 v[118:119], s[0:1], v126, s17, v[140:141]
	v_mul_f32_e32 v117, 0xbfb8aa3b, v112
	v_exp_f32_e32 v117, v117
	s_nop 0
	v_add_f32_e32 v117, 1.0, v117
	v_rcp_f32_e32 v120, v117
	v_pk_mul_f32 v[104:105], v[104:105], v[116:117] op_sel_hi:[1,0]
	v_mul_f32_e32 v117, 0xbfb8aa3b, v113
	v_exp_f32_e32 v117, v117
	s_nop 0
	v_add_f32_e32 v117, 1.0, v117
	v_rcp_f32_e32 v121, v117
	v_pk_mul_f32 v[106:107], v[106:107], v[116:117] op_sel_hi:[1,0]
	v_pk_mul_f32 v[108:109], v[108:109], v[116:117] op_sel_hi:[1,0]
	v_pk_mul_f32 v[100:101], v[100:101], v[116:117] op_sel_hi:[1,0]
	v_pk_mul_f32 v[112:113], v[112:113], v[120:121]
	v_pk_mul_f32 v[102:103], v[102:103], v[116:117] op_sel_hi:[1,0]
	v_pk_mul_f32 v[104:105], v[104:105], v[112:113]
	v_pk_mul_f32 v[112:113], v[114:115], v[116:117] op_sel_hi:[1,0]
	s_nop 0
	v_mul_f32_e32 v114, 0xbfb8aa3b, v112
	v_mul_f32_e32 v115, 0xbfb8aa3b, v113
	v_exp_f32_e32 v114, v114
	v_exp_f32_e32 v115, v115
	v_add_f32_e32 v114, 1.0, v114
	v_add_f32_e32 v115, 1.0, v115
	v_rcp_f32_e32 v114, v114
	v_rcp_f32_e32 v115, v115
	s_nop 0
	v_pk_mul_f32 v[112:113], v[112:113], v[114:115]
	s_nop 0
	v_pk_mul_f32 v[106:107], v[106:107], v[112:113]
	v_mul_f32_e32 v112, 0xbfb8aa3b, v108
	v_mul_f32_e32 v113, 0xbfb8aa3b, v109
	v_exp_f32_e32 v112, v112
	v_exp_f32_e32 v113, v113
	v_add_f32_e32 v112, 1.0, v112
	v_add_f32_e32 v113, 1.0, v113
	v_rcp_f32_e32 v112, v112
	v_rcp_f32_e32 v113, v113
	s_nop 0
	v_pk_mul_f32 v[108:109], v[108:109], v[112:113]
	s_nop 0
	v_pk_mul_f32 v[108:109], v[100:101], v[108:109]
	v_pk_mul_f32 v[100:101], v[110:111], v[116:117] op_sel_hi:[1,0]
	v_lshl_add_u64 v[112:113], v[118:119], 0, v[124:125]
	v_mul_f32_e32 v110, 0xbfb8aa3b, v100
	v_mul_f32_e32 v111, 0xbfb8aa3b, v101
	v_exp_f32_e32 v110, v110
	v_exp_f32_e32 v111, v111
	v_add_f32_e32 v110, 1.0, v110
	v_add_f32_e32 v111, 1.0, v111
	v_rcp_f32_e32 v110, v110
	v_rcp_f32_e32 v111, v111
	s_nop 0
	v_pk_mul_f32 v[100:101], v[100:101], v[110:111]
	s_nop 0
	v_pk_mul_f32 v[110:111], v[102:103], v[100:101]
	v_cvt_pk_bf16_f32 v102, v108, v109
	v_or_b32_e32 v108, 32, v142
	v_cvt_pk_bf16_f32 v100, v104, v105
	v_cvt_pk_bf16_f32 v101, v106, v107
	v_cvt_pk_bf16_f32 v103, v110, v111
	global_store_dwordx4 v[112:113], v[100:103], off sc1
	s_nop 1
	v_mov_b32_e32 v100, v220
	v_pk_mul_f32 v[96:97], v[96:97], v[100:101] op_sel_hi:[1,0]
	v_mad_i64_i32 v[102:103], s[0:1], v108, s17, v[140:141]
	v_mul_f32_e32 v101, 0xbfb8aa3b, v96
	v_exp_f32_e32 v101, v101
	s_nop 0
	v_add_f32_e32 v101, 1.0, v101
	v_rcp_f32_e32 v104, v101
	v_pk_mul_f32 v[88:89], v[88:89], v[100:101] op_sel_hi:[1,0]
	v_mul_f32_e32 v101, 0xbfb8aa3b, v97
	v_exp_f32_e32 v101, v101
	s_nop 0
	v_add_f32_e32 v101, 1.0, v101
	v_rcp_f32_e32 v105, v101
	v_pk_mul_f32 v[90:91], v[90:91], v[100:101] op_sel_hi:[1,0]
	v_pk_mul_f32 v[92:93], v[92:93], v[100:101] op_sel_hi:[1,0]
	v_pk_mul_f32 v[84:85], v[84:85], v[100:101] op_sel_hi:[1,0]
	v_pk_mul_f32 v[96:97], v[96:97], v[104:105]
; __device__ __forceinline__ unsigned pk2(float lo, float hi) { return pg8::cvt_pk_bf16(lo, hi); }
; __device__ __forceinline__ float fast_exp2(float x) { return __builtin_amdgcn_exp2f(x); }
; __device__ __forceinline__ float fast_rcp(float x) { return __builtin_amdgcn_rcpf(x); }
;     __device__ __forceinline__ void operator()(const pg8::f32x4 (&acc)[2][2][4][2], const pg8::Unit& u, int wr, int wc, int fr, int fq) const {
;         const int row0 = u.pm * 256 + wr * 64 + fr, col0 = u.pn * 128 + wc * 32 + 8 * fq;
; #pragma unroll
;         for (int ai = 0; ai < 2; ++ai)
; #pragma unroll
;             for (int m = 0; m < 4; ++m) {
;                 const int row = row0 + ai * 128 + m * 16; const float rs = rstd_of(ssq, row);
;                 bf16_t* dst = O + (size_t)row * DFF + col0;
;                 float v[8];
; #pragma unroll
;                 for (int n = 0; n < 2; ++n)
; #pragma unroll
;                     for (int j = 0; j < 4; ++j) { const float g = acc[ai][0][m][n][j] * rs, uu = acc[ai][1][m][n][j] * rs; v[n * 4 + j] = g * fast_rcp(1.0f + fast_exp2(-g * LOG2E)) * uu; }
;                 u32x4 w; w.x = pk2(v[0], v[1]); w.y = pk2(v[2], v[3]); w.z = pk2(v[4], v[5]); w.w = pk2(v[6], v[7]);
;                 *(u32x4*)dst = w;
;             }
	v_pk_mul_f32 v[86:87], v[86:87], v[100:101] op_sel_hi:[1,0]
	v_pk_mul_f32 v[88:89], v[88:89], v[96:97]
	v_pk_mul_f32 v[96:97], v[98:99], v[100:101] op_sel_hi:[1,0]
	s_nop 0
	v_mul_f32_e32 v98, 0xbfb8aa3b, v96
	v_mul_f32_e32 v99, 0xbfb8aa3b, v97
	v_exp_f32_e32 v98, v98
	v_exp_f32_e32 v99, v99
	v_add_f32_e32 v98, 1.0, v98
	v_add_f32_e32 v99, 1.0, v99
	v_rcp_f32_e32 v98, v98
	v_rcp_f32_e32 v99, v99
	s_nop 0
	v_pk_mul_f32 v[96:97], v[96:97], v[98:99]
	s_nop 0
	v_pk_mul_f32 v[90:91], v[90:91], v[96:97]
	v_mul_f32_e32 v96, 0xbfb8aa3b, v92
	v_mul_f32_e32 v97, 0xbfb8aa3b, v93
	v_exp_f32_e32 v96, v96
	v_exp_f32_e32 v97, v97
	v_add_f32_e32 v96, 1.0, v96
	v_add_f32_e32 v97, 1.0, v97
	v_rcp_f32_e32 v96, v96
	v_rcp_f32_e32 v97, v97
	s_nop 0
	v_pk_mul_f32 v[92:93], v[92:93], v[96:97]
	s_nop 0
	v_pk_mul_f32 v[92:93], v[84:85], v[92:93]
	v_pk_mul_f32 v[84:85], v[94:95], v[100:101] op_sel_hi:[1,0]
	v_lshl_add_u64 v[96:97], v[102:103], 0, v[124:125]
	v_mul_f32_e32 v94, 0xbfb8aa3b, v84
	v_mul_f32_e32 v95, 0xbfb8aa3b, v85
	v_exp_f32_e32 v94, v94
	v_exp_f32_e32 v95, v95
	v_add_f32_e32 v94, 1.0, v94
	v_add_f32_e32 v95, 1.0, v95
	v_rcp_f32_e32 v94, v94
	v_rcp_f32_e32 v95, v95
	s_nop 0
	v_pk_mul_f32 v[84:85], v[84:85], v[94:95]
	s_nop 0
	v_pk_mul_f32 v[94:95], v[86:87], v[84:85]
	v_cvt_pk_bf16_f32 v86, v92, v93
	v_or_b32_e32 v92, 48, v142
	v_cvt_pk_bf16_f32 v84, v88, v89
	v_cvt_pk_bf16_f32 v85, v90, v91
	v_cvt_pk_bf16_f32 v87, v94, v95
	global_store_dwordx4 v[96:97], v[84:87], off sc1
	s_nop 1
	v_mov_b32_e32 v84, v221
	v_pk_mul_f32 v[80:81], v[80:81], v[84:85] op_sel_hi:[1,0]
	v_mad_i64_i32 v[86:87], s[0:1], v92, s17, v[140:141]
	v_mul_f32_e32 v85, 0xbfb8aa3b, v80
	v_exp_f32_e32 v85, v85
	s_nop 0
	v_add_f32_e32 v85, 1.0, v85
	v_rcp_f32_e32 v88, v85
	v_pk_mul_f32 v[72:73], v[72:73], v[84:85] op_sel_hi:[1,0]
	v_mul_f32_e32 v85, 0xbfb8aa3b, v81
	v_exp_f32_e32 v85, v85
	s_nop 0
	v_add_f32_e32 v85, 1.0, v85
	v_rcp_f32_e32 v89, v85
	v_pk_mul_f32 v[74:75], v[74:75], v[84:85] op_sel_hi:[1,0]
	v_pk_mul_f32 v[76:77], v[76:77], v[84:85] op_sel_hi:[1,0]
	v_pk_mul_f32 v[68:69], v[68:69], v[84:85] op_sel_hi:[1,0]
	v_pk_mul_f32 v[80:81], v[80:81], v[88:89]
	v_pk_mul_f32 v[70:71], v[70:71], v[84:85] op_sel_hi:[1,0]
	v_pk_mul_f32 v[72:73], v[72:73], v[80:81]
	v_pk_mul_f32 v[80:81], v[82:83], v[84:85] op_sel_hi:[1,0]
	s_nop 0
	v_mul_f32_e32 v82, 0xbfb8aa3b, v80
	v_mul_f32_e32 v83, 0xbfb8aa3b, v81
	v_exp_f32_e32 v82, v82
	v_exp_f32_e32 v83, v83
	v_add_f32_e32 v82, 1.0, v82
	v_add_f32_e32 v83, 1.0, v83
	v_rcp_f32_e32 v82, v82
	v_rcp_f32_e32 v83, v83
	s_nop 0
	v_pk_mul_f32 v[80:81], v[80:81], v[82:83]
	s_nop 0
	v_pk_mul_f32 v[74:75], v[74:75], v[80:81]
	v_mul_f32_e32 v80, 0xbfb8aa3b, v76
	v_mul_f32_e32 v81, 0xbfb8aa3b, v77
	v_exp_f32_e32 v80, v80
	v_exp_f32_e32 v81, v81
	v_add_f32_e32 v80, 1.0, v80
	v_add_f32_e32 v81, 1.0, v81
	v_rcp_f32_e32 v80, v80
	v_rcp_f32_e32 v81, v81
	s_nop 0
	v_pk_mul_f32 v[76:77], v[76:77], v[80:81]
	s_nop 0
	v_pk_mul_f32 v[76:77], v[68:69], v[76:77]
	v_pk_mul_f32 v[68:69], v[78:79], v[84:85] op_sel_hi:[1,0]
	v_lshl_add_u64 v[80:81], v[86:87], 0, v[124:125]
	v_mul_f32_e32 v78, 0xbfb8aa3b, v68
	v_mul_f32_e32 v79, 0xbfb8aa3b, v69
	v_exp_f32_e32 v78, v78
	v_exp_f32_e32 v79, v79
	v_add_f32_e32 v78, 1.0, v78
	v_add_f32_e32 v79, 1.0, v79
	v_rcp_f32_e32 v78, v78
	v_rcp_f32_e32 v79, v79
	s_nop 0
	v_pk_mul_f32 v[68:69], v[68:69], v[78:79]
	s_nop 0
	v_pk_mul_f32 v[78:79], v[70:71], v[68:69]
	v_cvt_pk_bf16_f32 v70, v76, v77
	v_add_u32_e32 v76, 0x80, v142
	v_cvt_pk_bf16_f32 v68, v72, v73
	v_cvt_pk_bf16_f32 v69, v74, v75
	v_cvt_pk_bf16_f32 v71, v78, v79
	global_store_dwordx4 v[80:81], v[68:71], off sc1
	s_nop 1
	v_mov_b32_e32 v68, v222
	v_pk_mul_f32 v[64:65], v[64:65], v[68:69] op_sel_hi:[1,0]
	v_mad_i64_i32 v[70:71], s[0:1], v76, s17, v[140:141]
	v_mul_f32_e32 v69, 0xbfb8aa3b, v64
	v_exp_f32_e32 v69, v69
	s_nop 0
	v_add_f32_e32 v69, 1.0, v69
	v_rcp_f32_e32 v72, v69
	v_pk_mul_f32 v[56:57], v[56:57], v[68:69] op_sel_hi:[1,0]
	v_mul_f32_e32 v69, 0xbfb8aa3b, v65
	v_exp_f32_e32 v69, v69
	s_nop 0
	v_add_f32_e32 v69, 1.0, v69
	v_rcp_f32_e32 v73, v69
	v_pk_mul_f32 v[58:59], v[58:59], v[68:69] op_sel_hi:[1,0]
	v_pk_mul_f32 v[60:61], v[60:61], v[68:69] op_sel_hi:[1,0]
	v_pk_mul_f32 v[52:53], v[52:53], v[68:69] op_sel_hi:[1,0]
	v_pk_mul_f32 v[64:65], v[64:65], v[72:73]
	v_pk_mul_f32 v[54:55], v[54:55], v[68:69] op_sel_hi:[1,0]
	v_pk_mul_f32 v[56:57], v[56:57], v[64:65]
	v_pk_mul_f32 v[64:65], v[66:67], v[68:69] op_sel_hi:[1,0]
	s_nop 0
	v_mul_f32_e32 v66, 0xbfb8aa3b, v64
	v_mul_f32_e32 v67, 0xbfb8aa3b, v65
	v_exp_f32_e32 v66, v66
	v_exp_f32_e32 v67, v67
	v_add_f32_e32 v66, 1.0, v66
	v_add_f32_e32 v67, 1.0, v67
	v_rcp_f32_e32 v66, v66
	v_rcp_f32_e32 v67, v67
	s_nop 0
	v_pk_mul_f32 v[64:65], v[64:65], v[66:67]
	s_nop 0
	v_pk_mul_f32 v[58:59], v[58:59], v[64:65]
	v_mul_f32_e32 v64, 0xbfb8aa3b, v60
	v_mul_f32_e32 v65, 0xbfb8aa3b, v61
	v_exp_f32_e32 v64, v64
	v_exp_f32_e32 v65, v65
	v_add_f32_e32 v64, 1.0, v64
	v_add_f32_e32 v65, 1.0, v65
	v_rcp_f32_e32 v64, v64
	v_rcp_f32_e32 v65, v65
	s_nop 0
	v_pk_mul_f32 v[60:61], v[60:61], v[64:65]
	s_nop 0
	v_pk_mul_f32 v[60:61], v[52:53], v[60:61]
	v_pk_mul_f32 v[52:53], v[62:63], v[68:69] op_sel_hi:[1,0]
	v_lshl_add_u64 v[64:65], v[70:71], 0, v[124:125]
	v_mul_f32_e32 v62, 0xbfb8aa3b, v52
	v_mul_f32_e32 v63, 0xbfb8aa3b, v53
	v_exp_f32_e32 v62, v62
	v_exp_f32_e32 v63, v63
	v_add_f32_e32 v62, 1.0, v62
	v_add_f32_e32 v63, 1.0, v63
	v_rcp_f32_e32 v62, v62
	v_rcp_f32_e32 v63, v63
	s_nop 0
	v_pk_mul_f32 v[52:53], v[52:53], v[62:63]
	s_nop 0
	v_pk_mul_f32 v[62:63], v[54:55], v[52:53]
	v_cvt_pk_bf16_f32 v54, v60, v61
	v_add_u32_e32 v60, 0x90, v142
; #define PG8_BAR __builtin_amdgcn_s_barrier()
; __device__ __forceinline__ unsigned pk2(float lo, float hi) { return pg8::cvt_pk_bf16(lo, hi); }
; __device__ __forceinline__ float fast_exp2(float x) { return __builtin_amdgcn_exp2f(x); }
; __device__ __forceinline__ float fast_rcp(float x) { return __builtin_amdgcn_rcpf(x); }
; template <class Epi, class Sched, bool ALIGN_EPI = false, bool SP2 = false>
; __device__ __forceinline__ void gemm_phase(PG8_LAS unsigned char* lds, const Gemm g, const Sched& S, const Epi& E) {
;     ...
;         if constexpr (!Epi::AFTER_DRAIN) { E(acc, cur, wr, wc, fr, fq); S.done(cur); }
;         if (!has_next) break;
; #pragma unroll
;         for (int a = 0; a < 2; ++a)
; #pragma unroll
;             for (int b = 0; b < 2; ++b)
; #pragma unroll
;                 for (int m = 0; m < 4; ++m)
; #pragma unroll
;                     for (int n = 0; n < 2; ++n) acc[a][b][m][n] = (f32x4){0.f, 0.f, 0.f, 0.f};
;         cur = nxt; cA = nA; cB = nB; ++ui;
;         if constexpr (ALIGN_EPI) { if (wr == 1) PG8_BAR; }
;     __device__ __forceinline__ void operator()(const pg8::f32x4 (&acc)[2][2][4][2], const pg8::Unit& u, int wr, int wc, int fr, int fq) const {
;         const int row0 = u.pm * 256 + wr * 64 + fr, col0 = u.pn * 128 + wc * 32 + 8 * fq;
; #pragma unroll
;         for (int ai = 0; ai < 2; ++ai)
; #pragma unroll
;             for (int m = 0; m < 4; ++m) {
;                 const int row = row0 + ai * 128 + m * 16; const float rs = rstd_of(ssq, row);
;                 bf16_t* dst = O + (size_t)row * DFF + col0;
;                 float v[8];
; #pragma unroll
;                 for (int n = 0; n < 2; ++n)
; #pragma unroll
;                     for (int j = 0; j < 4; ++j) { const float g = acc[ai][0][m][n][j] * rs, uu = acc[ai][1][m][n][j] * rs; v[n * 4 + j] = g * fast_rcp(1.0f + fast_exp2(-g * LOG2E)) * uu; }
;                 u32x4 w; w.x = pk2(v[0], v[1]); w.y = pk2(v[2], v[3]); w.z = pk2(v[4], v[5]); w.w = pk2(v[6], v[7]);
;                 *(u32x4*)dst = w;
;             }
	v_cvt_pk_bf16_f32 v52, v56, v57
	v_cvt_pk_bf16_f32 v53, v58, v59
	v_cvt_pk_bf16_f32 v55, v62, v63
	global_store_dwordx4 v[64:65], v[52:55], off sc1
	s_nop 1
	v_mov_b32_e32 v52, v223
	v_pk_mul_f32 v[48:49], v[48:49], v[52:53] op_sel_hi:[1,0]
	v_mad_i64_i32 v[54:55], s[0:1], v60, s17, v[140:141]
	v_mul_f32_e32 v53, 0xbfb8aa3b, v48
	v_exp_f32_e32 v53, v53
	s_nop 0
	v_add_f32_e32 v53, 1.0, v53
	v_rcp_f32_e32 v56, v53
	v_pk_mul_f32 v[40:41], v[40:41], v[52:53] op_sel_hi:[1,0]
	v_mul_f32_e32 v53, 0xbfb8aa3b, v49
	v_exp_f32_e32 v53, v53
	s_nop 0
	v_add_f32_e32 v53, 1.0, v53
	v_rcp_f32_e32 v57, v53
	v_pk_mul_f32 v[42:43], v[42:43], v[52:53] op_sel_hi:[1,0]
	v_pk_mul_f32 v[44:45], v[44:45], v[52:53] op_sel_hi:[1,0]
	v_pk_mul_f32 v[36:37], v[36:37], v[52:53] op_sel_hi:[1,0]
	v_pk_mul_f32 v[48:49], v[48:49], v[56:57]
	v_pk_mul_f32 v[38:39], v[38:39], v[52:53] op_sel_hi:[1,0]
	v_pk_mul_f32 v[40:41], v[40:41], v[48:49]
	v_pk_mul_f32 v[48:49], v[50:51], v[52:53] op_sel_hi:[1,0]
	s_nop 0
	v_mul_f32_e32 v50, 0xbfb8aa3b, v48
	v_mul_f32_e32 v51, 0xbfb8aa3b, v49
	v_exp_f32_e32 v50, v50
	v_exp_f32_e32 v51, v51
	v_add_f32_e32 v50, 1.0, v50
	v_add_f32_e32 v51, 1.0, v51
	v_rcp_f32_e32 v50, v50
	v_rcp_f32_e32 v51, v51
	s_nop 0
	v_pk_mul_f32 v[48:49], v[48:49], v[50:51]
	s_nop 0
	v_pk_mul_f32 v[42:43], v[42:43], v[48:49]
	v_mul_f32_e32 v48, 0xbfb8aa3b, v44
	v_mul_f32_e32 v49, 0xbfb8aa3b, v45
	v_exp_f32_e32 v48, v48
	v_exp_f32_e32 v49, v49
	v_add_f32_e32 v48, 1.0, v48
	v_add_f32_e32 v49, 1.0, v49
	v_rcp_f32_e32 v48, v48
	v_rcp_f32_e32 v49, v49
	s_nop 0
	v_pk_mul_f32 v[44:45], v[44:45], v[48:49]
	s_nop 0
	v_pk_mul_f32 v[44:45], v[36:37], v[44:45]
	v_pk_mul_f32 v[36:37], v[46:47], v[52:53] op_sel_hi:[1,0]
	v_lshl_add_u64 v[48:49], v[54:55], 0, v[124:125]
	v_mul_f32_e32 v46, 0xbfb8aa3b, v36
	v_mul_f32_e32 v47, 0xbfb8aa3b, v37
	v_exp_f32_e32 v46, v46
	v_exp_f32_e32 v47, v47
	v_add_f32_e32 v46, 1.0, v46
	v_add_f32_e32 v47, 1.0, v47
	v_rcp_f32_e32 v46, v46
	v_rcp_f32_e32 v47, v47
	s_nop 0
	v_pk_mul_f32 v[36:37], v[36:37], v[46:47]
	s_nop 0
	v_pk_mul_f32 v[46:47], v[38:39], v[36:37]
	v_cvt_pk_bf16_f32 v38, v44, v45
	v_add_u32_e32 v44, 0xa0, v142
	v_cvt_pk_bf16_f32 v36, v40, v41
	v_cvt_pk_bf16_f32 v37, v42, v43
	v_cvt_pk_bf16_f32 v39, v46, v47
	global_store_dwordx4 v[48:49], v[36:39], off sc1
	s_nop 1
	v_mov_b32_e32 v36, v194
	v_pk_mul_f32 v[28:29], v[28:29], v[36:37] op_sel_hi:[1,0]
	v_mad_i64_i32 v[38:39], s[0:1], v44, s17, v[140:141]
	v_mul_f32_e32 v37, 0xbfb8aa3b, v28
	v_exp_f32_e32 v37, v37
	s_nop 0
	v_add_f32_e32 v37, 1.0, v37
	v_rcp_f32_e32 v40, v37
	v_pk_mul_f32 v[20:21], v[20:21], v[36:37] op_sel_hi:[1,0]
	v_mul_f32_e32 v37, 0xbfb8aa3b, v29
	v_exp_f32_e32 v37, v37
	s_nop 0
	v_add_f32_e32 v37, 1.0, v37
	v_rcp_f32_e32 v41, v37
	v_pk_mul_f32 v[22:23], v[22:23], v[36:37] op_sel_hi:[1,0]
	v_pk_mul_f32 v[24:25], v[24:25], v[36:37] op_sel_hi:[1,0]
	v_pk_mul_f32 v[16:17], v[16:17], v[36:37] op_sel_hi:[1,0]
	v_pk_mul_f32 v[28:29], v[28:29], v[40:41]
	v_pk_mul_f32 v[18:19], v[18:19], v[36:37] op_sel_hi:[1,0]
	v_pk_mul_f32 v[20:21], v[20:21], v[28:29]
	v_pk_mul_f32 v[28:29], v[30:31], v[36:37] op_sel_hi:[1,0]
	s_nop 0
	v_mul_f32_e32 v30, 0xbfb8aa3b, v28
	v_mul_f32_e32 v31, 0xbfb8aa3b, v29
	v_exp_f32_e32 v30, v30
	v_exp_f32_e32 v31, v31
	v_add_f32_e32 v30, 1.0, v30
	v_add_f32_e32 v31, 1.0, v31
	v_rcp_f32_e32 v30, v30
	v_rcp_f32_e32 v31, v31
	s_nop 0
	v_pk_mul_f32 v[28:29], v[28:29], v[30:31]
	s_nop 0
	v_pk_mul_f32 v[22:23], v[22:23], v[28:29]
	v_mul_f32_e32 v28, 0xbfb8aa3b, v24
	v_mul_f32_e32 v29, 0xbfb8aa3b, v25
	v_exp_f32_e32 v28, v28
	v_exp_f32_e32 v29, v29
	v_add_f32_e32 v28, 1.0, v28
	v_add_f32_e32 v29, 1.0, v29
	v_rcp_f32_e32 v28, v28
	v_rcp_f32_e32 v29, v29
	s_nop 0
	v_pk_mul_f32 v[24:25], v[24:25], v[28:29]
	s_nop 0
	v_pk_mul_f32 v[24:25], v[16:17], v[24:25]
	v_pk_mul_f32 v[16:17], v[26:27], v[36:37] op_sel_hi:[1,0]
	v_lshl_add_u64 v[28:29], v[38:39], 0, v[124:125]
	v_mul_f32_e32 v26, 0xbfb8aa3b, v16
	v_mul_f32_e32 v27, 0xbfb8aa3b, v17
	v_exp_f32_e32 v26, v26
	v_exp_f32_e32 v27, v27
	v_add_f32_e32 v26, 1.0, v26
	v_add_f32_e32 v27, 1.0, v27
	v_rcp_f32_e32 v26, v26
	v_rcp_f32_e32 v27, v27
	s_nop 0
	v_pk_mul_f32 v[16:17], v[16:17], v[26:27]
	s_nop 0
	v_pk_mul_f32 v[26:27], v[18:19], v[16:17]
	v_cvt_pk_bf16_f32 v18, v24, v25
	v_add_u32_e32 v24, 0xb0, v142
	v_cvt_pk_bf16_f32 v16, v20, v21
	v_cvt_pk_bf16_f32 v17, v22, v23
	v_cvt_pk_bf16_f32 v19, v26, v27
	global_store_dwordx4 v[28:29], v[16:19], off sc1
	s_nop 1
	v_mov_b32_e32 v16, v195
	v_pk_mul_f32 v[12:13], v[12:13], v[16:17] op_sel_hi:[1,0]
	v_mad_i64_i32 v[18:19], s[0:1], v24, s17, v[140:141]
	v_mul_f32_e32 v17, 0xbfb8aa3b, v12
	v_exp_f32_e32 v17, v17
	s_mov_b64 s[0:1], -1
	s_andn2_b64 vcc, exec, s[38:39]
	v_add_f32_e32 v17, 1.0, v17
	v_rcp_f32_e32 v20, v17
	v_pk_mul_f32 v[4:5], v[4:5], v[16:17] op_sel_hi:[1,0]
	v_mul_f32_e32 v17, 0xbfb8aa3b, v13
	v_exp_f32_e32 v17, v17
	s_nop 0
	v_add_f32_e32 v17, 1.0, v17
	v_rcp_f32_e32 v21, v17
	v_pk_mul_f32 v[6:7], v[6:7], v[16:17] op_sel_hi:[1,0]
	v_pk_mul_f32 v[8:9], v[8:9], v[16:17] op_sel_hi:[1,0]
	v_pk_mul_f32 v[0:1], v[0:1], v[16:17] op_sel_hi:[1,0]
	v_pk_mul_f32 v[12:13], v[12:13], v[20:21]
	v_pk_mul_f32 v[2:3], v[2:3], v[16:17] op_sel_hi:[1,0]
	v_pk_mul_f32 v[4:5], v[4:5], v[12:13]
	v_pk_mul_f32 v[12:13], v[14:15], v[16:17] op_sel_hi:[1,0]
	s_nop 0
	v_mul_f32_e32 v14, 0xbfb8aa3b, v12
	v_mul_f32_e32 v15, 0xbfb8aa3b, v13
	v_exp_f32_e32 v14, v14
	v_exp_f32_e32 v15, v15
	v_add_f32_e32 v14, 1.0, v14
	v_add_f32_e32 v15, 1.0, v15
	v_rcp_f32_e32 v14, v14
	v_rcp_f32_e32 v15, v15
	s_nop 0
	v_pk_mul_f32 v[12:13], v[12:13], v[14:15]
	s_nop 0
	v_pk_mul_f32 v[6:7], v[6:7], v[12:13]
	v_mul_f32_e32 v12, 0xbfb8aa3b, v8
	v_mul_f32_e32 v13, 0xbfb8aa3b, v9
	v_exp_f32_e32 v12, v12
	v_exp_f32_e32 v13, v13
	v_add_f32_e32 v12, 1.0, v12
	v_add_f32_e32 v13, 1.0, v13
	v_rcp_f32_e32 v12, v12
	v_rcp_f32_e32 v13, v13
	s_nop 0
	v_pk_mul_f32 v[8:9], v[8:9], v[12:13]
	s_nop 0
	v_pk_mul_f32 v[8:9], v[0:1], v[8:9]
	v_pk_mul_f32 v[0:1], v[10:11], v[16:17] op_sel_hi:[1,0]
	v_lshl_add_u64 v[12:13], v[18:19], 0, v[124:125]
	v_mul_f32_e32 v10, 0xbfb8aa3b, v0
	v_mul_f32_e32 v11, 0xbfb8aa3b, v1
	v_exp_f32_e32 v10, v10
	v_exp_f32_e32 v11, v11
	v_add_f32_e32 v10, 1.0, v10
	v_add_f32_e32 v11, 1.0, v11
	v_rcp_f32_e32 v10, v10
	v_rcp_f32_e32 v11, v11
	s_nop 0
	v_pk_mul_f32 v[0:1], v[0:1], v[10:11]
	s_nop 0
	v_pk_mul_f32 v[10:11], v[2:3], v[0:1]
	v_cvt_pk_bf16_f32 v0, v4, v5
	v_cvt_pk_bf16_f32 v1, v6, v7
	v_cvt_pk_bf16_f32 v2, v8, v9
	v_cvt_pk_bf16_f32 v3, v10, v11
	global_store_dwordx4 v[12:13], v[0:3], off sc1
	s_cbranch_vccnz .LBB0_619
	s_andn2_b64 vcc, exec, s[4:5]
	s_cbranch_vccnz .LBB0_618
	s_barrier
	s_branch .LBB0_618

; #define LAS __attribute__((address_space(3)))
; __device__ __forceinline__ unsigned pk2(float lo, float hi) { return pg8::cvt_pk_bf16(lo, hi); }
; __device__ __forceinline__ void transpose_tile(const float* src, int srcN, const float* gk, bf16_t* dst, int dstK, LAS float* scr, int lane) {
;     ...
;     asm volatile("s_waitcnt lgkmcnt(0)" ::: "memory");
;     const int c = lane & 7;
; #pragma unroll
;     for (int j = 0; j < 4; ++j) {
;         const int n = (lane >> 3) + 8 * j; const LAS float* s = scr + (8 * c) * 33 + n;
;         u32x4 o; o.x = pk2(s[0 * 33], s[1 * 33]); o.y = pk2(s[2 * 33], s[3 * 33]); o.z = pk2(s[4 * 33], s[5 * 33]); o.w = pk2(s[6 * 33], s[7 * 33]);
;         *(u32x4*)(dst + (size_t)n * dstK + 8 * c) = o;
;     }
;     asm volatile("s_waitcnt lgkmcnt(0)" ::: "memory");
; }
; __device__ __forceinline__ void convert_layer(const Params& p, int l, LAS unsigned char* lds, int it_lo, int it_hi, int worker, int nworkers) {
;     ...
;         if (r < 2 * I_GU) {
;             const int f = r / I_GU; r -= f * I_GU; const int nb = r / (DM / 64), kb = r % (DM / 64), n0 = nb * 32, k0 = kb * 64;
;             const int pn = n0 >> 8, w = n0 & 255; const float* src = ((w < 128) ? p.ffn_w_gate : p.ffn_w_up) + (size_t)(l * 2 + f) * DM * DFF;
;             transpose_tile(src + (size_t)k0 * DFF + pn * 128 + (w & 127), DFF, ng + (f ? 2 : 0) * DM + k0, W + (f ? O_WGU1 : O_WGU0) + (size_t)n0 * DM + k0, DM, scr, lane); continue; }
.LBB0_634:
	v_add_u32_e32 v13, v1, v3
	s_waitcnt vmcnt(30)
	ds_write2_b32 v13, v14, v15 offset1:66
	s_waitcnt vmcnt(28)
	ds_write2_b32 v13, v20, v21 offset0:132 offset1:198
	v_add_u32_e32 v13, 0x400, v13
	s_waitcnt vmcnt(26)
	ds_write2_b32 v13, v18, v19 offset0:8 offset1:74
	v_add_u32_e32 v13, v1, v5
	s_waitcnt vmcnt(24)
	ds_write2_b32 v13, v16, v17 offset1:66
	s_waitcnt vmcnt(22)
	ds_write2_b32 v13, v26, v27 offset0:132 offset1:198
	v_add_u32_e32 v13, 0x400, v13
	s_waitcnt vmcnt(20)
	ds_write2_b32 v13, v24, v25 offset0:8 offset1:74
	v_add_u32_e32 v13, v1, v7
	s_lshl_b32 s40, s8, 5
	s_waitcnt vmcnt(18)
	ds_write2_b32 v13, v22, v23 offset1:66
	s_waitcnt vmcnt(16)
	ds_write2_b32 v13, v32, v33 offset0:132 offset1:198
	v_add_u32_e32 v13, 0x400, v13
	s_and_b64 s[10:11], s[10:11], exec
	s_waitcnt vmcnt(14)
	ds_write2_b32 v13, v30, v31 offset0:8 offset1:74
	v_add_u32_e32 v13, v1, v9
	s_cselect_b32 s8, 0, 0x2300000
	v_add_u32_e32 v14, 0x400, v13
	s_add_u32 s8, s14, s8
	s_waitcnt vmcnt(12)
	ds_write2_b32 v13, v28, v29 offset1:66
	s_waitcnt vmcnt(10)
	ds_write2_b32 v13, v38, v39 offset0:132 offset1:198
	s_waitcnt vmcnt(8)
	ds_write2_b32 v14, v36, v37 offset0:8 offset1:74
	s_waitcnt vmcnt(6)
	ds_write2_b32 v14, v44, v45 offset0:140 offset1:206
	v_add_u32_e32 v14, 0x800, v13
	v_add_u32_e32 v13, 0xc00, v13
	s_addc_u32 s39, s15, 0
	s_ashr_i32 s41, s40, 31
	s_waitcnt vmcnt(4)
	ds_write2_b32 v14, v42, v43 offset0:16 offset1:82
	s_waitcnt vmcnt(2)
	ds_write2_b32 v14, v46, v47 offset0:148 offset1:214
	s_waitcnt vmcnt(0)
	ds_write2_b32 v13, v40, v41 offset0:24 offset1:90
	s_lshl_b64 s[10:11], s[40:41], 11
	s_waitcnt lgkmcnt(0)
	s_add_u32 s8, s8, s10
	ds_read2_b32 v[18:19], v35 offset0:33 offset1:41
	ds_read2_b32 v[20:21], v35 offset1:8
	ds_read2_b32 v[22:23], v35 offset0:66 offset1:74
	ds_read2_b32 v[24:25], v35 offset0:99 offset1:107
	ds_read2_b32 v[26:27], v35 offset0:132 offset1:140
	ds_read2_b32 v[28:29], v35 offset0:165 offset1:173
	ds_read2_b32 v[30:31], v35 offset0:198 offset1:206
	ds_read2_b32 v[32:33], v35 offset0:231 offset1:239
	s_addc_u32 s10, s39, s11
	s_lshl_b64 s[4:5], s[4:5], 1
	s_add_u32 s4, s8, s4
	s_addc_u32 s5, s10, s5
	v_lshlrev_b32_e32 v196, 1, v0
	v_lshl_add_u64 v[36:37], s[4:5], 0, v[196:197]
	v_lshlrev_b32_e32 v196, 1, v2
	s_waitcnt lgkmcnt(6)
	v_cvt_pk_bf16_f32 v14, v20, v18
	s_waitcnt lgkmcnt(4)
	v_cvt_pk_bf16_f32 v15, v22, v24
	s_waitcnt lgkmcnt(2)
	v_cvt_pk_bf16_f32 v16, v26, v28
	s_waitcnt lgkmcnt(0)
	v_cvt_pk_bf16_f32 v17, v30, v32
	v_lshl_add_u64 v[38:39], v[36:37], 0, v[196:197]
	global_store_dwordx4 v[38:39], v[14:17], off sc1
	v_lshlrev_b32_e32 v196, 1, v4
	s_nop 0
	v_cvt_pk_bf16_f32 v14, v21, v19
	v_cvt_pk_bf16_f32 v15, v23, v25
	v_cvt_pk_bf16_f32 v16, v27, v29
	v_cvt_pk_bf16_f32 v17, v31, v33
	ds_read2_b32 v[20:21], v35 offset0:49 offset1:57
	ds_read2_b32 v[22:23], v35 offset0:16 offset1:24
	ds_read2_b32 v[24:25], v35 offset0:82 offset1:90
	ds_read2_b32 v[26:27], v35 offset0:115 offset1:123
	ds_read2_b32 v[28:29], v35 offset0:148 offset1:156
	ds_read2_b32 v[30:31], v35 offset0:181 offset1:189
	ds_read2_b32 v[32:33], v35 offset0:214 offset1:222
	ds_read2_b32 v[38:39], v35 offset0:247 offset1:255
	v_lshl_add_u64 v[18:19], v[36:37], 0, v[196:197]
	v_lshlrev_b32_e32 v196, 1, v6
	global_store_dwordx4 v[18:19], v[14:17], off sc1
	v_lshl_add_u64 v[18:19], v[36:37], 0, v[196:197]
	v_lshlrev_b32_e32 v196, 1, v8
	s_waitcnt lgkmcnt(6)
	v_cvt_pk_bf16_f32 v14, v22, v20
	s_waitcnt lgkmcnt(4)
	v_cvt_pk_bf16_f32 v15, v24, v26
	s_waitcnt lgkmcnt(2)
	v_cvt_pk_bf16_f32 v16, v28, v30
	s_waitcnt lgkmcnt(0)
	v_cvt_pk_bf16_f32 v17, v32, v38
	global_store_dwordx4 v[18:19], v[14:17], off sc1
	v_lshl_add_u64 v[18:19], v[36:37], 0, v[196:197]
	s_nop 0
	v_cvt_pk_bf16_f32 v14, v23, v21
	v_cvt_pk_bf16_f32 v15, v25, v27
	v_cvt_pk_bf16_f32 v16, v29, v31
	v_cvt_pk_bf16_f32 v17, v33, v39
	global_store_dwordx4 v[18:19], v[14:17], off sc1
	s_waitcnt lgkmcnt(0)

; #define LAS __attribute__((address_space(3)))
; __device__ __forceinline__ void transpose_tile(const float* src, int srcN, const float* gk, bf16_t* dst, int dstK, LAS float* scr, int lane) {
;     float tv[32];
; #pragma unroll
;     for (int i = 0; i < 32; ++i) tv[i] = src[(size_t)(2 * i + (lane >> 5)) * srcN + (lane & 31)];
;     if (gk) {
; #pragma unroll
;         for (int i = 0; i < 32; ++i) tv[i] *= gk[2 * i + (lane >> 5)];
;     }
; #pragma unroll
;     for (int i = 0; i < 32; ++i) scr[(2 * i + (lane >> 5)) * 33 + (lane & 31)] = tv[i];
; __device__ __forceinline__ void convert_layer(const Params& p, int l, LAS unsigned char* lds, int it_lo, int it_hi, int worker, int nworkers) {
;     ...
;         int r = it;
;         if (r < 2 * I_GU) {
;             const int f = r / I_GU; r -= f * I_GU; const int nb = r / (DM / 64), kb = r % (DM / 64), n0 = nb * 32, k0 = kb * 64;
;             const int pn = n0 >> 8, w = n0 & 255; const float* src = ((w < 128) ? p.ffn_w_gate : p.ffn_w_up) + (size_t)(l * 2 + f) * DM * DFF;
;             transpose_tile(src + (size_t)k0 * DFF + pn * 128 + (w & 127), DFF, ng + (f ? 2 : 0) * DM + k0, W + (f ? O_WGU1 : O_WGU0) + (size_t)n0 * DM + k0, DM, scr, lane); continue; }
;         r -= 2 * I_GU;
;         if (r < 2 * I_D) {
;             const int f = r / I_D; r -= f * I_D; const int nb = r / (DFF / 64), kb = r % (DFF / 64), n0 = nb * 32, k0 = kb * 64;
;             const float* src = p.ffn_w_down + (size_t)(l * 2 + f) * DFF * DM;
;             transpose_tile(src + (size_t)k0 * DM + n0, DM, nullptr, W + (f ? O_WD1 : O_WD0) + (size_t)n0 * DFF + k0, DFF, scr, lane); continue; }
;         r -= 2 * I_D;
;         if (r < I_ING) {
;             const int nb = r / (DM / 64), kb = r % (DM / 64), n0 = nb * 32, k0 = kb * 64;
;             if (n0 < NPROJ) transpose_tile(p.w_in + (size_t)l * DM * NPROJ + (size_t)k0 * NPROJ + n0, NPROJ, ng + DM + k0, W + O_WING + (size_t)n0 * DM + k0, DM, scr, lane);
;             else transpose_tile(p.w_gate + (size_t)l * DM * NGATE + (size_t)k0 * NGATE + (n0 - NPROJ), NGATE, ng + DM + k0, W + O_WING + (size_t)n0 * DM + k0, DM, scr, lane);
;             continue; }
.LBB0_636:
	s_cmpk_gt_i32 s13, 0x15ff
	s_mov_b64 s[4:5], -1
	s_cbranch_scc0 .LBB0_646
	s_cmpk_gt_u32 s13, 0x20ff
	s_cbranch_scc0 .LBB0_643
	s_and_b32 s11, s23, 0x7fe0
	s_add_i32 s8, s11, 0xffffbe00
	s_and_b32 s10, s38, 0x3c0
	s_cmpk_gt_u32 s8, 0xeff
	s_cbranch_scc0 .LBB0_640
	s_mul_i32 s4, s10, 0x3000
	s_add_u32 s4, s19, s4
	s_addc_u32 s5, s20, 0
	s_lshl_b32 s11, s11, 2
	s_add_u32 s4, s4, s11
	s_addc_u32 s5, s5, 0
	s_add_u32 s40, s4, 0xfffebc00
	s_addc_u32 s41, s5, -1
	s_lshl_b64 s[4:5], s[8:9], 11
	s_add_u32 s4, s16, s4
	s_addc_u32 s5, s17, s5
	s_lshl_b32 s11, s10, 1
	s_add_u32 s4, s4, s11
	s_addc_u32 s5, s5, 0
	global_load_dword v13, v49, s[40:41]
	global_load_dword v16, v51, s[40:41]
	global_load_dword v17, v53, s[40:41]
	global_load_dword v18, v55, s[40:41]
	global_load_dword v19, v57, s[40:41]
	global_load_dword v20, v59, s[40:41]
	global_load_dword v21, v61, s[40:41]
	global_load_dword v22, v63, s[40:41]
	global_load_dword v23, v65, s[40:41]
	global_load_dword v24, v67, s[40:41]
	global_load_dword v25, v69, s[40:41]
	global_load_dword v26, v71, s[40:41]
	global_load_dword v27, v73, s[40:41]
	global_load_dword v28, v75, s[40:41]
	global_load_dword v29, v77, s[40:41]
	global_load_dword v30, v79, s[40:41]
	global_load_dword v31, v235, s[40:41]
	global_load_dword v32, v177, s[40:41]
	global_load_dword v33, v231, s[40:41]
	global_load_dword v36, v179, s[40:41]
	global_load_dword v37, v85, s[40:41]
	global_load_dword v38, v181, s[40:41]
	global_load_dword v39, v87, s[40:41]
	global_load_dword v40, v183, s[40:41]
	global_load_dword v41, v89, s[40:41]
	global_load_dword v42, v185, s[40:41]
	global_load_dword v43, v91, s[40:41]
	global_load_dword v44, v187, s[40:41]
	global_load_dword v45, v93, s[40:41]
	global_load_dword v46, v189, s[40:41]
	global_load_dword v47, v95, s[40:41]
	global_load_dword v80, v191, s[40:41]
	s_lshl_b32 s40, s10, 2
	s_mov_b32 s41, s9
	v_lshl_add_u64 v[14:15], v[10:11], 0, s[40:41]
	global_load_dword v81, v[14:15], off
	v_lshlrev_b32_e32 v196, 1, v0
	s_waitcnt vmcnt(0)
	v_mul_f32_e32 v13, v13, v81
	global_load_dword v81, v[14:15], off offset:8
	s_waitcnt vmcnt(0)
	v_mul_f32_e32 v16, v16, v81
	global_load_dword v81, v[14:15], off offset:16
	s_waitcnt vmcnt(0)
	v_mul_f32_e32 v17, v17, v81
	global_load_dword v81, v[14:15], off offset:24
	s_waitcnt vmcnt(0)
	v_mul_f32_e32 v18, v18, v81
	global_load_dword v81, v[14:15], off offset:32
	s_waitcnt vmcnt(0)
	v_mul_f32_e32 v19, v19, v81
	global_load_dword v81, v[14:15], off offset:40
	s_waitcnt vmcnt(0)
	v_mul_f32_e32 v20, v20, v81
	global_load_dword v81, v[14:15], off offset:48
	s_waitcnt vmcnt(0)
	v_mul_f32_e32 v21, v21, v81
	global_load_dword v81, v[14:15], off offset:56
	s_waitcnt vmcnt(0)
	v_mul_f32_e32 v22, v22, v81
	global_load_dword v81, v[14:15], off offset:64
	s_waitcnt vmcnt(0)
	v_mul_f32_e32 v23, v23, v81
	global_load_dword v81, v[14:15], off offset:72
	s_waitcnt vmcnt(0)
	v_mul_f32_e32 v24, v24, v81
	global_load_dword v81, v[14:15], off offset:80
	s_waitcnt vmcnt(0)
	v_mul_f32_e32 v25, v25, v81
	global_load_dword v81, v[14:15], off offset:88
	s_waitcnt vmcnt(0)
	v_mul_f32_e32 v26, v26, v81
	global_load_dword v81, v[14:15], off offset:96
	s_waitcnt vmcnt(0)
	v_mul_f32_e32 v27, v27, v81
	global_load_dword v81, v[14:15], off offset:104
	s_waitcnt vmcnt(0)
	v_mul_f32_e32 v28, v28, v81
	global_load_dword v81, v[14:15], off offset:112
	s_waitcnt vmcnt(0)
	v_mul_f32_e32 v29, v29, v81
	global_load_dword v81, v[14:15], off offset:120
	s_waitcnt vmcnt(0)
	v_mul_f32_e32 v30, v30, v81
	global_load_dword v81, v[14:15], off offset:128
	s_waitcnt vmcnt(0)
	v_mul_f32_e32 v31, v31, v81
	global_load_dword v81, v[14:15], off offset:136
	s_waitcnt vmcnt(0)
	v_mul_f32_e32 v32, v32, v81
	global_load_dword v81, v[14:15], off offset:144
	s_waitcnt vmcnt(0)
	v_mul_f32_e32 v33, v33, v81
	global_load_dword v81, v[14:15], off offset:152
	s_waitcnt vmcnt(0)
	v_mul_f32_e32 v36, v36, v81
	global_load_dword v81, v[14:15], off offset:160
	s_waitcnt vmcnt(0)
	v_mul_f32_e32 v37, v37, v81
	global_load_dword v81, v[14:15], off offset:168
	s_waitcnt vmcnt(0)
	v_mul_f32_e32 v38, v38, v81
	global_load_dword v81, v[14:15], off offset:176
	s_waitcnt vmcnt(0)
	v_mul_f32_e32 v39, v39, v81
	global_load_dword v81, v[14:15], off offset:184
	s_waitcnt vmcnt(0)
	v_mul_f32_e32 v40, v40, v81
	global_load_dword v81, v[14:15], off offset:192
	s_waitcnt vmcnt(0)
	v_mul_f32_e32 v41, v41, v81
	global_load_dword v81, v[14:15], off offset:200
	s_waitcnt vmcnt(0)
	v_mul_f32_e32 v42, v42, v81
	global_load_dword v81, v[14:15], off offset:208
	s_waitcnt vmcnt(0)
	v_mul_f32_e32 v43, v43, v81
	global_load_dword v81, v[14:15], off offset:216
	s_waitcnt vmcnt(0)
	v_mul_f32_e32 v44, v44, v81
	global_load_dword v81, v[14:15], off offset:224
	s_waitcnt vmcnt(0)
	v_mul_f32_e32 v45, v45, v81
	global_load_dword v81, v[14:15], off offset:232
	s_waitcnt vmcnt(0)
	v_mul_f32_e32 v46, v46, v81
	global_load_dword v81, v[14:15], off offset:240
	s_waitcnt vmcnt(0)
	v_mul_f32_e32 v47, v47, v81
	global_load_dword v14, v[14:15], off offset:248
	v_add_u32_e32 v15, v1, v3
	ds_write2_b32 v15, v13, v16 offset1:66
	ds_write2_b32 v15, v17, v18 offset0:132 offset1:198
	v_add_u32_e32 v13, 0x400, v15
	ds_write2_b32 v13, v19, v20 offset0:8 offset1:74
	v_add_u32_e32 v13, v1, v5
	ds_write2_b32 v13, v21, v22 offset1:66
	ds_write2_b32 v13, v23, v24 offset0:132 offset1:198
	v_add_u32_e32 v13, 0x400, v13
	ds_write2_b32 v13, v25, v26 offset0:8 offset1:74
	v_add_u32_e32 v13, v1, v7
	ds_write2_b32 v13, v27, v28 offset1:66
	ds_write2_b32 v13, v29, v30 offset0:132 offset1:198
	v_add_u32_e32 v13, 0x400, v13
	ds_write2_b32 v13, v31, v32 offset0:8 offset1:74
	v_add_u32_e32 v13, v1, v9
	v_add_u32_e32 v15, 0x400, v13
	ds_write2_b32 v13, v33, v36 offset1:66
	ds_write2_b32 v13, v37, v38 offset0:132 offset1:198
	ds_write2_b32 v15, v39, v40 offset0:8 offset1:74
	ds_write2_b32 v15, v41, v42 offset0:140 offset1:206
	v_add_u32_e32 v15, 0x800, v13
	v_add_u32_e32 v13, 0xc00, v13
	ds_write2_b32 v15, v43, v44 offset0:16 offset1:82
	ds_write2_b32 v15, v45, v46 offset0:148 offset1:214
	v_lshl_add_u64 v[18:19], s[4:5], 0, v[196:197]
	v_lshlrev_b32_e32 v196, 1, v2
	v_lshl_add_u64 v[38:39], v[18:19], 0, v[196:197]
	v_lshlrev_b32_e32 v196, 1, v4
	s_mov_b64 s[4:5], 0
	s_waitcnt vmcnt(0)
; #define LAS __attribute__((address_space(3)))
; __device__ __forceinline__ unsigned pk2(float lo, float hi) { return pg8::cvt_pk_bf16(lo, hi); }
; __device__ __forceinline__ void transpose_tile(const float* src, int srcN, const float* gk, bf16_t* dst, int dstK, LAS float* scr, int lane) {
;     ...
;     asm volatile("s_waitcnt lgkmcnt(0)" ::: "memory");
;     const int c = lane & 7;
; #pragma unroll
;     for (int j = 0; j < 4; ++j) {
;         const int n = (lane >> 3) + 8 * j; const LAS float* s = scr + (8 * c) * 33 + n;
;         u32x4 o; o.x = pk2(s[0 * 33], s[1 * 33]); o.y = pk2(s[2 * 33], s[3 * 33]); o.z = pk2(s[4 * 33], s[5 * 33]); o.w = pk2(s[6 * 33], s[7 * 33]);
;         *(u32x4*)(dst + (size_t)n * dstK + 8 * c) = o;
;     }
;     asm volatile("s_waitcnt lgkmcnt(0)" ::: "memory");
; }
; __device__ __forceinline__ void convert_layer(const Params& p, int l, LAS unsigned char* lds, int it_lo, int it_hi, int worker, int nworkers) {
;     ...
;         if (r < I_ING) {
;             const int nb = r / (DM / 64), kb = r % (DM / 64), n0 = nb * 32, k0 = kb * 64;
;             if (n0 < NPROJ) transpose_tile(p.w_in + (size_t)l * DM * NPROJ + (size_t)k0 * NPROJ + n0, NPROJ, ng + DM + k0, W + O_WING + (size_t)n0 * DM + k0, DM, scr, lane);
;             else transpose_tile(p.w_gate + (size_t)l * DM * NGATE + (size_t)k0 * NGATE + (n0 - NPROJ), NGATE, ng + DM + k0, W + O_WING + (size_t)n0 * DM + k0, DM, scr, lane);
;             continue; }
	v_mul_f32_e32 v14, v80, v14
	ds_write2_b32 v13, v47, v14 offset0:24 offset1:90
	s_waitcnt lgkmcnt(0)
	ds_read2_b32 v[20:21], v35 offset0:33 offset1:41
	ds_read2_b32 v[22:23], v35 offset1:8
	ds_read2_b32 v[24:25], v35 offset0:66 offset1:74
	ds_read2_b32 v[26:27], v35 offset0:99 offset1:107
	ds_read2_b32 v[28:29], v35 offset0:132 offset1:140
	ds_read2_b32 v[30:31], v35 offset0:165 offset1:173
	ds_read2_b32 v[32:33], v35 offset0:198 offset1:206
	ds_read2_b32 v[36:37], v35 offset0:231 offset1:239
	s_waitcnt lgkmcnt(6)
	v_cvt_pk_bf16_f32 v14, v22, v20
	s_waitcnt lgkmcnt(4)
	v_cvt_pk_bf16_f32 v15, v24, v26
	s_waitcnt lgkmcnt(2)
	v_cvt_pk_bf16_f32 v16, v28, v30
	s_waitcnt lgkmcnt(0)
	v_cvt_pk_bf16_f32 v17, v32, v36
	global_store_dwordx4 v[38:39], v[14:17], off sc1
	s_nop 1
	v_cvt_pk_bf16_f32 v14, v23, v21
	v_cvt_pk_bf16_f32 v15, v25, v27
	v_cvt_pk_bf16_f32 v16, v29, v31
	v_cvt_pk_bf16_f32 v17, v33, v37
	v_lshl_add_u64 v[20:21], v[18:19], 0, v[196:197]
	global_store_dwordx4 v[20:21], v[14:17], off sc1
	ds_read2_b32 v[20:21], v35 offset0:49 offset1:57
	ds_read2_b32 v[22:23], v35 offset0:16 offset1:24
	ds_read2_b32 v[24:25], v35 offset0:82 offset1:90
	ds_read2_b32 v[26:27], v35 offset0:115 offset1:123
	ds_read2_b32 v[28:29], v35 offset0:148 offset1:156
	ds_read2_b32 v[30:31], v35 offset0:181 offset1:189
	ds_read2_b32 v[32:33], v35 offset0:214 offset1:222
	ds_read2_b32 v[36:37], v35 offset0:247 offset1:255
	v_lshlrev_b32_e32 v196, 1, v6
	s_waitcnt lgkmcnt(6)
	v_cvt_pk_bf16_f32 v14, v22, v20
	s_waitcnt lgkmcnt(4)
	v_cvt_pk_bf16_f32 v15, v24, v26
	s_waitcnt lgkmcnt(2)
	v_cvt_pk_bf16_f32 v16, v28, v30
	s_waitcnt lgkmcnt(0)
	v_cvt_pk_bf16_f32 v17, v32, v36
	v_lshl_add_u64 v[38:39], v[18:19], 0, v[196:197]
	v_lshlrev_b32_e32 v196, 1, v8
	global_store_dwordx4 v[38:39], v[14:17], off sc1
	v_lshl_add_u64 v[18:19], v[18:19], 0, v[196:197]
	s_nop 0
	v_cvt_pk_bf16_f32 v14, v23, v21
	v_cvt_pk_bf16_f32 v15, v25, v27
	v_cvt_pk_bf16_f32 v16, v29, v31
	v_cvt_pk_bf16_f32 v17, v33, v37
	global_store_dwordx4 v[18:19], v[14:17], off sc1
	s_waitcnt lgkmcnt(0)
.LBB0_640:
	s_andn2_b64 vcc, exec, s[4:5]
	s_cbranch_vccnz .LBB0_642
	s_mul_i32 s4, s10, 0x3c00
	s_add_u32 s11, s21, s4
	s_addc_u32 s39, s22, 0
	s_lshl_b64 s[4:5], s[8:9], 2
	s_add_u32 s40, s11, s4
	s_addc_u32 s41, s39, s5
	s_lshl_b64 s[4:5], s[8:9], 11
	s_add_u32 s4, s16, s4
	s_addc_u32 s5, s17, s5
	s_lshl_b32 s8, s10, 1
	s_add_u32 s4, s4, s8
	s_addc_u32 s5, s5, 0
	s_lshl_b32 s8, s10, 2
	v_lshl_add_u64 v[14:15], v[10:11], 0, s[8:9]
	global_load_dword v13, v97, s[40:41]
	global_load_dword v16, v193, s[40:41]
	global_load_dword v17, v99, s[40:41]
	global_load_dword v18, v195, s[40:41]
	global_load_dword v19, v101, s[40:41]
	global_load_dword v20, v203, s[40:41]
	global_load_dword v21, v103, s[40:41]
	global_load_dword v22, v205, s[40:41]
	global_load_dword v23, v105, s[40:41]
	global_load_dword v24, v207, s[40:41]
	global_load_dword v25, v107, s[40:41]
	global_load_dword v26, v209, s[40:41]
	global_load_dword v27, v109, s[40:41]
	global_load_dword v28, v211, s[40:41]
	global_load_dword v29, v111, s[40:41]
	global_load_dword v30, v213, s[40:41]
	global_load_dword v31, v112, s[40:41]
	global_load_dword v32, v113, s[40:41]
	global_load_dword v33, v114, s[40:41]
	global_load_dword v36, v115, s[40:41]
	global_load_dword v37, v116, s[40:41]
	global_load_dword v38, v117, s[40:41]
	global_load_dword v39, v118, s[40:41]
	global_load_dword v40, v119, s[40:41]
	global_load_dword v41, v120, s[40:41]
	global_load_dword v42, v121, s[40:41]
	global_load_dword v43, v122, s[40:41]
	global_load_dword v44, v123, s[40:41]
	global_load_dword v45, v124, s[40:41]
	global_load_dword v46, v125, s[40:41]
	global_load_dword v47, v126, s[40:41]
	global_load_dword v80, v127, s[40:41]
	global_load_dword v81, v[14:15], off
	v_lshlrev_b32_e32 v196, 1, v0
	s_waitcnt vmcnt(0)
	v_mul_f32_e32 v13, v13, v81
	global_load_dword v81, v[14:15], off offset:8
	s_waitcnt vmcnt(0)
	v_mul_f32_e32 v16, v16, v81
	global_load_dword v81, v[14:15], off offset:16
	s_waitcnt vmcnt(0)
	v_mul_f32_e32 v17, v17, v81
	global_load_dword v81, v[14:15], off offset:24
	s_waitcnt vmcnt(0)
	v_mul_f32_e32 v18, v18, v81
	global_load_dword v81, v[14:15], off offset:32
	s_waitcnt vmcnt(0)
	v_mul_f32_e32 v19, v19, v81
	global_load_dword v81, v[14:15], off offset:40
	s_waitcnt vmcnt(0)
	v_mul_f32_e32 v20, v20, v81
	global_load_dword v81, v[14:15], off offset:48
	s_waitcnt vmcnt(0)
	v_mul_f32_e32 v21, v21, v81
	global_load_dword v81, v[14:15], off offset:56
	s_waitcnt vmcnt(0)
	v_mul_f32_e32 v22, v22, v81
	global_load_dword v81, v[14:15], off offset:64
	s_waitcnt vmcnt(0)
	v_mul_f32_e32 v23, v23, v81
	global_load_dword v81, v[14:15], off offset:72
	s_waitcnt vmcnt(0)
	v_mul_f32_e32 v24, v24, v81
	global_load_dword v81, v[14:15], off offset:80
	s_waitcnt vmcnt(0)
	v_mul_f32_e32 v25, v25, v81
	global_load_dword v81, v[14:15], off offset:88
	s_waitcnt vmcnt(0)
	v_mul_f32_e32 v26, v26, v81
	global_load_dword v81, v[14:15], off offset:96
	s_waitcnt vmcnt(0)
	v_mul_f32_e32 v27, v27, v81
	global_load_dword v81, v[14:15], off offset:104
	s_waitcnt vmcnt(0)
; #define LAS __attribute__((address_space(3)))
; __device__ __forceinline__ unsigned pk2(float lo, float hi) { return pg8::cvt_pk_bf16(lo, hi); }
; __device__ __forceinline__ void transpose_tile(const float* src, int srcN, const float* gk, bf16_t* dst, int dstK, LAS float* scr, int lane) {
;     float tv[32];
; #pragma unroll
;     for (int i = 0; i < 32; ++i) tv[i] = src[(size_t)(2 * i + (lane >> 5)) * srcN + (lane & 31)];
;     if (gk) {
; #pragma unroll
;         for (int i = 0; i < 32; ++i) tv[i] *= gk[2 * i + (lane >> 5)];
;     }
; #pragma unroll
;     for (int i = 0; i < 32; ++i) scr[(2 * i + (lane >> 5)) * 33 + (lane & 31)] = tv[i];
;     asm volatile("s_waitcnt lgkmcnt(0)" ::: "memory");
;     const int c = lane & 7;
; #pragma unroll
;     for (int j = 0; j < 4; ++j) {
;         const int n = (lane >> 3) + 8 * j; const LAS float* s = scr + (8 * c) * 33 + n;
;         u32x4 o; o.x = pk2(s[0 * 33], s[1 * 33]); o.y = pk2(s[2 * 33], s[3 * 33]); o.z = pk2(s[4 * 33], s[5 * 33]); o.w = pk2(s[6 * 33], s[7 * 33]);
;         *(u32x4*)(dst + (size_t)n * dstK + 8 * c) = o;
;     }
;     asm volatile("s_waitcnt lgkmcnt(0)" ::: "memory");
; }
; __device__ __forceinline__ void convert_layer(const Params& p, int l, LAS unsigned char* lds, int it_lo, int it_hi, int worker, int nworkers) {
;     ...
;         if (r < I_ING) {
;             const int nb = r / (DM / 64), kb = r % (DM / 64), n0 = nb * 32, k0 = kb * 64;
;             if (n0 < NPROJ) transpose_tile(p.w_in + (size_t)l * DM * NPROJ + (size_t)k0 * NPROJ + n0, NPROJ, ng + DM + k0, W + O_WING + (size_t)n0 * DM + k0, DM, scr, lane);
;             else transpose_tile(p.w_gate + (size_t)l * DM * NGATE + (size_t)k0 * NGATE + (n0 - NPROJ), NGATE, ng + DM + k0, W + O_WING + (size_t)n0 * DM + k0, DM, scr, lane);
;             continue; }
	v_mul_f32_e32 v28, v28, v81
	global_load_dword v81, v[14:15], off offset:112
	s_waitcnt vmcnt(0)
	v_mul_f32_e32 v29, v29, v81
	global_load_dword v81, v[14:15], off offset:120
	s_waitcnt vmcnt(0)
	v_mul_f32_e32 v30, v30, v81
	global_load_dword v81, v[14:15], off offset:128
	s_waitcnt vmcnt(0)
	v_mul_f32_e32 v31, v31, v81
	global_load_dword v81, v[14:15], off offset:136
	s_waitcnt vmcnt(0)
	v_mul_f32_e32 v32, v32, v81
	global_load_dword v81, v[14:15], off offset:144
	s_waitcnt vmcnt(0)
	v_mul_f32_e32 v33, v33, v81
	global_load_dword v81, v[14:15], off offset:152
	s_waitcnt vmcnt(0)
	v_mul_f32_e32 v36, v36, v81
	global_load_dword v81, v[14:15], off offset:160
	s_waitcnt vmcnt(0)
	v_mul_f32_e32 v37, v37, v81
	global_load_dword v81, v[14:15], off offset:168
	s_waitcnt vmcnt(0)
	v_mul_f32_e32 v38, v38, v81
	global_load_dword v81, v[14:15], off offset:176
	s_waitcnt vmcnt(0)
	v_mul_f32_e32 v39, v39, v81
	global_load_dword v81, v[14:15], off offset:184
	s_waitcnt vmcnt(0)
	v_mul_f32_e32 v40, v40, v81
	global_load_dword v81, v[14:15], off offset:192
	s_waitcnt vmcnt(0)
	v_mul_f32_e32 v41, v41, v81
	global_load_dword v81, v[14:15], off offset:200
	s_waitcnt vmcnt(0)
	v_mul_f32_e32 v42, v42, v81
	global_load_dword v81, v[14:15], off offset:208
	s_waitcnt vmcnt(0)
	v_mul_f32_e32 v43, v43, v81
	global_load_dword v81, v[14:15], off offset:216
	s_waitcnt vmcnt(0)
	v_mul_f32_e32 v44, v44, v81
	global_load_dword v81, v[14:15], off offset:224
	s_waitcnt vmcnt(0)
	v_mul_f32_e32 v45, v45, v81
	global_load_dword v81, v[14:15], off offset:232
	s_waitcnt vmcnt(0)
	v_mul_f32_e32 v46, v46, v81
	global_load_dword v81, v[14:15], off offset:240
	s_waitcnt vmcnt(0)
	v_mul_f32_e32 v47, v47, v81
	global_load_dword v14, v[14:15], off offset:248
	v_add_u32_e32 v15, v1, v3
	ds_write2_b32 v15, v13, v16 offset1:66
	ds_write2_b32 v15, v17, v18 offset0:132 offset1:198
	v_add_u32_e32 v13, 0x400, v15
	ds_write2_b32 v13, v19, v20 offset0:8 offset1:74
	v_add_u32_e32 v13, v1, v5
	ds_write2_b32 v13, v21, v22 offset1:66
	ds_write2_b32 v13, v23, v24 offset0:132 offset1:198
	v_add_u32_e32 v13, 0x400, v13
	ds_write2_b32 v13, v25, v26 offset0:8 offset1:74
	v_add_u32_e32 v13, v1, v7
	ds_write2_b32 v13, v27, v28 offset1:66
	ds_write2_b32 v13, v29, v30 offset0:132 offset1:198
	v_add_u32_e32 v13, 0x400, v13
	ds_write2_b32 v13, v31, v32 offset0:8 offset1:74
	v_add_u32_e32 v13, v1, v9
	v_add_u32_e32 v15, 0x400, v13
	ds_write2_b32 v13, v33, v36 offset1:66
	ds_write2_b32 v13, v37, v38 offset0:132 offset1:198
	ds_write2_b32 v15, v39, v40 offset0:8 offset1:74
	ds_write2_b32 v15, v41, v42 offset0:140 offset1:206
	v_add_u32_e32 v15, 0x800, v13
	v_add_u32_e32 v13, 0xc00, v13
	ds_write2_b32 v15, v43, v44 offset0:16 offset1:82
	ds_write2_b32 v15, v45, v46 offset0:148 offset1:214
	v_lshl_add_u64 v[18:19], s[4:5], 0, v[196:197]
	v_lshlrev_b32_e32 v196, 1, v2
	v_lshl_add_u64 v[38:39], v[18:19], 0, v[196:197]
	v_lshlrev_b32_e32 v196, 1, v4
	s_waitcnt vmcnt(0)
	v_mul_f32_e32 v14, v80, v14
	ds_write2_b32 v13, v47, v14 offset0:24 offset1:90
	s_waitcnt lgkmcnt(0)
	ds_read2_b32 v[20:21], v35 offset0:33 offset1:41
	ds_read2_b32 v[22:23], v35 offset1:8
	ds_read2_b32 v[24:25], v35 offset0:66 offset1:74
	ds_read2_b32 v[26:27], v35 offset0:99 offset1:107
	ds_read2_b32 v[28:29], v35 offset0:132 offset1:140
	ds_read2_b32 v[30:31], v35 offset0:165 offset1:173
	ds_read2_b32 v[32:33], v35 offset0:198 offset1:206
	ds_read2_b32 v[36:37], v35 offset0:231 offset1:239
	s_waitcnt lgkmcnt(6)
	v_cvt_pk_bf16_f32 v14, v22, v20
	s_waitcnt lgkmcnt(4)
	v_cvt_pk_bf16_f32 v15, v24, v26
	s_waitcnt lgkmcnt(2)
	v_cvt_pk_bf16_f32 v16, v28, v30
	s_waitcnt lgkmcnt(0)
	v_cvt_pk_bf16_f32 v17, v32, v36
	global_store_dwordx4 v[38:39], v[14:17], off sc1
	s_nop 1
	v_cvt_pk_bf16_f32 v14, v23, v21
	v_cvt_pk_bf16_f32 v15, v25, v27
	v_cvt_pk_bf16_f32 v16, v29, v31
	v_cvt_pk_bf16_f32 v17, v33, v37
	v_lshl_add_u64 v[20:21], v[18:19], 0, v[196:197]
	global_store_dwordx4 v[20:21], v[14:17], off sc1
	ds_read2_b32 v[20:21], v35 offset0:49 offset1:57
	ds_read2_b32 v[22:23], v35 offset0:16 offset1:24
	ds_read2_b32 v[24:25], v35 offset0:82 offset1:90
	ds_read2_b32 v[26:27], v35 offset0:115 offset1:123
	ds_read2_b32 v[28:29], v35 offset0:148 offset1:156
	ds_read2_b32 v[30:31], v35 offset0:181 offset1:189
	ds_read2_b32 v[32:33], v35 offset0:214 offset1:222
	ds_read2_b32 v[36:37], v35 offset0:247 offset1:255
	v_lshlrev_b32_e32 v196, 1, v6
	s_waitcnt lgkmcnt(6)
	v_cvt_pk_bf16_f32 v14, v22, v20
	s_waitcnt lgkmcnt(4)
	v_cvt_pk_bf16_f32 v15, v24, v26
	s_waitcnt lgkmcnt(2)
	v_cvt_pk_bf16_f32 v16, v28, v30
	s_waitcnt lgkmcnt(0)
	v_cvt_pk_bf16_f32 v17, v32, v36
	v_lshl_add_u64 v[38:39], v[18:19], 0, v[196:197]
	v_lshlrev_b32_e32 v196, 1, v8
	global_store_dwordx4 v[38:39], v[14:17], off sc1
	v_lshl_add_u64 v[18:19], v[18:19], 0, v[196:197]
	s_nop 0
	v_cvt_pk_bf16_f32 v14, v23, v21
	v_cvt_pk_bf16_f32 v15, v25, v27
	v_cvt_pk_bf16_f32 v16, v29, v31
	v_cvt_pk_bf16_f32 v17, v33, v37
	global_store_dwordx4 v[18:19], v[14:17], off sc1
	s_waitcnt lgkmcnt(0)

; #define LAS __attribute__((address_space(3)))
; __device__ __forceinline__ unsigned pk2(float lo, float hi) { return pg8::cvt_pk_bf16(lo, hi); }
; __device__ __forceinline__ void transpose_tile(const float* src, int srcN, const float* gk, bf16_t* dst, int dstK, LAS float* scr, int lane) {
;     ...
;     asm volatile("s_waitcnt lgkmcnt(0)" ::: "memory");
;     const int c = lane & 7;
; #pragma unroll
;     for (int j = 0; j < 4; ++j) {
;         const int n = (lane >> 3) + 8 * j; const LAS float* s = scr + (8 * c) * 33 + n;
;         u32x4 o; o.x = pk2(s[0 * 33], s[1 * 33]); o.y = pk2(s[2 * 33], s[3 * 33]); o.z = pk2(s[4 * 33], s[5 * 33]); o.w = pk2(s[6 * 33], s[7 * 33]);
;         *(u32x4*)(dst + (size_t)n * dstK + 8 * c) = o;
;     }
;     asm volatile("s_waitcnt lgkmcnt(0)" ::: "memory");
; }
; __device__ __forceinline__ void convert_layer(const Params& p, int l, LAS unsigned char* lds, int it_lo, int it_hi, int worker, int nworkers) {
;     ...
;         if (r < 2 * I_D) {
;             const int f = r / I_D; r -= f * I_D; const int nb = r / (DFF / 64), kb = r % (DFF / 64), n0 = nb * 32, k0 = kb * 64;
;             const float* src = p.ffn_w_down + (size_t)(l * 2 + f) * DFF * DM;
;             transpose_tile(src + (size_t)k0 * DM + n0, DM, nullptr, W + (f ? O_WD1 : O_WD0) + (size_t)n0 * DFF + k0, DFF, scr, lane); continue; }
.LBB0_643:
	s_andn2_b64 vcc, exec, s[4:5]
	s_cbranch_vccnz .LBB0_645
	s_add_i32 s8, s13, 0xffffea00
	s_cmpk_gt_u32 s8, 0x57f
	s_cselect_b64 s[4:5], -1, 0
	v_cndmask_b32_e64 v13, 0, 1, s[4:5]
	s_and_b64 s[4:5], s[4:5], exec
	s_cselect_b32 s4, 0xfa80, 0
	s_add_i32 s4, s8, s4
	s_sext_i32_i16 s5, s4
	s_mulk_i32 s5, 0xba3
	s_lshr_b32 s10, s5, 31
	s_ashr_i32 s5, s5, 17
	s_add_i32 s39, s5, s10
	s_mul_i32 s5, s39, 44
	s_sub_i32 s4, s4, s5
	s_sext_i32_i16 s5, s4
	s_lshl_b32 s10, s5, 6
	v_readfirstlane_b32 s5, v13
	s_or_b32 s5, s18, s5
	v_readlane_b32 s40, v254, 57
	s_lshl_b32 s4, s39, 5
	s_mul_hi_i32 s11, s5, 0xb00000
	s_mul_i32 s5, s5, 0xb00000
	v_readlane_b32 s44, v254, 61
	v_readlane_b32 s42, v254, 59
	v_readlane_b32 s45, v254, 62
	s_add_u32 s5, s44, s5
	v_readlane_b32 s41, v254, 58
	s_addc_u32 s42, s45, s11
	s_ashr_i32 s11, s10, 31
	v_readlane_b32 s43, v254, 60
	s_lshl_b64 s[40:41], s[10:11], 12
	s_add_u32 s43, s5, s40
	s_addc_u32 s42, s42, s41
	s_ashr_i32 s5, s4, 31
	s_lshl_b64 s[40:41], s[4:5], 2
	s_add_u32 s40, s43, s40
	s_addc_u32 s41, s42, s41
	global_load_dword v13, v128, s[40:41]
	global_load_dword v14, v129, s[40:41]
	global_load_dword v15, v130, s[40:41]
	global_load_dword v16, v131, s[40:41]
	global_load_dword v17, v132, s[40:41]
	global_load_dword v18, v133, s[40:41]
	global_load_dword v19, v134, s[40:41]
	global_load_dword v20, v135, s[40:41]
	global_load_dword v21, v136, s[40:41]
	global_load_dword v22, v137, s[40:41]
	global_load_dword v23, v138, s[40:41]
	global_load_dword v24, v139, s[40:41]
	global_load_dword v25, v140, s[40:41]
	global_load_dword v26, v141, s[40:41]
	global_load_dword v27, v142, s[40:41]
	global_load_dword v28, v143, s[40:41]
	global_load_dword v29, v48, s[40:41]
	global_load_dword v30, v50, s[40:41]
	global_load_dword v31, v52, s[40:41]
	global_load_dword v32, v54, s[40:41]
	global_load_dword v33, v56, s[40:41]
	global_load_dword v36, v58, s[40:41]
	global_load_dword v37, v60, s[40:41]
	global_load_dword v38, v62, s[40:41]
	global_load_dword v39, v64, s[40:41]
	global_load_dword v40, v66, s[40:41]
	global_load_dword v41, v68, s[40:41]
	global_load_dword v42, v70, s[40:41]
	global_load_dword v43, v72, s[40:41]
	global_load_dword v44, v74, s[40:41]
	global_load_dword v45, v76, s[40:41]
	global_load_dword v46, v78, s[40:41]
	v_add_u32_e32 v47, v1, v3
	s_cmpk_lt_u32 s8, 0x580
	s_mov_b32 s5, 0x2e00000
	s_cselect_b32 s5, 0xb00000, s5
	s_add_u32 s5, s14, s5
	s_addc_u32 s8, s15, 0
	s_mul_i32 s39, s39, 0x2c000
	s_mul_hi_i32 s4, s4, 0x1600
	s_add_u32 s39, s5, s39
	s_addc_u32 s8, s8, s4
	s_lshl_b64 s[4:5], s[10:11], 1
	s_add_u32 s4, s39, s4
	s_addc_u32 s5, s8, s5
	v_lshlrev_b32_e32 v196, 1, v0
	v_readlane_b32 s46, v254, 63
	v_readlane_b32 s47, v255, 0
	v_readlane_b32 s48, v255, 1
	v_readlane_b32 s49, v255, 2
	v_readlane_b32 s50, v255, 3
	v_readlane_b32 s51, v255, 4
	v_readlane_b32 s52, v255, 5
	v_readlane_b32 s53, v255, 6
	v_readlane_b32 s54, v255, 7
	v_readlane_b32 s55, v255, 8
	s_waitcnt vmcnt(30)
	ds_write2_b32 v47, v13, v14 offset1:66
	s_waitcnt vmcnt(28)
	ds_write2_b32 v47, v15, v16 offset0:132 offset1:198
	v_add_u32_e32 v13, 0x400, v47
	s_waitcnt vmcnt(26)
	ds_write2_b32 v13, v17, v18 offset0:8 offset1:74
	v_add_u32_e32 v13, v1, v5
	s_waitcnt vmcnt(24)
	ds_write2_b32 v13, v19, v20 offset1:66
	s_waitcnt vmcnt(22)
	ds_write2_b32 v13, v21, v22 offset0:132 offset1:198
	v_add_u32_e32 v13, 0x400, v13
	s_waitcnt vmcnt(20)
	ds_write2_b32 v13, v23, v24 offset0:8 offset1:74
	v_add_u32_e32 v13, v1, v7
	s_waitcnt vmcnt(18)
	ds_write2_b32 v13, v25, v26 offset1:66
	s_waitcnt vmcnt(16)
	ds_write2_b32 v13, v27, v28 offset0:132 offset1:198
	v_add_u32_e32 v13, 0x400, v13
	s_waitcnt vmcnt(14)
	ds_write2_b32 v13, v29, v30 offset0:8 offset1:74
	v_add_u32_e32 v13, v1, v9
	v_add_u32_e32 v14, 0x400, v13
	s_waitcnt vmcnt(12)
	ds_write2_b32 v13, v31, v32 offset1:66
	s_waitcnt vmcnt(10)
	ds_write2_b32 v13, v33, v36 offset0:132 offset1:198
	s_waitcnt vmcnt(8)
	ds_write2_b32 v14, v37, v38 offset0:8 offset1:74
	s_waitcnt vmcnt(6)
	ds_write2_b32 v14, v39, v40 offset0:140 offset1:206
	v_add_u32_e32 v14, 0x800, v13
	v_add_u32_e32 v13, 0xc00, v13
	s_waitcnt vmcnt(4)
	ds_write2_b32 v14, v41, v42 offset0:16 offset1:82
	s_waitcnt vmcnt(2)
	ds_write2_b32 v14, v43, v44 offset0:148 offset1:214
	v_lshl_add_u64 v[18:19], s[4:5], 0, v[196:197]
	s_waitcnt vmcnt(0)
	ds_write2_b32 v13, v45, v46 offset0:24 offset1:90
	s_waitcnt lgkmcnt(0)
	ds_read2_b32 v[20:21], v35 offset0:33 offset1:41
	ds_read2_b32 v[22:23], v35 offset1:8
	ds_read2_b32 v[24:25], v35 offset0:66 offset1:74
	ds_read2_b32 v[26:27], v35 offset0:99 offset1:107
	ds_read2_b32 v[28:29], v35 offset0:132 offset1:140
	ds_read2_b32 v[30:31], v35 offset0:165 offset1:173
	ds_read2_b32 v[32:33], v35 offset0:198 offset1:206
	ds_read2_b32 v[36:37], v35 offset0:231 offset1:239
	v_mov_b32_e32 v13, v197
	v_lshl_add_u64 v[18:19], v[18:19], 0, v[12:13]
	s_mov_b32 s4, 0xb000
	s_waitcnt lgkmcnt(6)
	v_cvt_pk_bf16_f32 v14, v22, v20
	s_waitcnt lgkmcnt(4)
	v_cvt_pk_bf16_f32 v15, v24, v26
	s_waitcnt lgkmcnt(2)
	v_cvt_pk_bf16_f32 v16, v28, v30
	s_waitcnt lgkmcnt(0)
	v_cvt_pk_bf16_f32 v17, v32, v36
	v_add_co_u32_e32 v20, vcc, s4, v18
	global_store_dwordx4 v[18:19], v[14:17], off sc1
	s_mov_b32 s4, 0x16000
	s_nop 0
	v_cvt_pk_bf16_f32 v14, v23, v21
	v_cvt_pk_bf16_f32 v15, v25, v27
	v_cvt_pk_bf16_f32 v16, v29, v31
	v_cvt_pk_bf16_f32 v17, v33, v37
	v_addc_co_u32_e32 v21, vcc, 0, v19, vcc
	global_store_dwordx4 v[20:21], v[14:17], off sc1
	ds_read2_b32 v[20:21], v35 offset0:49 offset1:57
	ds_read2_b32 v[22:23], v35 offset0:16 offset1:24
	ds_read2_b32 v[24:25], v35 offset0:82 offset1:90
	ds_read2_b32 v[26:27], v35 offset0:115 offset1:123
	ds_read2_b32 v[28:29], v35 offset0:148 offset1:156
	ds_read2_b32 v[30:31], v35 offset0:181 offset1:189
	ds_read2_b32 v[32:33], v35 offset0:214 offset1:222
	ds_read2_b32 v[36:37], v35 offset0:247 offset1:255
	v_add_co_u32_e32 v38, vcc, s4, v18
	s_waitcnt lgkmcnt(6)
	v_cvt_pk_bf16_f32 v14, v22, v20
	v_addc_co_u32_e32 v39, vcc, 0, v19, vcc
	s_waitcnt lgkmcnt(4)
	v_cvt_pk_bf16_f32 v15, v24, v26
	s_waitcnt lgkmcnt(2)
	v_cvt_pk_bf16_f32 v16, v28, v30
	s_waitcnt lgkmcnt(0)
	v_cvt_pk_bf16_f32 v17, v32, v36
	v_add_co_u32_e32 v18, vcc, 0x21000, v18
	global_store_dwordx4 v[38:39], v[14:17], off sc1
	s_nop 0
	v_addc_co_u32_e32 v19, vcc, 0, v19, vcc
	v_cvt_pk_bf16_f32 v14, v23, v21
	v_cvt_pk_bf16_f32 v15, v25, v27
	v_cvt_pk_bf16_f32 v16, v29, v31
	v_cvt_pk_bf16_f32 v17, v33, v37
	global_store_dwordx4 v[18:19], v[14:17], off sc1
	s_waitcnt lgkmcnt(0)

; #define LAS __attribute__((address_space(3)))
; __device__ __forceinline__ void transpose_tile(const float* src, int srcN, const float* gk, bf16_t* dst, int dstK, LAS float* scr, int lane) {
;     float tv[32];
; #pragma unroll
;     for (int i = 0; i < 32; ++i) tv[i] = src[(size_t)(2 * i + (lane >> 5)) * srcN + (lane & 31)];
;     if (gk) {
; #pragma unroll
;         for (int i = 0; i < 32; ++i) tv[i] *= gk[2 * i + (lane >> 5)];
;     }
; #pragma unroll
;     for (int i = 0; i < 32; ++i) scr[(2 * i + (lane >> 5)) * 33 + (lane & 31)] = tv[i];
; __device__ __forceinline__ void convert_layer(const Params& p, int l, LAS unsigned char* lds, int it_lo, int it_hi, int worker, int nworkers) {
;     ...
;         int r = it;
;         if (r < 2 * I_GU) {
;             const int f = r / I_GU; r -= f * I_GU; const int nb = r / (DM / 64), kb = r % (DM / 64), n0 = nb * 32, k0 = kb * 64;
;             const int pn = n0 >> 8, w = n0 & 255; const float* src = ((w < 128) ? p.ffn_w_gate : p.ffn_w_up) + (size_t)(l * 2 + f) * DM * DFF;
;             transpose_tile(src + (size_t)k0 * DFF + pn * 128 + (w & 127), DFF, ng + (f ? 2 : 0) * DM + k0, W + (f ? O_WGU1 : O_WGU0) + (size_t)n0 * DM + k0, DM, scr, lane); continue; }
;         r -= 2 * I_GU;
;         if (r < 2 * I_D) {
;             const int f = r / I_D; r -= f * I_D; const int nb = r / (DFF / 64), kb = r % (DFF / 64), n0 = nb * 32, k0 = kb * 64;
;             const float* src = p.ffn_w_down + (size_t)(l * 2 + f) * DFF * DM;
;             transpose_tile(src + (size_t)k0 * DM + n0, DM, nullptr, W + (f ? O_WD1 : O_WD0) + (size_t)n0 * DFF + k0, DFF, scr, lane); continue; }
;         r -= 2 * I_D;
;         if (r < I_ING) {
;             const int nb = r / (DM / 64), kb = r % (DM / 64), n0 = nb * 32, k0 = kb * 64;
;             if (n0 < NPROJ) transpose_tile(p.w_in + (size_t)l * DM * NPROJ + (size_t)k0 * NPROJ + n0, NPROJ, ng + DM + k0, W + O_WING + (size_t)n0 * DM + k0, DM, scr, lane);
;             else transpose_tile(p.w_gate + (size_t)l * DM * NGATE + (size_t)k0 * NGATE + (n0 - NPROJ), NGATE, ng + DM + k0, W + O_WING + (size_t)n0 * DM + k0, DM, scr, lane);
;             continue; }
.LBB0_656:
	s_add_i32 s10, s38, 0x1600
	s_cmpk_gt_i32 s10, 0x15ff
	s_mov_b64 s[4:5], -1
	s_cbranch_scc0 .LBB0_666
	s_cmpk_gt_u32 s10, 0x20ff
	s_cbranch_scc0 .LBB0_663
	s_and_b32 s39, s22, 0x7fe0
	s_add_i32 s8, s39, 0xffffbe00
	s_and_b32 s11, s23, 0x3c0
	s_cmpk_gt_u32 s8, 0xeff
	s_cbranch_scc0 .LBB0_660
	s_mul_i32 s4, s11, 0x3000
	s_add_u32 s4, s18, s4
	s_addc_u32 s5, s19, 0
	s_lshl_b32 s39, s39, 2
	s_add_u32 s4, s4, s39
	s_addc_u32 s5, s5, 0
	s_add_u32 s40, s4, 0xfffebc00
	s_addc_u32 s41, s5, -1
	s_lshl_b64 s[4:5], s[8:9], 11
	s_add_u32 s4, s16, s4
	s_addc_u32 s5, s17, s5
	s_lshl_b32 s39, s11, 1
	s_add_u32 s4, s4, s39
	s_addc_u32 s5, s5, 0
	global_load_dword v13, v49, s[40:41]
	global_load_dword v16, v51, s[40:41]
	global_load_dword v17, v53, s[40:41]
	global_load_dword v18, v55, s[40:41]
	global_load_dword v19, v57, s[40:41]
	global_load_dword v20, v59, s[40:41]
	global_load_dword v21, v61, s[40:41]
	global_load_dword v22, v63, s[40:41]
	global_load_dword v23, v65, s[40:41]
	global_load_dword v24, v67, s[40:41]
	global_load_dword v25, v69, s[40:41]
	global_load_dword v26, v71, s[40:41]
	global_load_dword v27, v73, s[40:41]
	global_load_dword v28, v75, s[40:41]
	global_load_dword v29, v77, s[40:41]
	global_load_dword v30, v79, s[40:41]
	global_load_dword v31, v242, s[40:41]
	global_load_dword v32, v177, s[40:41]
	global_load_dword v33, v232, s[40:41]
	global_load_dword v36, v179, s[40:41]
	global_load_dword v37, v235, s[40:41]
	global_load_dword v38, v181, s[40:41]
	global_load_dword v39, v87, s[40:41]
	global_load_dword v40, v183, s[40:41]
	global_load_dword v41, v89, s[40:41]
	global_load_dword v42, v185, s[40:41]
	global_load_dword v43, v91, s[40:41]
	global_load_dword v44, v187, s[40:41]
	global_load_dword v45, v93, s[40:41]
	global_load_dword v46, v189, s[40:41]
	global_load_dword v47, v95, s[40:41]
	global_load_dword v80, v191, s[40:41]
	s_lshl_b32 s40, s11, 2
	s_mov_b32 s41, s9
	v_lshl_add_u64 v[14:15], v[10:11], 0, s[40:41]
	global_load_dword v81, v[14:15], off
	v_lshlrev_b32_e32 v196, 1, v0
	s_waitcnt vmcnt(0)
	v_mul_f32_e32 v13, v13, v81
	global_load_dword v81, v[14:15], off offset:8
	s_waitcnt vmcnt(0)
	v_mul_f32_e32 v16, v16, v81
	global_load_dword v81, v[14:15], off offset:16
	s_waitcnt vmcnt(0)
	v_mul_f32_e32 v17, v17, v81
	global_load_dword v81, v[14:15], off offset:24
	s_waitcnt vmcnt(0)
	v_mul_f32_e32 v18, v18, v81
	global_load_dword v81, v[14:15], off offset:32
	s_waitcnt vmcnt(0)
	v_mul_f32_e32 v19, v19, v81
	global_load_dword v81, v[14:15], off offset:40
	s_waitcnt vmcnt(0)
	v_mul_f32_e32 v20, v20, v81
	global_load_dword v81, v[14:15], off offset:48
	s_waitcnt vmcnt(0)
	v_mul_f32_e32 v21, v21, v81
	global_load_dword v81, v[14:15], off offset:56
	s_waitcnt vmcnt(0)
	v_mul_f32_e32 v22, v22, v81
	global_load_dword v81, v[14:15], off offset:64
	s_waitcnt vmcnt(0)
	v_mul_f32_e32 v23, v23, v81
	global_load_dword v81, v[14:15], off offset:72
	s_waitcnt vmcnt(0)
	v_mul_f32_e32 v24, v24, v81
	global_load_dword v81, v[14:15], off offset:80
	s_waitcnt vmcnt(0)
	v_mul_f32_e32 v25, v25, v81
	global_load_dword v81, v[14:15], off offset:88
	s_waitcnt vmcnt(0)
	v_mul_f32_e32 v26, v26, v81
	global_load_dword v81, v[14:15], off offset:96
	s_waitcnt vmcnt(0)
	v_mul_f32_e32 v27, v27, v81
	global_load_dword v81, v[14:15], off offset:104
	s_waitcnt vmcnt(0)
	v_mul_f32_e32 v28, v28, v81
	global_load_dword v81, v[14:15], off offset:112
	s_waitcnt vmcnt(0)
	v_mul_f32_e32 v29, v29, v81
	global_load_dword v81, v[14:15], off offset:120
	s_waitcnt vmcnt(0)
	v_mul_f32_e32 v30, v30, v81
	global_load_dword v81, v[14:15], off offset:128
	s_waitcnt vmcnt(0)
	v_mul_f32_e32 v31, v31, v81
	global_load_dword v81, v[14:15], off offset:136
	s_waitcnt vmcnt(0)
	v_mul_f32_e32 v32, v32, v81
	global_load_dword v81, v[14:15], off offset:144
	s_waitcnt vmcnt(0)
	v_mul_f32_e32 v33, v33, v81
	global_load_dword v81, v[14:15], off offset:152
	s_waitcnt vmcnt(0)
	v_mul_f32_e32 v36, v36, v81
	global_load_dword v81, v[14:15], off offset:160
	s_waitcnt vmcnt(0)
	v_mul_f32_e32 v37, v37, v81
	global_load_dword v81, v[14:15], off offset:168
	s_waitcnt vmcnt(0)
	v_mul_f32_e32 v38, v38, v81
	global_load_dword v81, v[14:15], off offset:176
	s_waitcnt vmcnt(0)
	v_mul_f32_e32 v39, v39, v81
	global_load_dword v81, v[14:15], off offset:184
	s_waitcnt vmcnt(0)
	v_mul_f32_e32 v40, v40, v81
	global_load_dword v81, v[14:15], off offset:192
	s_waitcnt vmcnt(0)
	v_mul_f32_e32 v41, v41, v81
	global_load_dword v81, v[14:15], off offset:200
	s_waitcnt vmcnt(0)
	v_mul_f32_e32 v42, v42, v81
	global_load_dword v81, v[14:15], off offset:208
	s_waitcnt vmcnt(0)
	v_mul_f32_e32 v43, v43, v81
	global_load_dword v81, v[14:15], off offset:216
	s_waitcnt vmcnt(0)
	v_mul_f32_e32 v44, v44, v81
	global_load_dword v81, v[14:15], off offset:224
	s_waitcnt vmcnt(0)
	v_mul_f32_e32 v45, v45, v81
	global_load_dword v81, v[14:15], off offset:232
	s_waitcnt vmcnt(0)
	v_mul_f32_e32 v46, v46, v81
	global_load_dword v81, v[14:15], off offset:240
	s_waitcnt vmcnt(0)
	v_mul_f32_e32 v47, v47, v81
	global_load_dword v14, v[14:15], off offset:248
	v_add_u32_e32 v15, v1, v3
	ds_write2_b32 v15, v13, v16 offset1:66
	ds_write2_b32 v15, v17, v18 offset0:132 offset1:198
	v_add_u32_e32 v13, 0x400, v15
	ds_write2_b32 v13, v19, v20 offset0:8 offset1:74
	v_add_u32_e32 v13, v1, v5
	ds_write2_b32 v13, v21, v22 offset1:66
	ds_write2_b32 v13, v23, v24 offset0:132 offset1:198
	v_add_u32_e32 v13, 0x400, v13
	ds_write2_b32 v13, v25, v26 offset0:8 offset1:74
	v_add_u32_e32 v13, v1, v7
	ds_write2_b32 v13, v27, v28 offset1:66
	ds_write2_b32 v13, v29, v30 offset0:132 offset1:198
	v_add_u32_e32 v13, 0x400, v13
	ds_write2_b32 v13, v31, v32 offset0:8 offset1:74
	v_add_u32_e32 v13, v1, v9
	v_add_u32_e32 v15, 0x400, v13
	ds_write2_b32 v13, v33, v36 offset1:66
	ds_write2_b32 v13, v37, v38 offset0:132 offset1:198
	ds_write2_b32 v15, v39, v40 offset0:8 offset1:74
	ds_write2_b32 v15, v41, v42 offset0:140 offset1:206
	v_add_u32_e32 v15, 0x800, v13
	v_add_u32_e32 v13, 0xc00, v13
	ds_write2_b32 v15, v43, v44 offset0:16 offset1:82
	ds_write2_b32 v15, v45, v46 offset0:148 offset1:214
	v_lshl_add_u64 v[18:19], s[4:5], 0, v[196:197]
	v_lshlrev_b32_e32 v196, 1, v2
	v_lshl_add_u64 v[38:39], v[18:19], 0, v[196:197]
	v_lshlrev_b32_e32 v196, 1, v4
	s_mov_b64 s[4:5], 0
	s_waitcnt vmcnt(0)
; #define LAS __attribute__((address_space(3)))
; __device__ __forceinline__ unsigned pk2(float lo, float hi) { return pg8::cvt_pk_bf16(lo, hi); }
; __device__ __forceinline__ void transpose_tile(const float* src, int srcN, const float* gk, bf16_t* dst, int dstK, LAS float* scr, int lane) {
;     float tv[32];
; #pragma unroll
;     for (int i = 0; i < 32; ++i) tv[i] = src[(size_t)(2 * i + (lane >> 5)) * srcN + (lane & 31)];
;     if (gk) {
; #pragma unroll
;         for (int i = 0; i < 32; ++i) tv[i] *= gk[2 * i + (lane >> 5)];
;     }
; #pragma unroll
;     for (int i = 0; i < 32; ++i) scr[(2 * i + (lane >> 5)) * 33 + (lane & 31)] = tv[i];
;     asm volatile("s_waitcnt lgkmcnt(0)" ::: "memory");
;     const int c = lane & 7;
; #pragma unroll
;     for (int j = 0; j < 4; ++j) {
;         const int n = (lane >> 3) + 8 * j; const LAS float* s = scr + (8 * c) * 33 + n;
;         u32x4 o; o.x = pk2(s[0 * 33], s[1 * 33]); o.y = pk2(s[2 * 33], s[3 * 33]); o.z = pk2(s[4 * 33], s[5 * 33]); o.w = pk2(s[6 * 33], s[7 * 33]);
;         *(u32x4*)(dst + (size_t)n * dstK + 8 * c) = o;
;     }
;     asm volatile("s_waitcnt lgkmcnt(0)" ::: "memory");
; __device__ __forceinline__ void convert_layer(const Params& p, int l, LAS unsigned char* lds, int it_lo, int it_hi, int worker, int nworkers) {
;     ...
;         if (r < I_ING) {
;             const int nb = r / (DM / 64), kb = r % (DM / 64), n0 = nb * 32, k0 = kb * 64;
;             if (n0 < NPROJ) transpose_tile(p.w_in + (size_t)l * DM * NPROJ + (size_t)k0 * NPROJ + n0, NPROJ, ng + DM + k0, W + O_WING + (size_t)n0 * DM + k0, DM, scr, lane);
	v_mul_f32_e32 v14, v80, v14
	ds_write2_b32 v13, v47, v14 offset0:24 offset1:90
	s_waitcnt lgkmcnt(0)
	ds_read2_b32 v[20:21], v35 offset0:33 offset1:41
	ds_read2_b32 v[22:23], v35 offset1:8
	ds_read2_b32 v[24:25], v35 offset0:66 offset1:74
	ds_read2_b32 v[26:27], v35 offset0:99 offset1:107
	ds_read2_b32 v[28:29], v35 offset0:132 offset1:140
	ds_read2_b32 v[30:31], v35 offset0:165 offset1:173
	ds_read2_b32 v[32:33], v35 offset0:198 offset1:206
	ds_read2_b32 v[36:37], v35 offset0:231 offset1:239
	s_waitcnt lgkmcnt(6)
	v_cvt_pk_bf16_f32 v14, v22, v20
	s_waitcnt lgkmcnt(4)
	v_cvt_pk_bf16_f32 v15, v24, v26
	s_waitcnt lgkmcnt(2)
	v_cvt_pk_bf16_f32 v16, v28, v30
	s_waitcnt lgkmcnt(0)
	v_cvt_pk_bf16_f32 v17, v32, v36
	global_store_dwordx4 v[38:39], v[14:17], off sc1
	s_nop 1
	v_cvt_pk_bf16_f32 v14, v23, v21
	v_cvt_pk_bf16_f32 v15, v25, v27
	v_cvt_pk_bf16_f32 v16, v29, v31
	v_cvt_pk_bf16_f32 v17, v33, v37
	v_lshl_add_u64 v[20:21], v[18:19], 0, v[196:197]
	global_store_dwordx4 v[20:21], v[14:17], off sc1
	ds_read2_b32 v[20:21], v35 offset0:49 offset1:57
	ds_read2_b32 v[22:23], v35 offset0:16 offset1:24
	ds_read2_b32 v[24:25], v35 offset0:82 offset1:90
	ds_read2_b32 v[26:27], v35 offset0:115 offset1:123
	ds_read2_b32 v[28:29], v35 offset0:148 offset1:156
	ds_read2_b32 v[30:31], v35 offset0:181 offset1:189
	ds_read2_b32 v[32:33], v35 offset0:214 offset1:222
	ds_read2_b32 v[36:37], v35 offset0:247 offset1:255
	v_lshlrev_b32_e32 v196, 1, v6
	s_waitcnt lgkmcnt(6)
	v_cvt_pk_bf16_f32 v14, v22, v20
	s_waitcnt lgkmcnt(4)
	v_cvt_pk_bf16_f32 v15, v24, v26
	s_waitcnt lgkmcnt(2)
	v_cvt_pk_bf16_f32 v16, v28, v30
	s_waitcnt lgkmcnt(0)
	v_cvt_pk_bf16_f32 v17, v32, v36
	v_lshl_add_u64 v[38:39], v[18:19], 0, v[196:197]
	v_lshlrev_b32_e32 v196, 1, v8
	global_store_dwordx4 v[38:39], v[14:17], off sc1
	v_lshl_add_u64 v[18:19], v[18:19], 0, v[196:197]
	s_nop 0
	v_cvt_pk_bf16_f32 v14, v23, v21
	v_cvt_pk_bf16_f32 v15, v25, v27
	v_cvt_pk_bf16_f32 v16, v29, v31
	v_cvt_pk_bf16_f32 v17, v33, v37
	global_store_dwordx4 v[18:19], v[14:17], off sc1
	s_waitcnt lgkmcnt(0)
.LBB0_660:
	s_andn2_b64 vcc, exec, s[4:5]
	s_cbranch_vccnz .LBB0_662
	s_mul_i32 s4, s11, 0x3c00
	s_add_u32 s39, s20, s4
	s_addc_u32 s41, s21, 0
	s_lshl_b64 s[4:5], s[8:9], 2
	s_add_u32 s40, s39, s4
	s_addc_u32 s41, s41, s5
	s_lshl_b64 s[4:5], s[8:9], 11
	s_add_u32 s4, s16, s4
	s_addc_u32 s5, s17, s5
	s_lshl_b32 s8, s11, 1
	s_add_u32 s4, s4, s8
	s_addc_u32 s5, s5, 0
	s_lshl_b32 s8, s11, 2
	v_lshl_add_u64 v[14:15], v[10:11], 0, s[8:9]
	global_load_dword v13, v97, s[40:41]
	global_load_dword v16, v193, s[40:41]
	global_load_dword v17, v99, s[40:41]
	global_load_dword v18, v195, s[40:41]
	global_load_dword v19, v101, s[40:41]
	global_load_dword v20, v203, s[40:41]
	global_load_dword v21, v103, s[40:41]
	global_load_dword v22, v205, s[40:41]
	global_load_dword v23, v105, s[40:41]
	global_load_dword v24, v207, s[40:41]
	global_load_dword v25, v107, s[40:41]
	global_load_dword v26, v209, s[40:41]
	global_load_dword v27, v109, s[40:41]
	global_load_dword v28, v211, s[40:41]
	global_load_dword v29, v111, s[40:41]
	global_load_dword v30, v213, s[40:41]
	global_load_dword v31, v113, s[40:41]
	global_load_dword v32, v215, s[40:41]
	global_load_dword v33, v115, s[40:41]
	global_load_dword v36, v178, s[40:41]
	global_load_dword v37, v116, s[40:41]
	global_load_dword v38, v117, s[40:41]
	global_load_dword v39, v118, s[40:41]
	global_load_dword v40, v119, s[40:41]
	global_load_dword v41, v120, s[40:41]
	global_load_dword v42, v121, s[40:41]
	global_load_dword v43, v122, s[40:41]
	global_load_dword v44, v123, s[40:41]
	global_load_dword v45, v124, s[40:41]
	global_load_dword v46, v125, s[40:41]
	global_load_dword v47, v126, s[40:41]
	global_load_dword v80, v127, s[40:41]
	global_load_dword v81, v[14:15], off
	v_lshlrev_b32_e32 v196, 1, v0
	s_waitcnt vmcnt(0)
	v_mul_f32_e32 v13, v13, v81
	global_load_dword v81, v[14:15], off offset:8
	s_waitcnt vmcnt(0)
	v_mul_f32_e32 v16, v16, v81
	global_load_dword v81, v[14:15], off offset:16
	s_waitcnt vmcnt(0)
	v_mul_f32_e32 v17, v17, v81
	global_load_dword v81, v[14:15], off offset:24
	s_waitcnt vmcnt(0)
	v_mul_f32_e32 v18, v18, v81
	global_load_dword v81, v[14:15], off offset:32
	s_waitcnt vmcnt(0)
	v_mul_f32_e32 v19, v19, v81
	global_load_dword v81, v[14:15], off offset:40
	s_waitcnt vmcnt(0)
	v_mul_f32_e32 v20, v20, v81
	global_load_dword v81, v[14:15], off offset:48
	s_waitcnt vmcnt(0)
	v_mul_f32_e32 v21, v21, v81
	global_load_dword v81, v[14:15], off offset:56
	s_waitcnt vmcnt(0)
	v_mul_f32_e32 v22, v22, v81
	global_load_dword v81, v[14:15], off offset:64
	s_waitcnt vmcnt(0)
	v_mul_f32_e32 v23, v23, v81
	global_load_dword v81, v[14:15], off offset:72
	s_waitcnt vmcnt(0)
	v_mul_f32_e32 v24, v24, v81
	global_load_dword v81, v[14:15], off offset:80
	s_waitcnt vmcnt(0)
	v_mul_f32_e32 v25, v25, v81
	global_load_dword v81, v[14:15], off offset:88
	s_waitcnt vmcnt(0)
	v_mul_f32_e32 v26, v26, v81
	global_load_dword v81, v[14:15], off offset:96
	s_waitcnt vmcnt(0)
	v_mul_f32_e32 v27, v27, v81
	global_load_dword v81, v[14:15], off offset:104
	s_waitcnt vmcnt(0)
; #define LAS __attribute__((address_space(3)))
; __device__ __forceinline__ unsigned pk2(float lo, float hi) { return pg8::cvt_pk_bf16(lo, hi); }
; __device__ __forceinline__ void transpose_tile(const float* src, int srcN, const float* gk, bf16_t* dst, int dstK, LAS float* scr, int lane) {
;     float tv[32];
; #pragma unroll
;     for (int i = 0; i < 32; ++i) tv[i] = src[(size_t)(2 * i + (lane >> 5)) * srcN + (lane & 31)];
;     if (gk) {
; #pragma unroll
;         for (int i = 0; i < 32; ++i) tv[i] *= gk[2 * i + (lane >> 5)];
;     }
; #pragma unroll
;     for (int i = 0; i < 32; ++i) scr[(2 * i + (lane >> 5)) * 33 + (lane & 31)] = tv[i];
;     asm volatile("s_waitcnt lgkmcnt(0)" ::: "memory");
;     const int c = lane & 7;
; #pragma unroll
;     for (int j = 0; j < 4; ++j) {
;         const int n = (lane >> 3) + 8 * j; const LAS float* s = scr + (8 * c) * 33 + n;
;         u32x4 o; o.x = pk2(s[0 * 33], s[1 * 33]); o.y = pk2(s[2 * 33], s[3 * 33]); o.z = pk2(s[4 * 33], s[5 * 33]); o.w = pk2(s[6 * 33], s[7 * 33]);
;         *(u32x4*)(dst + (size_t)n * dstK + 8 * c) = o;
;     }
;     asm volatile("s_waitcnt lgkmcnt(0)" ::: "memory");
	v_mul_f32_e32 v28, v28, v81
	global_load_dword v81, v[14:15], off offset:112
	s_waitcnt vmcnt(0)
	v_mul_f32_e32 v29, v29, v81
	global_load_dword v81, v[14:15], off offset:120
	s_waitcnt vmcnt(0)
	v_mul_f32_e32 v30, v30, v81
	global_load_dword v81, v[14:15], off offset:128
	s_waitcnt vmcnt(0)
	v_mul_f32_e32 v31, v31, v81
	global_load_dword v81, v[14:15], off offset:136
	s_waitcnt vmcnt(0)
	v_mul_f32_e32 v32, v32, v81
	global_load_dword v81, v[14:15], off offset:144
	s_waitcnt vmcnt(0)
	v_mul_f32_e32 v33, v33, v81
	global_load_dword v81, v[14:15], off offset:152
	s_waitcnt vmcnt(0)
	v_mul_f32_e32 v36, v36, v81
	global_load_dword v81, v[14:15], off offset:160
	s_waitcnt vmcnt(0)
	v_mul_f32_e32 v37, v37, v81
	global_load_dword v81, v[14:15], off offset:168
	s_waitcnt vmcnt(0)
	v_mul_f32_e32 v38, v38, v81
	global_load_dword v81, v[14:15], off offset:176
	s_waitcnt vmcnt(0)
	v_mul_f32_e32 v39, v39, v81
	global_load_dword v81, v[14:15], off offset:184
	s_waitcnt vmcnt(0)
	v_mul_f32_e32 v40, v40, v81
	global_load_dword v81, v[14:15], off offset:192
	s_waitcnt vmcnt(0)
	v_mul_f32_e32 v41, v41, v81
	global_load_dword v81, v[14:15], off offset:200
	s_waitcnt vmcnt(0)
	v_mul_f32_e32 v42, v42, v81
	global_load_dword v81, v[14:15], off offset:208
	s_waitcnt vmcnt(0)
	v_mul_f32_e32 v43, v43, v81
	global_load_dword v81, v[14:15], off offset:216
	s_waitcnt vmcnt(0)
	v_mul_f32_e32 v44, v44, v81
	global_load_dword v81, v[14:15], off offset:224
	s_waitcnt vmcnt(0)
	v_mul_f32_e32 v45, v45, v81
	global_load_dword v81, v[14:15], off offset:232
	s_waitcnt vmcnt(0)
	v_mul_f32_e32 v46, v46, v81
	global_load_dword v81, v[14:15], off offset:240
	s_waitcnt vmcnt(0)
	v_mul_f32_e32 v47, v47, v81
	global_load_dword v14, v[14:15], off offset:248
	v_add_u32_e32 v15, v1, v3
	ds_write2_b32 v15, v13, v16 offset1:66
	ds_write2_b32 v15, v17, v18 offset0:132 offset1:198
	v_add_u32_e32 v13, 0x400, v15
	ds_write2_b32 v13, v19, v20 offset0:8 offset1:74
	v_add_u32_e32 v13, v1, v5
	ds_write2_b32 v13, v21, v22 offset1:66
	ds_write2_b32 v13, v23, v24 offset0:132 offset1:198
	v_add_u32_e32 v13, 0x400, v13
	ds_write2_b32 v13, v25, v26 offset0:8 offset1:74
	v_add_u32_e32 v13, v1, v7
	ds_write2_b32 v13, v27, v28 offset1:66
	ds_write2_b32 v13, v29, v30 offset0:132 offset1:198
	v_add_u32_e32 v13, 0x400, v13
	ds_write2_b32 v13, v31, v32 offset0:8 offset1:74
	v_add_u32_e32 v13, v1, v9
	v_add_u32_e32 v15, 0x400, v13
	ds_write2_b32 v13, v33, v36 offset1:66
	ds_write2_b32 v13, v37, v38 offset0:132 offset1:198
	ds_write2_b32 v15, v39, v40 offset0:8 offset1:74
	ds_write2_b32 v15, v41, v42 offset0:140 offset1:206
	v_add_u32_e32 v15, 0x800, v13
	v_add_u32_e32 v13, 0xc00, v13
	ds_write2_b32 v15, v43, v44 offset0:16 offset1:82
	ds_write2_b32 v15, v45, v46 offset0:148 offset1:214
	v_lshl_add_u64 v[18:19], s[4:5], 0, v[196:197]
	v_lshlrev_b32_e32 v196, 1, v2
	v_lshl_add_u64 v[38:39], v[18:19], 0, v[196:197]
	v_lshlrev_b32_e32 v196, 1, v4
	s_waitcnt vmcnt(0)
	v_mul_f32_e32 v14, v80, v14
	ds_write2_b32 v13, v47, v14 offset0:24 offset1:90
	s_waitcnt lgkmcnt(0)
	ds_read2_b32 v[20:21], v35 offset0:33 offset1:41
	ds_read2_b32 v[22:23], v35 offset1:8
	ds_read2_b32 v[24:25], v35 offset0:66 offset1:74
	ds_read2_b32 v[26:27], v35 offset0:99 offset1:107
	ds_read2_b32 v[28:29], v35 offset0:132 offset1:140
	ds_read2_b32 v[30:31], v35 offset0:165 offset1:173
	ds_read2_b32 v[32:33], v35 offset0:198 offset1:206
	ds_read2_b32 v[36:37], v35 offset0:231 offset1:239
	s_waitcnt lgkmcnt(6)
	v_cvt_pk_bf16_f32 v14, v22, v20
	s_waitcnt lgkmcnt(4)
	v_cvt_pk_bf16_f32 v15, v24, v26
	s_waitcnt lgkmcnt(2)
	v_cvt_pk_bf16_f32 v16, v28, v30
	s_waitcnt lgkmcnt(0)
	v_cvt_pk_bf16_f32 v17, v32, v36
	global_store_dwordx4 v[38:39], v[14:17], off sc1
	s_nop 1
	v_cvt_pk_bf16_f32 v14, v23, v21
	v_cvt_pk_bf16_f32 v15, v25, v27
	v_cvt_pk_bf16_f32 v16, v29, v31
	v_cvt_pk_bf16_f32 v17, v33, v37
	v_lshl_add_u64 v[20:21], v[18:19], 0, v[196:197]
	global_store_dwordx4 v[20:21], v[14:17], off sc1
	ds_read2_b32 v[20:21], v35 offset0:49 offset1:57
	ds_read2_b32 v[22:23], v35 offset0:16 offset1:24
	ds_read2_b32 v[24:25], v35 offset0:82 offset1:90
	ds_read2_b32 v[26:27], v35 offset0:115 offset1:123
	ds_read2_b32 v[28:29], v35 offset0:148 offset1:156
	ds_read2_b32 v[30:31], v35 offset0:181 offset1:189
	ds_read2_b32 v[32:33], v35 offset0:214 offset1:222
	ds_read2_b32 v[36:37], v35 offset0:247 offset1:255
	v_lshlrev_b32_e32 v196, 1, v6
	s_waitcnt lgkmcnt(6)
	v_cvt_pk_bf16_f32 v14, v22, v20
	s_waitcnt lgkmcnt(4)
	v_cvt_pk_bf16_f32 v15, v24, v26
	s_waitcnt lgkmcnt(2)
	v_cvt_pk_bf16_f32 v16, v28, v30
	s_waitcnt lgkmcnt(0)
	v_cvt_pk_bf16_f32 v17, v32, v36
	v_lshl_add_u64 v[38:39], v[18:19], 0, v[196:197]
	v_lshlrev_b32_e32 v196, 1, v8
	global_store_dwordx4 v[38:39], v[14:17], off sc1
	v_lshl_add_u64 v[18:19], v[18:19], 0, v[196:197]
	s_nop 0
	v_cvt_pk_bf16_f32 v14, v23, v21
	v_cvt_pk_bf16_f32 v15, v25, v27
	v_cvt_pk_bf16_f32 v16, v29, v31
	v_cvt_pk_bf16_f32 v17, v33, v37
	global_store_dwordx4 v[18:19], v[14:17], off sc1
	s_waitcnt lgkmcnt(0)

; #define LAS __attribute__((address_space(3)))
; __device__ __forceinline__ unsigned pk2(float lo, float hi) { return pg8::cvt_pk_bf16(lo, hi); }
; __device__ __forceinline__ void transpose_tile(const float* src, int srcN, const float* gk, bf16_t* dst, int dstK, LAS float* scr, int lane) {
;     float tv[32];
; #pragma unroll
;     for (int i = 0; i < 32; ++i) tv[i] = src[(size_t)(2 * i + (lane >> 5)) * srcN + (lane & 31)];
;     if (gk) {
; #pragma unroll
;         for (int i = 0; i < 32; ++i) tv[i] *= gk[2 * i + (lane >> 5)];
;     }
; #pragma unroll
;     for (int i = 0; i < 32; ++i) scr[(2 * i + (lane >> 5)) * 33 + (lane & 31)] = tv[i];
;     asm volatile("s_waitcnt lgkmcnt(0)" ::: "memory");
;     const int c = lane & 7;
; #pragma unroll
;     for (int j = 0; j < 4; ++j) {
;         const int n = (lane >> 3) + 8 * j; const LAS float* s = scr + (8 * c) * 33 + n;
;         u32x4 o; o.x = pk2(s[0 * 33], s[1 * 33]); o.y = pk2(s[2 * 33], s[3 * 33]); o.z = pk2(s[4 * 33], s[5 * 33]); o.w = pk2(s[6 * 33], s[7 * 33]);
;         *(u32x4*)(dst + (size_t)n * dstK + 8 * c) = o;
;     }
;     asm volatile("s_waitcnt lgkmcnt(0)" ::: "memory");
; __device__ __forceinline__ void convert_layer(const Params& p, int l, LAS unsigned char* lds, int it_lo, int it_hi, int worker, int nworkers) {
;     ...
;         if (r < 2 * I_D) {
;             const int f = r / I_D; r -= f * I_D; const int nb = r / (DFF / 64), kb = r % (DFF / 64), n0 = nb * 32, k0 = kb * 64;
;             const float* src = p.ffn_w_down + (size_t)(l * 2 + f) * DFF * DM;
;             transpose_tile(src + (size_t)k0 * DM + n0, DM, nullptr, W + (f ? O_WD1 : O_WD0) + (size_t)n0 * DFF + k0, DFF, scr, lane); continue; }
.LBB0_663:
	s_andn2_b64 vcc, exec, s[4:5]
	s_cbranch_vccnz .LBB0_665
	s_cmpk_gt_u32 s38, 0x57f
	s_cselect_b64 s[4:5], -1, 0
	v_cndmask_b32_e64 v13, 0, 1, s[4:5]
	s_and_b64 s[4:5], s[4:5], exec
	s_cselect_b32 s4, 0xfa80, 0
	s_add_i32 s4, s4, s38
	s_sext_i32_i16 s5, s4
	s_mulk_i32 s5, 0xba3
	s_lshr_b32 s8, s5, 31
	s_ashr_i32 s5, s5, 17
	s_add_i32 s8, s5, s8
	s_mul_i32 s5, s8, 44
	s_sub_i32 s4, s4, s5
	s_sext_i32_i16 s5, s4
	s_lshl_b32 s40, s5, 6
	v_readfirstlane_b32 s5, v13
	s_or_b32 s5, s12, s5
	v_readlane_b32 s44, v254, 57
	s_lshl_b32 s4, s8, 5
	s_mul_hi_i32 s11, s5, 0xb00000
	s_mul_i32 s5, s5, 0xb00000
	v_readlane_b32 s48, v254, 61
	v_readlane_b32 s49, v254, 62
	s_add_u32 s5, s48, s5
	s_addc_u32 s11, s49, s11
	s_ashr_i32 s41, s40, 31
	s_lshl_b64 s[42:43], s[40:41], 12
	s_add_u32 s39, s5, s42
	s_addc_u32 s11, s11, s43
	s_ashr_i32 s5, s4, 31
	s_lshl_b64 s[42:43], s[4:5], 2
	s_add_u32 s42, s39, s42
	s_addc_u32 s43, s11, s43
	global_load_dword v13, v128, s[42:43]
	global_load_dword v14, v129, s[42:43]
	global_load_dword v15, v130, s[42:43]
	global_load_dword v16, v131, s[42:43]
	global_load_dword v17, v132, s[42:43]
	global_load_dword v18, v133, s[42:43]
	global_load_dword v19, v134, s[42:43]
	global_load_dword v20, v135, s[42:43]
	global_load_dword v21, v136, s[42:43]
	global_load_dword v22, v137, s[42:43]
	global_load_dword v23, v138, s[42:43]
	global_load_dword v24, v139, s[42:43]
	global_load_dword v25, v140, s[42:43]
	global_load_dword v26, v141, s[42:43]
	global_load_dword v27, v142, s[42:43]
	global_load_dword v28, v143, s[42:43]
	global_load_dword v29, v48, s[42:43]
	global_load_dword v30, v50, s[42:43]
	global_load_dword v31, v52, s[42:43]
	global_load_dword v32, v54, s[42:43]
	global_load_dword v33, v56, s[42:43]
	global_load_dword v36, v58, s[42:43]
	global_load_dword v37, v60, s[42:43]
	global_load_dword v38, v62, s[42:43]
	global_load_dword v39, v64, s[42:43]
	global_load_dword v40, v66, s[42:43]
	global_load_dword v41, v68, s[42:43]
	global_load_dword v42, v70, s[42:43]
	global_load_dword v43, v72, s[42:43]
	global_load_dword v44, v74, s[42:43]
	global_load_dword v45, v76, s[42:43]
	global_load_dword v46, v78, s[42:43]
	v_add_u32_e32 v47, v1, v3
	s_cmpk_lt_u32 s38, 0x580
	s_mov_b32 s5, 0x2e00000
	s_cselect_b32 s5, 0xb00000, s5
	s_add_u32 s5, s14, s5
	s_addc_u32 s11, s15, 0
	s_mul_i32 s8, s8, 0x2c000
	s_mul_hi_i32 s4, s4, 0x1600
	s_add_u32 s8, s5, s8
	s_addc_u32 s11, s11, s4
	s_lshl_b64 s[4:5], s[40:41], 1
	s_add_u32 s4, s8, s4
	s_addc_u32 s5, s11, s5
	v_lshlrev_b32_e32 v196, 1, v0
	v_readlane_b32 s45, v254, 58
	v_readlane_b32 s46, v254, 59
	v_readlane_b32 s47, v254, 60
	v_readlane_b32 s50, v254, 63
	v_readlane_b32 s51, v255, 0
	v_readlane_b32 s52, v255, 1
	v_readlane_b32 s53, v255, 2
	v_readlane_b32 s54, v255, 3
	v_readlane_b32 s55, v255, 4
	v_readlane_b32 s56, v255, 5
	v_readlane_b32 s57, v255, 6
	v_readlane_b32 s58, v255, 7
	v_readlane_b32 s59, v255, 8
	s_waitcnt vmcnt(30)
	ds_write2_b32 v47, v13, v14 offset1:66
	s_waitcnt vmcnt(28)
	ds_write2_b32 v47, v15, v16 offset0:132 offset1:198
	v_add_u32_e32 v13, 0x400, v47
	s_waitcnt vmcnt(26)
	ds_write2_b32 v13, v17, v18 offset0:8 offset1:74
	v_add_u32_e32 v13, v1, v5
	s_waitcnt vmcnt(24)
	ds_write2_b32 v13, v19, v20 offset1:66
	s_waitcnt vmcnt(22)
	ds_write2_b32 v13, v21, v22 offset0:132 offset1:198
	v_add_u32_e32 v13, 0x400, v13
	s_waitcnt vmcnt(20)
	ds_write2_b32 v13, v23, v24 offset0:8 offset1:74
	v_add_u32_e32 v13, v1, v7
	s_waitcnt vmcnt(18)
	ds_write2_b32 v13, v25, v26 offset1:66
	s_waitcnt vmcnt(16)
	ds_write2_b32 v13, v27, v28 offset0:132 offset1:198
	v_add_u32_e32 v13, 0x400, v13
	s_waitcnt vmcnt(14)
	ds_write2_b32 v13, v29, v30 offset0:8 offset1:74
	v_add_u32_e32 v13, v1, v9
	v_add_u32_e32 v14, 0x400, v13
	s_waitcnt vmcnt(12)
	ds_write2_b32 v13, v31, v32 offset1:66
	s_waitcnt vmcnt(10)
	ds_write2_b32 v13, v33, v36 offset0:132 offset1:198
	s_waitcnt vmcnt(8)
	ds_write2_b32 v14, v37, v38 offset0:8 offset1:74
	s_waitcnt vmcnt(6)
	ds_write2_b32 v14, v39, v40 offset0:140 offset1:206
	v_add_u32_e32 v14, 0x800, v13
	v_add_u32_e32 v13, 0xc00, v13
	s_waitcnt vmcnt(4)
	ds_write2_b32 v14, v41, v42 offset0:16 offset1:82
	s_waitcnt vmcnt(2)
	ds_write2_b32 v14, v43, v44 offset0:148 offset1:214
	v_lshl_add_u64 v[18:19], s[4:5], 0, v[196:197]
	s_waitcnt vmcnt(0)
	ds_write2_b32 v13, v45, v46 offset0:24 offset1:90
	s_waitcnt lgkmcnt(0)
	ds_read2_b32 v[20:21], v35 offset0:33 offset1:41
	ds_read2_b32 v[22:23], v35 offset1:8
	ds_read2_b32 v[24:25], v35 offset0:66 offset1:74
	ds_read2_b32 v[26:27], v35 offset0:99 offset1:107
	ds_read2_b32 v[28:29], v35 offset0:132 offset1:140
	ds_read2_b32 v[30:31], v35 offset0:165 offset1:173
	ds_read2_b32 v[32:33], v35 offset0:198 offset1:206
	ds_read2_b32 v[36:37], v35 offset0:231 offset1:239
	v_mov_b32_e32 v13, v197
	v_lshl_add_u64 v[18:19], v[18:19], 0, v[12:13]
	s_mov_b32 s4, 0xb000
	s_waitcnt lgkmcnt(6)
	v_cvt_pk_bf16_f32 v14, v22, v20
	s_waitcnt lgkmcnt(4)
	v_cvt_pk_bf16_f32 v15, v24, v26
	s_waitcnt lgkmcnt(2)
	v_cvt_pk_bf16_f32 v16, v28, v30
	s_waitcnt lgkmcnt(0)
	v_cvt_pk_bf16_f32 v17, v32, v36
	v_add_co_u32_e32 v20, vcc, s4, v18
	global_store_dwordx4 v[18:19], v[14:17], off sc1
	s_mov_b32 s4, 0x16000
	s_nop 0
	v_cvt_pk_bf16_f32 v14, v23, v21
	v_cvt_pk_bf16_f32 v15, v25, v27
	v_cvt_pk_bf16_f32 v16, v29, v31
	v_cvt_pk_bf16_f32 v17, v33, v37
	v_addc_co_u32_e32 v21, vcc, 0, v19, vcc
	global_store_dwordx4 v[20:21], v[14:17], off sc1
	ds_read2_b32 v[20:21], v35 offset0:49 offset1:57
	ds_read2_b32 v[22:23], v35 offset0:16 offset1:24
	ds_read2_b32 v[24:25], v35 offset0:82 offset1:90
	ds_read2_b32 v[26:27], v35 offset0:115 offset1:123
	ds_read2_b32 v[28:29], v35 offset0:148 offset1:156
	ds_read2_b32 v[30:31], v35 offset0:181 offset1:189
	ds_read2_b32 v[32:33], v35 offset0:214 offset1:222
	ds_read2_b32 v[36:37], v35 offset0:247 offset1:255
	v_add_co_u32_e32 v38, vcc, s4, v18
	s_waitcnt lgkmcnt(6)
	v_cvt_pk_bf16_f32 v14, v22, v20
	v_addc_co_u32_e32 v39, vcc, 0, v19, vcc
	s_waitcnt lgkmcnt(4)
	v_cvt_pk_bf16_f32 v15, v24, v26
	s_waitcnt lgkmcnt(2)
	v_cvt_pk_bf16_f32 v16, v28, v30
	s_waitcnt lgkmcnt(0)
	v_cvt_pk_bf16_f32 v17, v32, v36
	v_add_co_u32_e32 v18, vcc, 0x21000, v18
	global_store_dwordx4 v[38:39], v[14:17], off sc1
	s_nop 0
	v_addc_co_u32_e32 v19, vcc, 0, v19, vcc
	v_cvt_pk_bf16_f32 v14, v23, v21
	v_cvt_pk_bf16_f32 v15, v25, v27
	v_cvt_pk_bf16_f32 v16, v29, v31
	v_cvt_pk_bf16_f32 v17, v33, v37
	global_store_dwordx4 v[18:19], v[14:17], off sc1
	s_waitcnt lgkmcnt(0)

; #define LAS __attribute__((address_space(3)))
; __device__ __forceinline__ unsigned pk2(float lo, float hi) { return pg8::cvt_pk_bf16(lo, hi); }
; __device__ __forceinline__ void transpose_tile(const float* src, int srcN, const float* gk, bf16_t* dst, int dstK, LAS float* scr, int lane) {
;     ...
;     for (int i = 0; i < 32; ++i) scr[(2 * i + (lane >> 5)) * 33 + (lane & 31)] = tv[i];
;     asm volatile("s_waitcnt lgkmcnt(0)" ::: "memory");
;     const int c = lane & 7;
; #pragma unroll
;     for (int j = 0; j < 4; ++j) {
;         const int n = (lane >> 3) + 8 * j; const LAS float* s = scr + (8 * c) * 33 + n;
;         u32x4 o; o.x = pk2(s[0 * 33], s[1 * 33]); o.y = pk2(s[2 * 33], s[3 * 33]); o.z = pk2(s[4 * 33], s[5 * 33]); o.w = pk2(s[6 * 33], s[7 * 33]);
;         *(u32x4*)(dst + (size_t)n * dstK + 8 * c) = o;
;     }
;     asm volatile("s_waitcnt lgkmcnt(0)" ::: "memory");
; __device__ __forceinline__ void convert_layer(const Params& p, int l, LAS unsigned char* lds, int it_lo, int it_hi, int worker, int nworkers) {
;     ...
;         if (r < 2 * I_GU) {
;             const int f = r / I_GU; r -= f * I_GU; const int nb = r / (DM / 64), kb = r % (DM / 64), n0 = nb * 32, k0 = kb * 64;
;             const int pn = n0 >> 8, w = n0 & 255; const float* src = ((w < 128) ? p.ffn_w_gate : p.ffn_w_up) + (size_t)(l * 2 + f) * DM * DFF;
;             transpose_tile(src + (size_t)k0 * DFF + pn * 128 + (w & 127), DFF, ng + (f ? 2 : 0) * DM + k0, W + (f ? O_WGU1 : O_WGU0) + (size_t)n0 * DM + k0, DM, scr, lane); continue; }
.LBB0_672:
	v_add_u32_e32 v5, v185, v179
	s_waitcnt vmcnt(30)
	ds_write2_b32 v5, v88, v89 offset1:66
	s_waitcnt vmcnt(28)
	ds_write2_b32 v5, v94, v95 offset0:132 offset1:198
	v_add_u32_e32 v5, 0x400, v5
	s_waitcnt vmcnt(26)
	ds_write2_b32 v5, v92, v93 offset0:8 offset1:74
	v_add_u32_e32 v5, v185, v180
	s_waitcnt vmcnt(24)
	ds_write2_b32 v5, v90, v91 offset1:66
	s_waitcnt vmcnt(22)
	ds_write2_b32 v5, v100, v101 offset0:132 offset1:198
	v_add_u32_e32 v5, 0x400, v5
	s_waitcnt vmcnt(20)
	ds_write2_b32 v5, v98, v99 offset0:8 offset1:74
	v_add_u32_e32 v5, v185, v181
	s_waitcnt vmcnt(18)
	ds_write2_b32 v5, v96, v97 offset1:66
	s_waitcnt vmcnt(16)
	ds_write2_b32 v5, v106, v107 offset0:132 offset1:198
	v_add_u32_e32 v5, 0x400, v5
	s_lshl_b32 s10, s8, 5
	s_waitcnt vmcnt(14)
	ds_write2_b32 v5, v104, v105 offset0:8 offset1:74
	v_add_u32_e32 v5, v185, v182
	s_and_b64 s[4:5], s[4:5], exec
	s_waitcnt vmcnt(12)
	ds_write2_b32 v5, v102, v103 offset1:66
	s_waitcnt vmcnt(10)
	ds_write2_b32 v5, v112, v113 offset0:132 offset1:198
	v_add_u32_e32 v5, 0x400, v5
	s_cselect_b32 s4, 0, 0x2300000
	s_waitcnt vmcnt(8)
	ds_write2_b32 v5, v110, v111 offset0:8 offset1:74
	v_add_u32_e32 v5, v185, v183
	s_add_u32 s8, s26, s4
	s_waitcnt vmcnt(6)
	ds_write2_b32 v5, v108, v109 offset1:66
	s_waitcnt vmcnt(4)
	ds_write2_b32 v5, v118, v119 offset0:132 offset1:198
	v_add_u32_e32 v5, 0x400, v5
	s_addc_u32 s16, s27, 0
	s_ashr_i32 s11, s10, 31
	s_waitcnt vmcnt(2)
	ds_write2_b32 v5, v116, v117 offset0:8 offset1:74
	s_waitcnt vmcnt(0)
	ds_write2_b32 v5, v114, v115 offset0:140 offset1:206
	s_lshl_b64 s[4:5], s[10:11], 11
	s_waitcnt lgkmcnt(0)
	s_add_u32 s4, s8, s4
	ds_read2_b32 v[92:93], v1 offset0:33 offset1:41
	ds_read2_b32 v[94:95], v1 offset1:8
	ds_read2_b32 v[96:97], v1 offset0:66 offset1:74
	ds_read2_b32 v[98:99], v1 offset0:99 offset1:107
	ds_read2_b32 v[100:101], v1 offset0:132 offset1:140
	ds_read2_b32 v[102:103], v1 offset0:165 offset1:173
	ds_read2_b32 v[104:105], v1 offset0:198 offset1:206
	ds_read2_b32 v[106:107], v1 offset0:231 offset1:239
	s_addc_u32 s5, s16, s5
	s_lshl_b64 s[0:1], s[0:1], 1
	s_add_u32 s0, s4, s0
	s_addc_u32 s1, s5, s1
	v_lshlrev_b32_e32 v196, 1, v0
	v_lshl_add_u64 v[108:109], s[0:1], 0, v[196:197]
	v_lshlrev_b32_e32 v196, 1, v14
	s_waitcnt lgkmcnt(6)
	v_cvt_pk_bf16_f32 v88, v94, v92
	s_waitcnt lgkmcnt(4)
	v_cvt_pk_bf16_f32 v89, v96, v98
	s_waitcnt lgkmcnt(2)
	v_cvt_pk_bf16_f32 v90, v100, v102
	s_waitcnt lgkmcnt(0)
	v_cvt_pk_bf16_f32 v91, v104, v106
	v_lshl_add_u64 v[110:111], v[108:109], 0, v[196:197]
	global_store_dwordx4 v[110:111], v[88:91], off sc1
	v_lshlrev_b32_e32 v196, 1, v16
	s_nop 0
	v_cvt_pk_bf16_f32 v88, v95, v93
	v_cvt_pk_bf16_f32 v89, v97, v99
	v_cvt_pk_bf16_f32 v90, v101, v103
	v_cvt_pk_bf16_f32 v91, v105, v107
	ds_read2_b32 v[94:95], v1 offset0:49 offset1:57
	ds_read2_b32 v[96:97], v1 offset0:16 offset1:24
	ds_read2_b32 v[98:99], v1 offset0:82 offset1:90
	ds_read2_b32 v[100:101], v1 offset0:115 offset1:123
	ds_read2_b32 v[102:103], v1 offset0:148 offset1:156
	ds_read2_b32 v[104:105], v1 offset0:181 offset1:189
	ds_read2_b32 v[106:107], v1 offset0:214 offset1:222
	ds_read2_b32 v[110:111], v1 offset0:247 offset1:255
	v_lshl_add_u64 v[92:93], v[108:109], 0, v[196:197]
	v_lshlrev_b32_e32 v196, 1, v18
	global_store_dwordx4 v[92:93], v[88:91], off sc1
	v_lshl_add_u64 v[92:93], v[108:109], 0, v[196:197]
	v_lshlrev_b32_e32 v196, 1, v20
	s_waitcnt lgkmcnt(6)
	v_cvt_pk_bf16_f32 v88, v96, v94
	s_waitcnt lgkmcnt(4)
	v_cvt_pk_bf16_f32 v89, v98, v100
	s_waitcnt lgkmcnt(2)
	v_cvt_pk_bf16_f32 v90, v102, v104
	s_waitcnt lgkmcnt(0)
	v_cvt_pk_bf16_f32 v91, v106, v110
	global_store_dwordx4 v[92:93], v[88:91], off sc1
	v_lshl_add_u64 v[92:93], v[108:109], 0, v[196:197]
	s_nop 0
	v_cvt_pk_bf16_f32 v88, v97, v95
	v_cvt_pk_bf16_f32 v89, v99, v101
	v_cvt_pk_bf16_f32 v90, v103, v105
	v_cvt_pk_bf16_f32 v91, v107, v111
	global_store_dwordx4 v[92:93], v[88:91], off sc1
	s_waitcnt lgkmcnt(0)

; #define LAS __attribute__((address_space(3)))
; __device__ __forceinline__ unsigned pk2(float lo, float hi) { return pg8::cvt_pk_bf16(lo, hi); }
; __device__ __forceinline__ void transpose_tile(const float* src, int srcN, const float* gk, bf16_t* dst, int dstK, LAS float* scr, int lane) {
;     float tv[32];
; #pragma unroll
;     for (int i = 0; i < 32; ++i) tv[i] = src[(size_t)(2 * i + (lane >> 5)) * srcN + (lane & 31)];
;     if (gk) {
; #pragma unroll
;         for (int i = 0; i < 32; ++i) tv[i] *= gk[2 * i + (lane >> 5)];
;     }
; #pragma unroll
;     for (int i = 0; i < 32; ++i) scr[(2 * i + (lane >> 5)) * 33 + (lane & 31)] = tv[i];
;     asm volatile("s_waitcnt lgkmcnt(0)" ::: "memory");
;     const int c = lane & 7;
; #pragma unroll
;     for (int j = 0; j < 4; ++j) {
;         const int n = (lane >> 3) + 8 * j; const LAS float* s = scr + (8 * c) * 33 + n;
;         u32x4 o; o.x = pk2(s[0 * 33], s[1 * 33]); o.y = pk2(s[2 * 33], s[3 * 33]); o.z = pk2(s[4 * 33], s[5 * 33]); o.w = pk2(s[6 * 33], s[7 * 33]);
;         *(u32x4*)(dst + (size_t)n * dstK + 8 * c) = o;
;     }
;     asm volatile("s_waitcnt lgkmcnt(0)" ::: "memory");
; __device__ __forceinline__ void convert_layer(const Params& p, int l, LAS unsigned char* lds, int it_lo, int it_hi, int worker, int nworkers) {
;     ...
;         r -= I_ING;
;         if (r < 3 * I_B) {
;             const int i = r / I_B; r -= i * I_B; const int nb = r / 8, kb = r % 8, n0 = nb * 32, k0 = kb * 64;
;             transpose_tile(p.w_branch + (size_t)(l * 3 + i) * 512 * DM + (size_t)k0 * DM + n0, DM, nullptr, W + O_WB + (size_t)i * E_WB + (size_t)n0 * 512 + k0, 512, scr, lane); continue; }
;         r -= 3 * I_B;
;         {
;             const int nb = r / (DM / 64), kb = r % (DM / 64), n0 = nb * 32, k0 = kb * 64;
;             transpose_tile(p.w_o + (size_t)l * DM * DM + (size_t)k0 * DM + n0, DM, nullptr, W + O_WO + (size_t)n0 * DM + k0, DM, scr, lane); }
.LBB0_674:
	s_add_i32 s16, s14, 0x2e80
	s_cmpk_gt_i32 s16, 0x15ff
	s_mov_b64 s[0:1], -1
	s_cbranch_scc0 .LBB0_691
	s_cmpk_gt_u32 s16, 0x20ff
	s_cbranch_scc0 .LBB0_688
	s_cmpk_gt_u32 s16, 0x2e7f
	s_cbranch_scc0 .LBB0_682
	s_cmpk_gt_u32 s16, 0x317f
	s_cbranch_scc0 .LBB0_679
	s_and_b32 s0, s12, 0x7fffffe0
	s_and_b32 s10, s13, 0x3c0
	s_add_i32 s8, s0, 0xffff9d00
	s_lshl_b32 s0, s10, 12
	s_add_u32 s4, s82, s0
	s_addc_u32 s5, s83, 0
	s_lshl_b64 s[0:1], s[8:9], 2
	s_add_u32 s4, s4, s0
	s_addc_u32 s5, s5, s1
	v_lshlrev_b32_e32 v5, 2, v2
	v_lshlrev_b32_e32 v7, 2, v22
	global_load_dword v5, v5, s[4:5]
	v_lshlrev_b32_e32 v9, 2, v24
	global_load_dword v7, v7, s[4:5]
	v_lshlrev_b32_e32 v11, 2, v26
	v_lshlrev_b32_e32 v13, 2, v28
	v_lshlrev_b32_e32 v88, 2, v30
	global_load_dword v9, v9, s[4:5]
	v_lshlrev_b32_e32 v89, 2, v32
	global_load_dword v11, v11, s[4:5]
	v_lshlrev_b32_e32 v90, 2, v36
	global_load_dword v13, v13, s[4:5]
	v_lshlrev_b32_e32 v91, 2, v38
	global_load_dword v88, v88, s[4:5]
	v_lshlrev_b32_e32 v92, 2, v40
	global_load_dword v89, v89, s[4:5]
	v_lshlrev_b32_e32 v93, 2, v42
	global_load_dword v90, v90, s[4:5]
	v_lshlrev_b32_e32 v94, 2, v44
	global_load_dword v91, v91, s[4:5]
	v_lshlrev_b32_e32 v95, 2, v46
	global_load_dword v92, v92, s[4:5]
	v_lshlrev_b32_e32 v96, 2, v48
	global_load_dword v93, v93, s[4:5]
	v_lshlrev_b32_e32 v97, 2, v50
	global_load_dword v94, v94, s[4:5]
	v_lshlrev_b32_e32 v98, 2, v52
	global_load_dword v95, v95, s[4:5]
	v_lshlrev_b32_e32 v99, 2, v54
	global_load_dword v96, v96, s[4:5]
	v_lshlrev_b32_e32 v100, 2, v56
	global_load_dword v97, v97, s[4:5]
	v_lshlrev_b32_e32 v101, 2, v58
	global_load_dword v98, v98, s[4:5]
	v_lshlrev_b32_e32 v102, 2, v60
	global_load_dword v99, v99, s[4:5]
	v_lshlrev_b32_e32 v103, 2, v62
	global_load_dword v100, v100, s[4:5]
	v_lshlrev_b32_e32 v104, 2, v64
	global_load_dword v101, v101, s[4:5]
	v_lshlrev_b32_e32 v105, 2, v66
	global_load_dword v102, v102, s[4:5]
	v_lshlrev_b32_e32 v106, 2, v68
	global_load_dword v103, v103, s[4:5]
	v_lshlrev_b32_e32 v107, 2, v70
	global_load_dword v104, v104, s[4:5]
	v_lshlrev_b32_e32 v108, 2, v72
	global_load_dword v105, v105, s[4:5]
	v_lshlrev_b32_e32 v109, 2, v74
	global_load_dword v106, v106, s[4:5]
	v_lshlrev_b32_e32 v110, 2, v76
	global_load_dword v107, v107, s[4:5]
	v_lshlrev_b32_e32 v111, 2, v78
	global_load_dword v108, v108, s[4:5]
	v_lshlrev_b32_e32 v112, 2, v80
	global_load_dword v109, v109, s[4:5]
	v_lshlrev_b32_e32 v113, 2, v82
	global_load_dword v110, v110, s[4:5]
	v_lshlrev_b32_e32 v114, 2, v84
	global_load_dword v111, v111, s[4:5]
	v_add_u32_e32 v115, v185, v179
	global_load_dword v112, v112, s[4:5]
	s_lshl_b64 s[0:1], s[8:9], 11
	global_load_dword v113, v113, s[4:5]
	v_readlane_b32 s8, v252, 11
	global_load_dword v114, v114, s[4:5]
	s_add_u32 s0, s8, s0
	v_readlane_b32 s8, v252, 12
	s_addc_u32 s1, s8, s1
	s_lshl_b32 s8, s10, 1
	s_add_u32 s0, s0, s8
	s_addc_u32 s1, s1, 0
	v_lshlrev_b32_e32 v196, 1, v0
	s_waitcnt vmcnt(30)
	ds_write2_b32 v115, v5, v7 offset1:66
	s_waitcnt vmcnt(28)
	ds_write2_b32 v115, v9, v11 offset0:132 offset1:198
	v_add_u32_e32 v5, 0x400, v115
	s_waitcnt vmcnt(26)
	ds_write2_b32 v5, v13, v88 offset0:8 offset1:74
	v_add_u32_e32 v5, v185, v180
	s_waitcnt vmcnt(24)
	ds_write2_b32 v5, v89, v90 offset1:66
	s_waitcnt vmcnt(22)
	ds_write2_b32 v5, v91, v92 offset0:132 offset1:198
	v_add_u32_e32 v5, 0x400, v5
	s_waitcnt vmcnt(20)
	ds_write2_b32 v5, v93, v94 offset0:8 offset1:74
	v_add_u32_e32 v5, v185, v181
	s_waitcnt vmcnt(18)
	ds_write2_b32 v5, v95, v96 offset1:66
	s_waitcnt vmcnt(16)
	ds_write2_b32 v5, v97, v98 offset0:132 offset1:198
	v_add_u32_e32 v5, 0x400, v5
	v_lshl_add_u64 v[92:93], s[0:1], 0, v[196:197]
	v_lshlrev_b32_e32 v196, 1, v14
	s_mov_b64 s[0:1], 0
	s_waitcnt vmcnt(14)
	ds_write2_b32 v5, v99, v100 offset0:8 offset1:74
	v_add_u32_e32 v5, v185, v182
	s_waitcnt vmcnt(12)
	ds_write2_b32 v5, v101, v102 offset1:66
	s_waitcnt vmcnt(10)
	ds_write2_b32 v5, v103, v104 offset0:132 offset1:198
	v_add_u32_e32 v5, 0x400, v5
	s_waitcnt vmcnt(8)
	ds_write2_b32 v5, v105, v106 offset0:8 offset1:74
	v_add_u32_e32 v5, v185, v183
	s_waitcnt vmcnt(6)
	ds_write2_b32 v5, v107, v108 offset1:66
	s_waitcnt vmcnt(4)
	ds_write2_b32 v5, v109, v110 offset0:132 offset1:198
	v_add_u32_e32 v5, 0x400, v5
	s_waitcnt vmcnt(2)
	ds_write2_b32 v5, v111, v112 offset0:8 offset1:74
	s_waitcnt vmcnt(0)
	ds_write2_b32 v5, v113, v114 offset0:140 offset1:206
	s_waitcnt lgkmcnt(0)
	ds_read2_b32 v[94:95], v1 offset0:33 offset1:41
	ds_read2_b32 v[96:97], v1 offset1:8
	ds_read2_b32 v[98:99], v1 offset0:66 offset1:74
	ds_read2_b32 v[100:101], v1 offset0:99 offset1:107
	ds_read2_b32 v[102:103], v1 offset0:132 offset1:140
	ds_read2_b32 v[104:105], v1 offset0:165 offset1:173
	ds_read2_b32 v[106:107], v1 offset0:198 offset1:206
	ds_read2_b32 v[108:109], v1 offset0:231 offset1:239
	v_lshl_add_u64 v[110:111], v[92:93], 0, v[196:197]
	s_waitcnt lgkmcnt(6)
	v_cvt_pk_bf16_f32 v88, v96, v94
	s_waitcnt lgkmcnt(4)
	v_cvt_pk_bf16_f32 v89, v98, v100
	s_waitcnt lgkmcnt(2)
	v_cvt_pk_bf16_f32 v90, v102, v104
	s_waitcnt lgkmcnt(0)
	v_cvt_pk_bf16_f32 v91, v106, v108
	v_lshlrev_b32_e32 v196, 1, v16
	global_store_dwordx4 v[110:111], v[88:91], off sc1
	s_nop 1
	v_cvt_pk_bf16_f32 v88, v97, v95
	v_cvt_pk_bf16_f32 v89, v99, v101
	v_cvt_pk_bf16_f32 v90, v103, v105
	v_cvt_pk_bf16_f32 v91, v107, v109
	v_lshl_add_u64 v[94:95], v[92:93], 0, v[196:197]
	global_store_dwordx4 v[94:95], v[88:91], off sc1
	ds_read2_b32 v[94:95], v1 offset0:49 offset1:57
	ds_read2_b32 v[96:97], v1 offset0:16 offset1:24
	ds_read2_b32 v[98:99], v1 offset0:82 offset1:90
	ds_read2_b32 v[100:101], v1 offset0:115 offset1:123
	ds_read2_b32 v[102:103], v1 offset0:148 offset1:156
	ds_read2_b32 v[104:105], v1 offset0:181 offset1:189
	ds_read2_b32 v[106:107], v1 offset0:214 offset1:222
	ds_read2_b32 v[108:109], v1 offset0:247 offset1:255
	v_lshlrev_b32_e32 v196, 1, v18
	s_waitcnt lgkmcnt(6)
	v_cvt_pk_bf16_f32 v88, v96, v94
	s_waitcnt lgkmcnt(4)
	v_cvt_pk_bf16_f32 v89, v98, v100
	s_waitcnt lgkmcnt(2)
	v_cvt_pk_bf16_f32 v90, v102, v104
	s_waitcnt lgkmcnt(0)
	v_cvt_pk_bf16_f32 v91, v106, v108
	v_lshl_add_u64 v[110:111], v[92:93], 0, v[196:197]
	v_lshlrev_b32_e32 v196, 1, v20
	global_store_dwordx4 v[110:111], v[88:91], off sc1
	v_lshl_add_u64 v[92:93], v[92:93], 0, v[196:197]
	s_nop 0
	v_cvt_pk_bf16_f32 v88, v97, v95
	v_cvt_pk_bf16_f32 v89, v99, v101
	v_cvt_pk_bf16_f32 v90, v103, v105
	v_cvt_pk_bf16_f32 v91, v107, v109
	global_store_dwordx4 v[92:93], v[88:91], off sc1
	s_waitcnt lgkmcnt(0)
; #define LAS __attribute__((address_space(3)))
; __device__ __forceinline__ unsigned pk2(float lo, float hi) { return pg8::cvt_pk_bf16(lo, hi); }
; __device__ __forceinline__ void transpose_tile(const float* src, int srcN, const float* gk, bf16_t* dst, int dstK, LAS float* scr, int lane) {
;     float tv[32];
; #pragma unroll
;     for (int i = 0; i < 32; ++i) tv[i] = src[(size_t)(2 * i + (lane >> 5)) * srcN + (lane & 31)];
;     if (gk) {
; #pragma unroll
;         for (int i = 0; i < 32; ++i) tv[i] *= gk[2 * i + (lane >> 5)];
;     }
; #pragma unroll
;     for (int i = 0; i < 32; ++i) scr[(2 * i + (lane >> 5)) * 33 + (lane & 31)] = tv[i];
;     asm volatile("s_waitcnt lgkmcnt(0)" ::: "memory");
;     const int c = lane & 7;
; #pragma unroll
;     for (int j = 0; j < 4; ++j) {
;         const int n = (lane >> 3) + 8 * j; const LAS float* s = scr + (8 * c) * 33 + n;
;         u32x4 o; o.x = pk2(s[0 * 33], s[1 * 33]); o.y = pk2(s[2 * 33], s[3 * 33]); o.z = pk2(s[4 * 33], s[5 * 33]); o.w = pk2(s[6 * 33], s[7 * 33]);
;         *(u32x4*)(dst + (size_t)n * dstK + 8 * c) = o;
;     }
;     asm volatile("s_waitcnt lgkmcnt(0)" ::: "memory");
; __device__ __forceinline__ void convert_layer(const Params& p, int l, LAS unsigned char* lds, int it_lo, int it_hi, int worker, int nworkers) {
;     ...
;         if (r < 3 * I_B) {
;             const int i = r / I_B; r -= i * I_B; const int nb = r / 8, kb = r % 8, n0 = nb * 32, k0 = kb * 64;
;             transpose_tile(p.w_branch + (size_t)(l * 3 + i) * 512 * DM + (size_t)k0 * DM + n0, DM, nullptr, W + O_WB + (size_t)i * E_WB + (size_t)n0 * 512 + k0, 512, scr, lane); continue; }
.LBB0_679:
	s_andn2_b64 vcc, exec, s[0:1]
	s_cbranch_vccnz .LBB0_681
	s_lshr_b32 s8, s14, 8
	s_and_b32 s4, s15, 0x3e0
	s_and_b32 s5, s13, 0x1c0
	s_lshl_b64 s[0:1], s[8:9], 21
	s_add_u32 s0, s76, s0
	s_addc_u32 s1, s77, s1
	s_lshl_b32 s10, s5, 12
	s_add_u32 s0, s0, s10
	s_addc_u32 s1, s1, 0
	s_lshl_b32 s10, s4, 2
	s_add_u32 s0, s0, s10
	s_addc_u32 s1, s1, 0
	v_lshlrev_b32_e32 v5, 2, v2
	v_lshlrev_b32_e32 v7, 2, v22
	v_lshlrev_b32_e32 v9, 2, v24
	v_lshlrev_b32_e32 v11, 2, v26
	v_lshlrev_b32_e32 v13, 2, v28
	v_lshlrev_b32_e32 v88, 2, v30
	v_lshlrev_b32_e32 v89, 2, v32
	v_lshlrev_b32_e32 v90, 2, v36
	global_load_dword v5, v5, s[0:1]
	s_nop 0
	global_load_dword v7, v7, s[0:1]
	s_nop 0
	global_load_dword v9, v9, s[0:1]
	s_nop 0
	global_load_dword v11, v11, s[0:1]
	s_nop 0
	global_load_dword v13, v13, s[0:1]
	s_nop 0
	global_load_dword v88, v88, s[0:1]
	s_nop 0
	global_load_dword v89, v89, s[0:1]
	s_nop 0
	global_load_dword v90, v90, s[0:1]
	v_lshlrev_b32_e32 v91, 2, v38
	v_lshlrev_b32_e32 v92, 2, v40
	v_lshlrev_b32_e32 v93, 2, v42
	v_lshlrev_b32_e32 v94, 2, v44
	v_lshlrev_b32_e32 v95, 2, v46
	v_lshlrev_b32_e32 v96, 2, v48
	v_lshlrev_b32_e32 v97, 2, v50
	v_lshlrev_b32_e32 v98, 2, v52
	global_load_dword v91, v91, s[0:1]
	s_nop 0
	global_load_dword v92, v92, s[0:1]
	s_nop 0
	global_load_dword v93, v93, s[0:1]
	s_nop 0
	global_load_dword v94, v94, s[0:1]
	s_nop 0
	global_load_dword v95, v95, s[0:1]
	s_nop 0
	global_load_dword v96, v96, s[0:1]
	s_nop 0
	global_load_dword v97, v97, s[0:1]
	s_nop 0
	global_load_dword v98, v98, s[0:1]
	v_lshlrev_b32_e32 v99, 2, v54
	v_lshlrev_b32_e32 v100, 2, v56
	v_lshlrev_b32_e32 v101, 2, v58
	v_lshlrev_b32_e32 v102, 2, v60
	v_lshlrev_b32_e32 v103, 2, v62
	v_lshlrev_b32_e32 v104, 2, v64
	v_lshlrev_b32_e32 v105, 2, v66
	v_lshlrev_b32_e32 v106, 2, v68
	global_load_dword v99, v99, s[0:1]
	s_nop 0
	global_load_dword v100, v100, s[0:1]
	s_nop 0
	global_load_dword v101, v101, s[0:1]
	s_nop 0
	global_load_dword v102, v102, s[0:1]
	s_nop 0
	global_load_dword v103, v103, s[0:1]
	s_nop 0
	global_load_dword v104, v104, s[0:1]
	s_nop 0
	global_load_dword v105, v105, s[0:1]
	s_nop 0
	global_load_dword v106, v106, s[0:1]
	v_lshlrev_b32_e32 v107, 2, v70
	v_lshlrev_b32_e32 v108, 2, v72
	v_lshlrev_b32_e32 v109, 2, v74
	v_lshlrev_b32_e32 v110, 2, v76
	v_lshlrev_b32_e32 v111, 2, v78
	v_lshlrev_b32_e32 v112, 2, v80
	v_lshlrev_b32_e32 v113, 2, v82
	v_lshlrev_b32_e32 v114, 2, v84
	global_load_dword v107, v107, s[0:1]
	s_nop 0
	global_load_dword v108, v108, s[0:1]
	s_nop 0
	global_load_dword v109, v109, s[0:1]
	s_nop 0
	global_load_dword v110, v110, s[0:1]
	s_nop 0
	global_load_dword v111, v111, s[0:1]
	s_nop 0
	global_load_dword v112, v112, s[0:1]
	s_nop 0
	global_load_dword v113, v113, s[0:1]
	s_nop 0
	global_load_dword v114, v114, s[0:1]
	v_add_u32_e32 v115, v185, v179
	v_add_u32_e32 v116, 0x400, v115
	s_lshl_b64 s[0:1], s[8:9], 20
	v_readlane_b32 s8, v252, 13
	s_add_u32 s0, s8, s0
	v_readlane_b32 s8, v252, 14
	s_addc_u32 s1, s8, s1
	s_lshl_b32 s4, s4, 10
	s_add_u32 s0, s0, s4
	s_addc_u32 s1, s1, 0
	s_lshl_b32 s4, s5, 1
	s_add_u32 s0, s0, s4
	s_addc_u32 s1, s1, 0
	v_lshlrev_b32_e32 v196, 1, v0
	s_waitcnt vmcnt(30)
	ds_write2_b32 v115, v5, v7 offset1:66
	s_waitcnt vmcnt(28)
	ds_write2_b32 v115, v9, v11 offset0:132 offset1:198
	s_waitcnt vmcnt(26)
	ds_write2_b32 v116, v13, v88 offset0:8 offset1:74
	v_add_u32_e32 v5, v185, v180
	s_waitcnt vmcnt(24)
	ds_write2_b32 v5, v89, v90 offset1:66
	s_waitcnt vmcnt(22)
	ds_write2_b32 v5, v91, v92 offset0:132 offset1:198
	v_add_u32_e32 v5, 0x400, v5
	s_waitcnt vmcnt(20)
	ds_write2_b32 v5, v93, v94 offset0:8 offset1:74
	v_add_u32_e32 v5, v185, v181
	s_waitcnt vmcnt(18)
	ds_write2_b32 v5, v95, v96 offset1:66
	s_waitcnt vmcnt(16)
	ds_write2_b32 v5, v97, v98 offset0:132 offset1:198
	v_add_u32_e32 v5, 0x400, v5
	v_mov_b32_e32 v7, v197
	s_waitcnt vmcnt(14)
	ds_write2_b32 v5, v99, v100 offset0:8 offset1:74
	v_add_u32_e32 v5, v185, v182
	s_waitcnt vmcnt(12)
	ds_write2_b32 v5, v101, v102 offset1:66
	s_waitcnt vmcnt(10)
	ds_write2_b32 v5, v103, v104 offset0:132 offset1:198
	v_add_u32_e32 v5, 0x400, v5
	s_waitcnt vmcnt(8)
	ds_write2_b32 v5, v105, v106 offset0:8 offset1:74
	v_add_u32_e32 v5, v185, v183
	s_waitcnt vmcnt(6)
	ds_write2_b32 v5, v107, v108 offset1:66
	s_waitcnt vmcnt(4)
	ds_write2_b32 v5, v109, v110 offset0:132 offset1:198
	v_add_u32_e32 v5, 0x400, v5
	s_waitcnt vmcnt(2)
	ds_write2_b32 v5, v111, v112 offset0:8 offset1:74
	s_waitcnt vmcnt(0)
	ds_write2_b32 v5, v113, v114 offset0:140 offset1:206
	s_waitcnt lgkmcnt(0)
	ds_read2_b32 v[92:93], v1 offset0:33 offset1:41
	ds_read2_b32 v[94:95], v1 offset1:8
	ds_read2_b32 v[96:97], v1 offset0:66 offset1:74
	ds_read2_b32 v[98:99], v1 offset0:99 offset1:107
	ds_read2_b32 v[100:101], v1 offset0:132 offset1:140
	ds_read2_b32 v[102:103], v1 offset0:165 offset1:173
	ds_read2_b32 v[104:105], v1 offset0:198 offset1:206
	ds_read2_b32 v[106:107], v1 offset0:231 offset1:239
	v_lshl_add_u64 v[108:109], s[0:1], 0, v[196:197]
	v_mov_b32_e32 v5, v197
	s_waitcnt lgkmcnt(6)
	v_cvt_pk_bf16_f32 v88, v94, v92
	s_waitcnt lgkmcnt(4)
	v_cvt_pk_bf16_f32 v89, v96, v98
	s_waitcnt lgkmcnt(2)
	v_cvt_pk_bf16_f32 v90, v100, v102
	s_waitcnt lgkmcnt(0)
	v_cvt_pk_bf16_f32 v91, v104, v106
	v_lshl_add_u64 v[110:111], v[108:109], 0, v[4:5]
	global_store_dwordx4 v[110:111], v[88:91], off sc1
	v_mov_b32_e32 v9, v197
	v_mov_b32_e32 v11, v197
	v_cvt_pk_bf16_f32 v88, v95, v93
	v_cvt_pk_bf16_f32 v89, v97, v99
	v_cvt_pk_bf16_f32 v90, v101, v103
	v_cvt_pk_bf16_f32 v91, v105, v107
	ds_read2_b32 v[94:95], v1 offset0:49 offset1:57
	ds_read2_b32 v[96:97], v1 offset0:16 offset1:24
	ds_read2_b32 v[98:99], v1 offset0:82 offset1:90
	ds_read2_b32 v[100:101], v1 offset0:115 offset1:123
	ds_read2_b32 v[102:103], v1 offset0:148 offset1:156
	ds_read2_b32 v[104:105], v1 offset0:181 offset1:189
	ds_read2_b32 v[106:107], v1 offset0:214 offset1:222
	ds_read2_b32 v[110:111], v1 offset0:247 offset1:255
	v_lshl_add_u64 v[92:93], v[108:109], 0, v[6:7]
	global_store_dwordx4 v[92:93], v[88:91], off sc1
	v_lshl_add_u64 v[92:93], v[108:109], 0, v[8:9]
	s_waitcnt lgkmcnt(6)
	v_cvt_pk_bf16_f32 v88, v96, v94
	s_waitcnt lgkmcnt(4)
	v_cvt_pk_bf16_f32 v89, v98, v100
	s_waitcnt lgkmcnt(2)
	v_cvt_pk_bf16_f32 v90, v102, v104
	s_waitcnt lgkmcnt(0)
	v_cvt_pk_bf16_f32 v91, v106, v110
	global_store_dwordx4 v[92:93], v[88:91], off sc1
	v_lshl_add_u64 v[92:93], v[108:109], 0, v[10:11]
	s_nop 0
	v_cvt_pk_bf16_f32 v88, v97, v95
	v_cvt_pk_bf16_f32 v89, v99, v101
	v_cvt_pk_bf16_f32 v90, v103, v105
	v_cvt_pk_bf16_f32 v91, v107, v111
	global_store_dwordx4 v[92:93], v[88:91], off sc1
	s_waitcnt lgkmcnt(0)

; #define LAS __attribute__((address_space(3)))
; __device__ __forceinline__ void transpose_tile(const float* src, int srcN, const float* gk, bf16_t* dst, int dstK, LAS float* scr, int lane) {
;     float tv[32];
; #pragma unroll
;     for (int i = 0; i < 32; ++i) tv[i] = src[(size_t)(2 * i + (lane >> 5)) * srcN + (lane & 31)];
;     if (gk) {
; #pragma unroll
;         for (int i = 0; i < 32; ++i) tv[i] *= gk[2 * i + (lane >> 5)];
;     }
; __device__ __forceinline__ void convert_layer(const Params& p, int l, LAS unsigned char* lds, int it_lo, int it_hi, int worker, int nworkers) {
;     ...
;         if (r < I_ING) {
;             const int nb = r / (DM / 64), kb = r % (DM / 64), n0 = nb * 32, k0 = kb * 64;
;             if (n0 < NPROJ) transpose_tile(p.w_in + (size_t)l * DM * NPROJ + (size_t)k0 * NPROJ + n0, NPROJ, ng + DM + k0, W + O_WING + (size_t)n0 * DM + k0, DM, scr, lane);
;             else transpose_tile(p.w_gate + (size_t)l * DM * NGATE + (size_t)k0 * NGATE + (n0 - NPROJ), NGATE, ng + DM + k0, W + O_WING + (size_t)n0 * DM + k0, DM, scr, lane);
.LBB0_682:
	s_andn2_b64 vcc, exec, s[0:1]
	s_cbranch_vccnz .LBB0_687
	s_and_b32 s5, s12, 0x7fe0
	s_add_i32 s8, s5, 0xffffbe00
	s_and_b32 s4, s13, 0x3c0
	s_cmpk_gt_u32 s8, 0xeff
	s_mov_b64 s[0:1], -1
	s_cbranch_scc0 .LBB0_685
	s_mul_i32 s0, s4, 0x3000
	s_add_u32 s0, s78, s0
	s_addc_u32 s1, s79, 0
	s_lshl_b32 s5, s5, 2
	s_add_u32 s0, s0, s5
	s_addc_u32 s1, s1, 0
	s_add_u32 s10, s0, 0xfffebc00
	s_addc_u32 s11, s1, -1
	s_lshl_b64 s[0:1], s[8:9], 11
	v_readlane_b32 s5, v252, 17
	s_add_u32 s0, s5, s0
	v_readlane_b32 s5, v252, 18
	s_addc_u32 s1, s5, s1
	s_lshl_b32 s5, s4, 1
	s_add_u32 s0, s0, s5
	s_addc_u32 s1, s1, 0
	global_load_dword v5, v29, s[10:11]
	global_load_dword v7, v3, s[10:11]
	global_load_dword v9, v15, s[10:11]
	global_load_dword v11, v17, s[10:11]
	global_load_dword v13, v19, s[10:11]
	global_load_dword v90, v21, s[10:11]
	global_load_dword v91, v23, s[10:11]
	global_load_dword v92, v25, s[10:11]
	global_load_dword v93, v27, s[10:11]
	global_load_dword v94, v31, s[10:11]
	global_load_dword v95, v33, s[10:11]
	global_load_dword v96, v35, s[10:11]
	global_load_dword v97, v37, s[10:11]
	global_load_dword v98, v39, s[10:11]
	global_load_dword v99, v41, s[10:11]
	global_load_dword v100, v43, s[10:11]
	global_load_dword v101, v45, s[10:11]
	global_load_dword v102, v47, s[10:11]
	global_load_dword v103, v49, s[10:11]
	global_load_dword v104, v51, s[10:11]
	global_load_dword v105, v53, s[10:11]
	global_load_dword v106, v55, s[10:11]
	global_load_dword v107, v57, s[10:11]
	global_load_dword v108, v59, s[10:11]
	global_load_dword v109, v61, s[10:11]
	global_load_dword v110, v63, s[10:11]
	global_load_dword v111, v65, s[10:11]
	global_load_dword v112, v67, s[10:11]
	global_load_dword v113, v69, s[10:11]
	global_load_dword v114, v71, s[10:11]
	global_load_dword v115, v73, s[10:11]
	global_load_dword v116, v75, s[10:11]
	s_lshl_b32 s10, s4, 2
	s_mov_b32 s11, s9
	v_lshl_add_u64 v[88:89], v[86:87], 0, s[10:11]
	global_load_dword v117, v[88:89], off
	v_lshlrev_b32_e32 v196, 1, v0
	s_waitcnt vmcnt(0)
	v_mul_f32_e32 v5, v5, v117
	global_load_dword v117, v[88:89], off offset:8
	s_waitcnt vmcnt(0)
	v_mul_f32_e32 v7, v7, v117
	global_load_dword v117, v[88:89], off offset:16
	s_waitcnt vmcnt(0)
	v_mul_f32_e32 v9, v9, v117
	global_load_dword v117, v[88:89], off offset:24
	s_waitcnt vmcnt(0)
	v_mul_f32_e32 v11, v11, v117
	global_load_dword v117, v[88:89], off offset:32
	s_waitcnt vmcnt(0)
	v_mul_f32_e32 v13, v13, v117
	global_load_dword v117, v[88:89], off offset:40
	s_waitcnt vmcnt(0)
	v_mul_f32_e32 v90, v90, v117
	global_load_dword v117, v[88:89], off offset:48
	s_waitcnt vmcnt(0)
	v_mul_f32_e32 v91, v91, v117
	global_load_dword v117, v[88:89], off offset:56
	s_waitcnt vmcnt(0)
	v_mul_f32_e32 v92, v92, v117
	global_load_dword v117, v[88:89], off offset:64
	s_waitcnt vmcnt(0)
	v_mul_f32_e32 v93, v93, v117
	global_load_dword v117, v[88:89], off offset:72
	s_waitcnt vmcnt(0)
	v_mul_f32_e32 v94, v94, v117
	global_load_dword v117, v[88:89], off offset:80
	s_waitcnt vmcnt(0)
	v_mul_f32_e32 v95, v95, v117
	global_load_dword v117, v[88:89], off offset:88
	s_waitcnt vmcnt(0)
	v_mul_f32_e32 v96, v96, v117
	global_load_dword v117, v[88:89], off offset:96
	s_waitcnt vmcnt(0)
	v_mul_f32_e32 v97, v97, v117
	global_load_dword v117, v[88:89], off offset:104
	s_waitcnt vmcnt(0)
	v_mul_f32_e32 v98, v98, v117
	global_load_dword v117, v[88:89], off offset:112
	s_waitcnt vmcnt(0)
	v_mul_f32_e32 v99, v99, v117
	global_load_dword v117, v[88:89], off offset:120
	s_waitcnt vmcnt(0)
	v_mul_f32_e32 v100, v100, v117
	global_load_dword v117, v[88:89], off offset:128
	s_waitcnt vmcnt(0)
	v_mul_f32_e32 v101, v101, v117
	global_load_dword v117, v[88:89], off offset:136
	s_waitcnt vmcnt(0)
	v_mul_f32_e32 v102, v102, v117
	global_load_dword v117, v[88:89], off offset:144
	s_waitcnt vmcnt(0)
	v_mul_f32_e32 v103, v103, v117
	global_load_dword v117, v[88:89], off offset:152
	s_waitcnt vmcnt(0)
	v_mul_f32_e32 v104, v104, v117
	global_load_dword v117, v[88:89], off offset:160
	s_waitcnt vmcnt(0)
	v_mul_f32_e32 v105, v105, v117
	global_load_dword v117, v[88:89], off offset:168
	s_waitcnt vmcnt(0)
	v_mul_f32_e32 v106, v106, v117
	global_load_dword v117, v[88:89], off offset:176
	s_waitcnt vmcnt(0)
	v_mul_f32_e32 v107, v107, v117
	global_load_dword v117, v[88:89], off offset:184
	s_waitcnt vmcnt(0)
	v_mul_f32_e32 v108, v108, v117
	global_load_dword v117, v[88:89], off offset:192
	s_waitcnt vmcnt(0)
	v_mul_f32_e32 v109, v109, v117
	global_load_dword v117, v[88:89], off offset:200
	s_waitcnt vmcnt(0)
	v_mul_f32_e32 v110, v110, v117
	global_load_dword v117, v[88:89], off offset:208
	s_waitcnt vmcnt(0)
	v_mul_f32_e32 v111, v111, v117
	global_load_dword v117, v[88:89], off offset:216
	s_waitcnt vmcnt(0)
	v_mul_f32_e32 v112, v112, v117
	global_load_dword v117, v[88:89], off offset:224
	s_waitcnt vmcnt(0)
	v_mul_f32_e32 v113, v113, v117
	global_load_dword v117, v[88:89], off offset:232
	s_waitcnt vmcnt(0)
	v_mul_f32_e32 v114, v114, v117
	global_load_dword v117, v[88:89], off offset:240
	s_waitcnt vmcnt(0)
; #define LAS __attribute__((address_space(3)))
; __device__ __forceinline__ unsigned pk2(float lo, float hi) { return pg8::cvt_pk_bf16(lo, hi); }
; __device__ __forceinline__ void transpose_tile(const float* src, int srcN, const float* gk, bf16_t* dst, int dstK, LAS float* scr, int lane) {
;     float tv[32];
; #pragma unroll
;     for (int i = 0; i < 32; ++i) tv[i] = src[(size_t)(2 * i + (lane >> 5)) * srcN + (lane & 31)];
;     if (gk) {
; #pragma unroll
;         for (int i = 0; i < 32; ++i) tv[i] *= gk[2 * i + (lane >> 5)];
;     }
; #pragma unroll
;     for (int i = 0; i < 32; ++i) scr[(2 * i + (lane >> 5)) * 33 + (lane & 31)] = tv[i];
;     asm volatile("s_waitcnt lgkmcnt(0)" ::: "memory");
;     const int c = lane & 7;
; #pragma unroll
;     for (int j = 0; j < 4; ++j) {
;         const int n = (lane >> 3) + 8 * j; const LAS float* s = scr + (8 * c) * 33 + n;
;         u32x4 o; o.x = pk2(s[0 * 33], s[1 * 33]); o.y = pk2(s[2 * 33], s[3 * 33]); o.z = pk2(s[4 * 33], s[5 * 33]); o.w = pk2(s[6 * 33], s[7 * 33]);
;         *(u32x4*)(dst + (size_t)n * dstK + 8 * c) = o;
;     }
;     asm volatile("s_waitcnt lgkmcnt(0)" ::: "memory");
; __device__ __forceinline__ void convert_layer(const Params& p, int l, LAS unsigned char* lds, int it_lo, int it_hi, int worker, int nworkers) {
;     ...
;         if (r < I_ING) {
;             const int nb = r / (DM / 64), kb = r % (DM / 64), n0 = nb * 32, k0 = kb * 64;
;             if (n0 < NPROJ) transpose_tile(p.w_in + (size_t)l * DM * NPROJ + (size_t)k0 * NPROJ + n0, NPROJ, ng + DM + k0, W + O_WING + (size_t)n0 * DM + k0, DM, scr, lane);
;             else transpose_tile(p.w_gate + (size_t)l * DM * NGATE + (size_t)k0 * NGATE + (n0 - NPROJ), NGATE, ng + DM + k0, W + O_WING + (size_t)n0 * DM + k0, DM, scr, lane);
	v_mul_f32_e32 v115, v115, v117
	global_load_dword v88, v[88:89], off offset:248
	v_add_u32_e32 v89, v185, v179
	ds_write2_b32 v89, v5, v7 offset1:66
	ds_write2_b32 v89, v9, v11 offset0:132 offset1:198
	v_add_u32_e32 v5, 0x400, v89
	ds_write2_b32 v5, v13, v90 offset0:8 offset1:74
	v_add_u32_e32 v5, v185, v180
	ds_write2_b32 v5, v91, v92 offset1:66
	ds_write2_b32 v5, v93, v94 offset0:132 offset1:198
	v_add_u32_e32 v5, 0x400, v5
	ds_write2_b32 v5, v95, v96 offset0:8 offset1:74
	v_add_u32_e32 v5, v185, v181
	ds_write2_b32 v5, v97, v98 offset1:66
	ds_write2_b32 v5, v99, v100 offset0:132 offset1:198
	v_add_u32_e32 v5, 0x400, v5
	ds_write2_b32 v5, v101, v102 offset0:8 offset1:74
	v_add_u32_e32 v5, v185, v182
	ds_write2_b32 v5, v103, v104 offset1:66
	ds_write2_b32 v5, v105, v106 offset0:132 offset1:198
	v_add_u32_e32 v5, 0x400, v5
	ds_write2_b32 v5, v107, v108 offset0:8 offset1:74
	v_add_u32_e32 v5, v185, v183
	ds_write2_b32 v5, v109, v110 offset1:66
	ds_write2_b32 v5, v111, v112 offset0:132 offset1:198
	v_add_u32_e32 v5, 0x400, v5
	v_lshl_add_u64 v[92:93], s[0:1], 0, v[196:197]
	v_lshlrev_b32_e32 v196, 1, v14
	v_lshl_add_u64 v[110:111], v[92:93], 0, v[196:197]
	v_lshlrev_b32_e32 v196, 1, v16
	s_mov_b64 s[0:1], 0
	s_waitcnt vmcnt(0)
	v_mul_f32_e32 v88, v116, v88
	ds_write2_b32 v5, v113, v114 offset0:8 offset1:74
	ds_write2_b32 v5, v115, v88 offset0:140 offset1:206
	s_waitcnt lgkmcnt(0)
	ds_read2_b32 v[94:95], v1 offset0:33 offset1:41
	ds_read2_b32 v[96:97], v1 offset1:8
	ds_read2_b32 v[98:99], v1 offset0:66 offset1:74
	ds_read2_b32 v[100:101], v1 offset0:99 offset1:107
	ds_read2_b32 v[102:103], v1 offset0:132 offset1:140
	ds_read2_b32 v[104:105], v1 offset0:165 offset1:173
	ds_read2_b32 v[106:107], v1 offset0:198 offset1:206
	ds_read2_b32 v[108:109], v1 offset0:231 offset1:239
	s_waitcnt lgkmcnt(6)
	v_cvt_pk_bf16_f32 v88, v96, v94
	s_waitcnt lgkmcnt(4)
	v_cvt_pk_bf16_f32 v89, v98, v100
	s_waitcnt lgkmcnt(2)
	v_cvt_pk_bf16_f32 v90, v102, v104
	s_waitcnt lgkmcnt(0)
	v_cvt_pk_bf16_f32 v91, v106, v108
	global_store_dwordx4 v[110:111], v[88:91], off sc1
	s_nop 1
	v_cvt_pk_bf16_f32 v88, v97, v95
	v_cvt_pk_bf16_f32 v89, v99, v101
	v_cvt_pk_bf16_f32 v90, v103, v105
	v_cvt_pk_bf16_f32 v91, v107, v109
	v_lshl_add_u64 v[94:95], v[92:93], 0, v[196:197]
	global_store_dwordx4 v[94:95], v[88:91], off sc1
	ds_read2_b32 v[94:95], v1 offset0:49 offset1:57
	ds_read2_b32 v[96:97], v1 offset0:16 offset1:24
	ds_read2_b32 v[98:99], v1 offset0:82 offset1:90
	ds_read2_b32 v[100:101], v1 offset0:115 offset1:123
	ds_read2_b32 v[102:103], v1 offset0:148 offset1:156
	ds_read2_b32 v[104:105], v1 offset0:181 offset1:189
	ds_read2_b32 v[106:107], v1 offset0:214 offset1:222
	ds_read2_b32 v[108:109], v1 offset0:247 offset1:255
	v_lshlrev_b32_e32 v196, 1, v18
	s_waitcnt lgkmcnt(6)
	v_cvt_pk_bf16_f32 v88, v96, v94
	s_waitcnt lgkmcnt(4)
	v_cvt_pk_bf16_f32 v89, v98, v100
	s_waitcnt lgkmcnt(2)
	v_cvt_pk_bf16_f32 v90, v102, v104
	s_waitcnt lgkmcnt(0)
	v_cvt_pk_bf16_f32 v91, v106, v108
	v_lshl_add_u64 v[110:111], v[92:93], 0, v[196:197]
	v_lshlrev_b32_e32 v196, 1, v20
	global_store_dwordx4 v[110:111], v[88:91], off sc1
	v_lshl_add_u64 v[92:93], v[92:93], 0, v[196:197]
	s_nop 0
	v_cvt_pk_bf16_f32 v88, v97, v95
	v_cvt_pk_bf16_f32 v89, v99, v101
	v_cvt_pk_bf16_f32 v90, v103, v105
	v_cvt_pk_bf16_f32 v91, v107, v109
	global_store_dwordx4 v[92:93], v[88:91], off sc1
	s_waitcnt lgkmcnt(0)
.LBB0_685:
	s_andn2_b64 vcc, exec, s[0:1]
	s_cbranch_vccnz .LBB0_687
	s_mul_i32 s0, s4, 0x3c00
	s_add_u32 s5, s74, s0
	s_addc_u32 s11, s75, 0
	s_lshl_b64 s[0:1], s[8:9], 2
	s_add_u32 s10, s5, s0
	s_addc_u32 s11, s11, s1
	s_lshl_b64 s[0:1], s[8:9], 11
	v_readlane_b32 s5, v252, 17
	s_add_u32 s0, s5, s0
	v_readlane_b32 s5, v252, 18
	s_addc_u32 s1, s5, s1
	s_lshl_b32 s5, s4, 1
	s_add_u32 s0, s0, s5
	s_addc_u32 s1, s1, 0
	s_lshl_b32 s8, s4, 2
	v_lshl_add_u64 v[88:89], v[86:87], 0, s[8:9]
	global_load_dword v5, v145, s[10:11]
	global_load_dword v7, v77, s[10:11]
	global_load_dword v9, v79, s[10:11]
	global_load_dword v11, v81, s[10:11]
	global_load_dword v13, v83, s[10:11]
	global_load_dword v90, v85, s[10:11]
	global_load_dword v91, v120, s[10:11]
	global_load_dword v92, v121, s[10:11]
	global_load_dword v93, v122, s[10:11]
	global_load_dword v94, v123, s[10:11]
	global_load_dword v95, v124, s[10:11]
	global_load_dword v96, v125, s[10:11]
	global_load_dword v97, v126, s[10:11]
	global_load_dword v98, v127, s[10:11]
	global_load_dword v99, v128, s[10:11]
	global_load_dword v100, v129, s[10:11]
	global_load_dword v101, v130, s[10:11]
	global_load_dword v102, v131, s[10:11]
	global_load_dword v103, v132, s[10:11]
	global_load_dword v104, v133, s[10:11]
	global_load_dword v105, v134, s[10:11]
	global_load_dword v106, v135, s[10:11]
	global_load_dword v107, v136, s[10:11]
	global_load_dword v108, v137, s[10:11]
	global_load_dword v109, v138, s[10:11]
	global_load_dword v110, v139, s[10:11]
	global_load_dword v111, v140, s[10:11]
	global_load_dword v112, v141, s[10:11]
	global_load_dword v113, v142, s[10:11]
	global_load_dword v114, v143, s[10:11]
	global_load_dword v115, v144, s[10:11]
	global_load_dword v116, v146, s[10:11]
	global_load_dword v117, v[88:89], off
	v_lshlrev_b32_e32 v196, 1, v0
	s_waitcnt vmcnt(0)
	v_mul_f32_e32 v5, v5, v117
	global_load_dword v117, v[88:89], off offset:8
	s_waitcnt vmcnt(0)
	v_mul_f32_e32 v7, v7, v117
	global_load_dword v117, v[88:89], off offset:16
	s_waitcnt vmcnt(0)
	v_mul_f32_e32 v9, v9, v117
	global_load_dword v117, v[88:89], off offset:24
	s_waitcnt vmcnt(0)
	v_mul_f32_e32 v11, v11, v117
	global_load_dword v117, v[88:89], off offset:32
	s_waitcnt vmcnt(0)
; #define LAS __attribute__((address_space(3)))
; __device__ __forceinline__ unsigned pk2(float lo, float hi) { return pg8::cvt_pk_bf16(lo, hi); }
; __device__ __forceinline__ void transpose_tile(const float* src, int srcN, const float* gk, bf16_t* dst, int dstK, LAS float* scr, int lane) {
;     float tv[32];
; #pragma unroll
;     for (int i = 0; i < 32; ++i) tv[i] = src[(size_t)(2 * i + (lane >> 5)) * srcN + (lane & 31)];
;     if (gk) {
; #pragma unroll
;         for (int i = 0; i < 32; ++i) tv[i] *= gk[2 * i + (lane >> 5)];
;     }
; #pragma unroll
;     for (int i = 0; i < 32; ++i) scr[(2 * i + (lane >> 5)) * 33 + (lane & 31)] = tv[i];
;     asm volatile("s_waitcnt lgkmcnt(0)" ::: "memory");
;     const int c = lane & 7;
; #pragma unroll
;     for (int j = 0; j < 4; ++j) {
;         const int n = (lane >> 3) + 8 * j; const LAS float* s = scr + (8 * c) * 33 + n;
;         u32x4 o; o.x = pk2(s[0 * 33], s[1 * 33]); o.y = pk2(s[2 * 33], s[3 * 33]); o.z = pk2(s[4 * 33], s[5 * 33]); o.w = pk2(s[6 * 33], s[7 * 33]);
;         *(u32x4*)(dst + (size_t)n * dstK + 8 * c) = o;
;     }
;     asm volatile("s_waitcnt lgkmcnt(0)" ::: "memory");
	v_mul_f32_e32 v13, v13, v117
	global_load_dword v117, v[88:89], off offset:40
	s_waitcnt vmcnt(0)
	v_mul_f32_e32 v90, v90, v117
	global_load_dword v117, v[88:89], off offset:48
	s_waitcnt vmcnt(0)
	v_mul_f32_e32 v91, v91, v117
	global_load_dword v117, v[88:89], off offset:56
	s_waitcnt vmcnt(0)
	v_mul_f32_e32 v92, v92, v117
	global_load_dword v117, v[88:89], off offset:64
	s_waitcnt vmcnt(0)
	v_mul_f32_e32 v93, v93, v117
	global_load_dword v117, v[88:89], off offset:72
	s_waitcnt vmcnt(0)
	v_mul_f32_e32 v94, v94, v117
	global_load_dword v117, v[88:89], off offset:80
	s_waitcnt vmcnt(0)
	v_mul_f32_e32 v95, v95, v117
	global_load_dword v117, v[88:89], off offset:88
	s_waitcnt vmcnt(0)
	v_mul_f32_e32 v96, v96, v117
	global_load_dword v117, v[88:89], off offset:96
	s_waitcnt vmcnt(0)
	v_mul_f32_e32 v97, v97, v117
	global_load_dword v117, v[88:89], off offset:104
	s_waitcnt vmcnt(0)
	v_mul_f32_e32 v98, v98, v117
	global_load_dword v117, v[88:89], off offset:112
	s_waitcnt vmcnt(0)
	v_mul_f32_e32 v99, v99, v117
	global_load_dword v117, v[88:89], off offset:120
	s_waitcnt vmcnt(0)
	v_mul_f32_e32 v100, v100, v117
	global_load_dword v117, v[88:89], off offset:128
	s_waitcnt vmcnt(0)
	v_mul_f32_e32 v101, v101, v117
	global_load_dword v117, v[88:89], off offset:136
	s_waitcnt vmcnt(0)
	v_mul_f32_e32 v102, v102, v117
	global_load_dword v117, v[88:89], off offset:144
	s_waitcnt vmcnt(0)
	v_mul_f32_e32 v103, v103, v117
	global_load_dword v117, v[88:89], off offset:152
	s_waitcnt vmcnt(0)
	v_mul_f32_e32 v104, v104, v117
	global_load_dword v117, v[88:89], off offset:160
	s_waitcnt vmcnt(0)
	v_mul_f32_e32 v105, v105, v117
	global_load_dword v117, v[88:89], off offset:168
	s_waitcnt vmcnt(0)
	v_mul_f32_e32 v106, v106, v117
	global_load_dword v117, v[88:89], off offset:176
	s_waitcnt vmcnt(0)
	v_mul_f32_e32 v107, v107, v117
	global_load_dword v117, v[88:89], off offset:184
	s_waitcnt vmcnt(0)
	v_mul_f32_e32 v108, v108, v117
	global_load_dword v117, v[88:89], off offset:192
	s_waitcnt vmcnt(0)
	v_mul_f32_e32 v109, v109, v117
	global_load_dword v117, v[88:89], off offset:200
	s_waitcnt vmcnt(0)
	v_mul_f32_e32 v110, v110, v117
	global_load_dword v117, v[88:89], off offset:208
	s_waitcnt vmcnt(0)
	v_mul_f32_e32 v111, v111, v117
	global_load_dword v117, v[88:89], off offset:216
	s_waitcnt vmcnt(0)
	v_mul_f32_e32 v112, v112, v117
	global_load_dword v117, v[88:89], off offset:224
	s_waitcnt vmcnt(0)
	v_mul_f32_e32 v113, v113, v117
	global_load_dword v117, v[88:89], off offset:232
	s_waitcnt vmcnt(0)
	v_mul_f32_e32 v114, v114, v117
	global_load_dword v117, v[88:89], off offset:240
	s_waitcnt vmcnt(0)
	v_mul_f32_e32 v115, v115, v117
	global_load_dword v88, v[88:89], off offset:248
	v_add_u32_e32 v89, v185, v179
	ds_write2_b32 v89, v5, v7 offset1:66
	ds_write2_b32 v89, v9, v11 offset0:132 offset1:198
	v_add_u32_e32 v5, 0x400, v89
	ds_write2_b32 v5, v13, v90 offset0:8 offset1:74
	v_add_u32_e32 v5, v185, v180
	ds_write2_b32 v5, v91, v92 offset1:66
	ds_write2_b32 v5, v93, v94 offset0:132 offset1:198
	v_add_u32_e32 v5, 0x400, v5
	ds_write2_b32 v5, v95, v96 offset0:8 offset1:74
	v_add_u32_e32 v5, v185, v181
	ds_write2_b32 v5, v97, v98 offset1:66
	ds_write2_b32 v5, v99, v100 offset0:132 offset1:198
	v_add_u32_e32 v5, 0x400, v5
	ds_write2_b32 v5, v101, v102 offset0:8 offset1:74
	v_add_u32_e32 v5, v185, v182
	ds_write2_b32 v5, v103, v104 offset1:66
	ds_write2_b32 v5, v105, v106 offset0:132 offset1:198
	v_add_u32_e32 v5, 0x400, v5
	ds_write2_b32 v5, v107, v108 offset0:8 offset1:74
	v_add_u32_e32 v5, v185, v183
	ds_write2_b32 v5, v109, v110 offset1:66
	ds_write2_b32 v5, v111, v112 offset0:132 offset1:198
	v_add_u32_e32 v5, 0x400, v5
	v_lshl_add_u64 v[92:93], s[0:1], 0, v[196:197]
	v_lshlrev_b32_e32 v196, 1, v14
	v_lshl_add_u64 v[110:111], v[92:93], 0, v[196:197]
	v_lshlrev_b32_e32 v196, 1, v16
	s_waitcnt vmcnt(0)
	v_mul_f32_e32 v88, v116, v88
	ds_write2_b32 v5, v113, v114 offset0:8 offset1:74
	ds_write2_b32 v5, v115, v88 offset0:140 offset1:206
	s_waitcnt lgkmcnt(0)
	ds_read2_b32 v[94:95], v1 offset0:33 offset1:41
	ds_read2_b32 v[96:97], v1 offset1:8
	ds_read2_b32 v[98:99], v1 offset0:66 offset1:74
	ds_read2_b32 v[100:101], v1 offset0:99 offset1:107
	ds_read2_b32 v[102:103], v1 offset0:132 offset1:140
	ds_read2_b32 v[104:105], v1 offset0:165 offset1:173
	ds_read2_b32 v[106:107], v1 offset0:198 offset1:206
	ds_read2_b32 v[108:109], v1 offset0:231 offset1:239
	s_waitcnt lgkmcnt(6)
	v_cvt_pk_bf16_f32 v88, v96, v94
	s_waitcnt lgkmcnt(4)
	v_cvt_pk_bf16_f32 v89, v98, v100
	s_waitcnt lgkmcnt(2)
	v_cvt_pk_bf16_f32 v90, v102, v104
	s_waitcnt lgkmcnt(0)
	v_cvt_pk_bf16_f32 v91, v106, v108
	global_store_dwordx4 v[110:111], v[88:91], off sc1
	s_nop 1
	v_cvt_pk_bf16_f32 v88, v97, v95
	v_cvt_pk_bf16_f32 v89, v99, v101
	v_cvt_pk_bf16_f32 v90, v103, v105
	v_cvt_pk_bf16_f32 v91, v107, v109
	v_lshl_add_u64 v[94:95], v[92:93], 0, v[196:197]
	global_store_dwordx4 v[94:95], v[88:91], off sc1
	ds_read2_b32 v[94:95], v1 offset0:49 offset1:57
	ds_read2_b32 v[96:97], v1 offset0:16 offset1:24
	ds_read2_b32 v[98:99], v1 offset0:82 offset1:90
	ds_read2_b32 v[100:101], v1 offset0:115 offset1:123
	ds_read2_b32 v[102:103], v1 offset0:148 offset1:156
	ds_read2_b32 v[104:105], v1 offset0:181 offset1:189
	ds_read2_b32 v[106:107], v1 offset0:214 offset1:222
	ds_read2_b32 v[108:109], v1 offset0:247 offset1:255
	v_lshlrev_b32_e32 v196, 1, v18
	s_waitcnt lgkmcnt(6)
	v_cvt_pk_bf16_f32 v88, v96, v94
	s_waitcnt lgkmcnt(4)
	v_cvt_pk_bf16_f32 v89, v98, v100
	s_waitcnt lgkmcnt(2)
	v_cvt_pk_bf16_f32 v90, v102, v104
	s_waitcnt lgkmcnt(0)
	v_cvt_pk_bf16_f32 v91, v106, v108
	v_lshl_add_u64 v[110:111], v[92:93], 0, v[196:197]
	v_lshlrev_b32_e32 v196, 1, v20
	global_store_dwordx4 v[110:111], v[88:91], off sc1
	v_lshl_add_u64 v[92:93], v[92:93], 0, v[196:197]
	s_nop 0
	v_cvt_pk_bf16_f32 v88, v97, v95
	v_cvt_pk_bf16_f32 v89, v99, v101
	v_cvt_pk_bf16_f32 v90, v103, v105
	v_cvt_pk_bf16_f32 v91, v107, v109
	global_store_dwordx4 v[92:93], v[88:91], off sc1
	s_waitcnt lgkmcnt(0)

; #define LAS __attribute__((address_space(3)))
; __device__ __forceinline__ void transpose_tile(const float* src, int srcN, const float* gk, bf16_t* dst, int dstK, LAS float* scr, int lane) {
;     float tv[32];
; #pragma unroll
;     for (int i = 0; i < 32; ++i) tv[i] = src[(size_t)(2 * i + (lane >> 5)) * srcN + (lane & 31)];
; __device__ __forceinline__ void convert_layer(const Params& p, int l, LAS unsigned char* lds, int it_lo, int it_hi, int worker, int nworkers) {
;     ...
;         if (r < 2 * I_D) {
;             const int f = r / I_D; r -= f * I_D; const int nb = r / (DFF / 64), kb = r % (DFF / 64), n0 = nb * 32, k0 = kb * 64;
;             const float* src = p.ffn_w_down + (size_t)(l * 2 + f) * DFF * DM;
;             transpose_tile(src + (size_t)k0 * DM + n0, DM, nullptr, W + (f ? O_WD1 : O_WD0) + (size_t)n0 * DFF + k0, DFF, scr, lane); continue; }
.LBB0_688:
	s_andn2_b64 vcc, exec, s[0:1]
	s_cbranch_vccnz .LBB0_690
	s_add_i32 s8, s14, 0x1880
	s_cmpk_gt_u32 s8, 0x57f
	s_cselect_b32 s0, 0xfa80, 0
	s_cselect_b32 s1, 0xb00000, 0
	s_add_i32 s0, s8, s0
	s_sext_i32_i16 s4, s0
	s_mulk_i32 s4, 0xba3
	s_lshr_b32 s5, s4, 31
	s_ashr_i32 s4, s4, 17
	s_add_i32 s17, s4, s5
	s_mul_i32 s4, s17, 44
	s_sub_i32 s0, s0, s4
	s_sext_i32_i16 s0, s0
	v_readlane_b32 s40, v254, 57
	s_lshl_b32 s4, s17, 5
	s_lshl_b32 s0, s0, 6
	v_readlane_b32 s44, v254, 61
	v_readlane_b32 s45, v254, 62
	s_add_u32 s5, s44, s1
	s_addc_u32 s18, s45, 0
	s_ashr_i32 s1, s0, 31
	s_lshl_b64 s[10:11], s[0:1], 12
	s_add_u32 s19, s5, s10
	s_addc_u32 s18, s18, s11
	s_ashr_i32 s5, s4, 31
	s_lshl_b64 s[10:11], s[4:5], 2
	s_add_u32 s10, s19, s10
	s_addc_u32 s11, s18, s11
	v_lshlrev_b32_e32 v5, 2, v2
	v_lshlrev_b32_e32 v7, 2, v22
	v_lshlrev_b32_e32 v9, 2, v24
	v_lshlrev_b32_e32 v11, 2, v26
	v_lshlrev_b32_e32 v13, 2, v28
	v_lshlrev_b32_e32 v88, 2, v30
	v_lshlrev_b32_e32 v89, 2, v32
	v_lshlrev_b32_e32 v90, 2, v36
	global_load_dword v5, v5, s[10:11]
	s_nop 0
	global_load_dword v7, v7, s[10:11]
	s_nop 0
	global_load_dword v9, v9, s[10:11]
	s_nop 0
	global_load_dword v11, v11, s[10:11]
	s_nop 0
	global_load_dword v13, v13, s[10:11]
	s_nop 0
	global_load_dword v88, v88, s[10:11]
	s_nop 0
	global_load_dword v89, v89, s[10:11]
	s_nop 0
	global_load_dword v90, v90, s[10:11]
	v_lshlrev_b32_e32 v91, 2, v38
	v_lshlrev_b32_e32 v92, 2, v40
	v_lshlrev_b32_e32 v93, 2, v42
	v_lshlrev_b32_e32 v94, 2, v44
	v_lshlrev_b32_e32 v95, 2, v46
	v_lshlrev_b32_e32 v96, 2, v48
	v_lshlrev_b32_e32 v97, 2, v50
	v_lshlrev_b32_e32 v98, 2, v52
	global_load_dword v91, v91, s[10:11]
	s_nop 0
	global_load_dword v92, v92, s[10:11]
	s_nop 0
	global_load_dword v93, v93, s[10:11]
	s_nop 0
	global_load_dword v94, v94, s[10:11]
	s_nop 0
	global_load_dword v95, v95, s[10:11]
	s_nop 0
	global_load_dword v96, v96, s[10:11]
	s_nop 0
	global_load_dword v97, v97, s[10:11]
	s_nop 0
	global_load_dword v98, v98, s[10:11]
	v_lshlrev_b32_e32 v99, 2, v54
	v_lshlrev_b32_e32 v100, 2, v56
	v_lshlrev_b32_e32 v101, 2, v58
	v_lshlrev_b32_e32 v102, 2, v60
	v_lshlrev_b32_e32 v103, 2, v62
	v_lshlrev_b32_e32 v104, 2, v64
	v_lshlrev_b32_e32 v105, 2, v66
	v_lshlrev_b32_e32 v106, 2, v68
	global_load_dword v99, v99, s[10:11]
	s_nop 0
	global_load_dword v100, v100, s[10:11]
	s_nop 0
	global_load_dword v101, v101, s[10:11]
	s_nop 0
	global_load_dword v102, v102, s[10:11]
	s_nop 0
	global_load_dword v103, v103, s[10:11]
	s_nop 0
	global_load_dword v104, v104, s[10:11]
	s_nop 0
	global_load_dword v105, v105, s[10:11]
	s_nop 0
	global_load_dword v106, v106, s[10:11]
	v_lshlrev_b32_e32 v107, 2, v70
	v_lshlrev_b32_e32 v108, 2, v72
	v_lshlrev_b32_e32 v109, 2, v74
	v_lshlrev_b32_e32 v110, 2, v76
	v_lshlrev_b32_e32 v111, 2, v78
	v_lshlrev_b32_e32 v112, 2, v80
	v_lshlrev_b32_e32 v113, 2, v82
	v_lshlrev_b32_e32 v114, 2, v84
	global_load_dword v107, v107, s[10:11]
	s_nop 0
	global_load_dword v108, v108, s[10:11]
	s_nop 0
	global_load_dword v109, v109, s[10:11]
	s_nop 0
	global_load_dword v110, v110, s[10:11]
	s_nop 0
	global_load_dword v111, v111, s[10:11]
	s_nop 0
	global_load_dword v112, v112, s[10:11]
	s_nop 0
	global_load_dword v113, v113, s[10:11]
	s_nop 0
	global_load_dword v114, v114, s[10:11]
	v_add_u32_e32 v115, v185, v179
	s_cmpk_lt_u32 s8, 0x580
	s_mov_b32 s5, 0x2e00000
	s_cselect_b32 s5, 0xb00000, s5
	s_add_u32 s5, s26, s5
	s_addc_u32 s8, s27, 0
	s_mul_i32 s17, s17, 0x2c000
	s_mul_hi_i32 s4, s4, 0x1600
	s_add_u32 s5, s5, s17
	s_addc_u32 s4, s8, s4
	s_lshl_b64 s[0:1], s[0:1], 1
	s_add_u32 s0, s5, s0
	s_addc_u32 s1, s4, s1
	v_lshlrev_b32_e32 v196, 1, v0
	v_readlane_b32 s41, v254, 58
	v_readlane_b32 s42, v254, 59
	v_readlane_b32 s43, v254, 60
	v_readlane_b32 s46, v254, 63
	v_readlane_b32 s47, v255, 0
	v_readlane_b32 s48, v255, 1
	v_readlane_b32 s49, v255, 2
	v_readlane_b32 s50, v255, 3
	v_readlane_b32 s51, v255, 4
	v_readlane_b32 s52, v255, 5
	v_readlane_b32 s53, v255, 6
	v_readlane_b32 s54, v255, 7
	v_readlane_b32 s55, v255, 8
	s_waitcnt vmcnt(30)
; #define LAS __attribute__((address_space(3)))
; __device__ __forceinline__ unsigned pk2(float lo, float hi) { return pg8::cvt_pk_bf16(lo, hi); }
; __device__ __forceinline__ void transpose_tile(const float* src, int srcN, const float* gk, bf16_t* dst, int dstK, LAS float* scr, int lane) {
;     ...
;     for (int i = 0; i < 32; ++i) scr[(2 * i + (lane >> 5)) * 33 + (lane & 31)] = tv[i];
;     asm volatile("s_waitcnt lgkmcnt(0)" ::: "memory");
;     const int c = lane & 7;
; #pragma unroll
;     for (int j = 0; j < 4; ++j) {
;         const int n = (lane >> 3) + 8 * j; const LAS float* s = scr + (8 * c) * 33 + n;
;         u32x4 o; o.x = pk2(s[0 * 33], s[1 * 33]); o.y = pk2(s[2 * 33], s[3 * 33]); o.z = pk2(s[4 * 33], s[5 * 33]); o.w = pk2(s[6 * 33], s[7 * 33]);
;         *(u32x4*)(dst + (size_t)n * dstK + 8 * c) = o;
;     }
;     asm volatile("s_waitcnt lgkmcnt(0)" ::: "memory");
	ds_write2_b32 v115, v5, v7 offset1:66
	s_waitcnt vmcnt(28)
	ds_write2_b32 v115, v9, v11 offset0:132 offset1:198
	v_add_u32_e32 v5, 0x400, v115
	s_waitcnt vmcnt(26)
	ds_write2_b32 v5, v13, v88 offset0:8 offset1:74
	v_add_u32_e32 v5, v185, v180
	s_waitcnt vmcnt(24)
	ds_write2_b32 v5, v89, v90 offset1:66
	s_waitcnt vmcnt(22)
	ds_write2_b32 v5, v91, v92 offset0:132 offset1:198
	v_add_u32_e32 v5, 0x400, v5
	s_waitcnt vmcnt(20)
	ds_write2_b32 v5, v93, v94 offset0:8 offset1:74
	v_add_u32_e32 v5, v185, v181
	s_waitcnt vmcnt(18)
	ds_write2_b32 v5, v95, v96 offset1:66
	s_waitcnt vmcnt(16)
	ds_write2_b32 v5, v97, v98 offset0:132 offset1:198
	v_add_u32_e32 v5, 0x400, v5
	v_mov_b32_e32 v13, v197
	s_waitcnt vmcnt(14)
	ds_write2_b32 v5, v99, v100 offset0:8 offset1:74
	v_add_u32_e32 v5, v185, v182
	s_waitcnt vmcnt(12)
	ds_write2_b32 v5, v101, v102 offset1:66
	s_waitcnt vmcnt(10)
	ds_write2_b32 v5, v103, v104 offset0:132 offset1:198
	v_add_u32_e32 v5, 0x400, v5
	s_waitcnt vmcnt(8)
	ds_write2_b32 v5, v105, v106 offset0:8 offset1:74
	v_add_u32_e32 v5, v185, v183
	s_waitcnt vmcnt(6)
	ds_write2_b32 v5, v107, v108 offset1:66
	s_waitcnt vmcnt(4)
	ds_write2_b32 v5, v109, v110 offset0:132 offset1:198
	v_add_u32_e32 v5, 0x400, v5
	s_waitcnt vmcnt(2)
	ds_write2_b32 v5, v111, v112 offset0:8 offset1:74
	s_waitcnt vmcnt(0)
	ds_write2_b32 v5, v113, v114 offset0:140 offset1:206
	s_waitcnt lgkmcnt(0)
	ds_read2_b32 v[92:93], v1 offset0:33 offset1:41
	ds_read2_b32 v[94:95], v1 offset1:8
	ds_read2_b32 v[96:97], v1 offset0:66 offset1:74
	ds_read2_b32 v[98:99], v1 offset0:99 offset1:107
	ds_read2_b32 v[100:101], v1 offset0:132 offset1:140
	ds_read2_b32 v[102:103], v1 offset0:165 offset1:173
	ds_read2_b32 v[104:105], v1 offset0:198 offset1:206
	ds_read2_b32 v[106:107], v1 offset0:231 offset1:239
	v_lshl_add_u64 v[108:109], s[0:1], 0, v[196:197]
	s_waitcnt lgkmcnt(6)
	v_cvt_pk_bf16_f32 v88, v94, v92
	s_waitcnt lgkmcnt(4)
	v_cvt_pk_bf16_f32 v89, v96, v98
	s_waitcnt lgkmcnt(2)
	v_cvt_pk_bf16_f32 v90, v100, v102
	s_waitcnt lgkmcnt(0)
	v_cvt_pk_bf16_f32 v91, v104, v106
	v_lshl_add_u64 v[108:109], v[108:109], 0, v[12:13]
	global_store_dwordx4 v[108:109], v[88:91], off sc1
	s_mov_b32 s0, 0xb000
	v_add_co_u32_e32 v92, vcc, s0, v108
	v_cvt_pk_bf16_f32 v88, v95, v93
	v_cvt_pk_bf16_f32 v89, v97, v99
	v_cvt_pk_bf16_f32 v90, v101, v103
	v_cvt_pk_bf16_f32 v91, v105, v107
	ds_read2_b32 v[94:95], v1 offset0:49 offset1:57
	ds_read2_b32 v[96:97], v1 offset0:16 offset1:24
	ds_read2_b32 v[98:99], v1 offset0:82 offset1:90
	ds_read2_b32 v[100:101], v1 offset0:115 offset1:123
	ds_read2_b32 v[102:103], v1 offset0:148 offset1:156
	ds_read2_b32 v[104:105], v1 offset0:181 offset1:189
	ds_read2_b32 v[106:107], v1 offset0:214 offset1:222
	ds_read2_b32 v[110:111], v1 offset0:247 offset1:255
	v_addc_co_u32_e32 v93, vcc, 0, v109, vcc
	s_mov_b32 s0, 0x16000
	global_store_dwordx4 v[92:93], v[88:91], off sc1
	v_add_co_u32_e32 v92, vcc, s0, v108
	s_waitcnt lgkmcnt(6)
	v_cvt_pk_bf16_f32 v88, v96, v94
	s_waitcnt lgkmcnt(4)
	v_cvt_pk_bf16_f32 v89, v98, v100
	s_waitcnt lgkmcnt(2)
	v_cvt_pk_bf16_f32 v90, v102, v104
	s_waitcnt lgkmcnt(0)
	v_cvt_pk_bf16_f32 v91, v106, v110
	v_addc_co_u32_e32 v93, vcc, 0, v109, vcc
	global_store_dwordx4 v[92:93], v[88:91], off sc1
	v_add_co_u32_e32 v92, vcc, 0x21000, v108
	s_nop 0
	v_cvt_pk_bf16_f32 v88, v97, v95
	v_cvt_pk_bf16_f32 v89, v99, v101
	v_cvt_pk_bf16_f32 v90, v103, v105
	v_cvt_pk_bf16_f32 v91, v107, v111
	v_addc_co_u32_e32 v93, vcc, 0, v109, vcc
	global_store_dwordx4 v[92:93], v[88:91], off sc1
	s_waitcnt lgkmcnt(0)
